# plus B/C epilogue gate loads hoisted (4 loads per row block issued together, one wait)
# speedup vs baseline: 1.0158x; 1.0033x over previous
; template <bool FIXM>
; __device__ __forceinline__ void partialSM(f32x16& p0, f32x16& p1, float& m_reg, float& mn, float& alpha, const float C, const float thrS, const int kb, const int hi) {
;   if constexpr (FIXM) {
; #pragma unroll
;     for (int r = 0; r < 16; ++r) p0[r] = __builtin_amdgcn_exp2f(p0[r]);
;     if (kb + KVBLK > LROWS) {
; #pragma unroll
;       for (int r = 0; r < 16; ++r) { if (kb + crow(r, hi) >= LROWS) p0[r] = 0.f; }
;     }
;     return;
;   }
;   if (kb + KVBLK > LROWS) {
; #pragma unroll
;     for (int r = 0; r < 16; ++r) { const int k0 = kb + crow(r, hi); if (k0 >= LROWS) p0[r] = -1e30f; if (k0 + 32 >= LROWS) p1[r] = -1e30f; }
;   }
;   float pmax = p0[0];
; #pragma unroll
;   for (int r = 1; r < 16; ++r) pmax = fmaxf(pmax, p0[r]);
; #pragma unroll
;   for (int r = 0; r < 16; ++r) pmax = fmaxf(pmax, p1[r]);
;   { auto rr = __builtin_amdgcn_permlane32_swap(__float_as_uint(pmax), __float_as_uint(pmax), false, false);
;     pmax = fmaxf(__uint_as_float(rr[0]), __uint_as_float(rr[1])); }
;   if (__builtin_expect(__all(pmax - m_reg <= thrS), 1)) { mn = m_reg; alpha = 1.f; }
;   else { mn = fmaxf(m_reg, pmax); alpha = __builtin_amdgcn_exp2f((m_reg - mn) * C); m_reg = mn; }
;   const float mnC = -mn * C;
; #pragma unroll
;   for (int r = 0; r < 16; ++r) p0[r] = fmaf(p0[r], C, mnC);
; #pragma unroll
;   for (int r = 0; r < 16; ++r) p1[r] = fmaf(p1[r], C, mnC);
; #pragma unroll
;   for (int r = 0; r < 16; ++r) p0[r] = __builtin_amdgcn_exp2f(p0[r]);
; }
; template <bool FIXM>
; __device__ __forceinline__ void finishSM(f32x16& p0, f32x16& p1, float alpha, float& l_reg, bf16x8& pa0, bf16x8& pa1, bf16x8& pa2, bf16x8& pa3, const int kb, const int hi) {
; #pragma unroll
;   for (int r = 0; r < 16; ++r) p1[r] = __builtin_amdgcn_exp2f(p1[r]);
;   if constexpr (FIXM) { if (kb + KVBLK > LROWS) {
; #pragma unroll
;     for (int r = 0; r < 16; ++r) { if (kb + 32 + crow(r, hi) >= LROWS) p1[r] = 0.f; } } }
;   float ps = 0;
; #pragma unroll
;   for (int r = 0; r < 16; ++r) ps += p0[r];
; #pragma unroll
;   for (int r = 0; r < 16; ++r) ps += p1[r];
;   if constexpr (FIXM) l_reg += ps; else l_reg = l_reg * alpha + ps;
;     ...
;   PK4(p0, 0, pa0); PK4(p0, 8, pa1); PK4(p1, 0, pa2); PK4(p1, 8, pa3);
; template <int DQK>
; __device__ __forceinline__ void qkt(f32x16& p0, f32x16& p1, const char* Ks, const bf16x8* qr, int r32, int hi) {
;     ...
; #pragma unroll
.LBB0_539:
	s_waitcnt lgkmcnt(0)
	s_barrier
	s_and_b32 s12, s7, 0x4000
	s_add_i32 s18, s6, s12
	v_add_u32_e32 v194, s12, v153
	v_add3_u32 v230, s18, v162, v154
	ds_read_b128 v[172:175], v230
	v_add3_u32 v231, s18, v161, v154
	ds_read_b128 v[176:179], v231
	v_add3_u32 v232, s18, v160, v154
	ds_read_b128 v[214:217], v232
	v_add3_u32 v233, s18, v159, v154
	ds_read_b128 v[218:221], v233
	v_add3_u32 v230, s18, v158, v154
	ds_read_b128 v[222:225], v230
	v_add3_u32 v231, s18, v157, v154
	ds_read_b128 v[226:229], v231
	s_waitcnt lgkmcnt(5)
	v_mfma_f32_32x32x16_bf16 v[80:95], v[172:175], v[128:131], 0
	v_add3_u32 v232, s18, v156, v154
	ds_read_b128 v[172:175], v232
	s_waitcnt lgkmcnt(5)
	v_mfma_f32_32x32x16_bf16 v[80:95], v[176:179], v[124:127], v[80:95]
	v_add3_u32 v233, s18, v155, v154
	ds_read_b128 v[176:179], v233
	s_waitcnt lgkmcnt(5)
	v_mfma_f32_32x32x16_bf16 v[80:95], v[214:217], v[120:123], v[80:95]
	v_add3_u32 v230, s18, v162, v154
	ds_read_b128 v[214:217], v230 offset:8192
	s_waitcnt lgkmcnt(5)
	v_mfma_f32_32x32x16_bf16 v[80:95], v[218:221], v[116:119], v[80:95]
	v_add3_u32 v231, s18, v161, v154
	ds_read_b128 v[218:221], v231 offset:8192
	s_waitcnt lgkmcnt(5)
	v_mfma_f32_32x32x16_bf16 v[80:95], v[222:225], v[112:115], v[80:95]
	v_add3_u32 v232, s18, v160, v154
	ds_read_b128 v[222:225], v232 offset:8192
	s_waitcnt lgkmcnt(5)
	v_mfma_f32_32x32x16_bf16 v[80:95], v[226:229], v[108:111], v[80:95]
	v_add3_u32 v233, s18, v159, v154
	ds_read_b128 v[226:229], v233 offset:8192
	s_waitcnt lgkmcnt(5)
	v_mfma_f32_32x32x16_bf16 v[80:95], v[172:175], v[104:107], v[80:95]
	v_add3_u32 v230, s18, v158, v154
	ds_read_b128 v[172:175], v230 offset:8192
	s_waitcnt lgkmcnt(5)
	v_mfma_f32_32x32x16_bf16 v[80:95], v[176:179], v[100:103], v[80:95]
	v_add3_u32 v231, s18, v157, v154
	ds_read_b128 v[176:179], v231 offset:8192
	s_waitcnt lgkmcnt(5)
	v_mfma_f32_32x32x16_bf16 v[64:79], v[214:217], v[128:131], 0
	v_add3_u32 v232, s18, v156, v154
	ds_read_b128 v[214:217], v232 offset:8192
	s_waitcnt lgkmcnt(5)
	v_mfma_f32_32x32x16_bf16 v[64:79], v[218:221], v[124:127], v[64:79]
	v_add3_u32 v233, s18, v155, v154
	ds_read_b128 v[218:221], v233 offset:8192
	s_xor_b32 s18, s12, 0x4000
	s_waitcnt lgkmcnt(5)
	v_mfma_f32_32x32x16_bf16 v[64:79], v[222:225], v[120:123], v[64:79]
	ds_read_b64_tr_b16 v[222:223], v194 offset:0x0
	ds_read_b64_tr_b16 v[224:225], v194 offset:0x800
	v_exp_f32_e32 v80, v80
	v_exp_f32_e32 v81, v81
	v_add_f32_e32 v195, 0, v80
	v_exp_f32_e32 v82, v82
	v_add_f32_e32 v195, v81, v195
	v_exp_f32_e32 v83, v83
	s_waitcnt lgkmcnt(6)
	v_mfma_f32_32x32x16_bf16 v[64:79], v[226:229], v[116:119], v[64:79]
	ds_read_b64_tr_b16 v[226:227], v194 offset:0x1000
	ds_read_b64_tr_b16 v[228:229], v194 offset:0x1800
	v_add_f32_e32 v195, v82, v195
	v_exp_f32_e32 v84, v84
	v_add_f32_e32 v195, v83, v195
	v_exp_f32_e32 v85, v85
	v_add_f32_e32 v195, v84, v195
	v_exp_f32_e32 v86, v86
	s_waitcnt lgkmcnt(7)
	v_mfma_f32_32x32x16_bf16 v[64:79], v[172:175], v[112:115], v[64:79]
	ds_read_b64_tr_b16 v[172:173], v194 offset:0x200
	ds_read_b64_tr_b16 v[174:175], v194 offset:0xa00
	v_add_f32_e32 v195, v85, v195
	v_exp_f32_e32 v87, v87
	v_add_f32_e32 v195, v86, v195
	v_exp_f32_e32 v88, v88
	v_add_f32_e32 v195, v87, v195
	v_exp_f32_e32 v89, v89
	s_waitcnt lgkmcnt(8)
	v_mfma_f32_32x32x16_bf16 v[64:79], v[176:179], v[108:111], v[64:79]
	ds_read_b64_tr_b16 v[176:177], v194 offset:0x1200
	ds_read_b64_tr_b16 v[178:179], v194 offset:0x1a00
	v_add_f32_e32 v195, v88, v195
	v_exp_f32_e32 v90, v90
	v_add_f32_e32 v195, v89, v195
	v_exp_f32_e32 v91, v91
	v_add_f32_e32 v195, v90, v195
	v_exp_f32_e32 v92, v92
	s_waitcnt lgkmcnt(9)
	v_mfma_f32_32x32x16_bf16 v[64:79], v[214:217], v[104:107], v[64:79]
	ds_read_b64_tr_b16 v[214:215], v194 offset:0x400
	ds_read_b64_tr_b16 v[216:217], v194 offset:0xc00
	v_add_f32_e32 v195, v91, v195
	v_exp_f32_e32 v93, v93
	v_add_f32_e32 v195, v92, v195
	v_exp_f32_e32 v94, v94
	v_add_f32_e32 v195, v93, v195
	v_exp_f32_e32 v95, v95
	s_waitcnt lgkmcnt(10)
	v_mfma_f32_32x32x16_bf16 v[64:79], v[218:221], v[100:103], v[64:79]
	ds_read_b64_tr_b16 v[218:219], v194 offset:0x1400
	ds_read_b64_tr_b16 v[220:221], v194 offset:0x1c00
	v_add_f32_e32 v195, v94, v195
	s_nop 0
	v_add_f32_e32 v195, v95, v195
	v_cvt_pk_bf16_f32 v80, v80, v81
	v_cvt_pk_bf16_f32 v81, v82, v83
	v_cvt_pk_bf16_f32 v82, v84, v85
	v_cvt_pk_bf16_f32 v83, v86, v87
	v_cvt_pk_bf16_f32 v84, v88, v89
	v_cvt_pk_bf16_f32 v85, v90, v91
	v_cvt_pk_bf16_f32 v86, v92, v93
	v_cvt_pk_bf16_f32 v87, v94, v95
	s_nop 1
	s_waitcnt lgkmcnt(10)
	v_mfma_f32_32x32x16_bf16 v[48:63], v[80:83], v[222:225], v[48:63]
	ds_read_b64_tr_b16 v[222:223], v194 offset:0x600
	ds_read_b64_tr_b16 v[224:225], v194 offset:0xe00
	v_exp_f32_e32 v64, v64
	v_exp_f32_e32 v65, v65
	v_add_f32_e32 v195, v64, v195
	s_waitcnt lgkmcnt(10)
	v_mfma_f32_32x32x16_bf16 v[48:63], v[84:87], v[226:229], v[48:63]
	ds_read_b64_tr_b16 v[226:227], v194 offset:0x1600
	ds_read_b64_tr_b16 v[228:229], v194 offset:0x1e00
	v_exp_f32_e32 v66, v66
	v_add_f32_e32 v195, v65, v195
	v_exp_f32_e32 v67, v67
	v_add_f32_e32 v195, v66, v195
	s_waitcnt lgkmcnt(10)
	v_mfma_f32_32x32x16_bf16 v[32:47], v[80:83], v[172:175], v[32:47]
	ds_read_b64_tr_b16 v[172:173], v194 offset:0x2000
	ds_read_b64_tr_b16 v[174:175], v194 offset:0x2800
	v_exp_f32_e32 v68, v68
	v_add_f32_e32 v195, v67, v195
	v_exp_f32_e32 v69, v69
	v_add_f32_e32 v195, v68, v195
	s_waitcnt lgkmcnt(10)
	v_mfma_f32_32x32x16_bf16 v[32:47], v[84:87], v[176:179], v[32:47]
	ds_read_b64_tr_b16 v[176:177], v194 offset:0x3000
	ds_read_b64_tr_b16 v[178:179], v194 offset:0x3800
	v_exp_f32_e32 v70, v70
	v_add_f32_e32 v195, v69, v195
	v_exp_f32_e32 v71, v71
	v_add_f32_e32 v195, v70, v195
	s_waitcnt lgkmcnt(10)
; #define SBAR() __builtin_amdgcn_sched_barrier(0)
; template <int DQK>
; __device__ __forceinline__ void qkt(f32x16& p0, f32x16& p1, const char* Ks, const bf16x8* qr, int r32, int hi) {
;     ...
; #pragma unroll
;   for (int d0 = 0; d0 < DQK / 16; ++d0) { const int cb = (d0 * 16 + hi * 8) * 2;
;     bf16x8 b0 = *reinterpret_cast<const bf16x8*>(Ks + KSWZ(KP, r32, cb));
;     bf16x8 b1 = *reinterpret_cast<const bf16x8*>(Ks + KSWZ(KP, 32 + r32, cb));
;     p0 = __builtin_amdgcn_mfma_f32_32x32x16_bf16(b0, qr[d0], p0, 0, 0, 0);
;     p1 = __builtin_amdgcn_mfma_f32_32x32x16_bf16(b1, qr[d0], p1, 0, 0, 0); }
; }
; __device__ __forceinline__ int v_st(int k, int c) { const int kk = k; return ((kk >> 3) * 4 + (c >> 5)) * 512 + ((kk & 7) * 32 + (c & 31)) * 2; }
; __device__ __forceinline__ int v_rd_base(int lane) { return ((lane & 3) << 3) | (((lane >> 2) & 3) << 6) | (((lane >> 4) & 1) << 5) | (((lane >> 5) & 1) << 8); }
; template <int OFF> __device__ __forceinline__ s16x4 tr_read(int vb) {
;   s16x4 r; asm volatile("ds_read_b64_tr_b16 %0, %1 offset:%2" : "=&v"(r) : "v"(vb), "i"(OFF) : "memory"); return r;
; }
; template <int D0> __device__ __forceinline__ void pv_one(f32x16& od, int vb, bf16x8 pa0, bf16x8 pa1, bf16x8 pa2, bf16x8 pa3) {
;   const s16x4 l0 = tr_read<v_rd_off(D0, 0, 0)>(vb), h0 = tr_read<v_rd_off(D0, 0, 1)>(vb), l1 = tr_read<v_rd_off(D0, 1, 0)>(vb), h1 = tr_read<v_rd_off(D0, 1, 1)>(vb);
;   const s16x4 l2 = tr_read<v_rd_off(D0, 2, 0)>(vb), h2 = tr_read<v_rd_off(D0, 2, 1)>(vb), l3 = tr_read<v_rd_off(D0, 3, 0)>(vb), h3 = tr_read<v_rd_off(D0, 3, 1)>(vb);
;   asm volatile("s_waitcnt lgkmcnt(0)" ::: "memory"); SBAR();
;     ...
;   od = __builtin_amdgcn_mfma_f32_32x32x16_bf16(pa0, PK(l0, h0), od, 0, 0, 0);
;   od = __builtin_amdgcn_mfma_f32_32x32x16_bf16(pa1, PK(l1, h1), od, 0, 0, 0);
;   od = __builtin_amdgcn_mfma_f32_32x32x16_bf16(pa2, PK(l2, h2), od, 0, 0, 0);
;   od = __builtin_amdgcn_mfma_f32_32x32x16_bf16(pa3, PK(l3, h3), od, 0, 0, 0);
;     ...
; }
; __device__ __forceinline__ void pv_d0(f32x16* o, int vb, bf16x8 pa0, bf16x8 pa1, bf16x8 pa2, bf16x8 pa3) {
;   pv_one<0>(o[0], vb, pa0, pa1, pa2, pa3); pv_one<1>(o[1], vb, pa0, pa1, pa2, pa3); pv_one<2>(o[2], vb, pa0, pa1, pa2, pa3); pv_one<3>(o[3], vb, pa0, pa1, pa2, pa3);
; }
; __device__ __forceinline__ float bf2f(unsigned short b) { return __uint_as_float((unsigned)b << 16); }
	v_mfma_f32_32x32x16_bf16 v[16:31], v[80:83], v[214:217], v[16:31]
	ds_read_b64_tr_b16 v[214:215], v194 offset:0x2200
	ds_read_b64_tr_b16 v[216:217], v194 offset:0x2a00
	v_exp_f32_e32 v72, v72
	v_add_f32_e32 v195, v71, v195
	v_exp_f32_e32 v73, v73
	v_add_f32_e32 v195, v72, v195
	s_waitcnt lgkmcnt(10)
	v_mfma_f32_32x32x16_bf16 v[16:31], v[84:87], v[218:221], v[16:31]
	ds_read_b64_tr_b16 v[218:219], v194 offset:0x3200
	ds_read_b64_tr_b16 v[220:221], v194 offset:0x3a00
	v_exp_f32_e32 v74, v74
	v_add_f32_e32 v195, v73, v195
	v_exp_f32_e32 v75, v75
	v_add_f32_e32 v195, v74, v195
	s_waitcnt lgkmcnt(10)
	v_mfma_f32_32x32x16_bf16 v[0:15], v[80:83], v[222:225], v[0:15]
	ds_read_b64_tr_b16 v[222:223], v194 offset:0x2400
	ds_read_b64_tr_b16 v[224:225], v194 offset:0x2c00
	v_exp_f32_e32 v76, v76
	v_add_f32_e32 v195, v75, v195
	v_exp_f32_e32 v77, v77
	v_add_f32_e32 v195, v76, v195
	s_waitcnt lgkmcnt(10)
	v_mfma_f32_32x32x16_bf16 v[0:15], v[84:87], v[226:229], v[0:15]
	ds_read_b64_tr_b16 v[226:227], v194 offset:0x3400
	ds_read_b64_tr_b16 v[228:229], v194 offset:0x3c00
	v_exp_f32_e32 v78, v78
	v_add_f32_e32 v195, v77, v195
	v_exp_f32_e32 v79, v79
	v_add_f32_e32 v195, v78, v195
	v_add_f32_e32 v195, v79, v195
	v_cvt_pk_bf16_f32 v64, v64, v65
	v_cvt_pk_bf16_f32 v65, v66, v67
	v_cvt_pk_bf16_f32 v66, v68, v69
	v_cvt_pk_bf16_f32 v67, v70, v71
	v_cvt_pk_bf16_f32 v68, v72, v73
	v_cvt_pk_bf16_f32 v69, v74, v75
	v_cvt_pk_bf16_f32 v70, v76, v77
	v_cvt_pk_bf16_f32 v71, v78, v79
	v_add_f32_e32 v187, v187, v195
	s_nop 0
	s_waitcnt lgkmcnt(10)
	v_mfma_f32_32x32x16_bf16 v[48:63], v[64:67], v[172:175], v[48:63]
	ds_read_b64_tr_b16 v[172:173], v194 offset:0x2600
	ds_read_b64_tr_b16 v[174:175], v194 offset:0x2e00
	s_waitcnt lgkmcnt(10)
	v_mfma_f32_32x32x16_bf16 v[48:63], v[68:71], v[176:179], v[48:63]
	ds_read_b64_tr_b16 v[176:177], v194 offset:0x3600
	ds_read_b64_tr_b16 v[178:179], v194 offset:0x3e00
	s_add_i32 s19, s18, 0
	v_add_u32_e32 v213, s19, v192
	s_waitcnt vmcnt(3)
	ds_write_b128 v213, v[136:139]
	s_waitcnt lgkmcnt(11)
	v_mfma_f32_32x32x16_bf16 v[32:47], v[64:67], v[214:217], v[32:47]
	v_add_u32_e32 v213, s19, v193
	s_add_i32 s18, s6, s18
	s_waitcnt vmcnt(2)
	ds_write_b128 v213, v[132:135]
	s_waitcnt lgkmcnt(10)
	v_mfma_f32_32x32x16_bf16 v[32:47], v[68:71], v[218:221], v[32:47]
	v_add_u32_e32 v213, s18, v163
	s_waitcnt vmcnt(1)
	ds_write_b128 v213, v[144:147]
	s_waitcnt lgkmcnt(9)
	v_mfma_f32_32x32x16_bf16 v[16:31], v[64:67], v[222:225], v[16:31]
	v_add_u32_e32 v213, s18, v164
	s_waitcnt vmcnt(0)
	ds_write_b128 v213, v[140:143]
	s_waitcnt lgkmcnt(8)
	v_mfma_f32_32x32x16_bf16 v[16:31], v[68:71], v[226:229], v[16:31]
	s_mov_b32 s38, s30
	s_mov_b32 s39, s31
	buffer_load_dwordx4 v[136:139], v165, s[28:31], s2 offen
	buffer_load_dwordx4 v[132:135], v166, s[28:31], s2 offen
	s_waitcnt lgkmcnt(6)
	v_mfma_f32_32x32x16_bf16 v[0:15], v[64:67], v[172:175], v[0:15]
	buffer_load_dwordx4 v[144:147], v167, s[36:39], s2 offen
	buffer_load_dwordx4 v[140:143], v186, s[36:39], s2 offen
	s_add_i32 s2, s2, 0xb8000
	s_addk_i32 s7, 0x4000
	s_cmp_eq_u32 s2, 0xb8b8000
	s_waitcnt lgkmcnt(4)
	v_mfma_f32_32x32x16_bf16 v[0:15], v[68:71], v[176:179], v[0:15]
	s_cbranch_scc0 .LBB0_539
	s_waitcnt lgkmcnt(0)
	s_barrier
	s_add_i32 s2, 0, 0x14000
	v_add3_u32 v68, s2, v162, v154
	ds_read_b128 v[64:67], v68
	v_add3_u32 v163, s2, v161, v154
	ds_read_b128 v[164:167], v163
	s_waitcnt lgkmcnt(1)
	v_mfma_f32_32x32x16_bf16 v[80:95], v[64:67], v[128:131], 0
	ds_read_b128 v[64:67], v68 offset:8192
	s_waitcnt lgkmcnt(1)
	v_mfma_f32_32x32x16_bf16 v[80:95], v[164:167], v[124:127], v[80:95]
	ds_read_b128 v[164:167], v163 offset:8192
	v_add3_u32 v163, s2, v160, v154
	s_waitcnt lgkmcnt(1)
	v_mfma_f32_32x32x16_bf16 v[64:79], v[64:67], v[128:131], 0
	s_waitcnt lgkmcnt(0)
	v_mfma_f32_32x32x16_bf16 v[64:79], v[164:167], v[124:127], v[64:79]
	ds_read_b128 v[164:167], v163
	s_waitcnt lgkmcnt(0)
	v_mfma_f32_32x32x16_bf16 v[80:95], v[164:167], v[120:123], v[80:95]
	ds_read_b128 v[164:167], v163 offset:8192
	v_add3_u32 v163, s2, v159, v154
	s_waitcnt lgkmcnt(0)
	v_mfma_f32_32x32x16_bf16 v[64:79], v[164:167], v[120:123], v[64:79]
	ds_read_b128 v[164:167], v163
	s_waitcnt lgkmcnt(0)
	v_mfma_f32_32x32x16_bf16 v[80:95], v[164:167], v[116:119], v[80:95]
	ds_read_b128 v[164:167], v163 offset:8192
	v_add3_u32 v163, s2, v158, v154
	s_waitcnt lgkmcnt(0)
	v_mfma_f32_32x32x16_bf16 v[64:79], v[164:167], v[116:119], v[64:79]
	ds_read_b128 v[164:167], v163
	s_waitcnt lgkmcnt(0)
	v_mfma_f32_32x32x16_bf16 v[80:95], v[164:167], v[112:115], v[80:95]
	ds_read_b128 v[164:167], v163 offset:8192
	v_add3_u32 v163, s2, v157, v154
	s_waitcnt lgkmcnt(0)
	v_mfma_f32_32x32x16_bf16 v[64:79], v[164:167], v[112:115], v[64:79]
	ds_read_b128 v[164:167], v163
	s_waitcnt lgkmcnt(0)
	v_mfma_f32_32x32x16_bf16 v[80:95], v[164:167], v[108:111], v[80:95]
	ds_read_b128 v[164:167], v163 offset:8192
	v_add3_u32 v163, s2, v156, v154
	s_waitcnt lgkmcnt(0)
	v_mfma_f32_32x32x16_bf16 v[64:79], v[164:167], v[108:111], v[64:79]
	ds_read_b128 v[164:167], v163
	s_waitcnt lgkmcnt(0)
	v_mfma_f32_32x32x16_bf16 v[80:95], v[164:167], v[104:107], v[80:95]
	ds_read_b128 v[164:167], v163 offset:8192
	v_add3_u32 v163, s2, v155, v154
	s_waitcnt lgkmcnt(0)
	v_mfma_f32_32x32x16_bf16 v[64:79], v[164:167], v[104:107], v[64:79]
	ds_read_b128 v[164:167], v163
	s_waitcnt lgkmcnt(0)
	v_mfma_f32_32x32x16_bf16 v[80:95], v[164:167], v[100:103], v[80:95]
	ds_read_b128 v[164:167], v163 offset:8192
	s_waitcnt lgkmcnt(0)
	v_mfma_f32_32x32x16_bf16 v[64:79], v[164:167], v[100:103], v[64:79]
	s_waitcnt vmcnt(3)
	ds_write_b128 v188, v[136:139]
	s_waitcnt vmcnt(2)
	ds_write_b128 v189, v[132:135]
	s_waitcnt vmcnt(1)
; #define SBAR() __builtin_amdgcn_sched_barrier(0)
; __device__ __forceinline__ int crow(int r, int hi) { return (r & 3) + 8 * (r >> 2) + 4 * hi; }
; template <bool FIXM>
; __device__ __forceinline__ void finishSM(f32x16& p0, f32x16& p1, float alpha, float& l_reg, bf16x8& pa0, bf16x8& pa1, bf16x8& pa2, bf16x8& pa3, const int kb, const int hi) {
; #pragma unroll
;   for (int r = 0; r < 16; ++r) p1[r] = __builtin_amdgcn_exp2f(p1[r]);
;   if constexpr (FIXM) { if (kb + KVBLK > LROWS) {
; #pragma unroll
;     for (int r = 0; r < 16; ++r) { if (kb + 32 + crow(r, hi) >= LROWS) p1[r] = 0.f; } } }
;   float ps = 0;
; #pragma unroll
;   for (int r = 0; r < 16; ++r) ps += p0[r];
; #pragma unroll
;   for (int r = 0; r < 16; ++r) ps += p1[r];
;   if constexpr (FIXM) l_reg += ps; else l_reg = l_reg * alpha + ps;
;     ...
;   PK4(p0, 0, pa0); PK4(p0, 8, pa1); PK4(p1, 0, pa2); PK4(p1, 8, pa3);
; template <int D0> __device__ __forceinline__ void v_issue(VF& f, int vb) {
;   f.l0 = tr_read<v_rd_off(D0, 0, 0)>(vb); f.h0 = tr_read<v_rd_off(D0, 0, 1)>(vb); f.l1 = tr_read<v_rd_off(D0, 1, 0)>(vb); f.h1 = tr_read<v_rd_off(D0, 1, 1)>(vb);
;   f.l2 = tr_read<v_rd_off(D0, 2, 0)>(vb); f.h2 = tr_read<v_rd_off(D0, 2, 1)>(vb); f.l3 = tr_read<v_rd_off(D0, 3, 0)>(vb); f.h3 = tr_read<v_rd_off(D0, 3, 1)>(vb);
; }
; __device__ __forceinline__ void pv_mma(f32x16& od, const VF& f, bf16x8 pa0, bf16x8 pa1, bf16x8 pa2, bf16x8 pa3) {
;     ...
;   od = __builtin_amdgcn_mfma_f32_32x32x16_bf16(pa0, PK(f.l0, f.h0), od, 0, 0, 0);
;   od = __builtin_amdgcn_mfma_f32_32x32x16_bf16(pa1, PK(f.l1, f.h1), od, 0, 0, 0);
;   od = __builtin_amdgcn_mfma_f32_32x32x16_bf16(pa2, PK(f.l2, f.h2), od, 0, 0, 0);
;   od = __builtin_amdgcn_mfma_f32_32x32x16_bf16(pa3, PK(f.l3, f.h3), od, 0, 0, 0);
;     ...
; }
; __device__ __forceinline__ void pv_pipe(f32x16* o, int vb, VF& f0, VF& f1, bf16x8 pa0, bf16x8 pa1, bf16x8 pa2, bf16x8 pa3) {
;   v_issue<1>(f1, vb); asm volatile("s_waitcnt lgkmcnt(8)" ::: "memory"); SBAR(); pv_mma(o[0], f0, pa0, pa1, pa2, pa3); SBAR();
;   v_issue<2>(f0, vb); asm volatile("s_waitcnt lgkmcnt(8)" ::: "memory"); SBAR(); pv_mma(o[1], f1, pa0, pa1, pa2, pa3); SBAR();
;   v_issue<3>(f1, vb); asm volatile("s_waitcnt lgkmcnt(8)" ::: "memory"); SBAR(); pv_mma(o[2], f0, pa0, pa1, pa2, pa3); SBAR();
;   asm volatile("s_waitcnt lgkmcnt(0)" ::: "memory"); SBAR(); pv_mma(o[3], f1, pa0, pa1, pa2, pa3);
; }
	ds_write_b128 v190, v[144:147]
	s_waitcnt vmcnt(0)
	ds_write_b128 v191, v[140:143]
	s_nop 0
	v_exp_f32_e32 v80, v80
	v_exp_f32_e32 v81, v81
	v_exp_f32_e32 v82, v82
	v_exp_f32_e32 v83, v83
	v_exp_f32_e32 v84, v84
	v_exp_f32_e32 v164, v64
	v_add_f32_e32 v64, 0, v80
	v_exp_f32_e32 v85, v85
	v_add_f32_e32 v64, v81, v64
	v_exp_f32_e32 v86, v86
	v_add_f32_e32 v64, v82, v64
	v_exp_f32_e32 v87, v87
	v_add_f32_e32 v64, v83, v64
	v_exp_f32_e32 v88, v88
	v_add_f32_e32 v64, v84, v64
	v_exp_f32_e32 v89, v89
	v_add_f32_e32 v64, v85, v64
	v_exp_f32_e32 v90, v90
	v_add_f32_e32 v64, v86, v64
	v_exp_f32_e32 v91, v91
	v_add_f32_e32 v64, v87, v64
	v_exp_f32_e32 v92, v92
	v_add_f32_e32 v64, v88, v64
	v_exp_f32_e32 v93, v93
	v_add_f32_e32 v64, v89, v64
	v_exp_f32_e32 v94, v94
	v_add_f32_e32 v64, v90, v64
	v_exp_f32_e32 v95, v95
	v_add_f32_e32 v64, v91, v64
	v_add_f32_e32 v64, v92, v64
	v_exp_f32_e32 v165, v65
	v_add_f32_e32 v64, v93, v64
	v_exp_f32_e32 v166, v66
	v_add_f32_e32 v64, v94, v64
	v_exp_f32_e32 v167, v67
	v_add_f32_e32 v64, v95, v64
	v_exp_f32_e32 v172, v68
	v_add_f32_e32 v64, v164, v64
	v_exp_f32_e32 v173, v69
	v_add_f32_e32 v64, v165, v64
	v_exp_f32_e32 v174, v70
	v_add_f32_e32 v64, v166, v64
	v_exp_f32_e32 v175, v71
	v_add_f32_e32 v64, v167, v64
	v_exp_f32_e32 v176, v72
	v_add_f32_e32 v64, v172, v64
	v_exp_f32_e32 v177, v73
	v_add_f32_e32 v64, v173, v64
	v_add_u32_e32 v163, 0x4000, v153
	ds_read_b64_tr_b16 v[132:133], v163 offset:0
	v_exp_f32_e32 v178, v74
	v_add_f32_e32 v64, v174, v64
	ds_read_b64_tr_b16 v[134:135], v163 offset:0x800
	v_exp_f32_e32 v179, v75
	v_add_f32_e32 v64, v175, v64
	ds_read_b64_tr_b16 v[136:137], v163 offset:0x1000
	v_exp_f32_e32 v186, v76
	v_add_f32_e32 v64, v176, v64
	ds_read_b64_tr_b16 v[138:139], v163 offset:0x1800
	v_exp_f32_e32 v188, v77
	v_add_f32_e32 v64, v177, v64
	ds_read_b64_tr_b16 v[140:141], v163 offset:0x2000
	v_exp_f32_e32 v189, v78
	v_add_f32_e32 v64, v178, v64
	ds_read_b64_tr_b16 v[142:143], v163 offset:0x2800
	v_exp_f32_e32 v79, v79
	v_add_f32_e32 v64, v179, v64
	ds_read_b64_tr_b16 v[144:145], v163 offset:0x3000
	v_add_f32_e32 v64, v186, v64
	ds_read_b64_tr_b16 v[146:147], v163 offset:0x3800
	v_add_f32_e32 v64, v188, v64
	v_add_f32_e32 v64, v189, v64
	v_add_f32_e32 v64, v79, v64
	v_add_f32_e32 v187, v187, v64
	v_cvt_pk_bf16_f32 v64, v80, v81
	v_cvt_pk_bf16_f32 v65, v82, v83
	v_cvt_pk_bf16_f32 v66, v84, v85
	v_cvt_pk_bf16_f32 v67, v86, v87
	v_cvt_pk_bf16_f32 v68, v88, v89
	v_cvt_pk_bf16_f32 v69, v90, v91
	v_cvt_pk_bf16_f32 v70, v92, v93
	v_cvt_pk_bf16_f32 v71, v94, v95
	v_cvt_pk_bf16_f32 v72, v164, v165
	v_cvt_pk_bf16_f32 v73, v166, v167
	v_cvt_pk_bf16_f32 v74, v172, v173
	v_cvt_pk_bf16_f32 v75, v174, v175
	v_cvt_pk_bf16_f32 v76, v176, v177
	v_cvt_pk_bf16_f32 v77, v178, v179
	v_cvt_pk_bf16_f32 v78, v186, v188
	v_cvt_pk_bf16_f32 v79, v189, v79
	ds_read_b64_tr_b16 v[80:81], v163 offset:0x200
	ds_read_b64_tr_b16 v[82:83], v163 offset:0xa00
	ds_read_b64_tr_b16 v[84:85], v163 offset:0x1200
	ds_read_b64_tr_b16 v[86:87], v163 offset:0x1a00
	ds_read_b64_tr_b16 v[88:89], v163 offset:0x2200
	ds_read_b64_tr_b16 v[90:91], v163 offset:0x2a00
	ds_read_b64_tr_b16 v[92:93], v163 offset:0x3200
	ds_read_b64_tr_b16 v[94:95], v163 offset:0x3a00
	s_waitcnt lgkmcnt(8)
	s_nop 0
	v_mfma_f32_32x32x16_bf16 v[48:63], v[64:67], v[132:135], v[48:63]
	v_mfma_f32_32x32x16_bf16 v[48:63], v[68:71], v[136:139], v[48:63]
	v_mfma_f32_32x32x16_bf16 v[48:63], v[72:75], v[140:143], v[48:63]
	v_mfma_f32_32x32x16_bf16 v[48:63], v[76:79], v[144:147], v[48:63]
	ds_read_b64_tr_b16 v[132:133], v163 offset:0x400
	ds_read_b64_tr_b16 v[134:135], v163 offset:0xc00
	ds_read_b64_tr_b16 v[136:137], v163 offset:0x1400
	ds_read_b64_tr_b16 v[138:139], v163 offset:0x1c00
	ds_read_b64_tr_b16 v[140:141], v163 offset:0x2400
	ds_read_b64_tr_b16 v[142:143], v163 offset:0x2c00
	ds_read_b64_tr_b16 v[144:145], v163 offset:0x3400
	ds_read_b64_tr_b16 v[146:147], v163 offset:0x3c00
	s_waitcnt lgkmcnt(8)
	v_mfma_f32_32x32x16_bf16 v[32:47], v[64:67], v[80:83], v[32:47]
	v_mfma_f32_32x32x16_bf16 v[32:47], v[68:71], v[84:87], v[32:47]
	v_mfma_f32_32x32x16_bf16 v[32:47], v[72:75], v[88:91], v[32:47]
	v_mfma_f32_32x32x16_bf16 v[32:47], v[76:79], v[92:95], v[32:47]
	ds_read_b64_tr_b16 v[80:81], v163 offset:0x600
	ds_read_b64_tr_b16 v[82:83], v163 offset:0xe00
	ds_read_b64_tr_b16 v[84:85], v163 offset:0x1600
	ds_read_b64_tr_b16 v[86:87], v163 offset:0x1e00
	ds_read_b64_tr_b16 v[88:89], v163 offset:0x2600
	ds_read_b64_tr_b16 v[90:91], v163 offset:0x2e00
	ds_read_b64_tr_b16 v[92:93], v163 offset:0x3600
	ds_read_b64_tr_b16 v[94:95], v163 offset:0x3e00
	s_waitcnt lgkmcnt(8)
	v_mfma_f32_32x32x16_bf16 v[16:31], v[64:67], v[132:135], v[16:31]
	v_mfma_f32_32x32x16_bf16 v[16:31], v[68:71], v[136:139], v[16:31]
	v_mfma_f32_32x32x16_bf16 v[16:31], v[72:75], v[140:143], v[16:31]
	v_mfma_f32_32x32x16_bf16 v[16:31], v[76:79], v[144:147], v[16:31]
	s_waitcnt lgkmcnt(0)
	v_mfma_f32_32x32x16_bf16 v[0:15], v[64:67], v[80:83], v[0:15]
	v_and_b32_e32 v132, 0x3fffffc0, v152
	s_waitcnt lgkmcnt(0)
	s_barrier
; #define SBAR() __builtin_amdgcn_sched_barrier(0)
; template <int DQK>
; __device__ __forceinline__ void qkt(f32x16& p0, f32x16& p1, const char* Ks, const bf16x8* qr, int r32, int hi) {
;     ...
; #pragma unroll
;   for (int d0 = 0; d0 < DQK / 16; ++d0) { const int cb = (d0 * 16 + hi * 8) * 2;
;     bf16x8 b0 = *reinterpret_cast<const bf16x8*>(Ks + KSWZ(KP, r32, cb));
;     bf16x8 b1 = *reinterpret_cast<const bf16x8*>(Ks + KSWZ(KP, 32 + r32, cb));
;     p0 = __builtin_amdgcn_mfma_f32_32x32x16_bf16(b0, qr[d0], p0, 0, 0, 0);
;     p1 = __builtin_amdgcn_mfma_f32_32x32x16_bf16(b1, qr[d0], p1, 0, 0, 0); }
; }
; __device__ __forceinline__ int v_st(int k, int c) { const int kk = k; return ((kk >> 3) * 4 + (c >> 5)) * 512 + ((kk & 7) * 32 + (c & 31)) * 2; }
; __device__ __forceinline__ int v_rd_base(int lane) { return ((lane & 3) << 3) | (((lane >> 2) & 3) << 6) | (((lane >> 4) & 1) << 5) | (((lane >> 5) & 1) << 8); }
; template <int OFF> __device__ __forceinline__ s16x4 tr_read(int vb) {
;   s16x4 r; asm volatile("ds_read_b64_tr_b16 %0, %1 offset:%2" : "=&v"(r) : "v"(vb), "i"(OFF) : "memory"); return r;
; }
; template <int D0> __device__ __forceinline__ void pv_one(f32x16& od, int vb, bf16x8 pa0, bf16x8 pa1, bf16x8 pa2, bf16x8 pa3) {
;   const s16x4 l0 = tr_read<v_rd_off(D0, 0, 0)>(vb), h0 = tr_read<v_rd_off(D0, 0, 1)>(vb), l1 = tr_read<v_rd_off(D0, 1, 0)>(vb), h1 = tr_read<v_rd_off(D0, 1, 1)>(vb);
;   const s16x4 l2 = tr_read<v_rd_off(D0, 2, 0)>(vb), h2 = tr_read<v_rd_off(D0, 2, 1)>(vb), l3 = tr_read<v_rd_off(D0, 3, 0)>(vb), h3 = tr_read<v_rd_off(D0, 3, 1)>(vb);
;   asm volatile("s_waitcnt lgkmcnt(0)" ::: "memory"); SBAR();
;     ...
;   od = __builtin_amdgcn_mfma_f32_32x32x16_bf16(pa0, PK(l0, h0), od, 0, 0, 0);
;   od = __builtin_amdgcn_mfma_f32_32x32x16_bf16(pa1, PK(l1, h1), od, 0, 0, 0);
;   od = __builtin_amdgcn_mfma_f32_32x32x16_bf16(pa2, PK(l2, h2), od, 0, 0, 0);
;   od = __builtin_amdgcn_mfma_f32_32x32x16_bf16(pa3, PK(l3, h3), od, 0, 0, 0);
;     ...
; }
; __device__ __forceinline__ void pv_d0(f32x16* o, int vb, bf16x8 pa0, bf16x8 pa1, bf16x8 pa2, bf16x8 pa3) {
;   pv_one<0>(o[0], vb, pa0, pa1, pa2, pa3); pv_one<1>(o[1], vb, pa0, pa1, pa2, pa3); pv_one<2>(o[2], vb, pa0, pa1, pa2, pa3); pv_one<3>(o[3], vb, pa0, pa1, pa2, pa3);
; }
; __device__ __forceinline__ float bf2f(unsigned short b) { return __uint_as_float((unsigned)b << 16); }
	v_mfma_f32_32x32x16_bf16 v[0:15], v[68:71], v[84:87], v[0:15]
	v_mfma_f32_32x32x16_bf16 v[0:15], v[72:75], v[88:91], v[0:15]
	v_mfma_f32_32x32x16_bf16 v[0:15], v[76:79], v[92:95], v[0:15]
	v_add3_u32 v64, s6, v162, v154
	ds_read_b128 v[64:67], v64
	v_add3_u32 v80, s6, v161, v154
	ds_read_b128 v[80:83], v80
	s_waitcnt lgkmcnt(1)
	v_mfma_f32_32x32x16_bf16 v[64:79], v[64:67], v[128:131], 0
	s_waitcnt lgkmcnt(0)
	v_mfma_f32_32x32x16_bf16 v[64:79], v[80:83], v[124:127], v[64:79]
	v_add3_u32 v80, s6, v160, v154
	ds_read_b128 v[80:83], v80
	s_waitcnt lgkmcnt(0)
	v_mfma_f32_32x32x16_bf16 v[64:79], v[80:83], v[120:123], v[64:79]
	v_add3_u32 v80, s6, v159, v154
	ds_read_b128 v[80:83], v80
	s_waitcnt lgkmcnt(0)
	v_mfma_f32_32x32x16_bf16 v[64:79], v[80:83], v[116:119], v[64:79]
	v_add3_u32 v80, s6, v158, v154
	ds_read_b128 v[80:83], v80
	s_waitcnt lgkmcnt(0)
	v_mfma_f32_32x32x16_bf16 v[64:79], v[80:83], v[112:115], v[64:79]
	v_add3_u32 v80, s6, v157, v154
	ds_read_b128 v[80:83], v80
	s_waitcnt lgkmcnt(0)
	v_mfma_f32_32x32x16_bf16 v[64:79], v[80:83], v[108:111], v[64:79]
	v_add3_u32 v80, s6, v156, v154
	ds_read_b128 v[80:83], v80
	s_waitcnt lgkmcnt(0)
	v_mfma_f32_32x32x16_bf16 v[64:79], v[80:83], v[104:107], v[64:79]
	v_add3_u32 v80, s6, v155, v154
	ds_read_b128 v[80:83], v80
	s_waitcnt lgkmcnt(0)
	v_mfma_f32_32x32x16_bf16 v[64:79], v[80:83], v[100:103], v[64:79]
	s_nop 11
	v_exp_f32_e32 v88, v64
	v_exp_f32_e32 v65, v65
	v_exp_f32_e32 v89, v66
	v_exp_f32_e32 v67, v67
	ds_read_b64_tr_b16 v[72:73], v153 offset:0
	v_exp_f32_e32 v68, v68
	v_add_f32_e32 v64, 0, v88
	ds_read_b64_tr_b16 v[74:75], v153 offset:0x800
	v_exp_f32_e32 v69, v69
	v_add_f32_e32 v64, v65, v64
	ds_read_b64_tr_b16 v[76:77], v153 offset:0x1000
	v_exp_f32_e32 v70, v70
	v_add_f32_e32 v64, v89, v64
	ds_read_b64_tr_b16 v[78:79], v153 offset:0x1800
	v_exp_f32_e32 v71, v71
	v_add_f32_e32 v64, v67, v64
	ds_read_b64_tr_b16 v[80:81], v153 offset:0x2000
	v_add_f32_e32 v64, v68, v64
	ds_read_b64_tr_b16 v[82:83], v153 offset:0x2800
	v_add_f32_e32 v64, v69, v64
	ds_read_b64_tr_b16 v[84:85], v153 offset:0x3000
	v_add_f32_e32 v64, v70, v64
	ds_read_b64_tr_b16 v[86:87], v153 offset:0x3800
	v_add_f32_e32 v64, v71, v64
	v_add_f32_e32 v64, 0, v64
	v_add_f32_e32 v64, v187, v64
	v_cvt_pk_bf16_f32 v66, v88, v65
	v_cvt_pk_bf16_f32 v67, v89, v67
	v_cvt_pk_bf16_f32 v68, v68, v69
	v_cvt_pk_bf16_f32 v69, v70, v71
	v_cvt_pk_bf16_f32 v88, v169, v169
	v_cvt_pk_bf16_f32 v89, v169, v169
	v_cvt_pk_bf16_f32 v90, v169, v169
	v_cvt_pk_bf16_f32 v91, v169, v169
	v_cvt_pk_bf16_f32 v92, v169, v169
	v_cvt_pk_bf16_f32 v93, v169, v169
	v_cvt_pk_bf16_f32 v94, v169, v169
	v_cvt_pk_bf16_f32 v95, v169, v169
	v_cvt_pk_bf16_f32 v100, v169, v169
	v_cvt_pk_bf16_f32 v101, v169, v169
	v_cvt_pk_bf16_f32 v102, v169, v169
	v_cvt_pk_bf16_f32 v103, v169, v169
	ds_read_b64_tr_b16 v[104:105], v153 offset:0x200
	ds_read_b64_tr_b16 v[106:107], v153 offset:0xa00
	ds_read_b64_tr_b16 v[108:109], v153 offset:0x1200
	ds_read_b64_tr_b16 v[110:111], v153 offset:0x1a00
	ds_read_b64_tr_b16 v[112:113], v153 offset:0x2200
	ds_read_b64_tr_b16 v[114:115], v153 offset:0x2a00
	ds_read_b64_tr_b16 v[116:117], v153 offset:0x3200
	ds_read_b64_tr_b16 v[118:119], v153 offset:0x3a00
	s_waitcnt lgkmcnt(8)
	s_nop 0
	v_mfma_f32_32x32x16_bf16 v[48:63], v[66:69], v[72:75], v[48:63]
	v_mfma_f32_32x32x16_bf16 v[48:63], v[88:91], v[76:79], v[48:63]
	v_mfma_f32_32x32x16_bf16 v[48:63], v[92:95], v[80:83], v[48:63]
	v_mfma_f32_32x32x16_bf16 v[48:63], v[100:103], v[84:87], v[48:63]
	ds_read_b64_tr_b16 v[70:71], v153 offset:0x400
	ds_read_b64_tr_b16 v[72:73], v153 offset:0xc00
	ds_read_b64_tr_b16 v[74:75], v153 offset:0x1400
	ds_read_b64_tr_b16 v[76:77], v153 offset:0x1c00
	ds_read_b64_tr_b16 v[78:79], v153 offset:0x2400
	ds_read_b64_tr_b16 v[80:81], v153 offset:0x2c00
	ds_read_b64_tr_b16 v[82:83], v153 offset:0x3400
	ds_read_b64_tr_b16 v[84:85], v153 offset:0x3c00
	s_waitcnt lgkmcnt(8)
	v_mfma_f32_32x32x16_bf16 v[32:47], v[66:69], v[104:107], v[32:47]
	v_mfma_f32_32x32x16_bf16 v[32:47], v[88:91], v[108:111], v[32:47]
	v_mfma_f32_32x32x16_bf16 v[32:47], v[92:95], v[112:115], v[32:47]
	v_mfma_f32_32x32x16_bf16 v[32:47], v[100:103], v[116:119], v[32:47]
	ds_read_b64_tr_b16 v[104:105], v153 offset:0x600
	ds_read_b64_tr_b16 v[106:107], v153 offset:0xe00
	ds_read_b64_tr_b16 v[108:109], v153 offset:0x1600
	ds_read_b64_tr_b16 v[110:111], v153 offset:0x1e00
	ds_read_b64_tr_b16 v[112:113], v153 offset:0x2600
	ds_read_b64_tr_b16 v[114:115], v153 offset:0x2e00
	ds_read_b64_tr_b16 v[116:117], v153 offset:0x3600
	ds_read_b64_tr_b16 v[118:119], v153 offset:0x3e00
	s_waitcnt lgkmcnt(8)
	v_mfma_f32_32x32x16_bf16 v[16:31], v[66:69], v[70:73], v[16:31]
	v_mfma_f32_32x32x16_bf16 v[16:31], v[88:91], v[74:77], v[16:31]
	v_mfma_f32_32x32x16_bf16 v[16:31], v[92:95], v[78:81], v[16:31]
	v_mfma_f32_32x32x16_bf16 v[16:31], v[100:103], v[82:85], v[16:31]
	s_waitcnt lgkmcnt(0)
	v_mfma_f32_32x32x16_bf16 v[0:15], v[66:69], v[104:107], v[0:15]
	s_add_i32 s2, 0, 0x20000
	v_mov_b32_e32 v65, v64
	v_lshl_add_u32 v69, v132, 2, s2
	s_nop 0
	v_permlane32_swap_b32_e32 v64, v65
	v_cmp_gt_u32_e32 vcc, 32, v151
	v_mfma_f32_32x32x16_bf16 v[0:15], v[88:91], v[108:111], v[0:15]
	v_mfma_f32_32x32x16_bf16 v[0:15], v[92:95], v[112:115], v[0:15]
	v_mfma_f32_32x32x16_bf16 v[0:15], v[100:103], v[116:119], v[0:15]
	s_and_saveexec_b64 s[6:7], vcc
	v_lshl_add_u32 v66, v149, 2, v69
	v_add_f32_e32 v64, v64, v65
	ds_write_b32 v66, v64
	s_or_b64 exec, exec, s[6:7]
	s_lshl_b64 s[6:7], s[4:5], 12
	v_readlane_b32 s18, v252, 49
	v_readlane_b32 s19, v252, 50
	s_add_u32 s2, s18, s6
	s_addc_u32 s7, s19, s7
	s_add_u32 s6, s2, s0
	s_addc_u32 s7, s7, s1
	s_add_u32 s0, s3, s0
	s_addc_u32 s1, s34, s1
	s_waitcnt lgkmcnt(0)
	v_lshlrev_b32_e32 v72, 2, v150
	v_lshlrev_b32_e32 v64, 1, v149
	v_mov_b32_e32 v65, v169
	v_lshl_add_u64 v[66:67], s[0:1], 0, v[64:65]
	s_mov_b64 s[0:1], 0x1800
	v_or_b32_e32 v68, v72, v148
	v_lshl_add_u64 v[66:67], v[66:67], 0, s[0:1]
	v_lshl_add_u64 v[64:65], s[6:7], 0, v[64:65]
	v_cmp_gt_i32_e32 vcc, s96, v68
	v_lshl_add_u32 v73, v72, 2, v69
	s_and_saveexec_b64 s[0:1], vcc
	s_cbranch_execz .LBB0_544
; __device__ __forceinline__ int crow(int r, int hi) { return (r & 3) + 8 * (r >> 2) + 4 * hi; }
; __device__ __forceinline__ float bf2f(unsigned short b) { return __uint_as_float((unsigned)b << 16); }
; __device__ __forceinline__ unsigned f2bf(float f) { unsigned u = __float_as_uint(f); return (u + 0x7fffu + ((u >> 16) & 1u)) >> 16; }
; __device__ __forceinline__ float bf2f(unsigned short b) { return __uint_as_float((unsigned)b << 16); }
; __device__ __forceinline__ unsigned f2bf(float f) { unsigned u = __float_as_uint(f); return (u + 0x7fffu + ((u >> 16) & 1u)) >> 16; }
;     ...
;   for (int r = 0; r < 16; ++r) { const int orow = wid * QBLK + crow(r, hi); const float rli = __builtin_amdgcn_rcpf(li_l[crow(r, hi)]);
;     if (orow < nvalid) {
;       if constexpr (MODE == 0) {
; #pragma unroll
;         for (int d0 = 0; d0 < 4; ++d0) Of[(long)orow * ldo + d0 * 32 + r32] = o[d0][r] * rli;
;       } else {
; #pragma unroll
;         for (int d0 = 0; d0 < 4; ++d0) { const float g = bf2f(Gb[(long)orow * ldg + d0 * 32 + r32]); const float sg = g / (1.f + __expf(-g));
;           Yb[(long)orow * ldy + d0 * 32 + r32] = (bf16)f2bf(o[d0][r] * rli * sg); }
	v_mad_i64_i32 v[70:71], s[2:3], v68, s20, v[66:67]
	global_load_ushort v75, v[70:71], off
	global_load_ushort v100, v[70:71], off offset:64
	global_load_ushort v101, v[70:71], off offset:128
	global_load_ushort v102, v[70:71], off offset:192
	ds_read_b32 v69, v73
	s_waitcnt lgkmcnt(0)
	v_rcp_f32_e32 v74, v69
	v_ashrrev_i32_e32 v69, 31, v68
	v_lshlrev_b64 v[68:69], 12, v[68:69]
	v_lshl_add_u64 v[68:69], v[64:65], 0, v[68:69]
	v_mul_f32_e32 v48, v48, v74
	v_mul_f32_e32 v32, v32, v74
	v_mul_f32_e32 v16, v16, v74
	v_mul_f32_e32 v0, v0, v74
	s_waitcnt vmcnt(0)
	v_lshlrev_b32_e32 v75, 16, v75
	v_mul_f32_e32 v76, 0xbfb8aa3b, v75
	v_exp_f32_e32 v76, v76
	s_nop 0
	v_add_f32_e32 v76, 1.0, v76
	v_div_scale_f32 v77, s[2:3], v76, v76, v75
	v_rcp_f32_e32 v78, v77
	s_nop 0
	v_fma_f32 v79, -v77, v78, 1.0
	v_fmac_f32_e32 v78, v79, v78
	v_div_scale_f32 v79, vcc, v75, v76, v75
	v_mul_f32_e32 v80, v79, v78
	v_fma_f32 v81, -v77, v80, v79
	v_fmac_f32_e32 v80, v81, v78
	v_fma_f32 v77, -v77, v80, v79
	v_div_fmas_f32 v77, v77, v78, v80
	v_div_fixup_f32 v75, v77, v76, v75
	v_mul_f32_e32 v48, v48, v75
	v_bfe_u32 v75, v48, 16, 1
	v_add3_u32 v48, v48, v75, s15
	global_store_short_d16_hi v[68:69], v48, off offset:1024


; __device__ __forceinline__ float bf2f(unsigned short b) { return __uint_as_float((unsigned)b << 16); }
; __device__ __forceinline__ unsigned f2bf(float f) { unsigned u = __float_as_uint(f); return (u + 0x7fffu + ((u >> 16) & 1u)) >> 16; }
; __device__ __forceinline__ float bf2f(unsigned short b) { return __uint_as_float((unsigned)b << 16); }
; __device__ __forceinline__ unsigned f2bf(float f) { unsigned u = __float_as_uint(f); return (u + 0x7fffu + ((u >> 16) & 1u)) >> 16; }
;     ...
;         for (int d0 = 0; d0 < 4; ++d0) { const float g = bf2f(Gb[(long)orow * ldg + d0 * 32 + r32]); const float sg = g / (1.f + __expf(-g));
;           Yb[(long)orow * ldy + d0 * 32 + r32] = (bf16)f2bf(o[d0][r] * rli * sg); }
	v_lshlrev_b32_e32 v48, 16, v100
	v_mul_f32_e32 v75, 0xbfb8aa3b, v48
	v_exp_f32_e32 v75, v75
	s_nop 0
	v_add_f32_e32 v75, 1.0, v75
	v_div_scale_f32 v76, s[2:3], v75, v75, v48
	v_rcp_f32_e32 v77, v76
	s_nop 0
	v_fma_f32 v78, -v76, v77, 1.0
	v_fmac_f32_e32 v77, v78, v77
	v_div_scale_f32 v78, vcc, v48, v75, v48
	v_mul_f32_e32 v79, v78, v77
	v_fma_f32 v80, -v76, v79, v78
	v_fmac_f32_e32 v79, v80, v77
	v_fma_f32 v76, -v76, v79, v78
	v_div_fmas_f32 v76, v76, v77, v79
	v_div_fixup_f32 v48, v76, v75, v48
	v_mul_f32_e32 v32, v32, v48
	v_bfe_u32 v48, v32, 16, 1
	v_add3_u32 v32, v32, v48, s15
	global_store_short_d16_hi v[68:69], v32, off offset:1088


; __device__ __forceinline__ float bf2f(unsigned short b) { return __uint_as_float((unsigned)b << 16); }
; __device__ __forceinline__ unsigned f2bf(float f) { unsigned u = __float_as_uint(f); return (u + 0x7fffu + ((u >> 16) & 1u)) >> 16; }
; __device__ __forceinline__ float bf2f(unsigned short b) { return __uint_as_float((unsigned)b << 16); }
; __device__ __forceinline__ unsigned f2bf(float f) { unsigned u = __float_as_uint(f); return (u + 0x7fffu + ((u >> 16) & 1u)) >> 16; }
;     ...
;         for (int d0 = 0; d0 < 4; ++d0) { const float g = bf2f(Gb[(long)orow * ldg + d0 * 32 + r32]); const float sg = g / (1.f + __expf(-g));
;           Yb[(long)orow * ldy + d0 * 32 + r32] = (bf16)f2bf(o[d0][r] * rli * sg); }
	v_lshlrev_b32_e32 v32, 16, v101
	v_mul_f32_e32 v48, 0xbfb8aa3b, v32
	v_exp_f32_e32 v48, v48
	s_nop 0
	v_add_f32_e32 v48, 1.0, v48
	v_div_scale_f32 v75, s[2:3], v48, v48, v32
	v_rcp_f32_e32 v76, v75
	s_nop 0
	v_fma_f32 v77, -v75, v76, 1.0
	v_fmac_f32_e32 v76, v77, v76
	v_div_scale_f32 v77, vcc, v32, v48, v32
	v_mul_f32_e32 v78, v77, v76
	v_fma_f32 v79, -v75, v78, v77
	v_fmac_f32_e32 v78, v79, v76
	v_fma_f32 v75, -v75, v78, v77
	v_div_fmas_f32 v75, v75, v76, v78
	v_div_fixup_f32 v32, v75, v48, v32
	v_mul_f32_e32 v16, v16, v32
	v_bfe_u32 v32, v16, 16, 1
	v_add3_u32 v16, v16, v32, s15
	global_store_short_d16_hi v[68:69], v16, off offset:1152


; __device__ __forceinline__ int crow(int r, int hi) { return (r & 3) + 8 * (r >> 2) + 4 * hi; }
; __device__ __forceinline__ float bf2f(unsigned short b) { return __uint_as_float((unsigned)b << 16); }
; __device__ __forceinline__ unsigned f2bf(float f) { unsigned u = __float_as_uint(f); return (u + 0x7fffu + ((u >> 16) & 1u)) >> 16; }
; __device__ __forceinline__ float bf2f(unsigned short b) { return __uint_as_float((unsigned)b << 16); }
; __device__ __forceinline__ unsigned f2bf(float f) { unsigned u = __float_as_uint(f); return (u + 0x7fffu + ((u >> 16) & 1u)) >> 16; }
;     ...
;   for (int r = 0; r < 16; ++r) { const int orow = wid * QBLK + crow(r, hi); const float rli = __builtin_amdgcn_rcpf(li_l[crow(r, hi)]);
;     if (orow < nvalid) {
;       if constexpr (MODE == 0) {
; #pragma unroll
;         for (int d0 = 0; d0 < 4; ++d0) Of[(long)orow * ldo + d0 * 32 + r32] = o[d0][r] * rli;
;       } else {
; #pragma unroll
;         for (int d0 = 0; d0 < 4; ++d0) { const float g = bf2f(Gb[(long)orow * ldg + d0 * 32 + r32]); const float sg = g / (1.f + __expf(-g));
;           Yb[(long)orow * ldy + d0 * 32 + r32] = (bf16)f2bf(o[d0][r] * rli * sg); }
	v_lshlrev_b32_e32 v16, 16, v102
	v_mul_f32_e32 v32, 0xbfb8aa3b, v16
	v_exp_f32_e32 v32, v32
	s_nop 0
	v_add_f32_e32 v32, 1.0, v32
	v_div_scale_f32 v48, s[2:3], v32, v32, v16
	v_rcp_f32_e32 v70, v48
	s_nop 0
	v_fma_f32 v71, -v48, v70, 1.0
	v_fmac_f32_e32 v70, v71, v70
	v_div_scale_f32 v71, vcc, v16, v32, v16
	v_mul_f32_e32 v75, v71, v70
	v_fma_f32 v76, -v48, v75, v71
	v_fmac_f32_e32 v75, v76, v70
	v_fma_f32 v48, -v48, v75, v71
	v_div_fmas_f32 v48, v48, v70, v75
	v_div_fixup_f32 v16, v48, v32, v16
	v_mul_f32_e32 v0, v0, v16
	v_bfe_u32 v16, v0, 16, 1
	v_add3_u32 v0, v0, v16, s15
	global_store_short_d16_hi v[68:69], v0, off offset:1216
.LBB0_544:
	s_or_b64 exec, exec, s[0:1]
	v_or3_b32 v68, v72, v148, 1
	v_cmp_gt_i32_e32 vcc, s96, v68
	s_and_saveexec_b64 s[0:1], vcc
	s_cbranch_execz .LBB0_546
	v_mad_i64_i32 v[70:71], s[2:3], v68, s20, v[66:67]
	global_load_ushort v16, v[70:71], off
	global_load_ushort v100, v[70:71], off offset:64
	global_load_ushort v101, v[70:71], off offset:128
	global_load_ushort v102, v[70:71], off offset:192
	ds_read_b32 v0, v73 offset:4
	v_ashrrev_i32_e32 v69, 31, v68
	v_lshlrev_b64 v[68:69], 12, v[68:69]
	v_lshl_add_u64 v[68:69], v[64:65], 0, v[68:69]
	s_waitcnt lgkmcnt(0)
	v_rcp_f32_e32 v0, v0
	s_nop 0
	v_mul_f32_e32 v17, v17, v0
	s_waitcnt vmcnt(0)
	v_lshlrev_b32_e32 v16, 16, v16
	v_mul_f32_e32 v32, 0xbfb8aa3b, v16
	v_exp_f32_e32 v32, v32
	s_nop 0
	v_add_f32_e32 v32, 1.0, v32
	v_div_scale_f32 v48, s[2:3], v32, v32, v16
	v_rcp_f32_e32 v74, v48
	s_nop 0
	v_fma_f32 v75, -v48, v74, 1.0
	v_fmac_f32_e32 v74, v75, v74
	v_div_scale_f32 v75, vcc, v16, v32, v16
	v_mul_f32_e32 v76, v75, v74
	v_fma_f32 v77, -v48, v76, v75
	v_fmac_f32_e32 v76, v77, v74
	v_fma_f32 v48, -v48, v76, v75
	v_div_fmas_f32 v48, v48, v74, v76
	v_div_fixup_f32 v16, v48, v32, v16
	v_mul_f32_e32 v32, v49, v0
	v_mul_f32_e32 v16, v32, v16
	v_bfe_u32 v32, v16, 16, 1
	v_add3_u32 v16, v16, v32, s15
	global_store_short_d16_hi v[68:69], v16, off offset:1024


; __device__ __forceinline__ float bf2f(unsigned short b) { return __uint_as_float((unsigned)b << 16); }
; __device__ __forceinline__ unsigned f2bf(float f) { unsigned u = __float_as_uint(f); return (u + 0x7fffu + ((u >> 16) & 1u)) >> 16; }
; __device__ __forceinline__ float bf2f(unsigned short b) { return __uint_as_float((unsigned)b << 16); }
; __device__ __forceinline__ unsigned f2bf(float f) { unsigned u = __float_as_uint(f); return (u + 0x7fffu + ((u >> 16) & 1u)) >> 16; }
;     ...
;         for (int d0 = 0; d0 < 4; ++d0) { const float g = bf2f(Gb[(long)orow * ldg + d0 * 32 + r32]); const float sg = g / (1.f + __expf(-g));
;           Yb[(long)orow * ldy + d0 * 32 + r32] = (bf16)f2bf(o[d0][r] * rli * sg); }
	v_lshlrev_b32_e32 v16, 16, v100
	v_mul_f32_e32 v32, 0xbfb8aa3b, v16
	v_exp_f32_e32 v32, v32
	s_nop 0
	v_add_f32_e32 v32, 1.0, v32
	v_div_scale_f32 v48, s[2:3], v32, v32, v16
	v_rcp_f32_e32 v49, v48
	s_nop 0
	v_fma_f32 v74, -v48, v49, 1.0
	v_fmac_f32_e32 v49, v74, v49
	v_div_scale_f32 v74, vcc, v16, v32, v16
	v_mul_f32_e32 v75, v74, v49
	v_fma_f32 v76, -v48, v75, v74
	v_fmac_f32_e32 v75, v76, v49
	v_fma_f32 v48, -v48, v75, v74
	v_div_fmas_f32 v48, v48, v49, v75
	v_div_fixup_f32 v16, v48, v32, v16
	v_mul_f32_e32 v32, v33, v0
	v_mul_f32_e32 v16, v32, v16
	v_bfe_u32 v32, v16, 16, 1
	v_add3_u32 v16, v16, v32, s15
	global_store_short_d16_hi v[68:69], v16, off offset:1088

; __device__ __forceinline__ float bf2f(unsigned short b) { return __uint_as_float((unsigned)b << 16); }
; __device__ __forceinline__ unsigned f2bf(float f) { unsigned u = __float_as_uint(f); return (u + 0x7fffu + ((u >> 16) & 1u)) >> 16; }
; __device__ __forceinline__ float bf2f(unsigned short b) { return __uint_as_float((unsigned)b << 16); }
; __device__ __forceinline__ unsigned f2bf(float f) { unsigned u = __float_as_uint(f); return (u + 0x7fffu + ((u >> 16) & 1u)) >> 16; }
;     ...
;         for (int d0 = 0; d0 < 4; ++d0) { const float g = bf2f(Gb[(long)orow * ldg + d0 * 32 + r32]); const float sg = g / (1.f + __expf(-g));
;           Yb[(long)orow * ldy + d0 * 32 + r32] = (bf16)f2bf(o[d0][r] * rli * sg); }
	v_mul_f32_e32 v0, v1, v0

; __device__ __forceinline__ float bf2f(unsigned short b) { return __uint_as_float((unsigned)b << 16); }
; __device__ __forceinline__ unsigned f2bf(float f) { unsigned u = __float_as_uint(f); return (u + 0x7fffu + ((u >> 16) & 1u)) >> 16; }
; __device__ __forceinline__ float bf2f(unsigned short b) { return __uint_as_float((unsigned)b << 16); }
; __device__ __forceinline__ unsigned f2bf(float f) { unsigned u = __float_as_uint(f); return (u + 0x7fffu + ((u >> 16) & 1u)) >> 16; }
;     ...
;         for (int d0 = 0; d0 < 4; ++d0) { const float g = bf2f(Gb[(long)orow * ldg + d0 * 32 + r32]); const float sg = g / (1.f + __expf(-g));
;           Yb[(long)orow * ldy + d0 * 32 + r32] = (bf16)f2bf(o[d0][r] * rli * sg); }
	v_lshlrev_b32_e32 v16, 16, v101
	v_mul_f32_e32 v32, 0xbfb8aa3b, v16
	v_exp_f32_e32 v32, v32
	s_nop 0
	v_add_f32_e32 v32, 1.0, v32
	v_div_scale_f32 v33, s[2:3], v32, v32, v16
	v_rcp_f32_e32 v48, v33
	s_nop 0
	v_fma_f32 v49, -v33, v48, 1.0
	v_fmac_f32_e32 v48, v49, v48
	v_div_scale_f32 v49, vcc, v16, v32, v16
	v_mul_f32_e32 v74, v49, v48
	v_fma_f32 v75, -v33, v74, v49
	v_fmac_f32_e32 v74, v75, v48
	v_fma_f32 v33, -v33, v74, v49
	v_div_fmas_f32 v33, v33, v48, v74
	v_div_fixup_f32 v16, v33, v32, v16
	v_mul_f32_e32 v16, v17, v16
	v_bfe_u32 v17, v16, 16, 1
	v_add3_u32 v16, v16, v17, s15
	global_store_short_d16_hi v[68:69], v16, off offset:1152


; __device__ __forceinline__ int crow(int r, int hi) { return (r & 3) + 8 * (r >> 2) + 4 * hi; }
; __device__ __forceinline__ float bf2f(unsigned short b) { return __uint_as_float((unsigned)b << 16); }
; __device__ __forceinline__ unsigned f2bf(float f) { unsigned u = __float_as_uint(f); return (u + 0x7fffu + ((u >> 16) & 1u)) >> 16; }
; __device__ __forceinline__ float bf2f(unsigned short b) { return __uint_as_float((unsigned)b << 16); }
; __device__ __forceinline__ unsigned f2bf(float f) { unsigned u = __float_as_uint(f); return (u + 0x7fffu + ((u >> 16) & 1u)) >> 16; }
;     ...
;   for (int r = 0; r < 16; ++r) { const int orow = wid * QBLK + crow(r, hi); const float rli = __builtin_amdgcn_rcpf(li_l[crow(r, hi)]);
;     if (orow < nvalid) {
;       if constexpr (MODE == 0) {
; #pragma unroll
;         for (int d0 = 0; d0 < 4; ++d0) Of[(long)orow * ldo + d0 * 32 + r32] = o[d0][r] * rli;
;       } else {
; #pragma unroll
;         for (int d0 = 0; d0 < 4; ++d0) { const float g = bf2f(Gb[(long)orow * ldg + d0 * 32 + r32]); const float sg = g / (1.f + __expf(-g));
;           Yb[(long)orow * ldy + d0 * 32 + r32] = (bf16)f2bf(o[d0][r] * rli * sg); }
	v_lshlrev_b32_e32 v16, 16, v102
	v_mul_f32_e32 v17, 0xbfb8aa3b, v16
	v_exp_f32_e32 v17, v17
	s_nop 0
	v_add_f32_e32 v17, 1.0, v17
	v_div_scale_f32 v32, s[2:3], v17, v17, v16
	v_rcp_f32_e32 v33, v32
	s_nop 0
	v_fma_f32 v48, -v32, v33, 1.0
	v_fmac_f32_e32 v33, v48, v33
	v_div_scale_f32 v48, vcc, v16, v17, v16
	v_mul_f32_e32 v49, v48, v33
	v_fma_f32 v70, -v32, v49, v48
	v_fmac_f32_e32 v49, v70, v33
	v_fma_f32 v32, -v32, v49, v48
	v_div_fmas_f32 v32, v32, v33, v49
	v_div_fixup_f32 v16, v32, v17, v16
	v_mul_f32_e32 v0, v0, v16
	v_bfe_u32 v1, v0, 16, 1
	v_add3_u32 v0, v0, v1, s15
	global_store_short_d16_hi v[68:69], v0, off offset:1216
.LBB0_546:
	s_or_b64 exec, exec, s[0:1]
	v_or3_b32 v0, v72, v148, 2
	v_cmp_gt_i32_e32 vcc, s96, v0
	s_and_saveexec_b64 s[0:1], vcc
	s_cbranch_execz .LBB0_548
	v_mad_i64_i32 v[16:17], s[2:3], v0, s20, v[66:67]
	global_load_ushort v33, v[16:17], off
	global_load_ushort v100, v[16:17], off offset:64
	global_load_ushort v101, v[16:17], off offset:128
	global_load_ushort v102, v[16:17], off offset:192
	ds_read_b32 v1, v73 offset:8
	s_waitcnt lgkmcnt(0)
	v_rcp_f32_e32 v32, v1
	v_ashrrev_i32_e32 v1, 31, v0
	v_lshlrev_b64 v[0:1], 12, v[0:1]
	v_lshl_add_u64 v[0:1], v[64:65], 0, v[0:1]
	v_mul_f32_e32 v34, v34, v32
	v_mul_f32_e32 v18, v18, v32
	v_mul_f32_e32 v2, v2, v32
	s_waitcnt vmcnt(0)
	v_lshlrev_b32_e32 v33, 16, v33
	v_mul_f32_e32 v48, 0xbfb8aa3b, v33
	v_exp_f32_e32 v48, v48
	s_nop 0
	v_add_f32_e32 v48, 1.0, v48
	v_div_scale_f32 v49, s[2:3], v48, v48, v33
	v_rcp_f32_e32 v68, v49
	s_nop 0
	v_fma_f32 v69, -v49, v68, 1.0
	v_fmac_f32_e32 v68, v69, v68
	v_div_scale_f32 v69, vcc, v33, v48, v33
	v_mul_f32_e32 v70, v69, v68
	v_fma_f32 v71, -v49, v70, v69
	v_fmac_f32_e32 v70, v71, v68
	v_fma_f32 v49, -v49, v70, v69
	v_div_fmas_f32 v49, v49, v68, v70
	v_div_fixup_f32 v33, v49, v48, v33
	v_mul_f32_e32 v48, v50, v32
	v_mul_f32_e32 v33, v48, v33
	v_bfe_u32 v48, v33, 16, 1
	v_add3_u32 v33, v33, v48, s15
	global_store_short_d16_hi v[0:1], v33, off offset:1024


; __device__ __forceinline__ float bf2f(unsigned short b) { return __uint_as_float((unsigned)b << 16); }
; __device__ __forceinline__ unsigned f2bf(float f) { unsigned u = __float_as_uint(f); return (u + 0x7fffu + ((u >> 16) & 1u)) >> 16; }
; __device__ __forceinline__ float bf2f(unsigned short b) { return __uint_as_float((unsigned)b << 16); }
; __device__ __forceinline__ unsigned f2bf(float f) { unsigned u = __float_as_uint(f); return (u + 0x7fffu + ((u >> 16) & 1u)) >> 16; }
;     ...
;         for (int d0 = 0; d0 < 4; ++d0) { const float g = bf2f(Gb[(long)orow * ldg + d0 * 32 + r32]); const float sg = g / (1.f + __expf(-g));
;           Yb[(long)orow * ldy + d0 * 32 + r32] = (bf16)f2bf(o[d0][r] * rli * sg); }
	v_lshlrev_b32_e32 v33, 16, v100
	v_mul_f32_e32 v48, 0xbfb8aa3b, v33
	v_exp_f32_e32 v48, v48
	s_nop 0
	v_add_f32_e32 v48, 1.0, v48
	v_div_scale_f32 v49, s[2:3], v48, v48, v33
	v_rcp_f32_e32 v50, v49
	s_nop 0
	v_fma_f32 v68, -v49, v50, 1.0
	v_fmac_f32_e32 v50, v68, v50
	v_div_scale_f32 v68, vcc, v33, v48, v33
	v_mul_f32_e32 v69, v68, v50
	v_fma_f32 v70, -v49, v69, v68
	v_fmac_f32_e32 v69, v70, v50
	v_fma_f32 v49, -v49, v69, v68
	v_div_fmas_f32 v49, v49, v50, v69
	v_div_fixup_f32 v33, v49, v48, v33
	v_mul_f32_e32 v33, v34, v33
	v_bfe_u32 v34, v33, 16, 1
	v_add3_u32 v33, v33, v34, s15
	global_store_short_d16_hi v[0:1], v33, off offset:1088


; __device__ __forceinline__ float bf2f(unsigned short b) { return __uint_as_float((unsigned)b << 16); }
; __device__ __forceinline__ unsigned f2bf(float f) { unsigned u = __float_as_uint(f); return (u + 0x7fffu + ((u >> 16) & 1u)) >> 16; }
; __device__ __forceinline__ float bf2f(unsigned short b) { return __uint_as_float((unsigned)b << 16); }
; __device__ __forceinline__ unsigned f2bf(float f) { unsigned u = __float_as_uint(f); return (u + 0x7fffu + ((u >> 16) & 1u)) >> 16; }
;     ...
;         for (int d0 = 0; d0 < 4; ++d0) { const float g = bf2f(Gb[(long)orow * ldg + d0 * 32 + r32]); const float sg = g / (1.f + __expf(-g));
;           Yb[(long)orow * ldy + d0 * 32 + r32] = (bf16)f2bf(o[d0][r] * rli * sg); }
	v_lshlrev_b32_e32 v33, 16, v101

; __device__ __forceinline__ float bf2f(unsigned short b) { return __uint_as_float((unsigned)b << 16); }
; __device__ __forceinline__ unsigned f2bf(float f) { unsigned u = __float_as_uint(f); return (u + 0x7fffu + ((u >> 16) & 1u)) >> 16; }
; __device__ __forceinline__ float bf2f(unsigned short b) { return __uint_as_float((unsigned)b << 16); }
; __device__ __forceinline__ unsigned f2bf(float f) { unsigned u = __float_as_uint(f); return (u + 0x7fffu + ((u >> 16) & 1u)) >> 16; }
;     ...
;         for (int d0 = 0; d0 < 4; ++d0) { const float g = bf2f(Gb[(long)orow * ldg + d0 * 32 + r32]); const float sg = g / (1.f + __expf(-g));
;           Yb[(long)orow * ldy + d0 * 32 + r32] = (bf16)f2bf(o[d0][r] * rli * sg); }
	v_mul_f32_e32 v34, 0xbfb8aa3b, v33
	v_exp_f32_e32 v34, v34

; __device__ __forceinline__ int crow(int r, int hi) { return (r & 3) + 8 * (r >> 2) + 4 * hi; }
; __device__ __forceinline__ float bf2f(unsigned short b) { return __uint_as_float((unsigned)b << 16); }
; __device__ __forceinline__ unsigned f2bf(float f) { unsigned u = __float_as_uint(f); return (u + 0x7fffu + ((u >> 16) & 1u)) >> 16; }
; __device__ __forceinline__ float bf2f(unsigned short b) { return __uint_as_float((unsigned)b << 16); }
; __device__ __forceinline__ unsigned f2bf(float f) { unsigned u = __float_as_uint(f); return (u + 0x7fffu + ((u >> 16) & 1u)) >> 16; }
;     ...
;   for (int r = 0; r < 16; ++r) { const int orow = wid * QBLK + crow(r, hi); const float rli = __builtin_amdgcn_rcpf(li_l[crow(r, hi)]);
;     if (orow < nvalid) {
;       if constexpr (MODE == 0) {
; #pragma unroll
;         for (int d0 = 0; d0 < 4; ++d0) Of[(long)orow * ldo + d0 * 32 + r32] = o[d0][r] * rli;
;       } else {
; #pragma unroll
;         for (int d0 = 0; d0 < 4; ++d0) { const float g = bf2f(Gb[(long)orow * ldg + d0 * 32 + r32]); const float sg = g / (1.f + __expf(-g));
;           Yb[(long)orow * ldy + d0 * 32 + r32] = (bf16)f2bf(o[d0][r] * rli * sg); }
	v_lshlrev_b32_e32 v16, 16, v102
	v_add_f32_e32 v34, 1.0, v34
	v_div_scale_f32 v48, s[2:3], v34, v34, v33
	v_rcp_f32_e32 v49, v48
	v_mul_f32_e32 v17, 0xbfb8aa3b, v16
	v_exp_f32_e32 v17, v17
	v_fma_f32 v50, -v48, v49, 1.0
	v_fmac_f32_e32 v49, v50, v49
	v_div_scale_f32 v50, vcc, v33, v34, v33
	v_mul_f32_e32 v68, v50, v49
	v_fma_f32 v69, -v48, v68, v50
	v_fmac_f32_e32 v68, v69, v49
	v_fma_f32 v48, -v48, v68, v50
	v_div_fmas_f32 v48, v48, v49, v68
	v_div_fixup_f32 v33, v48, v34, v33
	v_mul_f32_e32 v18, v18, v33
	v_bfe_u32 v33, v18, 16, 1
	v_add3_u32 v18, v18, v33, s15
	v_add_f32_e32 v17, 1.0, v17
	global_store_short_d16_hi v[0:1], v18, off offset:1152
	v_div_scale_f32 v18, s[2:3], v17, v17, v16
	v_rcp_f32_e32 v33, v18
	s_nop 0
	v_fma_f32 v34, -v18, v33, 1.0
	v_fmac_f32_e32 v33, v34, v33
	v_div_scale_f32 v34, vcc, v16, v17, v16
	v_mul_f32_e32 v48, v34, v33
	v_fma_f32 v49, -v18, v48, v34
	v_fmac_f32_e32 v48, v49, v33
	v_fma_f32 v18, -v18, v48, v34
	v_div_fmas_f32 v18, v18, v33, v48
	v_div_fixup_f32 v16, v18, v17, v16
	v_mul_f32_e32 v2, v2, v16
	v_bfe_u32 v16, v2, 16, 1
	v_add3_u32 v2, v2, v16, s15
	global_store_short_d16_hi v[0:1], v2, off offset:1216
.LBB0_548:
	s_or_b64 exec, exec, s[0:1]
	v_or3_b32 v0, v72, v148, 3
	v_cmp_gt_i32_e32 vcc, s96, v0
	s_and_saveexec_b64 s[0:1], vcc
	s_cbranch_execz .LBB0_550
	v_mad_i64_i32 v[16:17], s[2:3], v0, s20, v[66:67]
	global_load_ushort v18, v[16:17], off
	global_load_ushort v100, v[16:17], off offset:64
	global_load_ushort v101, v[16:17], off offset:128
	global_load_ushort v102, v[16:17], off offset:192
	ds_read_b32 v1, v73 offset:12
	s_waitcnt lgkmcnt(0)
	v_rcp_f32_e32 v2, v1
	v_ashrrev_i32_e32 v1, 31, v0
	v_lshlrev_b64 v[0:1], 12, v[0:1]
	v_lshl_add_u64 v[0:1], v[64:65], 0, v[0:1]
	v_mul_f32_e32 v19, v19, v2
	s_waitcnt vmcnt(0)
	v_lshlrev_b32_e32 v18, 16, v18
	v_mul_f32_e32 v32, 0xbfb8aa3b, v18
	v_exp_f32_e32 v32, v32
	s_nop 0
	v_add_f32_e32 v32, 1.0, v32
	v_div_scale_f32 v33, s[2:3], v32, v32, v18
	v_rcp_f32_e32 v34, v33
	s_nop 0
	v_fma_f32 v48, -v33, v34, 1.0
	v_fmac_f32_e32 v34, v48, v34
	v_div_scale_f32 v48, vcc, v18, v32, v18
	v_mul_f32_e32 v49, v48, v34
	v_fma_f32 v50, -v33, v49, v48
	v_fmac_f32_e32 v49, v50, v34
	v_fma_f32 v33, -v33, v49, v48
	v_div_fmas_f32 v33, v33, v34, v49
	v_div_fixup_f32 v18, v33, v32, v18
	v_mul_f32_e32 v32, v51, v2
	v_mul_f32_e32 v18, v32, v18
	v_bfe_u32 v32, v18, 16, 1
	v_add3_u32 v18, v18, v32, s15
	global_store_short_d16_hi v[0:1], v18, off offset:1024


; __device__ __forceinline__ float bf2f(unsigned short b) { return __uint_as_float((unsigned)b << 16); }
; __device__ __forceinline__ unsigned f2bf(float f) { unsigned u = __float_as_uint(f); return (u + 0x7fffu + ((u >> 16) & 1u)) >> 16; }
; __device__ __forceinline__ float bf2f(unsigned short b) { return __uint_as_float((unsigned)b << 16); }
; __device__ __forceinline__ unsigned f2bf(float f) { unsigned u = __float_as_uint(f); return (u + 0x7fffu + ((u >> 16) & 1u)) >> 16; }
;     ...
;         for (int d0 = 0; d0 < 4; ++d0) { const float g = bf2f(Gb[(long)orow * ldg + d0 * 32 + r32]); const float sg = g / (1.f + __expf(-g));
;           Yb[(long)orow * ldy + d0 * 32 + r32] = (bf16)f2bf(o[d0][r] * rli * sg); }
	v_lshlrev_b32_e32 v18, 16, v100
	v_mul_f32_e32 v32, 0xbfb8aa3b, v18
	v_exp_f32_e32 v32, v32
	s_nop 0
	v_add_f32_e32 v32, 1.0, v32
	v_div_scale_f32 v33, s[2:3], v32, v32, v18
	v_rcp_f32_e32 v34, v33
	s_nop 0
	v_fma_f32 v48, -v33, v34, 1.0
	v_fmac_f32_e32 v34, v48, v34
	v_div_scale_f32 v48, vcc, v18, v32, v18
	v_mul_f32_e32 v49, v48, v34
	v_fma_f32 v50, -v33, v49, v48
	v_fmac_f32_e32 v49, v50, v34
	v_fma_f32 v33, -v33, v49, v48
	v_div_fmas_f32 v33, v33, v34, v49
	v_div_fixup_f32 v18, v33, v32, v18
	v_mul_f32_e32 v32, v35, v2
	v_mul_f32_e32 v18, v32, v18
	v_bfe_u32 v32, v18, 16, 1
	v_add3_u32 v18, v18, v32, s15
	global_store_short_d16_hi v[0:1], v18, off offset:1088

; __device__ __forceinline__ float bf2f(unsigned short b) { return __uint_as_float((unsigned)b << 16); }
; __device__ __forceinline__ unsigned f2bf(float f) { unsigned u = __float_as_uint(f); return (u + 0x7fffu + ((u >> 16) & 1u)) >> 16; }
; __device__ __forceinline__ float bf2f(unsigned short b) { return __uint_as_float((unsigned)b << 16); }
; __device__ __forceinline__ unsigned f2bf(float f) { unsigned u = __float_as_uint(f); return (u + 0x7fffu + ((u >> 16) & 1u)) >> 16; }
;     ...
;         for (int d0 = 0; d0 < 4; ++d0) { const float g = bf2f(Gb[(long)orow * ldg + d0 * 32 + r32]); const float sg = g / (1.f + __expf(-g));
;           Yb[(long)orow * ldy + d0 * 32 + r32] = (bf16)f2bf(o[d0][r] * rli * sg); }
	v_mul_f32_e32 v2, v3, v2


; __device__ __forceinline__ float bf2f(unsigned short b) { return __uint_as_float((unsigned)b << 16); }
; __device__ __forceinline__ unsigned f2bf(float f) { unsigned u = __float_as_uint(f); return (u + 0x7fffu + ((u >> 16) & 1u)) >> 16; }
; __device__ __forceinline__ float bf2f(unsigned short b) { return __uint_as_float((unsigned)b << 16); }
; __device__ __forceinline__ unsigned f2bf(float f) { unsigned u = __float_as_uint(f); return (u + 0x7fffu + ((u >> 16) & 1u)) >> 16; }
;     ...
;         for (int d0 = 0; d0 < 4; ++d0) { const float g = bf2f(Gb[(long)orow * ldg + d0 * 32 + r32]); const float sg = g / (1.f + __expf(-g));
;           Yb[(long)orow * ldy + d0 * 32 + r32] = (bf16)f2bf(o[d0][r] * rli * sg); }
	v_lshlrev_b32_e32 v18, 16, v101
	v_mul_f32_e32 v32, 0xbfb8aa3b, v18
	v_exp_f32_e32 v32, v32

; __device__ __forceinline__ int crow(int r, int hi) { return (r & 3) + 8 * (r >> 2) + 4 * hi; }
; __device__ __forceinline__ float bf2f(unsigned short b) { return __uint_as_float((unsigned)b << 16); }
; __device__ __forceinline__ unsigned f2bf(float f) { unsigned u = __float_as_uint(f); return (u + 0x7fffu + ((u >> 16) & 1u)) >> 16; }
; __device__ __forceinline__ float bf2f(unsigned short b) { return __uint_as_float((unsigned)b << 16); }
; __device__ __forceinline__ unsigned f2bf(float f) { unsigned u = __float_as_uint(f); return (u + 0x7fffu + ((u >> 16) & 1u)) >> 16; }
;     ...
;   for (int r = 0; r < 16; ++r) { const int orow = wid * QBLK + crow(r, hi); const float rli = __builtin_amdgcn_rcpf(li_l[crow(r, hi)]);
;     if (orow < nvalid) {
;       if constexpr (MODE == 0) {
; #pragma unroll
;         for (int d0 = 0; d0 < 4; ++d0) Of[(long)orow * ldo + d0 * 32 + r32] = o[d0][r] * rli;
;       } else {
; #pragma unroll
;         for (int d0 = 0; d0 < 4; ++d0) { const float g = bf2f(Gb[(long)orow * ldg + d0 * 32 + r32]); const float sg = g / (1.f + __expf(-g));
;           Yb[(long)orow * ldy + d0 * 32 + r32] = (bf16)f2bf(o[d0][r] * rli * sg); }
	v_lshlrev_b32_e32 v16, 16, v102
	v_mul_f32_e32 v17, 0xbfb8aa3b, v16
	v_exp_f32_e32 v17, v17
	v_add_f32_e32 v32, 1.0, v32
	v_div_scale_f32 v33, s[2:3], v32, v32, v18
	v_rcp_f32_e32 v34, v33
	v_add_f32_e32 v17, 1.0, v17
	v_fma_f32 v35, -v33, v34, 1.0
	v_fmac_f32_e32 v34, v35, v34
	v_div_scale_f32 v35, vcc, v18, v32, v18
	v_mul_f32_e32 v48, v35, v34
	v_fma_f32 v49, -v33, v48, v35
	v_fmac_f32_e32 v48, v49, v34
	v_fma_f32 v33, -v33, v48, v35
	v_div_fmas_f32 v33, v33, v34, v48
	v_div_fixup_f32 v18, v33, v32, v18
	v_mul_f32_e32 v18, v19, v18
	v_bfe_u32 v19, v18, 16, 1
	v_add3_u32 v18, v18, v19, s15
	global_store_short_d16_hi v[0:1], v18, off offset:1152
	v_div_scale_f32 v18, s[2:3], v17, v17, v16
	v_rcp_f32_e32 v19, v18
	s_nop 0
	v_fma_f32 v32, -v18, v19, 1.0
	v_fmac_f32_e32 v19, v32, v19
	v_div_scale_f32 v32, vcc, v16, v17, v16
	v_mul_f32_e32 v33, v32, v19
	v_fma_f32 v34, -v18, v33, v32
	v_fmac_f32_e32 v33, v34, v19
	v_fma_f32 v18, -v18, v33, v32
	v_div_fmas_f32 v18, v18, v19, v33
	v_div_fixup_f32 v16, v18, v17, v16
	v_mul_f32_e32 v2, v2, v16
	v_bfe_u32 v3, v2, 16, 1
	v_add3_u32 v2, v2, v3, s15
	global_store_short_d16_hi v[0:1], v2, off offset:1216
.LBB0_550:
	s_or_b64 exec, exec, s[0:1]
	v_or3_b32 v0, v72, v148, 8
	v_cmp_gt_i32_e32 vcc, s96, v0
	s_and_saveexec_b64 s[0:1], vcc
	s_cbranch_execz .LBB0_552
	v_mad_i64_i32 v[2:3], s[2:3], v0, s20, v[66:67]
	global_load_ushort v17, v[2:3], off
	global_load_ushort v100, v[2:3], off offset:64
	global_load_ushort v101, v[2:3], off offset:128
	global_load_ushort v102, v[2:3], off offset:192
	ds_read_b32 v1, v73 offset:32
	s_waitcnt lgkmcnt(0)
	v_rcp_f32_e32 v16, v1
	v_ashrrev_i32_e32 v1, 31, v0
	v_lshlrev_b64 v[0:1], 12, v[0:1]
	v_lshl_add_u64 v[0:1], v[64:65], 0, v[0:1]
	s_waitcnt vmcnt(0)
	v_lshlrev_b32_e32 v17, 16, v17
	v_mul_f32_e32 v18, 0xbfb8aa3b, v17
	v_exp_f32_e32 v18, v18
	s_nop 0
	v_add_f32_e32 v18, 1.0, v18
	v_div_scale_f32 v19, s[2:3], v18, v18, v17
	v_rcp_f32_e32 v32, v19
	s_nop 0
	v_fma_f32 v33, -v19, v32, 1.0
	v_fmac_f32_e32 v32, v33, v32
	v_div_scale_f32 v33, vcc, v17, v18, v17
	v_mul_f32_e32 v34, v33, v32
	v_fma_f32 v35, -v19, v34, v33
	v_fmac_f32_e32 v34, v35, v32
	v_fma_f32 v19, -v19, v34, v33
	v_div_fmas_f32 v19, v19, v32, v34
	v_div_fixup_f32 v17, v19, v18, v17
	v_mul_f32_e32 v18, v52, v16
	v_mul_f32_e32 v17, v18, v17
	v_bfe_u32 v18, v17, 16, 1
	v_add3_u32 v17, v17, v18, s15
	global_store_short_d16_hi v[0:1], v17, off offset:1024


; __device__ __forceinline__ float bf2f(unsigned short b) { return __uint_as_float((unsigned)b << 16); }
; __device__ __forceinline__ unsigned f2bf(float f) { unsigned u = __float_as_uint(f); return (u + 0x7fffu + ((u >> 16) & 1u)) >> 16; }
; __device__ __forceinline__ float bf2f(unsigned short b) { return __uint_as_float((unsigned)b << 16); }
; __device__ __forceinline__ unsigned f2bf(float f) { unsigned u = __float_as_uint(f); return (u + 0x7fffu + ((u >> 16) & 1u)) >> 16; }
;     ...
;         for (int d0 = 0; d0 < 4; ++d0) { const float g = bf2f(Gb[(long)orow * ldg + d0 * 32 + r32]); const float sg = g / (1.f + __expf(-g));
;           Yb[(long)orow * ldy + d0 * 32 + r32] = (bf16)f2bf(o[d0][r] * rli * sg); }
	v_lshlrev_b32_e32 v17, 16, v100
	v_mul_f32_e32 v18, 0xbfb8aa3b, v17
	v_exp_f32_e32 v18, v18
	s_nop 0
	v_add_f32_e32 v18, 1.0, v18
	v_div_scale_f32 v19, s[2:3], v18, v18, v17
	v_rcp_f32_e32 v32, v19
	s_nop 0
	v_fma_f32 v33, -v19, v32, 1.0
	v_fmac_f32_e32 v32, v33, v32
	v_div_scale_f32 v33, vcc, v17, v18, v17
	v_mul_f32_e32 v34, v33, v32
	v_fma_f32 v35, -v19, v34, v33
	v_fmac_f32_e32 v34, v35, v32
	v_fma_f32 v19, -v19, v34, v33
	v_div_fmas_f32 v19, v19, v32, v34
	v_div_fixup_f32 v17, v19, v18, v17
	v_mul_f32_e32 v18, v36, v16
	v_mul_f32_e32 v17, v18, v17
	v_bfe_u32 v18, v17, 16, 1
	v_add3_u32 v17, v17, v18, s15
	global_store_short_d16_hi v[0:1], v17, off offset:1088


; __device__ __forceinline__ float bf2f(unsigned short b) { return __uint_as_float((unsigned)b << 16); }
; __device__ __forceinline__ unsigned f2bf(float f) { unsigned u = __float_as_uint(f); return (u + 0x7fffu + ((u >> 16) & 1u)) >> 16; }
; __device__ __forceinline__ float bf2f(unsigned short b) { return __uint_as_float((unsigned)b << 16); }
; __device__ __forceinline__ unsigned f2bf(float f) { unsigned u = __float_as_uint(f); return (u + 0x7fffu + ((u >> 16) & 1u)) >> 16; }
;     ...
;         for (int d0 = 0; d0 < 4; ++d0) { const float g = bf2f(Gb[(long)orow * ldg + d0 * 32 + r32]); const float sg = g / (1.f + __expf(-g));
;           Yb[(long)orow * ldy + d0 * 32 + r32] = (bf16)f2bf(o[d0][r] * rli * sg); }
	v_lshlrev_b32_e32 v17, 16, v101

; __device__ __forceinline__ float bf2f(unsigned short b) { return __uint_as_float((unsigned)b << 16); }
; __device__ __forceinline__ unsigned f2bf(float f) { unsigned u = __float_as_uint(f); return (u + 0x7fffu + ((u >> 16) & 1u)) >> 16; }
; __device__ __forceinline__ float bf2f(unsigned short b) { return __uint_as_float((unsigned)b << 16); }
; __device__ __forceinline__ unsigned f2bf(float f) { unsigned u = __float_as_uint(f); return (u + 0x7fffu + ((u >> 16) & 1u)) >> 16; }
;     ...
;         for (int d0 = 0; d0 < 4; ++d0) { const float g = bf2f(Gb[(long)orow * ldg + d0 * 32 + r32]); const float sg = g / (1.f + __expf(-g));
;           Yb[(long)orow * ldy + d0 * 32 + r32] = (bf16)f2bf(o[d0][r] * rli * sg); }
	v_mul_f32_e32 v18, 0xbfb8aa3b, v17
	v_exp_f32_e32 v18, v18

; __device__ __forceinline__ int crow(int r, int hi) { return (r & 3) + 8 * (r >> 2) + 4 * hi; }
; __device__ __forceinline__ float bf2f(unsigned short b) { return __uint_as_float((unsigned)b << 16); }
; __device__ __forceinline__ unsigned f2bf(float f) { unsigned u = __float_as_uint(f); return (u + 0x7fffu + ((u >> 16) & 1u)) >> 16; }
; __device__ __forceinline__ float bf2f(unsigned short b) { return __uint_as_float((unsigned)b << 16); }
; __device__ __forceinline__ unsigned f2bf(float f) { unsigned u = __float_as_uint(f); return (u + 0x7fffu + ((u >> 16) & 1u)) >> 16; }
;     ...
;   for (int r = 0; r < 16; ++r) { const int orow = wid * QBLK + crow(r, hi); const float rli = __builtin_amdgcn_rcpf(li_l[crow(r, hi)]);
;     if (orow < nvalid) {
;       if constexpr (MODE == 0) {
; #pragma unroll
;         for (int d0 = 0; d0 < 4; ++d0) Of[(long)orow * ldo + d0 * 32 + r32] = o[d0][r] * rli;
;       } else {
; #pragma unroll
;         for (int d0 = 0; d0 < 4; ++d0) { const float g = bf2f(Gb[(long)orow * ldg + d0 * 32 + r32]); const float sg = g / (1.f + __expf(-g));
;           Yb[(long)orow * ldy + d0 * 32 + r32] = (bf16)f2bf(o[d0][r] * rli * sg); }
	v_lshlrev_b32_e32 v2, 16, v102
	v_add_f32_e32 v18, 1.0, v18
	v_div_scale_f32 v19, s[2:3], v18, v18, v17
	v_rcp_f32_e32 v32, v19
	v_mul_f32_e32 v3, 0xbfb8aa3b, v2
	v_exp_f32_e32 v3, v3
	v_fma_f32 v33, -v19, v32, 1.0
	v_fmac_f32_e32 v32, v33, v32
	v_div_scale_f32 v33, vcc, v17, v18, v17
	v_mul_f32_e32 v34, v33, v32
	v_fma_f32 v35, -v19, v34, v33
	v_fmac_f32_e32 v34, v35, v32
	v_fma_f32 v19, -v19, v34, v33
	v_div_fmas_f32 v19, v19, v32, v34
	v_div_fixup_f32 v17, v19, v18, v17
	v_mul_f32_e32 v18, v20, v16
	v_mul_f32_e32 v17, v18, v17
	v_bfe_u32 v18, v17, 16, 1
	v_add3_u32 v17, v17, v18, s15
	v_add_f32_e32 v3, 1.0, v3
	global_store_short_d16_hi v[0:1], v17, off offset:1152
	v_div_scale_f32 v17, s[2:3], v3, v3, v2
	v_rcp_f32_e32 v18, v17
	s_nop 0
	v_fma_f32 v19, -v17, v18, 1.0
	v_fmac_f32_e32 v18, v19, v18
	v_div_scale_f32 v19, vcc, v2, v3, v2
	v_mul_f32_e32 v20, v19, v18
	v_fma_f32 v32, -v17, v20, v19
	v_fmac_f32_e32 v20, v32, v18
	v_fma_f32 v17, -v17, v20, v19
	v_div_fmas_f32 v17, v17, v18, v20
	v_div_fixup_f32 v2, v17, v3, v2
	v_mul_f32_e32 v3, v4, v16
	v_mul_f32_e32 v2, v3, v2
	v_bfe_u32 v3, v2, 16, 1
	v_add3_u32 v2, v2, v3, s15
	global_store_short_d16_hi v[0:1], v2, off offset:1216
.LBB0_552:
	s_or_b64 exec, exec, s[0:1]
	v_or3_b32 v0, v72, v148, 9
	v_cmp_gt_i32_e32 vcc, s96, v0
	s_and_saveexec_b64 s[0:1], vcc
	s_cbranch_execz .LBB0_554
	v_mad_i64_i32 v[2:3], s[2:3], v0, s20, v[66:67]
	global_load_ushort v16, v[2:3], off
	global_load_ushort v100, v[2:3], off offset:64
	global_load_ushort v101, v[2:3], off offset:128
	global_load_ushort v102, v[2:3], off offset:192
	ds_read_b32 v1, v73 offset:36
	s_waitcnt lgkmcnt(0)
	v_rcp_f32_e32 v4, v1
	v_ashrrev_i32_e32 v1, 31, v0
	v_lshlrev_b64 v[0:1], 12, v[0:1]
	v_lshl_add_u64 v[0:1], v[64:65], 0, v[0:1]
	s_waitcnt vmcnt(0)
	v_lshlrev_b32_e32 v16, 16, v16
	v_mul_f32_e32 v17, 0xbfb8aa3b, v16
	v_exp_f32_e32 v17, v17
	s_nop 0
	v_add_f32_e32 v17, 1.0, v17
	v_div_scale_f32 v18, s[2:3], v17, v17, v16
	v_rcp_f32_e32 v19, v18
	s_nop 0
	v_fma_f32 v20, -v18, v19, 1.0
	v_fmac_f32_e32 v19, v20, v19
	v_div_scale_f32 v20, vcc, v16, v17, v16
	v_mul_f32_e32 v32, v20, v19
	v_fma_f32 v33, -v18, v32, v20
	v_fmac_f32_e32 v32, v33, v19
	v_fma_f32 v18, -v18, v32, v20
	v_div_fmas_f32 v18, v18, v19, v32
	v_div_fixup_f32 v16, v18, v17, v16
	v_mul_f32_e32 v17, v53, v4
	v_mul_f32_e32 v16, v17, v16
	v_bfe_u32 v17, v16, 16, 1
	v_add3_u32 v16, v16, v17, s15
	global_store_short_d16_hi v[0:1], v16, off offset:1024


; __device__ __forceinline__ float bf2f(unsigned short b) { return __uint_as_float((unsigned)b << 16); }
; __device__ __forceinline__ unsigned f2bf(float f) { unsigned u = __float_as_uint(f); return (u + 0x7fffu + ((u >> 16) & 1u)) >> 16; }
; __device__ __forceinline__ float bf2f(unsigned short b) { return __uint_as_float((unsigned)b << 16); }
; __device__ __forceinline__ unsigned f2bf(float f) { unsigned u = __float_as_uint(f); return (u + 0x7fffu + ((u >> 16) & 1u)) >> 16; }
;     ...
;         for (int d0 = 0; d0 < 4; ++d0) { const float g = bf2f(Gb[(long)orow * ldg + d0 * 32 + r32]); const float sg = g / (1.f + __expf(-g));
;           Yb[(long)orow * ldy + d0 * 32 + r32] = (bf16)f2bf(o[d0][r] * rli * sg); }
	v_lshlrev_b32_e32 v16, 16, v100
	v_mul_f32_e32 v17, 0xbfb8aa3b, v16
	v_exp_f32_e32 v17, v17
	s_nop 0
	v_add_f32_e32 v17, 1.0, v17
	v_div_scale_f32 v18, s[2:3], v17, v17, v16
	v_rcp_f32_e32 v19, v18
	s_nop 0
	v_fma_f32 v20, -v18, v19, 1.0
	v_fmac_f32_e32 v19, v20, v19
	v_div_scale_f32 v20, vcc, v16, v17, v16
	v_mul_f32_e32 v32, v20, v19
	v_fma_f32 v33, -v18, v32, v20
	v_fmac_f32_e32 v32, v33, v19
	v_fma_f32 v18, -v18, v32, v20
	v_div_fmas_f32 v18, v18, v19, v32
	v_div_fixup_f32 v16, v18, v17, v16
	v_mul_f32_e32 v17, v37, v4
	v_mul_f32_e32 v16, v17, v16
	v_bfe_u32 v17, v16, 16, 1
	v_add3_u32 v16, v16, v17, s15
	global_store_short_d16_hi v[0:1], v16, off offset:1088


; __device__ __forceinline__ float bf2f(unsigned short b) { return __uint_as_float((unsigned)b << 16); }
; __device__ __forceinline__ unsigned f2bf(float f) { unsigned u = __float_as_uint(f); return (u + 0x7fffu + ((u >> 16) & 1u)) >> 16; }
; __device__ __forceinline__ float bf2f(unsigned short b) { return __uint_as_float((unsigned)b << 16); }
; __device__ __forceinline__ unsigned f2bf(float f) { unsigned u = __float_as_uint(f); return (u + 0x7fffu + ((u >> 16) & 1u)) >> 16; }
;     ...
;         for (int d0 = 0; d0 < 4; ++d0) { const float g = bf2f(Gb[(long)orow * ldg + d0 * 32 + r32]); const float sg = g / (1.f + __expf(-g));
;           Yb[(long)orow * ldy + d0 * 32 + r32] = (bf16)f2bf(o[d0][r] * rli * sg); }
	v_lshlrev_b32_e32 v16, 16, v101

; __device__ __forceinline__ float bf2f(unsigned short b) { return __uint_as_float((unsigned)b << 16); }
; __device__ __forceinline__ unsigned f2bf(float f) { unsigned u = __float_as_uint(f); return (u + 0x7fffu + ((u >> 16) & 1u)) >> 16; }
; __device__ __forceinline__ float bf2f(unsigned short b) { return __uint_as_float((unsigned)b << 16); }
; __device__ __forceinline__ unsigned f2bf(float f) { unsigned u = __float_as_uint(f); return (u + 0x7fffu + ((u >> 16) & 1u)) >> 16; }
;     ...
;         for (int d0 = 0; d0 < 4; ++d0) { const float g = bf2f(Gb[(long)orow * ldg + d0 * 32 + r32]); const float sg = g / (1.f + __expf(-g));
;           Yb[(long)orow * ldy + d0 * 32 + r32] = (bf16)f2bf(o[d0][r] * rli * sg); }
	v_mul_f32_e32 v17, 0xbfb8aa3b, v16
	v_exp_f32_e32 v17, v17

; __device__ __forceinline__ int crow(int r, int hi) { return (r & 3) + 8 * (r >> 2) + 4 * hi; }
; __device__ __forceinline__ float bf2f(unsigned short b) { return __uint_as_float((unsigned)b << 16); }
; __device__ __forceinline__ unsigned f2bf(float f) { unsigned u = __float_as_uint(f); return (u + 0x7fffu + ((u >> 16) & 1u)) >> 16; }
; __device__ __forceinline__ float bf2f(unsigned short b) { return __uint_as_float((unsigned)b << 16); }
; __device__ __forceinline__ unsigned f2bf(float f) { unsigned u = __float_as_uint(f); return (u + 0x7fffu + ((u >> 16) & 1u)) >> 16; }
;     ...
;   for (int r = 0; r < 16; ++r) { const int orow = wid * QBLK + crow(r, hi); const float rli = __builtin_amdgcn_rcpf(li_l[crow(r, hi)]);
;     if (orow < nvalid) {
;       if constexpr (MODE == 0) {
; #pragma unroll
;         for (int d0 = 0; d0 < 4; ++d0) Of[(long)orow * ldo + d0 * 32 + r32] = o[d0][r] * rli;
;       } else {
; #pragma unroll
;         for (int d0 = 0; d0 < 4; ++d0) { const float g = bf2f(Gb[(long)orow * ldg + d0 * 32 + r32]); const float sg = g / (1.f + __expf(-g));
;           Yb[(long)orow * ldy + d0 * 32 + r32] = (bf16)f2bf(o[d0][r] * rli * sg); }
	v_lshlrev_b32_e32 v2, 16, v102
	v_add_f32_e32 v17, 1.0, v17
	v_div_scale_f32 v18, s[2:3], v17, v17, v16
	v_rcp_f32_e32 v19, v18
	v_mul_f32_e32 v3, 0xbfb8aa3b, v2
	v_exp_f32_e32 v3, v3
	v_fma_f32 v20, -v18, v19, 1.0
	v_fmac_f32_e32 v19, v20, v19
	v_div_scale_f32 v20, vcc, v16, v17, v16
	v_mul_f32_e32 v32, v20, v19
	v_fma_f32 v33, -v18, v32, v20
	v_fmac_f32_e32 v32, v33, v19
	v_fma_f32 v18, -v18, v32, v20
	v_div_fmas_f32 v18, v18, v19, v32
	v_div_fixup_f32 v16, v18, v17, v16
	v_mul_f32_e32 v17, v21, v4
	v_mul_f32_e32 v16, v17, v16
	v_bfe_u32 v17, v16, 16, 1
	v_add3_u32 v16, v16, v17, s15
	v_add_f32_e32 v3, 1.0, v3
	global_store_short_d16_hi v[0:1], v16, off offset:1152
	v_div_scale_f32 v16, s[2:3], v3, v3, v2
	v_rcp_f32_e32 v17, v16
	s_nop 0
	v_fma_f32 v18, -v16, v17, 1.0
	v_fmac_f32_e32 v17, v18, v17
	v_div_scale_f32 v18, vcc, v2, v3, v2
	v_mul_f32_e32 v19, v18, v17
	v_fma_f32 v20, -v16, v19, v18
	v_fmac_f32_e32 v19, v20, v17
	v_fma_f32 v16, -v16, v19, v18
	v_div_fmas_f32 v16, v16, v17, v19
	v_div_fixup_f32 v2, v16, v3, v2
	v_mul_f32_e32 v3, v5, v4
	v_mul_f32_e32 v2, v3, v2
	v_bfe_u32 v3, v2, 16, 1
	v_add3_u32 v2, v2, v3, s15
	global_store_short_d16_hi v[0:1], v2, off offset:1216
.LBB0_554:
	s_or_b64 exec, exec, s[0:1]
	v_or3_b32 v0, v72, v148, 10
	v_cmp_gt_i32_e32 vcc, s96, v0
	s_and_saveexec_b64 s[0:1], vcc
	s_cbranch_execz .LBB0_556
	v_mad_i64_i32 v[2:3], s[2:3], v0, s20, v[66:67]
	global_load_ushort v5, v[2:3], off
	global_load_ushort v100, v[2:3], off offset:64
	global_load_ushort v101, v[2:3], off offset:128
	global_load_ushort v102, v[2:3], off offset:192
	ds_read_b32 v1, v73 offset:40
	s_waitcnt lgkmcnt(0)
	v_rcp_f32_e32 v4, v1
	v_ashrrev_i32_e32 v1, 31, v0
	v_lshlrev_b64 v[0:1], 12, v[0:1]
	v_lshl_add_u64 v[0:1], v[64:65], 0, v[0:1]
	s_waitcnt vmcnt(0)
	v_lshlrev_b32_e32 v5, 16, v5
	v_mul_f32_e32 v16, 0xbfb8aa3b, v5
	v_exp_f32_e32 v16, v16
	s_nop 0
	v_add_f32_e32 v16, 1.0, v16
	v_div_scale_f32 v17, s[2:3], v16, v16, v5
	v_rcp_f32_e32 v18, v17
	s_nop 0
	v_fma_f32 v19, -v17, v18, 1.0
	v_fmac_f32_e32 v18, v19, v18
	v_div_scale_f32 v19, vcc, v5, v16, v5
	v_mul_f32_e32 v20, v19, v18
	v_fma_f32 v21, -v17, v20, v19
	v_fmac_f32_e32 v20, v21, v18
	v_fma_f32 v17, -v17, v20, v19
	v_div_fmas_f32 v17, v17, v18, v20
	v_div_fixup_f32 v5, v17, v16, v5
	v_mul_f32_e32 v16, v54, v4
	v_mul_f32_e32 v5, v16, v5
	v_bfe_u32 v16, v5, 16, 1
	v_add3_u32 v5, v5, v16, s15
	global_store_short_d16_hi v[0:1], v5, off offset:1024


; __device__ __forceinline__ float bf2f(unsigned short b) { return __uint_as_float((unsigned)b << 16); }
; __device__ __forceinline__ unsigned f2bf(float f) { unsigned u = __float_as_uint(f); return (u + 0x7fffu + ((u >> 16) & 1u)) >> 16; }
; __device__ __forceinline__ float bf2f(unsigned short b) { return __uint_as_float((unsigned)b << 16); }
; __device__ __forceinline__ unsigned f2bf(float f) { unsigned u = __float_as_uint(f); return (u + 0x7fffu + ((u >> 16) & 1u)) >> 16; }
;     ...
;         for (int d0 = 0; d0 < 4; ++d0) { const float g = bf2f(Gb[(long)orow * ldg + d0 * 32 + r32]); const float sg = g / (1.f + __expf(-g));
;           Yb[(long)orow * ldy + d0 * 32 + r32] = (bf16)f2bf(o[d0][r] * rli * sg); }
	v_lshlrev_b32_e32 v5, 16, v100
	v_mul_f32_e32 v16, 0xbfb8aa3b, v5
	v_exp_f32_e32 v16, v16
	s_nop 0
	v_add_f32_e32 v16, 1.0, v16
	v_div_scale_f32 v17, s[2:3], v16, v16, v5
	v_rcp_f32_e32 v18, v17
	s_nop 0
	v_fma_f32 v19, -v17, v18, 1.0
	v_fmac_f32_e32 v18, v19, v18
	v_div_scale_f32 v19, vcc, v5, v16, v5
	v_mul_f32_e32 v20, v19, v18
	v_fma_f32 v21, -v17, v20, v19
	v_fmac_f32_e32 v20, v21, v18
	v_fma_f32 v17, -v17, v20, v19
	v_div_fmas_f32 v17, v17, v18, v20
	v_div_fixup_f32 v5, v17, v16, v5
	v_mul_f32_e32 v16, v38, v4
	v_mul_f32_e32 v5, v16, v5
	v_bfe_u32 v16, v5, 16, 1
	v_add3_u32 v5, v5, v16, s15
	global_store_short_d16_hi v[0:1], v5, off offset:1088


; __device__ __forceinline__ float bf2f(unsigned short b) { return __uint_as_float((unsigned)b << 16); }
; __device__ __forceinline__ unsigned f2bf(float f) { unsigned u = __float_as_uint(f); return (u + 0x7fffu + ((u >> 16) & 1u)) >> 16; }
; __device__ __forceinline__ float bf2f(unsigned short b) { return __uint_as_float((unsigned)b << 16); }
; __device__ __forceinline__ unsigned f2bf(float f) { unsigned u = __float_as_uint(f); return (u + 0x7fffu + ((u >> 16) & 1u)) >> 16; }
;     ...
;         for (int d0 = 0; d0 < 4; ++d0) { const float g = bf2f(Gb[(long)orow * ldg + d0 * 32 + r32]); const float sg = g / (1.f + __expf(-g));
;           Yb[(long)orow * ldy + d0 * 32 + r32] = (bf16)f2bf(o[d0][r] * rli * sg); }
	v_lshlrev_b32_e32 v5, 16, v101

; __device__ __forceinline__ float bf2f(unsigned short b) { return __uint_as_float((unsigned)b << 16); }
; __device__ __forceinline__ unsigned f2bf(float f) { unsigned u = __float_as_uint(f); return (u + 0x7fffu + ((u >> 16) & 1u)) >> 16; }
; __device__ __forceinline__ float bf2f(unsigned short b) { return __uint_as_float((unsigned)b << 16); }
; __device__ __forceinline__ unsigned f2bf(float f) { unsigned u = __float_as_uint(f); return (u + 0x7fffu + ((u >> 16) & 1u)) >> 16; }
;     ...
;         for (int d0 = 0; d0 < 4; ++d0) { const float g = bf2f(Gb[(long)orow * ldg + d0 * 32 + r32]); const float sg = g / (1.f + __expf(-g));
;           Yb[(long)orow * ldy + d0 * 32 + r32] = (bf16)f2bf(o[d0][r] * rli * sg); }
	v_mul_f32_e32 v16, 0xbfb8aa3b, v5
	v_exp_f32_e32 v16, v16

; __device__ __forceinline__ int crow(int r, int hi) { return (r & 3) + 8 * (r >> 2) + 4 * hi; }
; __device__ __forceinline__ float bf2f(unsigned short b) { return __uint_as_float((unsigned)b << 16); }
; __device__ __forceinline__ unsigned f2bf(float f) { unsigned u = __float_as_uint(f); return (u + 0x7fffu + ((u >> 16) & 1u)) >> 16; }
; __device__ __forceinline__ float bf2f(unsigned short b) { return __uint_as_float((unsigned)b << 16); }
; __device__ __forceinline__ unsigned f2bf(float f) { unsigned u = __float_as_uint(f); return (u + 0x7fffu + ((u >> 16) & 1u)) >> 16; }
;     ...
;   for (int r = 0; r < 16; ++r) { const int orow = wid * QBLK + crow(r, hi); const float rli = __builtin_amdgcn_rcpf(li_l[crow(r, hi)]);
;     if (orow < nvalid) {
;       if constexpr (MODE == 0) {
; #pragma unroll
;         for (int d0 = 0; d0 < 4; ++d0) Of[(long)orow * ldo + d0 * 32 + r32] = o[d0][r] * rli;
;       } else {
; #pragma unroll
;         for (int d0 = 0; d0 < 4; ++d0) { const float g = bf2f(Gb[(long)orow * ldg + d0 * 32 + r32]); const float sg = g / (1.f + __expf(-g));
;           Yb[(long)orow * ldy + d0 * 32 + r32] = (bf16)f2bf(o[d0][r] * rli * sg); }
	v_lshlrev_b32_e32 v2, 16, v102
	v_add_f32_e32 v16, 1.0, v16
	v_div_scale_f32 v17, s[2:3], v16, v16, v5
	v_rcp_f32_e32 v18, v17
	v_mul_f32_e32 v3, 0xbfb8aa3b, v2
	v_exp_f32_e32 v3, v3
	v_fma_f32 v19, -v17, v18, 1.0
	v_fmac_f32_e32 v18, v19, v18
	v_div_scale_f32 v19, vcc, v5, v16, v5
	v_mul_f32_e32 v20, v19, v18
	v_fma_f32 v21, -v17, v20, v19
	v_fmac_f32_e32 v20, v21, v18
	v_fma_f32 v17, -v17, v20, v19
	v_div_fmas_f32 v17, v17, v18, v20
	v_div_fixup_f32 v5, v17, v16, v5
	v_mul_f32_e32 v16, v22, v4
	v_mul_f32_e32 v5, v16, v5
	v_bfe_u32 v16, v5, 16, 1
	v_add3_u32 v5, v5, v16, s15
	v_add_f32_e32 v3, 1.0, v3
	global_store_short_d16_hi v[0:1], v5, off offset:1152
	v_div_scale_f32 v5, s[2:3], v3, v3, v2
	v_rcp_f32_e32 v16, v5
	s_nop 0
	v_fma_f32 v17, -v5, v16, 1.0
	v_fmac_f32_e32 v16, v17, v16
	v_div_scale_f32 v17, vcc, v2, v3, v2
	v_mul_f32_e32 v18, v17, v16
	v_fma_f32 v19, -v5, v18, v17
	v_fmac_f32_e32 v18, v19, v16
	v_fma_f32 v5, -v5, v18, v17
	v_div_fmas_f32 v5, v5, v16, v18
	v_div_fixup_f32 v2, v5, v3, v2
	v_mul_f32_e32 v3, v6, v4
	v_mul_f32_e32 v2, v3, v2
	v_bfe_u32 v3, v2, 16, 1
	v_add3_u32 v2, v2, v3, s15
	global_store_short_d16_hi v[0:1], v2, off offset:1216
.LBB0_556:
	s_or_b64 exec, exec, s[0:1]
	v_or3_b32 v0, v72, v148, 11
	v_cmp_gt_i32_e32 vcc, s96, v0
	s_and_saveexec_b64 s[0:1], vcc
	s_cbranch_execz .LBB0_558
	v_mad_i64_i32 v[2:3], s[2:3], v0, s20, v[66:67]
	global_load_ushort v5, v[2:3], off
	global_load_ushort v100, v[2:3], off offset:64
	global_load_ushort v101, v[2:3], off offset:128
	global_load_ushort v102, v[2:3], off offset:192
	ds_read_b32 v1, v73 offset:44
	s_waitcnt lgkmcnt(0)
	v_rcp_f32_e32 v4, v1
	v_ashrrev_i32_e32 v1, 31, v0
	v_lshlrev_b64 v[0:1], 12, v[0:1]
	v_lshl_add_u64 v[0:1], v[64:65], 0, v[0:1]
	s_waitcnt vmcnt(0)
	v_lshlrev_b32_e32 v5, 16, v5
	v_mul_f32_e32 v6, 0xbfb8aa3b, v5
	v_exp_f32_e32 v6, v6
	s_nop 0
	v_add_f32_e32 v6, 1.0, v6
	v_div_scale_f32 v16, s[2:3], v6, v6, v5
	v_rcp_f32_e32 v17, v16
	s_nop 0
	v_fma_f32 v18, -v16, v17, 1.0
	v_fmac_f32_e32 v17, v18, v17
	v_div_scale_f32 v18, vcc, v5, v6, v5
	v_mul_f32_e32 v19, v18, v17
	v_fma_f32 v20, -v16, v19, v18
	v_fmac_f32_e32 v19, v20, v17
	v_fma_f32 v16, -v16, v19, v18
	v_div_fmas_f32 v16, v16, v17, v19
	v_div_fixup_f32 v5, v16, v6, v5
	v_mul_f32_e32 v6, v55, v4
	v_mul_f32_e32 v5, v6, v5
	v_bfe_u32 v6, v5, 16, 1
	v_add3_u32 v5, v5, v6, s15
	global_store_short_d16_hi v[0:1], v5, off offset:1024


; __device__ __forceinline__ float bf2f(unsigned short b) { return __uint_as_float((unsigned)b << 16); }
; __device__ __forceinline__ unsigned f2bf(float f) { unsigned u = __float_as_uint(f); return (u + 0x7fffu + ((u >> 16) & 1u)) >> 16; }
; __device__ __forceinline__ float bf2f(unsigned short b) { return __uint_as_float((unsigned)b << 16); }
; __device__ __forceinline__ unsigned f2bf(float f) { unsigned u = __float_as_uint(f); return (u + 0x7fffu + ((u >> 16) & 1u)) >> 16; }
;     ...
;         for (int d0 = 0; d0 < 4; ++d0) { const float g = bf2f(Gb[(long)orow * ldg + d0 * 32 + r32]); const float sg = g / (1.f + __expf(-g));
;           Yb[(long)orow * ldy + d0 * 32 + r32] = (bf16)f2bf(o[d0][r] * rli * sg); }
	v_lshlrev_b32_e32 v5, 16, v100
	v_mul_f32_e32 v6, 0xbfb8aa3b, v5
	v_exp_f32_e32 v6, v6
	s_nop 0
	v_add_f32_e32 v6, 1.0, v6
	v_div_scale_f32 v16, s[2:3], v6, v6, v5
	v_rcp_f32_e32 v17, v16
	s_nop 0
	v_fma_f32 v18, -v16, v17, 1.0
	v_fmac_f32_e32 v17, v18, v17
	v_div_scale_f32 v18, vcc, v5, v6, v5
	v_mul_f32_e32 v19, v18, v17
	v_fma_f32 v20, -v16, v19, v18
	v_fmac_f32_e32 v19, v20, v17
	v_fma_f32 v16, -v16, v19, v18
	v_div_fmas_f32 v16, v16, v17, v19
	v_div_fixup_f32 v5, v16, v6, v5
	v_mul_f32_e32 v6, v39, v4
	v_mul_f32_e32 v5, v6, v5
	v_bfe_u32 v6, v5, 16, 1
	v_add3_u32 v5, v5, v6, s15
	global_store_short_d16_hi v[0:1], v5, off offset:1088


; __device__ __forceinline__ float bf2f(unsigned short b) { return __uint_as_float((unsigned)b << 16); }
; __device__ __forceinline__ unsigned f2bf(float f) { unsigned u = __float_as_uint(f); return (u + 0x7fffu + ((u >> 16) & 1u)) >> 16; }
; __device__ __forceinline__ float bf2f(unsigned short b) { return __uint_as_float((unsigned)b << 16); }
; __device__ __forceinline__ unsigned f2bf(float f) { unsigned u = __float_as_uint(f); return (u + 0x7fffu + ((u >> 16) & 1u)) >> 16; }
;     ...
;         for (int d0 = 0; d0 < 4; ++d0) { const float g = bf2f(Gb[(long)orow * ldg + d0 * 32 + r32]); const float sg = g / (1.f + __expf(-g));
;           Yb[(long)orow * ldy + d0 * 32 + r32] = (bf16)f2bf(o[d0][r] * rli * sg); }
	v_lshlrev_b32_e32 v5, 16, v101

; __device__ __forceinline__ float bf2f(unsigned short b) { return __uint_as_float((unsigned)b << 16); }
; __device__ __forceinline__ unsigned f2bf(float f) { unsigned u = __float_as_uint(f); return (u + 0x7fffu + ((u >> 16) & 1u)) >> 16; }
; __device__ __forceinline__ float bf2f(unsigned short b) { return __uint_as_float((unsigned)b << 16); }
; __device__ __forceinline__ unsigned f2bf(float f) { unsigned u = __float_as_uint(f); return (u + 0x7fffu + ((u >> 16) & 1u)) >> 16; }
;     ...
;         for (int d0 = 0; d0 < 4; ++d0) { const float g = bf2f(Gb[(long)orow * ldg + d0 * 32 + r32]); const float sg = g / (1.f + __expf(-g));
;           Yb[(long)orow * ldy + d0 * 32 + r32] = (bf16)f2bf(o[d0][r] * rli * sg); }
	v_mul_f32_e32 v6, 0xbfb8aa3b, v5
	v_exp_f32_e32 v6, v6

; __device__ __forceinline__ int crow(int r, int hi) { return (r & 3) + 8 * (r >> 2) + 4 * hi; }
; __device__ __forceinline__ float bf2f(unsigned short b) { return __uint_as_float((unsigned)b << 16); }
; __device__ __forceinline__ unsigned f2bf(float f) { unsigned u = __float_as_uint(f); return (u + 0x7fffu + ((u >> 16) & 1u)) >> 16; }
; __device__ __forceinline__ float bf2f(unsigned short b) { return __uint_as_float((unsigned)b << 16); }
; __device__ __forceinline__ unsigned f2bf(float f) { unsigned u = __float_as_uint(f); return (u + 0x7fffu + ((u >> 16) & 1u)) >> 16; }
;     ...
;   for (int r = 0; r < 16; ++r) { const int orow = wid * QBLK + crow(r, hi); const float rli = __builtin_amdgcn_rcpf(li_l[crow(r, hi)]);
;     if (orow < nvalid) {
;       if constexpr (MODE == 0) {
; #pragma unroll
;         for (int d0 = 0; d0 < 4; ++d0) Of[(long)orow * ldo + d0 * 32 + r32] = o[d0][r] * rli;
;       } else {
; #pragma unroll
;         for (int d0 = 0; d0 < 4; ++d0) { const float g = bf2f(Gb[(long)orow * ldg + d0 * 32 + r32]); const float sg = g / (1.f + __expf(-g));
;           Yb[(long)orow * ldy + d0 * 32 + r32] = (bf16)f2bf(o[d0][r] * rli * sg); }
	v_lshlrev_b32_e32 v2, 16, v102
	v_add_f32_e32 v6, 1.0, v6
	v_div_scale_f32 v16, s[2:3], v6, v6, v5
	v_rcp_f32_e32 v17, v16
	v_mul_f32_e32 v3, 0xbfb8aa3b, v2
	v_exp_f32_e32 v3, v3
	v_fma_f32 v18, -v16, v17, 1.0
	v_fmac_f32_e32 v17, v18, v17
	v_div_scale_f32 v18, vcc, v5, v6, v5
	v_mul_f32_e32 v19, v18, v17
	v_fma_f32 v20, -v16, v19, v18
	v_fmac_f32_e32 v19, v20, v17
	v_fma_f32 v16, -v16, v19, v18
	v_div_fmas_f32 v16, v16, v17, v19
	v_div_fixup_f32 v5, v16, v6, v5
	v_mul_f32_e32 v6, v23, v4
	v_mul_f32_e32 v5, v6, v5
	v_bfe_u32 v6, v5, 16, 1
	v_add3_u32 v5, v5, v6, s15
	v_add_f32_e32 v3, 1.0, v3
	global_store_short_d16_hi v[0:1], v5, off offset:1152
	v_div_scale_f32 v5, s[2:3], v3, v3, v2
	v_rcp_f32_e32 v6, v5
	s_nop 0
	v_fma_f32 v16, -v5, v6, 1.0
	v_fmac_f32_e32 v6, v16, v6
	v_div_scale_f32 v16, vcc, v2, v3, v2
	v_mul_f32_e32 v17, v16, v6
	v_fma_f32 v18, -v5, v17, v16
	v_fmac_f32_e32 v17, v18, v6
	v_fma_f32 v5, -v5, v17, v16
	v_div_fmas_f32 v5, v5, v6, v17
	v_div_fixup_f32 v2, v5, v3, v2
	v_mul_f32_e32 v3, v7, v4
	v_mul_f32_e32 v2, v3, v2
	v_bfe_u32 v3, v2, 16, 1
	v_add3_u32 v2, v2, v3, s15
	global_store_short_d16_hi v[0:1], v2, off offset:1216
.LBB0_558:
	s_or_b64 exec, exec, s[0:1]
	v_or3_b32 v0, v72, v148, 16
	v_cmp_gt_i32_e32 vcc, s96, v0
	s_and_saveexec_b64 s[0:1], vcc
	s_cbranch_execz .LBB0_560
	v_mad_i64_i32 v[2:3], s[2:3], v0, s20, v[66:67]
	global_load_ushort v5, v[2:3], off
	global_load_ushort v100, v[2:3], off offset:64
	global_load_ushort v101, v[2:3], off offset:128
	global_load_ushort v102, v[2:3], off offset:192
	ds_read_b32 v1, v73 offset:64
	s_waitcnt lgkmcnt(0)
	v_rcp_f32_e32 v4, v1
	v_ashrrev_i32_e32 v1, 31, v0
	v_lshlrev_b64 v[0:1], 12, v[0:1]
	v_lshl_add_u64 v[0:1], v[64:65], 0, v[0:1]
	s_waitcnt vmcnt(0)
	v_lshlrev_b32_e32 v5, 16, v5
	v_mul_f32_e32 v6, 0xbfb8aa3b, v5
	v_exp_f32_e32 v6, v6
	s_nop 0
	v_add_f32_e32 v6, 1.0, v6
	v_div_scale_f32 v7, s[2:3], v6, v6, v5
	v_rcp_f32_e32 v16, v7
	s_nop 0
	v_fma_f32 v17, -v7, v16, 1.0
	v_fmac_f32_e32 v16, v17, v16
	v_div_scale_f32 v17, vcc, v5, v6, v5
	v_mul_f32_e32 v18, v17, v16
	v_fma_f32 v19, -v7, v18, v17
	v_fmac_f32_e32 v18, v19, v16
	v_fma_f32 v7, -v7, v18, v17
	v_div_fmas_f32 v7, v7, v16, v18
	v_div_fixup_f32 v5, v7, v6, v5
	v_mul_f32_e32 v6, v56, v4
	v_mul_f32_e32 v5, v6, v5
	v_bfe_u32 v6, v5, 16, 1
	v_add3_u32 v5, v5, v6, s15
	global_store_short_d16_hi v[0:1], v5, off offset:1024


; __device__ __forceinline__ float bf2f(unsigned short b) { return __uint_as_float((unsigned)b << 16); }
; __device__ __forceinline__ unsigned f2bf(float f) { unsigned u = __float_as_uint(f); return (u + 0x7fffu + ((u >> 16) & 1u)) >> 16; }
; __device__ __forceinline__ float bf2f(unsigned short b) { return __uint_as_float((unsigned)b << 16); }
; __device__ __forceinline__ unsigned f2bf(float f) { unsigned u = __float_as_uint(f); return (u + 0x7fffu + ((u >> 16) & 1u)) >> 16; }
;     ...
;         for (int d0 = 0; d0 < 4; ++d0) { const float g = bf2f(Gb[(long)orow * ldg + d0 * 32 + r32]); const float sg = g / (1.f + __expf(-g));
;           Yb[(long)orow * ldy + d0 * 32 + r32] = (bf16)f2bf(o[d0][r] * rli * sg); }
	v_lshlrev_b32_e32 v5, 16, v100
	v_mul_f32_e32 v6, 0xbfb8aa3b, v5
	v_exp_f32_e32 v6, v6
	s_nop 0
	v_add_f32_e32 v6, 1.0, v6
	v_div_scale_f32 v7, s[2:3], v6, v6, v5
	v_rcp_f32_e32 v16, v7
	s_nop 0
	v_fma_f32 v17, -v7, v16, 1.0
	v_fmac_f32_e32 v16, v17, v16
	v_div_scale_f32 v17, vcc, v5, v6, v5
	v_mul_f32_e32 v18, v17, v16
	v_fma_f32 v19, -v7, v18, v17
	v_fmac_f32_e32 v18, v19, v16
	v_fma_f32 v7, -v7, v18, v17
	v_div_fmas_f32 v7, v7, v16, v18
	v_div_fixup_f32 v5, v7, v6, v5
	v_mul_f32_e32 v6, v40, v4
	v_mul_f32_e32 v5, v6, v5
	v_bfe_u32 v6, v5, 16, 1
	v_add3_u32 v5, v5, v6, s15
	global_store_short_d16_hi v[0:1], v5, off offset:1088


; __device__ __forceinline__ float bf2f(unsigned short b) { return __uint_as_float((unsigned)b << 16); }
; __device__ __forceinline__ unsigned f2bf(float f) { unsigned u = __float_as_uint(f); return (u + 0x7fffu + ((u >> 16) & 1u)) >> 16; }
; __device__ __forceinline__ float bf2f(unsigned short b) { return __uint_as_float((unsigned)b << 16); }
; __device__ __forceinline__ unsigned f2bf(float f) { unsigned u = __float_as_uint(f); return (u + 0x7fffu + ((u >> 16) & 1u)) >> 16; }
;     ...
;         for (int d0 = 0; d0 < 4; ++d0) { const float g = bf2f(Gb[(long)orow * ldg + d0 * 32 + r32]); const float sg = g / (1.f + __expf(-g));
;           Yb[(long)orow * ldy + d0 * 32 + r32] = (bf16)f2bf(o[d0][r] * rli * sg); }
	v_lshlrev_b32_e32 v5, 16, v101

; __device__ __forceinline__ float bf2f(unsigned short b) { return __uint_as_float((unsigned)b << 16); }
; __device__ __forceinline__ unsigned f2bf(float f) { unsigned u = __float_as_uint(f); return (u + 0x7fffu + ((u >> 16) & 1u)) >> 16; }
; __device__ __forceinline__ float bf2f(unsigned short b) { return __uint_as_float((unsigned)b << 16); }
; __device__ __forceinline__ unsigned f2bf(float f) { unsigned u = __float_as_uint(f); return (u + 0x7fffu + ((u >> 16) & 1u)) >> 16; }
;     ...
;         for (int d0 = 0; d0 < 4; ++d0) { const float g = bf2f(Gb[(long)orow * ldg + d0 * 32 + r32]); const float sg = g / (1.f + __expf(-g));
;           Yb[(long)orow * ldy + d0 * 32 + r32] = (bf16)f2bf(o[d0][r] * rli * sg); }
	v_mul_f32_e32 v6, 0xbfb8aa3b, v5
	v_exp_f32_e32 v6, v6

; __device__ __forceinline__ int crow(int r, int hi) { return (r & 3) + 8 * (r >> 2) + 4 * hi; }
; __device__ __forceinline__ float bf2f(unsigned short b) { return __uint_as_float((unsigned)b << 16); }
; __device__ __forceinline__ unsigned f2bf(float f) { unsigned u = __float_as_uint(f); return (u + 0x7fffu + ((u >> 16) & 1u)) >> 16; }
; __device__ __forceinline__ float bf2f(unsigned short b) { return __uint_as_float((unsigned)b << 16); }
; __device__ __forceinline__ unsigned f2bf(float f) { unsigned u = __float_as_uint(f); return (u + 0x7fffu + ((u >> 16) & 1u)) >> 16; }
;     ...
;   for (int r = 0; r < 16; ++r) { const int orow = wid * QBLK + crow(r, hi); const float rli = __builtin_amdgcn_rcpf(li_l[crow(r, hi)]);
;     if (orow < nvalid) {
;       if constexpr (MODE == 0) {
; #pragma unroll
;         for (int d0 = 0; d0 < 4; ++d0) Of[(long)orow * ldo + d0 * 32 + r32] = o[d0][r] * rli;
;       } else {
; #pragma unroll
;         for (int d0 = 0; d0 < 4; ++d0) { const float g = bf2f(Gb[(long)orow * ldg + d0 * 32 + r32]); const float sg = g / (1.f + __expf(-g));
;           Yb[(long)orow * ldy + d0 * 32 + r32] = (bf16)f2bf(o[d0][r] * rli * sg); }
	v_lshlrev_b32_e32 v2, 16, v102
	v_add_f32_e32 v6, 1.0, v6
	v_div_scale_f32 v7, s[2:3], v6, v6, v5
	v_rcp_f32_e32 v16, v7
	v_mul_f32_e32 v3, 0xbfb8aa3b, v2
	v_exp_f32_e32 v3, v3
	v_fma_f32 v17, -v7, v16, 1.0
	v_fmac_f32_e32 v16, v17, v16
	v_div_scale_f32 v17, vcc, v5, v6, v5
	v_mul_f32_e32 v18, v17, v16
	v_fma_f32 v19, -v7, v18, v17
	v_fmac_f32_e32 v18, v19, v16
	v_fma_f32 v7, -v7, v18, v17
	v_div_fmas_f32 v7, v7, v16, v18
	v_div_fixup_f32 v5, v7, v6, v5
	v_mul_f32_e32 v6, v24, v4
	v_mul_f32_e32 v5, v6, v5
	v_bfe_u32 v6, v5, 16, 1
	v_add3_u32 v5, v5, v6, s15
	v_add_f32_e32 v3, 1.0, v3
	global_store_short_d16_hi v[0:1], v5, off offset:1152
	v_div_scale_f32 v5, s[2:3], v3, v3, v2
	v_rcp_f32_e32 v6, v5
	s_nop 0
	v_fma_f32 v7, -v5, v6, 1.0
	v_fmac_f32_e32 v6, v7, v6
	v_div_scale_f32 v7, vcc, v2, v3, v2
	v_mul_f32_e32 v16, v7, v6
	v_fma_f32 v17, -v5, v16, v7
	v_fmac_f32_e32 v16, v17, v6
	v_fma_f32 v5, -v5, v16, v7
	v_div_fmas_f32 v5, v5, v6, v16
	v_div_fixup_f32 v2, v5, v3, v2
	v_mul_f32_e32 v3, v8, v4
	v_mul_f32_e32 v2, v3, v2
	v_bfe_u32 v3, v2, 16, 1
	v_add3_u32 v2, v2, v3, s15
	global_store_short_d16_hi v[0:1], v2, off offset:1216
.LBB0_560:
	s_or_b64 exec, exec, s[0:1]
	v_or3_b32 v0, v72, v148, 17
	v_cmp_gt_i32_e32 vcc, s96, v0
	s_and_saveexec_b64 s[0:1], vcc
	s_cbranch_execz .LBB0_562
	v_mad_i64_i32 v[2:3], s[2:3], v0, s20, v[66:67]
	global_load_ushort v5, v[2:3], off
	global_load_ushort v100, v[2:3], off offset:64
	global_load_ushort v101, v[2:3], off offset:128
	global_load_ushort v102, v[2:3], off offset:192
	ds_read_b32 v1, v73 offset:68
	s_waitcnt lgkmcnt(0)
	v_rcp_f32_e32 v4, v1
	v_ashrrev_i32_e32 v1, 31, v0
	v_lshlrev_b64 v[0:1], 12, v[0:1]
	v_lshl_add_u64 v[0:1], v[64:65], 0, v[0:1]
	s_waitcnt vmcnt(0)
	v_lshlrev_b32_e32 v5, 16, v5
	v_mul_f32_e32 v6, 0xbfb8aa3b, v5
	v_exp_f32_e32 v6, v6
	s_nop 0
	v_add_f32_e32 v6, 1.0, v6
	v_div_scale_f32 v7, s[2:3], v6, v6, v5
	v_rcp_f32_e32 v8, v7
	s_nop 0
	v_fma_f32 v16, -v7, v8, 1.0
	v_fmac_f32_e32 v8, v16, v8
	v_div_scale_f32 v16, vcc, v5, v6, v5
	v_mul_f32_e32 v17, v16, v8
	v_fma_f32 v18, -v7, v17, v16
	v_fmac_f32_e32 v17, v18, v8
	v_fma_f32 v7, -v7, v17, v16
	v_div_fmas_f32 v7, v7, v8, v17
	v_div_fixup_f32 v5, v7, v6, v5
	v_mul_f32_e32 v6, v57, v4
	v_mul_f32_e32 v5, v6, v5
	v_bfe_u32 v6, v5, 16, 1
	v_add3_u32 v5, v5, v6, s15
	global_store_short_d16_hi v[0:1], v5, off offset:1024


; __device__ __forceinline__ float bf2f(unsigned short b) { return __uint_as_float((unsigned)b << 16); }
; __device__ __forceinline__ unsigned f2bf(float f) { unsigned u = __float_as_uint(f); return (u + 0x7fffu + ((u >> 16) & 1u)) >> 16; }
; __device__ __forceinline__ float bf2f(unsigned short b) { return __uint_as_float((unsigned)b << 16); }
; __device__ __forceinline__ unsigned f2bf(float f) { unsigned u = __float_as_uint(f); return (u + 0x7fffu + ((u >> 16) & 1u)) >> 16; }
;     ...
;         for (int d0 = 0; d0 < 4; ++d0) { const float g = bf2f(Gb[(long)orow * ldg + d0 * 32 + r32]); const float sg = g / (1.f + __expf(-g));
;           Yb[(long)orow * ldy + d0 * 32 + r32] = (bf16)f2bf(o[d0][r] * rli * sg); }
	v_lshlrev_b32_e32 v5, 16, v100
	v_mul_f32_e32 v6, 0xbfb8aa3b, v5
	v_exp_f32_e32 v6, v6
	s_nop 0
	v_add_f32_e32 v6, 1.0, v6
	v_div_scale_f32 v7, s[2:3], v6, v6, v5
	v_rcp_f32_e32 v8, v7
	s_nop 0
	v_fma_f32 v16, -v7, v8, 1.0
	v_fmac_f32_e32 v8, v16, v8
	v_div_scale_f32 v16, vcc, v5, v6, v5
	v_mul_f32_e32 v17, v16, v8
	v_fma_f32 v18, -v7, v17, v16
	v_fmac_f32_e32 v17, v18, v8
	v_fma_f32 v7, -v7, v17, v16
	v_div_fmas_f32 v7, v7, v8, v17
	v_div_fixup_f32 v5, v7, v6, v5
	v_mul_f32_e32 v6, v41, v4
	v_mul_f32_e32 v5, v6, v5
	v_bfe_u32 v6, v5, 16, 1
	v_add3_u32 v5, v5, v6, s15
	global_store_short_d16_hi v[0:1], v5, off offset:1088


; __device__ __forceinline__ float bf2f(unsigned short b) { return __uint_as_float((unsigned)b << 16); }
; __device__ __forceinline__ unsigned f2bf(float f) { unsigned u = __float_as_uint(f); return (u + 0x7fffu + ((u >> 16) & 1u)) >> 16; }
; __device__ __forceinline__ float bf2f(unsigned short b) { return __uint_as_float((unsigned)b << 16); }
; __device__ __forceinline__ unsigned f2bf(float f) { unsigned u = __float_as_uint(f); return (u + 0x7fffu + ((u >> 16) & 1u)) >> 16; }
;     ...
;         for (int d0 = 0; d0 < 4; ++d0) { const float g = bf2f(Gb[(long)orow * ldg + d0 * 32 + r32]); const float sg = g / (1.f + __expf(-g));
;           Yb[(long)orow * ldy + d0 * 32 + r32] = (bf16)f2bf(o[d0][r] * rli * sg); }
	v_lshlrev_b32_e32 v5, 16, v101

; __device__ __forceinline__ float bf2f(unsigned short b) { return __uint_as_float((unsigned)b << 16); }
; __device__ __forceinline__ unsigned f2bf(float f) { unsigned u = __float_as_uint(f); return (u + 0x7fffu + ((u >> 16) & 1u)) >> 16; }
; __device__ __forceinline__ float bf2f(unsigned short b) { return __uint_as_float((unsigned)b << 16); }
; __device__ __forceinline__ unsigned f2bf(float f) { unsigned u = __float_as_uint(f); return (u + 0x7fffu + ((u >> 16) & 1u)) >> 16; }
;     ...
;         for (int d0 = 0; d0 < 4; ++d0) { const float g = bf2f(Gb[(long)orow * ldg + d0 * 32 + r32]); const float sg = g / (1.f + __expf(-g));
;           Yb[(long)orow * ldy + d0 * 32 + r32] = (bf16)f2bf(o[d0][r] * rli * sg); }
	v_mul_f32_e32 v6, 0xbfb8aa3b, v5
	v_exp_f32_e32 v6, v6

; __device__ __forceinline__ int crow(int r, int hi) { return (r & 3) + 8 * (r >> 2) + 4 * hi; }
; __device__ __forceinline__ float bf2f(unsigned short b) { return __uint_as_float((unsigned)b << 16); }
; __device__ __forceinline__ unsigned f2bf(float f) { unsigned u = __float_as_uint(f); return (u + 0x7fffu + ((u >> 16) & 1u)) >> 16; }
; __device__ __forceinline__ float bf2f(unsigned short b) { return __uint_as_float((unsigned)b << 16); }
; __device__ __forceinline__ unsigned f2bf(float f) { unsigned u = __float_as_uint(f); return (u + 0x7fffu + ((u >> 16) & 1u)) >> 16; }
;     ...
;   for (int r = 0; r < 16; ++r) { const int orow = wid * QBLK + crow(r, hi); const float rli = __builtin_amdgcn_rcpf(li_l[crow(r, hi)]);
;     if (orow < nvalid) {
;       if constexpr (MODE == 0) {
; #pragma unroll
;         for (int d0 = 0; d0 < 4; ++d0) Of[(long)orow * ldo + d0 * 32 + r32] = o[d0][r] * rli;
;       } else {
; #pragma unroll
;         for (int d0 = 0; d0 < 4; ++d0) { const float g = bf2f(Gb[(long)orow * ldg + d0 * 32 + r32]); const float sg = g / (1.f + __expf(-g));
;           Yb[(long)orow * ldy + d0 * 32 + r32] = (bf16)f2bf(o[d0][r] * rli * sg); }
	v_lshlrev_b32_e32 v2, 16, v102
	v_add_f32_e32 v6, 1.0, v6
	v_div_scale_f32 v7, s[2:3], v6, v6, v5
	v_rcp_f32_e32 v8, v7
	v_mul_f32_e32 v3, 0xbfb8aa3b, v2
	v_exp_f32_e32 v3, v3
	v_fma_f32 v16, -v7, v8, 1.0
	v_fmac_f32_e32 v8, v16, v8
	v_div_scale_f32 v16, vcc, v5, v6, v5
	v_mul_f32_e32 v17, v16, v8
	v_fma_f32 v18, -v7, v17, v16
	v_fmac_f32_e32 v17, v18, v8
	v_fma_f32 v7, -v7, v17, v16
	v_div_fmas_f32 v7, v7, v8, v17
	v_div_fixup_f32 v5, v7, v6, v5
	v_mul_f32_e32 v6, v25, v4
	v_mul_f32_e32 v5, v6, v5
	v_bfe_u32 v6, v5, 16, 1
	v_add3_u32 v5, v5, v6, s15
	v_add_f32_e32 v3, 1.0, v3
	global_store_short_d16_hi v[0:1], v5, off offset:1152
	v_div_scale_f32 v5, s[2:3], v3, v3, v2
	v_rcp_f32_e32 v6, v5
	s_nop 0
	v_fma_f32 v7, -v5, v6, 1.0
	v_fmac_f32_e32 v6, v7, v6
	v_div_scale_f32 v7, vcc, v2, v3, v2
	v_mul_f32_e32 v8, v7, v6
	v_fma_f32 v16, -v5, v8, v7
	v_fmac_f32_e32 v8, v16, v6
	v_fma_f32 v5, -v5, v8, v7
	v_div_fmas_f32 v5, v5, v6, v8
	v_div_fixup_f32 v2, v5, v3, v2
	v_mul_f32_e32 v3, v9, v4
	v_mul_f32_e32 v2, v3, v2
	v_bfe_u32 v3, v2, 16, 1
	v_add3_u32 v2, v2, v3, s15
	global_store_short_d16_hi v[0:1], v2, off offset:1216
.LBB0_562:
	s_or_b64 exec, exec, s[0:1]
	v_or3_b32 v0, v72, v148, 18
	v_cmp_gt_i32_e32 vcc, s96, v0
	s_and_saveexec_b64 s[0:1], vcc
	s_cbranch_execz .LBB0_564
	v_mad_i64_i32 v[2:3], s[2:3], v0, s20, v[66:67]
	global_load_ushort v5, v[2:3], off
	global_load_ushort v100, v[2:3], off offset:64
	global_load_ushort v101, v[2:3], off offset:128
	global_load_ushort v102, v[2:3], off offset:192
	ds_read_b32 v1, v73 offset:72
	s_waitcnt lgkmcnt(0)
	v_rcp_f32_e32 v4, v1
	v_ashrrev_i32_e32 v1, 31, v0
	v_lshlrev_b64 v[0:1], 12, v[0:1]
	v_lshl_add_u64 v[0:1], v[64:65], 0, v[0:1]
	s_waitcnt vmcnt(0)
	v_lshlrev_b32_e32 v5, 16, v5
	v_mul_f32_e32 v6, 0xbfb8aa3b, v5
	v_exp_f32_e32 v6, v6
	s_nop 0
	v_add_f32_e32 v6, 1.0, v6
	v_div_scale_f32 v7, s[2:3], v6, v6, v5
	v_rcp_f32_e32 v8, v7
	s_nop 0
	v_fma_f32 v9, -v7, v8, 1.0
	v_fmac_f32_e32 v8, v9, v8
	v_div_scale_f32 v9, vcc, v5, v6, v5
	v_mul_f32_e32 v16, v9, v8
	v_fma_f32 v17, -v7, v16, v9
	v_fmac_f32_e32 v16, v17, v8
	v_fma_f32 v7, -v7, v16, v9
	v_div_fmas_f32 v7, v7, v8, v16
	v_div_fixup_f32 v5, v7, v6, v5
	v_mul_f32_e32 v6, v58, v4
	v_mul_f32_e32 v5, v6, v5
	v_bfe_u32 v6, v5, 16, 1
	v_add3_u32 v5, v5, v6, s15
	global_store_short_d16_hi v[0:1], v5, off offset:1024


; __device__ __forceinline__ float bf2f(unsigned short b) { return __uint_as_float((unsigned)b << 16); }
; __device__ __forceinline__ unsigned f2bf(float f) { unsigned u = __float_as_uint(f); return (u + 0x7fffu + ((u >> 16) & 1u)) >> 16; }
; __device__ __forceinline__ float bf2f(unsigned short b) { return __uint_as_float((unsigned)b << 16); }
; __device__ __forceinline__ unsigned f2bf(float f) { unsigned u = __float_as_uint(f); return (u + 0x7fffu + ((u >> 16) & 1u)) >> 16; }
;     ...
;         for (int d0 = 0; d0 < 4; ++d0) { const float g = bf2f(Gb[(long)orow * ldg + d0 * 32 + r32]); const float sg = g / (1.f + __expf(-g));
;           Yb[(long)orow * ldy + d0 * 32 + r32] = (bf16)f2bf(o[d0][r] * rli * sg); }
	v_lshlrev_b32_e32 v5, 16, v100
	v_mul_f32_e32 v6, 0xbfb8aa3b, v5
	v_exp_f32_e32 v6, v6
	s_nop 0
	v_add_f32_e32 v6, 1.0, v6
	v_div_scale_f32 v7, s[2:3], v6, v6, v5
	v_rcp_f32_e32 v8, v7
	s_nop 0
	v_fma_f32 v9, -v7, v8, 1.0
	v_fmac_f32_e32 v8, v9, v8
	v_div_scale_f32 v9, vcc, v5, v6, v5
	v_mul_f32_e32 v16, v9, v8
	v_fma_f32 v17, -v7, v16, v9
	v_fmac_f32_e32 v16, v17, v8
	v_fma_f32 v7, -v7, v16, v9
	v_div_fmas_f32 v7, v7, v8, v16
	v_div_fixup_f32 v5, v7, v6, v5
	v_mul_f32_e32 v6, v42, v4
	v_mul_f32_e32 v5, v6, v5
	v_bfe_u32 v6, v5, 16, 1
	v_add3_u32 v5, v5, v6, s15
	global_store_short_d16_hi v[0:1], v5, off offset:1088


; __device__ __forceinline__ float bf2f(unsigned short b) { return __uint_as_float((unsigned)b << 16); }
; __device__ __forceinline__ unsigned f2bf(float f) { unsigned u = __float_as_uint(f); return (u + 0x7fffu + ((u >> 16) & 1u)) >> 16; }
; __device__ __forceinline__ float bf2f(unsigned short b) { return __uint_as_float((unsigned)b << 16); }
; __device__ __forceinline__ unsigned f2bf(float f) { unsigned u = __float_as_uint(f); return (u + 0x7fffu + ((u >> 16) & 1u)) >> 16; }
;     ...
;         for (int d0 = 0; d0 < 4; ++d0) { const float g = bf2f(Gb[(long)orow * ldg + d0 * 32 + r32]); const float sg = g / (1.f + __expf(-g));
;           Yb[(long)orow * ldy + d0 * 32 + r32] = (bf16)f2bf(o[d0][r] * rli * sg); }
	v_lshlrev_b32_e32 v5, 16, v101

; __device__ __forceinline__ float bf2f(unsigned short b) { return __uint_as_float((unsigned)b << 16); }
; __device__ __forceinline__ unsigned f2bf(float f) { unsigned u = __float_as_uint(f); return (u + 0x7fffu + ((u >> 16) & 1u)) >> 16; }
; __device__ __forceinline__ float bf2f(unsigned short b) { return __uint_as_float((unsigned)b << 16); }
; __device__ __forceinline__ unsigned f2bf(float f) { unsigned u = __float_as_uint(f); return (u + 0x7fffu + ((u >> 16) & 1u)) >> 16; }
;     ...
;         for (int d0 = 0; d0 < 4; ++d0) { const float g = bf2f(Gb[(long)orow * ldg + d0 * 32 + r32]); const float sg = g / (1.f + __expf(-g));
;           Yb[(long)orow * ldy + d0 * 32 + r32] = (bf16)f2bf(o[d0][r] * rli * sg); }
	v_mul_f32_e32 v6, 0xbfb8aa3b, v5
	v_exp_f32_e32 v6, v6

; __device__ __forceinline__ int crow(int r, int hi) { return (r & 3) + 8 * (r >> 2) + 4 * hi; }
; __device__ __forceinline__ float bf2f(unsigned short b) { return __uint_as_float((unsigned)b << 16); }
; __device__ __forceinline__ unsigned f2bf(float f) { unsigned u = __float_as_uint(f); return (u + 0x7fffu + ((u >> 16) & 1u)) >> 16; }
; __device__ __forceinline__ float bf2f(unsigned short b) { return __uint_as_float((unsigned)b << 16); }
; __device__ __forceinline__ unsigned f2bf(float f) { unsigned u = __float_as_uint(f); return (u + 0x7fffu + ((u >> 16) & 1u)) >> 16; }
;     ...
;   for (int r = 0; r < 16; ++r) { const int orow = wid * QBLK + crow(r, hi); const float rli = __builtin_amdgcn_rcpf(li_l[crow(r, hi)]);
;     if (orow < nvalid) {
;       if constexpr (MODE == 0) {
; #pragma unroll
;         for (int d0 = 0; d0 < 4; ++d0) Of[(long)orow * ldo + d0 * 32 + r32] = o[d0][r] * rli;
;       } else {
; #pragma unroll
;         for (int d0 = 0; d0 < 4; ++d0) { const float g = bf2f(Gb[(long)orow * ldg + d0 * 32 + r32]); const float sg = g / (1.f + __expf(-g));
;           Yb[(long)orow * ldy + d0 * 32 + r32] = (bf16)f2bf(o[d0][r] * rli * sg); }
	v_lshlrev_b32_e32 v2, 16, v102
	v_add_f32_e32 v6, 1.0, v6
	v_div_scale_f32 v7, s[2:3], v6, v6, v5
	v_rcp_f32_e32 v8, v7
	v_mul_f32_e32 v3, 0xbfb8aa3b, v2
	v_exp_f32_e32 v3, v3
	v_fma_f32 v9, -v7, v8, 1.0
	v_fmac_f32_e32 v8, v9, v8
	v_div_scale_f32 v9, vcc, v5, v6, v5
	v_mul_f32_e32 v16, v9, v8
	v_fma_f32 v17, -v7, v16, v9
	v_fmac_f32_e32 v16, v17, v8
	v_fma_f32 v7, -v7, v16, v9
	v_div_fmas_f32 v7, v7, v8, v16
	v_div_fixup_f32 v5, v7, v6, v5
	v_mul_f32_e32 v6, v26, v4
	v_mul_f32_e32 v5, v6, v5
	v_bfe_u32 v6, v5, 16, 1
	v_add3_u32 v5, v5, v6, s15
	v_add_f32_e32 v3, 1.0, v3
	global_store_short_d16_hi v[0:1], v5, off offset:1152
	v_div_scale_f32 v5, s[2:3], v3, v3, v2
	v_rcp_f32_e32 v6, v5
	s_nop 0
	v_fma_f32 v7, -v5, v6, 1.0
	v_fmac_f32_e32 v6, v7, v6
	v_div_scale_f32 v7, vcc, v2, v3, v2
	v_mul_f32_e32 v8, v7, v6
	v_fma_f32 v9, -v5, v8, v7
	v_fmac_f32_e32 v8, v9, v6
	v_fma_f32 v5, -v5, v8, v7
	v_div_fmas_f32 v5, v5, v6, v8
	v_div_fixup_f32 v2, v5, v3, v2
	v_mul_f32_e32 v3, v10, v4
	v_mul_f32_e32 v2, v3, v2
	v_bfe_u32 v3, v2, 16, 1
	v_add3_u32 v2, v2, v3, s15
	global_store_short_d16_hi v[0:1], v2, off offset:1216
.LBB0_564:
	s_or_b64 exec, exec, s[0:1]
	v_or3_b32 v0, v72, v148, 19
	v_cmp_gt_i32_e32 vcc, s96, v0
	s_and_saveexec_b64 s[0:1], vcc
	s_cbranch_execz .LBB0_566
	v_mad_i64_i32 v[2:3], s[2:3], v0, s20, v[66:67]
	global_load_ushort v5, v[2:3], off
	global_load_ushort v100, v[2:3], off offset:64
	global_load_ushort v101, v[2:3], off offset:128
	global_load_ushort v102, v[2:3], off offset:192
	ds_read_b32 v1, v73 offset:76
	s_waitcnt lgkmcnt(0)
	v_rcp_f32_e32 v4, v1
	v_ashrrev_i32_e32 v1, 31, v0
	v_lshlrev_b64 v[0:1], 12, v[0:1]
	v_lshl_add_u64 v[0:1], v[64:65], 0, v[0:1]
	s_waitcnt vmcnt(0)
	v_lshlrev_b32_e32 v5, 16, v5
	v_mul_f32_e32 v6, 0xbfb8aa3b, v5
	v_exp_f32_e32 v6, v6
	s_nop 0
	v_add_f32_e32 v6, 1.0, v6
	v_div_scale_f32 v7, s[2:3], v6, v6, v5
	v_rcp_f32_e32 v8, v7
	s_nop 0
	v_fma_f32 v9, -v7, v8, 1.0
	v_fmac_f32_e32 v8, v9, v8
	v_div_scale_f32 v9, vcc, v5, v6, v5
	v_mul_f32_e32 v10, v9, v8
	v_fma_f32 v16, -v7, v10, v9
	v_fmac_f32_e32 v10, v16, v8
	v_fma_f32 v7, -v7, v10, v9
	v_div_fmas_f32 v7, v7, v8, v10
	v_div_fixup_f32 v5, v7, v6, v5
	v_mul_f32_e32 v6, v59, v4
	v_mul_f32_e32 v5, v6, v5
	v_bfe_u32 v6, v5, 16, 1
	v_add3_u32 v5, v5, v6, s15
	global_store_short_d16_hi v[0:1], v5, off offset:1024


; __device__ __forceinline__ float bf2f(unsigned short b) { return __uint_as_float((unsigned)b << 16); }
; __device__ __forceinline__ unsigned f2bf(float f) { unsigned u = __float_as_uint(f); return (u + 0x7fffu + ((u >> 16) & 1u)) >> 16; }
; __device__ __forceinline__ float bf2f(unsigned short b) { return __uint_as_float((unsigned)b << 16); }
; __device__ __forceinline__ unsigned f2bf(float f) { unsigned u = __float_as_uint(f); return (u + 0x7fffu + ((u >> 16) & 1u)) >> 16; }
;     ...
;         for (int d0 = 0; d0 < 4; ++d0) { const float g = bf2f(Gb[(long)orow * ldg + d0 * 32 + r32]); const float sg = g / (1.f + __expf(-g));
;           Yb[(long)orow * ldy + d0 * 32 + r32] = (bf16)f2bf(o[d0][r] * rli * sg); }
	v_lshlrev_b32_e32 v5, 16, v100
	v_mul_f32_e32 v6, 0xbfb8aa3b, v5
	v_exp_f32_e32 v6, v6
	s_nop 0
	v_add_f32_e32 v6, 1.0, v6
	v_div_scale_f32 v7, s[2:3], v6, v6, v5
	v_rcp_f32_e32 v8, v7
	s_nop 0
	v_fma_f32 v9, -v7, v8, 1.0
	v_fmac_f32_e32 v8, v9, v8
	v_div_scale_f32 v9, vcc, v5, v6, v5
	v_mul_f32_e32 v10, v9, v8
	v_fma_f32 v16, -v7, v10, v9
	v_fmac_f32_e32 v10, v16, v8
	v_fma_f32 v7, -v7, v10, v9
	v_div_fmas_f32 v7, v7, v8, v10
	v_div_fixup_f32 v5, v7, v6, v5
	v_mul_f32_e32 v6, v43, v4
	v_mul_f32_e32 v5, v6, v5
	v_bfe_u32 v6, v5, 16, 1
	v_add3_u32 v5, v5, v6, s15
	global_store_short_d16_hi v[0:1], v5, off offset:1088


; __device__ __forceinline__ float bf2f(unsigned short b) { return __uint_as_float((unsigned)b << 16); }
; __device__ __forceinline__ unsigned f2bf(float f) { unsigned u = __float_as_uint(f); return (u + 0x7fffu + ((u >> 16) & 1u)) >> 16; }
; __device__ __forceinline__ float bf2f(unsigned short b) { return __uint_as_float((unsigned)b << 16); }
; __device__ __forceinline__ unsigned f2bf(float f) { unsigned u = __float_as_uint(f); return (u + 0x7fffu + ((u >> 16) & 1u)) >> 16; }
;     ...
;         for (int d0 = 0; d0 < 4; ++d0) { const float g = bf2f(Gb[(long)orow * ldg + d0 * 32 + r32]); const float sg = g / (1.f + __expf(-g));
;           Yb[(long)orow * ldy + d0 * 32 + r32] = (bf16)f2bf(o[d0][r] * rli * sg); }
	v_lshlrev_b32_e32 v5, 16, v101

; __device__ __forceinline__ float bf2f(unsigned short b) { return __uint_as_float((unsigned)b << 16); }
; __device__ __forceinline__ unsigned f2bf(float f) { unsigned u = __float_as_uint(f); return (u + 0x7fffu + ((u >> 16) & 1u)) >> 16; }
; __device__ __forceinline__ float bf2f(unsigned short b) { return __uint_as_float((unsigned)b << 16); }
; __device__ __forceinline__ unsigned f2bf(float f) { unsigned u = __float_as_uint(f); return (u + 0x7fffu + ((u >> 16) & 1u)) >> 16; }
;     ...
;         for (int d0 = 0; d0 < 4; ++d0) { const float g = bf2f(Gb[(long)orow * ldg + d0 * 32 + r32]); const float sg = g / (1.f + __expf(-g));
;           Yb[(long)orow * ldy + d0 * 32 + r32] = (bf16)f2bf(o[d0][r] * rli * sg); }
	v_mul_f32_e32 v6, 0xbfb8aa3b, v5
	v_exp_f32_e32 v6, v6

; __device__ __forceinline__ int crow(int r, int hi) { return (r & 3) + 8 * (r >> 2) + 4 * hi; }
; __device__ __forceinline__ float bf2f(unsigned short b) { return __uint_as_float((unsigned)b << 16); }
; __device__ __forceinline__ unsigned f2bf(float f) { unsigned u = __float_as_uint(f); return (u + 0x7fffu + ((u >> 16) & 1u)) >> 16; }
; __device__ __forceinline__ float bf2f(unsigned short b) { return __uint_as_float((unsigned)b << 16); }
; __device__ __forceinline__ unsigned f2bf(float f) { unsigned u = __float_as_uint(f); return (u + 0x7fffu + ((u >> 16) & 1u)) >> 16; }
;     ...
;   for (int r = 0; r < 16; ++r) { const int orow = wid * QBLK + crow(r, hi); const float rli = __builtin_amdgcn_rcpf(li_l[crow(r, hi)]);
;     if (orow < nvalid) {
;       if constexpr (MODE == 0) {
; #pragma unroll
;         for (int d0 = 0; d0 < 4; ++d0) Of[(long)orow * ldo + d0 * 32 + r32] = o[d0][r] * rli;
;       } else {
; #pragma unroll
;         for (int d0 = 0; d0 < 4; ++d0) { const float g = bf2f(Gb[(long)orow * ldg + d0 * 32 + r32]); const float sg = g / (1.f + __expf(-g));
;           Yb[(long)orow * ldy + d0 * 32 + r32] = (bf16)f2bf(o[d0][r] * rli * sg); }
	v_lshlrev_b32_e32 v2, 16, v102
	v_add_f32_e32 v6, 1.0, v6
	v_div_scale_f32 v7, s[2:3], v6, v6, v5
	v_rcp_f32_e32 v8, v7
	v_mul_f32_e32 v3, 0xbfb8aa3b, v2
	v_exp_f32_e32 v3, v3
	v_fma_f32 v9, -v7, v8, 1.0
	v_fmac_f32_e32 v8, v9, v8
	v_div_scale_f32 v9, vcc, v5, v6, v5
	v_mul_f32_e32 v10, v9, v8
	v_fma_f32 v16, -v7, v10, v9
	v_fmac_f32_e32 v10, v16, v8
	v_fma_f32 v7, -v7, v10, v9
	v_div_fmas_f32 v7, v7, v8, v10
	v_div_fixup_f32 v5, v7, v6, v5
	v_mul_f32_e32 v6, v27, v4
	v_mul_f32_e32 v5, v6, v5
	v_bfe_u32 v6, v5, 16, 1
	v_add3_u32 v5, v5, v6, s15
	v_add_f32_e32 v3, 1.0, v3
	global_store_short_d16_hi v[0:1], v5, off offset:1152
	v_div_scale_f32 v5, s[2:3], v3, v3, v2
	v_rcp_f32_e32 v6, v5
	s_nop 0
	v_fma_f32 v7, -v5, v6, 1.0
	v_fmac_f32_e32 v6, v7, v6
	v_div_scale_f32 v7, vcc, v2, v3, v2
	v_mul_f32_e32 v8, v7, v6
	v_fma_f32 v9, -v5, v8, v7
	v_fmac_f32_e32 v8, v9, v6
	v_fma_f32 v5, -v5, v8, v7
	v_div_fmas_f32 v5, v5, v6, v8
	v_div_fixup_f32 v2, v5, v3, v2
	v_mul_f32_e32 v3, v11, v4
	v_mul_f32_e32 v2, v3, v2
	v_bfe_u32 v3, v2, 16, 1
	v_add3_u32 v2, v2, v3, s15
	global_store_short_d16_hi v[0:1], v2, off offset:1216
.LBB0_566:
	s_or_b64 exec, exec, s[0:1]
	v_or3_b32 v0, v72, v148, 24
	v_cmp_gt_i32_e32 vcc, s96, v0
	s_and_saveexec_b64 s[0:1], vcc
	s_cbranch_execz .LBB0_568
	v_mad_i64_i32 v[2:3], s[2:3], v0, s20, v[66:67]
	global_load_ushort v5, v[2:3], off
	global_load_ushort v100, v[2:3], off offset:64
	global_load_ushort v101, v[2:3], off offset:128
	global_load_ushort v102, v[2:3], off offset:192
	ds_read_b32 v1, v73 offset:96
	s_waitcnt lgkmcnt(0)
	v_rcp_f32_e32 v4, v1
	v_ashrrev_i32_e32 v1, 31, v0
	v_lshlrev_b64 v[0:1], 12, v[0:1]
	v_lshl_add_u64 v[0:1], v[64:65], 0, v[0:1]
	s_waitcnt vmcnt(0)
	v_lshlrev_b32_e32 v5, 16, v5
	v_mul_f32_e32 v6, 0xbfb8aa3b, v5
	v_exp_f32_e32 v6, v6
	s_nop 0
	v_add_f32_e32 v6, 1.0, v6
	v_div_scale_f32 v7, s[2:3], v6, v6, v5
	v_rcp_f32_e32 v8, v7
	s_nop 0
	v_fma_f32 v9, -v7, v8, 1.0
	v_fmac_f32_e32 v8, v9, v8
	v_div_scale_f32 v9, vcc, v5, v6, v5
	v_mul_f32_e32 v10, v9, v8
	v_fma_f32 v11, -v7, v10, v9
	v_fmac_f32_e32 v10, v11, v8
	v_fma_f32 v7, -v7, v10, v9
	v_div_fmas_f32 v7, v7, v8, v10
	v_div_fixup_f32 v5, v7, v6, v5
	v_mul_f32_e32 v6, v60, v4
	v_mul_f32_e32 v5, v6, v5
	v_bfe_u32 v6, v5, 16, 1
	v_add3_u32 v5, v5, v6, s15
	global_store_short_d16_hi v[0:1], v5, off offset:1024


; __device__ __forceinline__ float bf2f(unsigned short b) { return __uint_as_float((unsigned)b << 16); }
; __device__ __forceinline__ unsigned f2bf(float f) { unsigned u = __float_as_uint(f); return (u + 0x7fffu + ((u >> 16) & 1u)) >> 16; }
; __device__ __forceinline__ float bf2f(unsigned short b) { return __uint_as_float((unsigned)b << 16); }
; __device__ __forceinline__ unsigned f2bf(float f) { unsigned u = __float_as_uint(f); return (u + 0x7fffu + ((u >> 16) & 1u)) >> 16; }
;     ...
;         for (int d0 = 0; d0 < 4; ++d0) { const float g = bf2f(Gb[(long)orow * ldg + d0 * 32 + r32]); const float sg = g / (1.f + __expf(-g));
;           Yb[(long)orow * ldy + d0 * 32 + r32] = (bf16)f2bf(o[d0][r] * rli * sg); }
	v_lshlrev_b32_e32 v5, 16, v100
	v_mul_f32_e32 v6, 0xbfb8aa3b, v5
	v_exp_f32_e32 v6, v6
	s_nop 0
	v_add_f32_e32 v6, 1.0, v6
	v_div_scale_f32 v7, s[2:3], v6, v6, v5
	v_rcp_f32_e32 v8, v7
	s_nop 0
	v_fma_f32 v9, -v7, v8, 1.0
	v_fmac_f32_e32 v8, v9, v8
	v_div_scale_f32 v9, vcc, v5, v6, v5
	v_mul_f32_e32 v10, v9, v8
	v_fma_f32 v11, -v7, v10, v9
	v_fmac_f32_e32 v10, v11, v8
	v_fma_f32 v7, -v7, v10, v9
	v_div_fmas_f32 v7, v7, v8, v10
	v_div_fixup_f32 v5, v7, v6, v5
	v_mul_f32_e32 v6, v44, v4
	v_mul_f32_e32 v5, v6, v5
	v_bfe_u32 v6, v5, 16, 1
	v_add3_u32 v5, v5, v6, s15
	global_store_short_d16_hi v[0:1], v5, off offset:1088


; __device__ __forceinline__ float bf2f(unsigned short b) { return __uint_as_float((unsigned)b << 16); }
; __device__ __forceinline__ unsigned f2bf(float f) { unsigned u = __float_as_uint(f); return (u + 0x7fffu + ((u >> 16) & 1u)) >> 16; }
; __device__ __forceinline__ float bf2f(unsigned short b) { return __uint_as_float((unsigned)b << 16); }
; __device__ __forceinline__ unsigned f2bf(float f) { unsigned u = __float_as_uint(f); return (u + 0x7fffu + ((u >> 16) & 1u)) >> 16; }
;     ...
;         for (int d0 = 0; d0 < 4; ++d0) { const float g = bf2f(Gb[(long)orow * ldg + d0 * 32 + r32]); const float sg = g / (1.f + __expf(-g));
;           Yb[(long)orow * ldy + d0 * 32 + r32] = (bf16)f2bf(o[d0][r] * rli * sg); }
	v_lshlrev_b32_e32 v5, 16, v101

; __device__ __forceinline__ float bf2f(unsigned short b) { return __uint_as_float((unsigned)b << 16); }
; __device__ __forceinline__ unsigned f2bf(float f) { unsigned u = __float_as_uint(f); return (u + 0x7fffu + ((u >> 16) & 1u)) >> 16; }
; __device__ __forceinline__ float bf2f(unsigned short b) { return __uint_as_float((unsigned)b << 16); }
; __device__ __forceinline__ unsigned f2bf(float f) { unsigned u = __float_as_uint(f); return (u + 0x7fffu + ((u >> 16) & 1u)) >> 16; }
;     ...
;         for (int d0 = 0; d0 < 4; ++d0) { const float g = bf2f(Gb[(long)orow * ldg + d0 * 32 + r32]); const float sg = g / (1.f + __expf(-g));
;           Yb[(long)orow * ldy + d0 * 32 + r32] = (bf16)f2bf(o[d0][r] * rli * sg); }
	v_mul_f32_e32 v6, 0xbfb8aa3b, v5
	v_exp_f32_e32 v6, v6

; __device__ __forceinline__ int crow(int r, int hi) { return (r & 3) + 8 * (r >> 2) + 4 * hi; }
; __device__ __forceinline__ float bf2f(unsigned short b) { return __uint_as_float((unsigned)b << 16); }
; __device__ __forceinline__ unsigned f2bf(float f) { unsigned u = __float_as_uint(f); return (u + 0x7fffu + ((u >> 16) & 1u)) >> 16; }
; __device__ __forceinline__ float bf2f(unsigned short b) { return __uint_as_float((unsigned)b << 16); }
; __device__ __forceinline__ unsigned f2bf(float f) { unsigned u = __float_as_uint(f); return (u + 0x7fffu + ((u >> 16) & 1u)) >> 16; }
;     ...
;   for (int r = 0; r < 16; ++r) { const int orow = wid * QBLK + crow(r, hi); const float rli = __builtin_amdgcn_rcpf(li_l[crow(r, hi)]);
;     if (orow < nvalid) {
;       if constexpr (MODE == 0) {
; #pragma unroll
;         for (int d0 = 0; d0 < 4; ++d0) Of[(long)orow * ldo + d0 * 32 + r32] = o[d0][r] * rli;
;       } else {
; #pragma unroll
;         for (int d0 = 0; d0 < 4; ++d0) { const float g = bf2f(Gb[(long)orow * ldg + d0 * 32 + r32]); const float sg = g / (1.f + __expf(-g));
;           Yb[(long)orow * ldy + d0 * 32 + r32] = (bf16)f2bf(o[d0][r] * rli * sg); }
	v_lshlrev_b32_e32 v2, 16, v102
	v_add_f32_e32 v6, 1.0, v6
	v_div_scale_f32 v7, s[2:3], v6, v6, v5
	v_rcp_f32_e32 v8, v7
	v_mul_f32_e32 v3, 0xbfb8aa3b, v2
	v_exp_f32_e32 v3, v3
	v_fma_f32 v9, -v7, v8, 1.0
	v_fmac_f32_e32 v8, v9, v8
	v_div_scale_f32 v9, vcc, v5, v6, v5
	v_mul_f32_e32 v10, v9, v8
	v_fma_f32 v11, -v7, v10, v9
	v_fmac_f32_e32 v10, v11, v8
	v_fma_f32 v7, -v7, v10, v9
	v_div_fmas_f32 v7, v7, v8, v10
	v_div_fixup_f32 v5, v7, v6, v5
	v_mul_f32_e32 v6, v28, v4
	v_mul_f32_e32 v5, v6, v5
	v_bfe_u32 v6, v5, 16, 1
	v_add3_u32 v5, v5, v6, s15
	v_add_f32_e32 v3, 1.0, v3
	global_store_short_d16_hi v[0:1], v5, off offset:1152
	v_div_scale_f32 v5, s[2:3], v3, v3, v2
	v_rcp_f32_e32 v6, v5
	s_nop 0
	v_fma_f32 v7, -v5, v6, 1.0
	v_fmac_f32_e32 v6, v7, v6
	v_div_scale_f32 v7, vcc, v2, v3, v2
	v_mul_f32_e32 v8, v7, v6
	v_fma_f32 v9, -v5, v8, v7
	v_fmac_f32_e32 v8, v9, v6
	v_fma_f32 v5, -v5, v8, v7
	v_div_fmas_f32 v5, v5, v6, v8
	v_div_fixup_f32 v2, v5, v3, v2
	v_mul_f32_e32 v3, v12, v4
	v_mul_f32_e32 v2, v3, v2
	v_bfe_u32 v3, v2, 16, 1
	v_add3_u32 v2, v2, v3, s15
	global_store_short_d16_hi v[0:1], v2, off offset:1216
.LBB0_568:
	s_or_b64 exec, exec, s[0:1]
	v_or3_b32 v0, v72, v148, 25
	v_cmp_gt_i32_e32 vcc, s96, v0
	s_and_saveexec_b64 s[0:1], vcc
	s_cbranch_execz .LBB0_570
	v_mad_i64_i32 v[2:3], s[2:3], v0, s20, v[66:67]
	global_load_ushort v5, v[2:3], off
	global_load_ushort v100, v[2:3], off offset:64
	global_load_ushort v101, v[2:3], off offset:128
	global_load_ushort v102, v[2:3], off offset:192
	ds_read_b32 v1, v73 offset:100
	s_waitcnt lgkmcnt(0)
	v_rcp_f32_e32 v4, v1
	v_ashrrev_i32_e32 v1, 31, v0
	v_lshlrev_b64 v[0:1], 12, v[0:1]
	v_lshl_add_u64 v[0:1], v[64:65], 0, v[0:1]
	s_waitcnt vmcnt(0)
	v_lshlrev_b32_e32 v5, 16, v5
	v_mul_f32_e32 v6, 0xbfb8aa3b, v5
	v_exp_f32_e32 v6, v6
	s_nop 0
	v_add_f32_e32 v6, 1.0, v6
	v_div_scale_f32 v7, s[2:3], v6, v6, v5
	v_rcp_f32_e32 v8, v7
	s_nop 0
	v_fma_f32 v9, -v7, v8, 1.0
	v_fmac_f32_e32 v8, v9, v8
	v_div_scale_f32 v9, vcc, v5, v6, v5
	v_mul_f32_e32 v10, v9, v8
	v_fma_f32 v11, -v7, v10, v9
	v_fmac_f32_e32 v10, v11, v8
	v_fma_f32 v7, -v7, v10, v9
	v_div_fmas_f32 v7, v7, v8, v10
	v_div_fixup_f32 v5, v7, v6, v5
	v_mul_f32_e32 v6, v61, v4
	v_mul_f32_e32 v5, v6, v5
	v_bfe_u32 v6, v5, 16, 1
	v_add3_u32 v5, v5, v6, s15
	global_store_short_d16_hi v[0:1], v5, off offset:1024


; __device__ __forceinline__ float bf2f(unsigned short b) { return __uint_as_float((unsigned)b << 16); }
; __device__ __forceinline__ unsigned f2bf(float f) { unsigned u = __float_as_uint(f); return (u + 0x7fffu + ((u >> 16) & 1u)) >> 16; }
; __device__ __forceinline__ float bf2f(unsigned short b) { return __uint_as_float((unsigned)b << 16); }
; __device__ __forceinline__ unsigned f2bf(float f) { unsigned u = __float_as_uint(f); return (u + 0x7fffu + ((u >> 16) & 1u)) >> 16; }
;     ...
;         for (int d0 = 0; d0 < 4; ++d0) { const float g = bf2f(Gb[(long)orow * ldg + d0 * 32 + r32]); const float sg = g / (1.f + __expf(-g));
;           Yb[(long)orow * ldy + d0 * 32 + r32] = (bf16)f2bf(o[d0][r] * rli * sg); }
	v_lshlrev_b32_e32 v5, 16, v100
	v_mul_f32_e32 v6, 0xbfb8aa3b, v5
	v_exp_f32_e32 v6, v6
	s_nop 0
	v_add_f32_e32 v6, 1.0, v6
	v_div_scale_f32 v7, s[2:3], v6, v6, v5
	v_rcp_f32_e32 v8, v7
	s_nop 0
	v_fma_f32 v9, -v7, v8, 1.0
	v_fmac_f32_e32 v8, v9, v8
	v_div_scale_f32 v9, vcc, v5, v6, v5
	v_mul_f32_e32 v10, v9, v8
	v_fma_f32 v11, -v7, v10, v9
	v_fmac_f32_e32 v10, v11, v8
	v_fma_f32 v7, -v7, v10, v9
	v_div_fmas_f32 v7, v7, v8, v10
	v_div_fixup_f32 v5, v7, v6, v5
	v_mul_f32_e32 v6, v45, v4
	v_mul_f32_e32 v5, v6, v5
	v_bfe_u32 v6, v5, 16, 1
	v_add3_u32 v5, v5, v6, s15
	global_store_short_d16_hi v[0:1], v5, off offset:1088


; __device__ __forceinline__ float bf2f(unsigned short b) { return __uint_as_float((unsigned)b << 16); }
; __device__ __forceinline__ float bf2f(unsigned short b) { return __uint_as_float((unsigned)b << 16); }
;     ...
;         for (int d0 = 0; d0 < 4; ++d0) { const float g = bf2f(Gb[(long)orow * ldg + d0 * 32 + r32]); const float sg = g / (1.f + __expf(-g));
	v_lshlrev_b32_e32 v5, 16, v101

; __device__ __forceinline__ float bf2f(unsigned short b) { return __uint_as_float((unsigned)b << 16); }
; __device__ __forceinline__ float bf2f(unsigned short b) { return __uint_as_float((unsigned)b << 16); }
;     ...
;         for (int d0 = 0; d0 < 4; ++d0) { const float g = bf2f(Gb[(long)orow * ldg + d0 * 32 + r32]); const float sg = g / (1.f + __expf(-g));
	v_mul_f32_e32 v6, 0xbfb8aa3b, v5
	v_exp_f32_e32 v6, v6

; __device__ __forceinline__ int crow(int r, int hi) { return (r & 3) + 8 * (r >> 2) + 4 * hi; }
; __device__ __forceinline__ float bf2f(unsigned short b) { return __uint_as_float((unsigned)b << 16); }
; __device__ __forceinline__ unsigned f2bf(float f) { unsigned u = __float_as_uint(f); return (u + 0x7fffu + ((u >> 16) & 1u)) >> 16; }
; __device__ __forceinline__ float bf2f(unsigned short b) { return __uint_as_float((unsigned)b << 16); }
; __device__ __forceinline__ unsigned f2bf(float f) { unsigned u = __float_as_uint(f); return (u + 0x7fffu + ((u >> 16) & 1u)) >> 16; }
;     ...
;   for (int r = 0; r < 16; ++r) { const int orow = wid * QBLK + crow(r, hi); const float rli = __builtin_amdgcn_rcpf(li_l[crow(r, hi)]);
;     if (orow < nvalid) {
;       if constexpr (MODE == 0) {
; #pragma unroll
;         for (int d0 = 0; d0 < 4; ++d0) Of[(long)orow * ldo + d0 * 32 + r32] = o[d0][r] * rli;
;       } else {
; #pragma unroll
;         for (int d0 = 0; d0 < 4; ++d0) { const float g = bf2f(Gb[(long)orow * ldg + d0 * 32 + r32]); const float sg = g / (1.f + __expf(-g));
;           Yb[(long)orow * ldy + d0 * 32 + r32] = (bf16)f2bf(o[d0][r] * rli * sg); }
	v_lshlrev_b32_e32 v2, 16, v102
	v_add_f32_e32 v6, 1.0, v6
	v_div_scale_f32 v7, s[2:3], v6, v6, v5
	v_rcp_f32_e32 v8, v7
	v_mul_f32_e32 v3, 0xbfb8aa3b, v2
	v_exp_f32_e32 v3, v3
	v_fma_f32 v9, -v7, v8, 1.0
	v_fmac_f32_e32 v8, v9, v8
	v_div_scale_f32 v9, vcc, v5, v6, v5
	v_mul_f32_e32 v10, v9, v8
	v_fma_f32 v11, -v7, v10, v9
	v_fmac_f32_e32 v10, v11, v8
	v_fma_f32 v7, -v7, v10, v9
	v_div_fmas_f32 v7, v7, v8, v10
	v_div_fixup_f32 v5, v7, v6, v5
	v_mul_f32_e32 v6, v29, v4
	v_mul_f32_e32 v5, v6, v5
	v_bfe_u32 v6, v5, 16, 1
	v_add3_u32 v5, v5, v6, s15
	v_add_f32_e32 v3, 1.0, v3
	global_store_short_d16_hi v[0:1], v5, off offset:1152
	v_div_scale_f32 v5, s[2:3], v3, v3, v2
	v_rcp_f32_e32 v6, v5
	s_nop 0
	v_fma_f32 v7, -v5, v6, 1.0
	v_fmac_f32_e32 v6, v7, v6
	v_div_scale_f32 v7, vcc, v2, v3, v2
	v_mul_f32_e32 v8, v7, v6
	v_fma_f32 v9, -v5, v8, v7
	v_fmac_f32_e32 v8, v9, v6
	v_fma_f32 v5, -v5, v8, v7
	v_div_fmas_f32 v5, v5, v6, v8
	v_div_fixup_f32 v2, v5, v3, v2
	v_mul_f32_e32 v3, v13, v4
	v_mul_f32_e32 v2, v3, v2
	v_bfe_u32 v3, v2, 16, 1
	v_add3_u32 v2, v2, v3, s15
	global_store_short_d16_hi v[0:1], v2, off offset:1216
.LBB0_570:
	s_or_b64 exec, exec, s[0:1]
	v_or3_b32 v0, v72, v148, 26
	v_cmp_gt_i32_e32 vcc, s96, v0
	s_and_saveexec_b64 s[0:1], vcc
	s_cbranch_execz .LBB0_572
	v_mad_i64_i32 v[2:3], s[2:3], v0, s20, v[66:67]
	global_load_ushort v5, v[2:3], off
	global_load_ushort v100, v[2:3], off offset:64
	global_load_ushort v101, v[2:3], off offset:128
	global_load_ushort v102, v[2:3], off offset:192
	ds_read_b32 v1, v73 offset:104
	s_waitcnt lgkmcnt(0)
	v_rcp_f32_e32 v4, v1
	v_ashrrev_i32_e32 v1, 31, v0
	v_lshlrev_b64 v[0:1], 12, v[0:1]
	v_lshl_add_u64 v[0:1], v[64:65], 0, v[0:1]
	s_waitcnt vmcnt(0)
	v_lshlrev_b32_e32 v5, 16, v5
	v_mul_f32_e32 v6, 0xbfb8aa3b, v5
	v_exp_f32_e32 v6, v6
	s_nop 0
	v_add_f32_e32 v6, 1.0, v6
	v_div_scale_f32 v7, s[2:3], v6, v6, v5
	v_rcp_f32_e32 v8, v7
	s_nop 0
	v_fma_f32 v9, -v7, v8, 1.0
	v_fmac_f32_e32 v8, v9, v8
	v_div_scale_f32 v9, vcc, v5, v6, v5
	v_mul_f32_e32 v10, v9, v8
	v_fma_f32 v11, -v7, v10, v9
	v_fmac_f32_e32 v10, v11, v8
	v_fma_f32 v7, -v7, v10, v9
	v_div_fmas_f32 v7, v7, v8, v10
	v_div_fixup_f32 v5, v7, v6, v5
	v_mul_f32_e32 v6, v62, v4
	v_mul_f32_e32 v5, v6, v5
	v_bfe_u32 v6, v5, 16, 1
	v_add3_u32 v5, v5, v6, s15
	global_store_short_d16_hi v[0:1], v5, off offset:1024


; __device__ __forceinline__ float bf2f(unsigned short b) { return __uint_as_float((unsigned)b << 16); }
; __device__ __forceinline__ unsigned f2bf(float f) { unsigned u = __float_as_uint(f); return (u + 0x7fffu + ((u >> 16) & 1u)) >> 16; }
; __device__ __forceinline__ float bf2f(unsigned short b) { return __uint_as_float((unsigned)b << 16); }
; __device__ __forceinline__ unsigned f2bf(float f) { unsigned u = __float_as_uint(f); return (u + 0x7fffu + ((u >> 16) & 1u)) >> 16; }
;     ...
;         for (int d0 = 0; d0 < 4; ++d0) { const float g = bf2f(Gb[(long)orow * ldg + d0 * 32 + r32]); const float sg = g / (1.f + __expf(-g));
;           Yb[(long)orow * ldy + d0 * 32 + r32] = (bf16)f2bf(o[d0][r] * rli * sg); }
	v_lshlrev_b32_e32 v5, 16, v100
	v_mul_f32_e32 v6, 0xbfb8aa3b, v5
	v_exp_f32_e32 v6, v6
	s_nop 0
	v_add_f32_e32 v6, 1.0, v6
	v_div_scale_f32 v7, s[2:3], v6, v6, v5
	v_rcp_f32_e32 v8, v7
	s_nop 0
	v_fma_f32 v9, -v7, v8, 1.0
	v_fmac_f32_e32 v8, v9, v8
	v_div_scale_f32 v9, vcc, v5, v6, v5
	v_mul_f32_e32 v10, v9, v8
	v_fma_f32 v11, -v7, v10, v9
	v_fmac_f32_e32 v10, v11, v8
	v_fma_f32 v7, -v7, v10, v9
	v_div_fmas_f32 v7, v7, v8, v10
	v_div_fixup_f32 v5, v7, v6, v5
	v_mul_f32_e32 v6, v46, v4
	v_mul_f32_e32 v5, v6, v5
	v_bfe_u32 v6, v5, 16, 1
	v_add3_u32 v5, v5, v6, s15
	global_store_short_d16_hi v[0:1], v5, off offset:1088


; __device__ __forceinline__ float bf2f(unsigned short b) { return __uint_as_float((unsigned)b << 16); }
; __device__ __forceinline__ float bf2f(unsigned short b) { return __uint_as_float((unsigned)b << 16); }
;     ...
;         for (int d0 = 0; d0 < 4; ++d0) { const float g = bf2f(Gb[(long)orow * ldg + d0 * 32 + r32]); const float sg = g / (1.f + __expf(-g));
	v_lshlrev_b32_e32 v5, 16, v101

; __device__ __forceinline__ float bf2f(unsigned short b) { return __uint_as_float((unsigned)b << 16); }
; __device__ __forceinline__ float bf2f(unsigned short b) { return __uint_as_float((unsigned)b << 16); }
;     ...
;         for (int d0 = 0; d0 < 4; ++d0) { const float g = bf2f(Gb[(long)orow * ldg + d0 * 32 + r32]); const float sg = g / (1.f + __expf(-g));
	v_mul_f32_e32 v6, 0xbfb8aa3b, v5
	v_exp_f32_e32 v6, v6

; __device__ __forceinline__ int crow(int r, int hi) { return (r & 3) + 8 * (r >> 2) + 4 * hi; }
; __device__ __forceinline__ float bf2f(unsigned short b) { return __uint_as_float((unsigned)b << 16); }
; __device__ __forceinline__ unsigned f2bf(float f) { unsigned u = __float_as_uint(f); return (u + 0x7fffu + ((u >> 16) & 1u)) >> 16; }
; __device__ __forceinline__ float bf2f(unsigned short b) { return __uint_as_float((unsigned)b << 16); }
; __device__ __forceinline__ unsigned f2bf(float f) { unsigned u = __float_as_uint(f); return (u + 0x7fffu + ((u >> 16) & 1u)) >> 16; }
;     ...
;   for (int r = 0; r < 16; ++r) { const int orow = wid * QBLK + crow(r, hi); const float rli = __builtin_amdgcn_rcpf(li_l[crow(r, hi)]);
;     if (orow < nvalid) {
;       if constexpr (MODE == 0) {
; #pragma unroll
;         for (int d0 = 0; d0 < 4; ++d0) Of[(long)orow * ldo + d0 * 32 + r32] = o[d0][r] * rli;
;       } else {
; #pragma unroll
;         for (int d0 = 0; d0 < 4; ++d0) { const float g = bf2f(Gb[(long)orow * ldg + d0 * 32 + r32]); const float sg = g / (1.f + __expf(-g));
;           Yb[(long)orow * ldy + d0 * 32 + r32] = (bf16)f2bf(o[d0][r] * rli * sg); }
	v_lshlrev_b32_e32 v2, 16, v102
	v_add_f32_e32 v6, 1.0, v6
	v_div_scale_f32 v7, s[2:3], v6, v6, v5
	v_rcp_f32_e32 v8, v7
	v_mul_f32_e32 v3, 0xbfb8aa3b, v2
	v_exp_f32_e32 v3, v3
	v_fma_f32 v9, -v7, v8, 1.0
	v_fmac_f32_e32 v8, v9, v8
	v_div_scale_f32 v9, vcc, v5, v6, v5
	v_mul_f32_e32 v10, v9, v8
	v_fma_f32 v11, -v7, v10, v9
	v_fmac_f32_e32 v10, v11, v8
	v_fma_f32 v7, -v7, v10, v9
	v_div_fmas_f32 v7, v7, v8, v10
	v_div_fixup_f32 v5, v7, v6, v5
	v_mul_f32_e32 v6, v30, v4
	v_mul_f32_e32 v5, v6, v5
	v_bfe_u32 v6, v5, 16, 1
	v_add3_u32 v5, v5, v6, s15
	v_add_f32_e32 v3, 1.0, v3
	global_store_short_d16_hi v[0:1], v5, off offset:1152
	v_div_scale_f32 v5, s[2:3], v3, v3, v2
	v_rcp_f32_e32 v6, v5
	s_nop 0
	v_fma_f32 v7, -v5, v6, 1.0
	v_fmac_f32_e32 v6, v7, v6
	v_div_scale_f32 v7, vcc, v2, v3, v2
	v_mul_f32_e32 v8, v7, v6
	v_fma_f32 v9, -v5, v8, v7
	v_fmac_f32_e32 v8, v9, v6
	v_fma_f32 v5, -v5, v8, v7
	v_div_fmas_f32 v5, v5, v6, v8
	v_div_fixup_f32 v2, v5, v3, v2
	v_mul_f32_e32 v3, v14, v4
	v_mul_f32_e32 v2, v3, v2
	v_bfe_u32 v3, v2, 16, 1
	v_add3_u32 v2, v2, v3, s15
	global_store_short_d16_hi v[0:1], v2, off offset:1216
.LBB0_572:
	s_or_b64 exec, exec, s[0:1]
	v_or3_b32 v0, v72, v148, 27
	v_cmp_gt_i32_e32 vcc, s96, v0
	s_and_saveexec_b64 s[0:1], vcc
	s_cbranch_execz .LBB0_574
	v_mad_i64_i32 v[2:3], s[2:3], v0, s20, v[66:67]
	global_load_ushort v5, v[2:3], off
	global_load_ushort v100, v[2:3], off offset:64
	global_load_ushort v101, v[2:3], off offset:128
	global_load_ushort v102, v[2:3], off offset:192
	ds_read_b32 v1, v73 offset:108
	s_waitcnt lgkmcnt(0)
	v_rcp_f32_e32 v4, v1
	v_ashrrev_i32_e32 v1, 31, v0
	v_lshlrev_b64 v[0:1], 12, v[0:1]
	v_lshl_add_u64 v[0:1], v[64:65], 0, v[0:1]
	s_waitcnt vmcnt(0)
	v_lshlrev_b32_e32 v5, 16, v5
	v_mul_f32_e32 v6, 0xbfb8aa3b, v5
	v_exp_f32_e32 v6, v6
	s_nop 0
	v_add_f32_e32 v6, 1.0, v6
	v_div_scale_f32 v7, s[2:3], v6, v6, v5
	v_rcp_f32_e32 v8, v7
	s_nop 0
	v_fma_f32 v9, -v7, v8, 1.0
	v_fmac_f32_e32 v8, v9, v8
	v_div_scale_f32 v9, vcc, v5, v6, v5
	v_mul_f32_e32 v10, v9, v8
	v_fma_f32 v11, -v7, v10, v9
	v_fmac_f32_e32 v10, v11, v8
	v_fma_f32 v7, -v7, v10, v9
	v_div_fmas_f32 v7, v7, v8, v10
	v_div_fixup_f32 v5, v7, v6, v5
	v_mul_f32_e32 v6, v63, v4
	v_mul_f32_e32 v5, v6, v5
	v_bfe_u32 v6, v5, 16, 1
	v_add3_u32 v5, v5, v6, s15
	global_store_short_d16_hi v[0:1], v5, off offset:1024


; __device__ __forceinline__ float bf2f(unsigned short b) { return __uint_as_float((unsigned)b << 16); }
; __device__ __forceinline__ unsigned f2bf(float f) { unsigned u = __float_as_uint(f); return (u + 0x7fffu + ((u >> 16) & 1u)) >> 16; }
; __device__ __forceinline__ float bf2f(unsigned short b) { return __uint_as_float((unsigned)b << 16); }
; __device__ __forceinline__ unsigned f2bf(float f) { unsigned u = __float_as_uint(f); return (u + 0x7fffu + ((u >> 16) & 1u)) >> 16; }
;     ...
;         for (int d0 = 0; d0 < 4; ++d0) { const float g = bf2f(Gb[(long)orow * ldg + d0 * 32 + r32]); const float sg = g / (1.f + __expf(-g));
;           Yb[(long)orow * ldy + d0 * 32 + r32] = (bf16)f2bf(o[d0][r] * rli * sg); }
	v_lshlrev_b32_e32 v5, 16, v100
	v_mul_f32_e32 v6, 0xbfb8aa3b, v5
	v_exp_f32_e32 v6, v6
	s_nop 0
	v_add_f32_e32 v6, 1.0, v6
	v_div_scale_f32 v7, s[2:3], v6, v6, v5
	v_rcp_f32_e32 v8, v7
	s_nop 0
	v_fma_f32 v9, -v7, v8, 1.0
	v_fmac_f32_e32 v8, v9, v8
	v_div_scale_f32 v9, vcc, v5, v6, v5
	v_mul_f32_e32 v10, v9, v8
	v_fma_f32 v11, -v7, v10, v9
	v_fmac_f32_e32 v10, v11, v8
	v_fma_f32 v7, -v7, v10, v9
	v_div_fmas_f32 v7, v7, v8, v10
	v_div_fixup_f32 v5, v7, v6, v5
	v_mul_f32_e32 v6, v47, v4
	v_mul_f32_e32 v5, v6, v5
	v_bfe_u32 v6, v5, 16, 1
	v_add3_u32 v5, v5, v6, s15
	global_store_short_d16_hi v[0:1], v5, off offset:1088


; __device__ __forceinline__ float bf2f(unsigned short b) { return __uint_as_float((unsigned)b << 16); }
; __device__ __forceinline__ float bf2f(unsigned short b) { return __uint_as_float((unsigned)b << 16); }
;     ...
;         for (int d0 = 0; d0 < 4; ++d0) { const float g = bf2f(Gb[(long)orow * ldg + d0 * 32 + r32]); const float sg = g / (1.f + __expf(-g));
	v_lshlrev_b32_e32 v5, 16, v101

; __device__ __forceinline__ float bf2f(unsigned short b) { return __uint_as_float((unsigned)b << 16); }
; __device__ __forceinline__ float bf2f(unsigned short b) { return __uint_as_float((unsigned)b << 16); }
;     ...
;         for (int d0 = 0; d0 < 4; ++d0) { const float g = bf2f(Gb[(long)orow * ldg + d0 * 32 + r32]); const float sg = g / (1.f + __expf(-g));
	v_mul_f32_e32 v6, 0xbfb8aa3b, v5
	v_exp_f32_e32 v6, v6

; __device__ __forceinline__ int crow(int r, int hi) { return (r & 3) + 8 * (r >> 2) + 4 * hi; }
; __device__ __forceinline__ float bf2f(unsigned short b) { return __uint_as_float((unsigned)b << 16); }
; __device__ __forceinline__ unsigned f2bf(float f) { unsigned u = __float_as_uint(f); return (u + 0x7fffu + ((u >> 16) & 1u)) >> 16; }
; __device__ __forceinline__ float bf2f(unsigned short b) { return __uint_as_float((unsigned)b << 16); }
; __device__ __forceinline__ unsigned f2bf(float f) { unsigned u = __float_as_uint(f); return (u + 0x7fffu + ((u >> 16) & 1u)) >> 16; }
;     ...
;   for (int r = 0; r < 16; ++r) { const int orow = wid * QBLK + crow(r, hi); const float rli = __builtin_amdgcn_rcpf(li_l[crow(r, hi)]);
;     if (orow < nvalid) {
;       if constexpr (MODE == 0) {
; #pragma unroll
;         for (int d0 = 0; d0 < 4; ++d0) Of[(long)orow * ldo + d0 * 32 + r32] = o[d0][r] * rli;
;       } else {
; #pragma unroll
;         for (int d0 = 0; d0 < 4; ++d0) { const float g = bf2f(Gb[(long)orow * ldg + d0 * 32 + r32]); const float sg = g / (1.f + __expf(-g));
;           Yb[(long)orow * ldy + d0 * 32 + r32] = (bf16)f2bf(o[d0][r] * rli * sg); }
	v_lshlrev_b32_e32 v2, 16, v102
	v_add_f32_e32 v6, 1.0, v6
	v_div_scale_f32 v7, s[2:3], v6, v6, v5
	v_rcp_f32_e32 v8, v7
	v_mul_f32_e32 v3, 0xbfb8aa3b, v2
	v_exp_f32_e32 v3, v3
	v_fma_f32 v9, -v7, v8, 1.0
	v_fmac_f32_e32 v8, v9, v8
	v_div_scale_f32 v9, vcc, v5, v6, v5
	v_mul_f32_e32 v10, v9, v8
	v_fma_f32 v11, -v7, v10, v9
	v_fmac_f32_e32 v10, v11, v8
	v_fma_f32 v7, -v7, v10, v9
	v_div_fmas_f32 v7, v7, v8, v10
	v_div_fixup_f32 v5, v7, v6, v5
	v_mul_f32_e32 v6, v31, v4
	v_mul_f32_e32 v5, v6, v5
	v_bfe_u32 v6, v5, 16, 1
	v_add3_u32 v5, v5, v6, s15
	v_add_f32_e32 v3, 1.0, v3
	global_store_short_d16_hi v[0:1], v5, off offset:1152
	v_div_scale_f32 v5, s[2:3], v3, v3, v2
	v_rcp_f32_e32 v6, v5
	s_nop 0
	v_fma_f32 v7, -v5, v6, 1.0
	v_fmac_f32_e32 v6, v7, v6
	v_div_scale_f32 v7, vcc, v2, v3, v2
	v_mul_f32_e32 v8, v7, v6
	v_fma_f32 v9, -v5, v8, v7
	v_fmac_f32_e32 v8, v9, v6
	v_fma_f32 v5, -v5, v8, v7
	v_div_fmas_f32 v5, v5, v6, v8
	v_div_fixup_f32 v2, v5, v3, v2
	v_mul_f32_e32 v3, v15, v4
	v_mul_f32_e32 v2, v3, v2
	v_bfe_u32 v3, v2, 16, 1
	v_add3_u32 v2, v2, v3, s15
	global_store_short_d16_hi v[0:1], v2, off offset:1216

; template <int DQK>
; __device__ __forceinline__ void qkt(f32x16& p0, f32x16& p1, const char* Ks, const bf16x8* qr, int r32, int hi) {
;   constexpr int KP = DQK * 2;
;   p0 = f32x16{}; p1 = f32x16{};
;   if constexpr (DQK == 64 && ATT_KPRELOAD) {
;     bf16x8 ka[4], kq[4];
; #pragma unroll
;     for (int d0 = 0; d0 < 4; ++d0) { const int cb = (d0 * 16 + hi * 8) * 2;
;       ka[d0] = *reinterpret_cast<const bf16x8*>(Ks + KSWZ(KP, r32, cb)); kq[d0] = *reinterpret_cast<const bf16x8*>(Ks + KSWZ(KP, 32 + r32, cb)); }
;     SBAR();
; #pragma unroll
;     for (int d0 = 0; d0 < 4; ++d0) { p0 = __builtin_amdgcn_mfma_f32_32x32x16_bf16(ka[d0], qr[d0], p0, 0, 0, 0); p1 = __builtin_amdgcn_mfma_f32_32x32x16_bf16(kq[d0], qr[d0], p1, 0, 0, 0); }
;     return;
;   }
; #pragma unroll
;   for (int d0 = 0; d0 < DQK / 16; ++d0) { const int cb = (d0 * 16 + hi * 8) * 2;
;     bf16x8 b0 = *reinterpret_cast<const bf16x8*>(Ks + KSWZ(KP, r32, cb));
;     bf16x8 b1 = *reinterpret_cast<const bf16x8*>(Ks + KSWZ(KP, 32 + r32, cb));
;     p0 = __builtin_amdgcn_mfma_f32_32x32x16_bf16(b0, qr[d0], p0, 0, 0, 0);
;     p1 = __builtin_amdgcn_mfma_f32_32x32x16_bf16(b1, qr[d0], p1, 0, 0, 0); }
; }
; __device__ __forceinline__ int v_st(int k, int c) { const int kk = k; return ((kk >> 3) * 4 + (c >> 5)) * 512 + ((kk & 7) * 32 + (c & 31)) * 2; }
; __device__ __forceinline__ int v_rd_base(int lane) { return ((lane & 3) << 3) | (((lane >> 2) & 3) << 6) | (((lane >> 4) & 1) << 5) | (((lane >> 5) & 1) << 8); }
; template <int OFF> __device__ __forceinline__ s16x4 tr_read(int vb) {
;   s16x4 r; asm volatile("ds_read_b64_tr_b16 %0, %1 offset:%2" : "=&v"(r) : "v"(vb), "i"(OFF) : "memory"); return r;
; }
; template <int D0> __device__ __forceinline__ void pv_one(f32x16& od, int vb, bf16x8 pa0, bf16x8 pa1, bf16x8 pa2, bf16x8 pa3) {
;   const s16x4 l0 = tr_read<v_rd_off(D0, 0, 0)>(vb), h0 = tr_read<v_rd_off(D0, 0, 1)>(vb), l1 = tr_read<v_rd_off(D0, 1, 0)>(vb), h1 = tr_read<v_rd_off(D0, 1, 1)>(vb);
;   const s16x4 l2 = tr_read<v_rd_off(D0, 2, 0)>(vb), h2 = tr_read<v_rd_off(D0, 2, 1)>(vb), l3 = tr_read<v_rd_off(D0, 3, 0)>(vb), h3 = tr_read<v_rd_off(D0, 3, 1)>(vb);
;   asm volatile("s_waitcnt lgkmcnt(0)" ::: "memory"); SBAR();
;     ...
;   od = __builtin_amdgcn_mfma_f32_32x32x16_bf16(pa0, PK(l0, h0), od, 0, 0, 0);
;   od = __builtin_amdgcn_mfma_f32_32x32x16_bf16(pa1, PK(l1, h1), od, 0, 0, 0);
.LBB0_578:
	s_and_b32 s6, s1, 1
	s_waitcnt lgkmcnt(0)
	s_barrier
	s_mul_i32 s7, s6, 0x6000
	s_add_i32 s7, s0, s7
	v_add3_u32 v218, s7, v224, v189
	v_add3_u32 v219, s7, v223, v189
	v_add3_u32 v220, s7, v222, v189
	v_add3_u32 v242, s7, v221, v189
	ds_read_b128 v[64:67], v218
	ds_read_b128 v[68:71], v219
	ds_read_b128 v[72:75], v220
	ds_read_b128 v[76:79], v242
	ds_read_b128 v[172:175], v218 offset:128
	ds_read_b128 v[176:179], v219 offset:128
	ds_read_b128 v[238:241], v220 offset:128
	ds_read_b128 v[214:217], v242 offset:128
	s_waitcnt lgkmcnt(7)
	v_mfma_f32_32x32x16_bf16 v[80:95], v[64:67], v[144:147], 0
	ds_read_b128 v[64:67], v218 offset:256
	s_waitcnt lgkmcnt(7)
	v_mfma_f32_32x32x16_bf16 v[80:95], v[68:71], v[140:143], v[80:95]
	ds_read_b128 v[68:71], v219 offset:256
	s_waitcnt lgkmcnt(7)
	v_mfma_f32_32x32x16_bf16 v[80:95], v[72:75], v[136:139], v[80:95]
	ds_read_b128 v[72:75], v220 offset:256
	s_waitcnt lgkmcnt(7)
	v_mfma_f32_32x32x16_bf16 v[80:95], v[76:79], v[132:135], v[80:95]
	ds_read_b128 v[76:79], v242 offset:256
	s_waitcnt lgkmcnt(7)
	v_mfma_f32_32x32x16_bf16 v[80:95], v[172:175], v[128:131], v[80:95]
	ds_read_b128 v[172:175], v218 offset:12288
	s_waitcnt lgkmcnt(7)
	v_mfma_f32_32x32x16_bf16 v[80:95], v[176:179], v[124:127], v[80:95]
	ds_read_b128 v[176:179], v219 offset:12288
	s_waitcnt lgkmcnt(7)
	v_mfma_f32_32x32x16_bf16 v[80:95], v[238:241], v[120:123], v[80:95]
	ds_read_b128 v[238:241], v220 offset:12288
	s_waitcnt lgkmcnt(7)
	v_mfma_f32_32x32x16_bf16 v[80:95], v[214:217], v[116:119], v[80:95]
	ds_read_b128 v[214:217], v242 offset:12288
	s_waitcnt lgkmcnt(7)
	v_mfma_f32_32x32x16_bf16 v[80:95], v[64:67], v[112:115], v[80:95]
	s_waitcnt lgkmcnt(6)
	v_mfma_f32_32x32x16_bf16 v[80:95], v[68:71], v[108:111], v[80:95]
	s_waitcnt lgkmcnt(5)
	v_mfma_f32_32x32x16_bf16 v[80:95], v[72:75], v[104:107], v[80:95]
	s_waitcnt lgkmcnt(4)
	v_mfma_f32_32x32x16_bf16 v[80:95], v[76:79], v[100:103], v[80:95]
	s_waitcnt lgkmcnt(3)
	v_mfma_f32_32x32x16_bf16 v[64:79], v[172:175], v[144:147], 0
	ds_read_b128 v[172:175], v218 offset:12416
	s_waitcnt lgkmcnt(3)
	v_mfma_f32_32x32x16_bf16 v[64:79], v[176:179], v[140:143], v[64:79]
	ds_read_b128 v[176:179], v219 offset:12416
	s_waitcnt lgkmcnt(3)
	v_mfma_f32_32x32x16_bf16 v[64:79], v[238:241], v[136:139], v[64:79]
	ds_read_b128 v[238:241], v220 offset:12416
	s_waitcnt lgkmcnt(3)
	v_mfma_f32_32x32x16_bf16 v[64:79], v[214:217], v[132:135], v[64:79]
	ds_read_b128 v[214:217], v242 offset:12416
	v_exp_f32_e32 v80, v80
	v_exp_f32_e32 v81, v81
	v_add_f32_e32 v191, 0, v80
	v_exp_f32_e32 v82, v82
	v_add_f32_e32 v191, v81, v191
	v_exp_f32_e32 v83, v83
	s_waitcnt lgkmcnt(3)
	v_mfma_f32_32x32x16_bf16 v[64:79], v[172:175], v[128:131], v[64:79]
	ds_read_b128 v[172:175], v218 offset:12544
	v_lshl_add_u32 v218, s6, 14, v187
	v_add_f32_e32 v191, v82, v191
	v_exp_f32_e32 v84, v84
	v_add_f32_e32 v191, v83, v191
	v_exp_f32_e32 v85, v85
	v_add_f32_e32 v191, v84, v191
	v_exp_f32_e32 v86, v86
	s_waitcnt lgkmcnt(3)
	v_mfma_f32_32x32x16_bf16 v[64:79], v[176:179], v[124:127], v[64:79]
	ds_read_b128 v[176:179], v219 offset:12544
	v_add_f32_e32 v191, v85, v191
	v_exp_f32_e32 v87, v87
	v_add_f32_e32 v191, v86, v191
	v_exp_f32_e32 v88, v88
	v_add_f32_e32 v191, v87, v191
	v_exp_f32_e32 v89, v89
	s_waitcnt lgkmcnt(3)
	v_mfma_f32_32x32x16_bf16 v[64:79], v[238:241], v[120:123], v[64:79]
	ds_read_b128 v[238:241], v220 offset:12544
	v_add_f32_e32 v191, v88, v191
	v_exp_f32_e32 v90, v90
	v_add_f32_e32 v191, v89, v191
	v_exp_f32_e32 v91, v91
	v_add_f32_e32 v191, v90, v191
	v_exp_f32_e32 v92, v92
	s_waitcnt lgkmcnt(3)
	v_mfma_f32_32x32x16_bf16 v[64:79], v[214:217], v[116:119], v[64:79]
	ds_read_b128 v[214:217], v242 offset:12544
	v_add_f32_e32 v191, v91, v191
	v_exp_f32_e32 v93, v93
	v_add_f32_e32 v191, v92, v191
	v_exp_f32_e32 v94, v94
	v_add_f32_e32 v191, v93, v191
	v_exp_f32_e32 v95, v95
	s_waitcnt lgkmcnt(3)
	v_mfma_f32_32x32x16_bf16 v[64:79], v[172:175], v[112:115], v[64:79]
	ds_read_b64_tr_b16 v[172:173], v218 offset:0x200
	ds_read_b64_tr_b16 v[174:175], v218 offset:0xa00
	v_add_f32_e32 v191, v94, v191
	s_nop 0
	v_add_f32_e32 v191, v95, v191
	v_cvt_pk_bf16_f32 v80, v80, v81
	v_cvt_pk_bf16_f32 v81, v82, v83
	v_cvt_pk_bf16_f32 v82, v84, v85
	s_waitcnt lgkmcnt(4)
	v_mfma_f32_32x32x16_bf16 v[64:79], v[176:179], v[108:111], v[64:79]
	ds_read_b64_tr_b16 v[176:177], v218 offset:0x1200
	ds_read_b64_tr_b16 v[178:179], v218 offset:0x1a00
	v_cvt_pk_bf16_f32 v83, v86, v87
	v_cvt_pk_bf16_f32 v84, v88, v89
	v_cvt_pk_bf16_f32 v85, v90, v91
	v_cvt_pk_bf16_f32 v86, v92, v93
	v_cvt_pk_bf16_f32 v87, v94, v95
	ds_read_b64_tr_b16 v[88:89], v218 offset:0x0
	ds_read_b64_tr_b16 v[90:91], v218 offset:0x800
	s_waitcnt lgkmcnt(7)
	v_mfma_f32_32x32x16_bf16 v[64:79], v[238:241], v[104:107], v[64:79]
	ds_read_b64_tr_b16 v[238:239], v218 offset:0x400
	ds_read_b64_tr_b16 v[240:241], v218 offset:0xc00
	ds_read_b64_tr_b16 v[92:93], v218 offset:0x1000
	ds_read_b64_tr_b16 v[94:95], v218 offset:0x1800
	s_waitcnt lgkmcnt(10)
	v_mfma_f32_32x32x16_bf16 v[64:79], v[214:217], v[100:103], v[64:79]
	ds_read_b64_tr_b16 v[214:215], v218 offset:0x1400
	ds_read_b64_tr_b16 v[216:217], v218 offset:0x1c00
	s_nop 1
	s_waitcnt lgkmcnt(6)
	v_mfma_f32_32x32x16_bf16 v[48:63], v[80:83], v[88:91], v[48:63]
	ds_read_b64_tr_b16 v[88:89], v218 offset:0x600
	ds_read_b64_tr_b16 v[90:91], v218 offset:0xe00
	v_exp_f32_e32 v64, v64
	v_exp_f32_e32 v65, v65
	v_add_f32_e32 v191, v64, v191
	s_waitcnt lgkmcnt(4)
; #define SBAR() __builtin_amdgcn_sched_barrier(0)
; template <int D0> __device__ __forceinline__ void pv_one(f32x16& od, int vb, bf16x8 pa0, bf16x8 pa1, bf16x8 pa2, bf16x8 pa3) {
;   const s16x4 l0 = tr_read<v_rd_off(D0, 0, 0)>(vb), h0 = tr_read<v_rd_off(D0, 0, 1)>(vb), l1 = tr_read<v_rd_off(D0, 1, 0)>(vb), h1 = tr_read<v_rd_off(D0, 1, 1)>(vb);
;   const s16x4 l2 = tr_read<v_rd_off(D0, 2, 0)>(vb), h2 = tr_read<v_rd_off(D0, 2, 1)>(vb), l3 = tr_read<v_rd_off(D0, 3, 0)>(vb), h3 = tr_read<v_rd_off(D0, 3, 1)>(vb);
;   asm volatile("s_waitcnt lgkmcnt(0)" ::: "memory"); SBAR();
;     ...
;   od = __builtin_amdgcn_mfma_f32_32x32x16_bf16(pa0, PK(l0, h0), od, 0, 0, 0);
;   od = __builtin_amdgcn_mfma_f32_32x32x16_bf16(pa1, PK(l1, h1), od, 0, 0, 0);
;   od = __builtin_amdgcn_mfma_f32_32x32x16_bf16(pa2, PK(l2, h2), od, 0, 0, 0);
;   od = __builtin_amdgcn_mfma_f32_32x32x16_bf16(pa3, PK(l3, h3), od, 0, 0, 0);
;     ...
; }
; __device__ __forceinline__ void pv_d0(f32x16* o, int vb, bf16x8 pa0, bf16x8 pa1, bf16x8 pa2, bf16x8 pa3) {
;   pv_one<0>(o[0], vb, pa0, pa1, pa2, pa3); pv_one<1>(o[1], vb, pa0, pa1, pa2, pa3); pv_one<2>(o[2], vb, pa0, pa1, pa2, pa3); pv_one<3>(o[3], vb, pa0, pa1, pa2, pa3);
	v_mfma_f32_32x32x16_bf16 v[48:63], v[84:87], v[92:95], v[48:63]
	ds_read_b64_tr_b16 v[92:93], v218 offset:0x1600
	ds_read_b64_tr_b16 v[94:95], v218 offset:0x1e00
	v_exp_f32_e32 v66, v66
	v_add_f32_e32 v191, v65, v191
	v_exp_f32_e32 v67, v67
	v_add_f32_e32 v191, v66, v191
	v_mfma_f32_32x32x16_bf16 v[32:47], v[80:83], v[172:175], v[32:47]
	ds_read_b64_tr_b16 v[172:173], v218 offset:0x2000
	ds_read_b64_tr_b16 v[174:175], v218 offset:0x2800
	v_exp_f32_e32 v68, v68
	v_add_f32_e32 v191, v67, v191
	v_exp_f32_e32 v69, v69
	v_add_f32_e32 v191, v68, v191
	v_mfma_f32_32x32x16_bf16 v[32:47], v[84:87], v[176:179], v[32:47]
	ds_read_b64_tr_b16 v[176:177], v218 offset:0x3000
	ds_read_b64_tr_b16 v[178:179], v218 offset:0x3800
	v_exp_f32_e32 v70, v70
	v_add_f32_e32 v191, v69, v191
	v_exp_f32_e32 v71, v71
	v_add_f32_e32 v191, v70, v191
	v_mfma_f32_32x32x16_bf16 v[16:31], v[80:83], v[238:241], v[16:31]
	ds_read_b64_tr_b16 v[238:239], v218 offset:0x2200
	ds_read_b64_tr_b16 v[240:241], v218 offset:0x2a00
	v_exp_f32_e32 v72, v72
	v_add_f32_e32 v191, v71, v191
	v_exp_f32_e32 v73, v73
	v_add_f32_e32 v191, v72, v191
	s_waitcnt lgkmcnt(10)
	v_mfma_f32_32x32x16_bf16 v[16:31], v[84:87], v[214:217], v[16:31]
	ds_read_b64_tr_b16 v[214:215], v218 offset:0x3200
	ds_read_b64_tr_b16 v[216:217], v218 offset:0x3a00
	v_exp_f32_e32 v74, v74
	v_add_f32_e32 v191, v73, v191
	v_exp_f32_e32 v75, v75
	v_add_f32_e32 v191, v74, v191
	s_waitcnt lgkmcnt(10)
	v_mfma_f32_32x32x16_bf16 v[0:15], v[80:83], v[88:91], v[0:15]
	ds_read_b64_tr_b16 v[88:89], v218 offset:0x2400
	ds_read_b64_tr_b16 v[90:91], v218 offset:0x2c00
	v_exp_f32_e32 v76, v76
	v_add_f32_e32 v191, v75, v191
	v_exp_f32_e32 v77, v77
	v_add_f32_e32 v191, v76, v191
	s_waitcnt lgkmcnt(10)
	v_mfma_f32_32x32x16_bf16 v[0:15], v[84:87], v[92:95], v[0:15]
	ds_read_b64_tr_b16 v[92:93], v218 offset:0x3400
	ds_read_b64_tr_b16 v[94:95], v218 offset:0x3c00
	v_exp_f32_e32 v78, v78
	v_add_f32_e32 v191, v77, v191
	v_exp_f32_e32 v79, v79
	v_add_f32_e32 v191, v78, v191
	s_nop 0
	v_add_f32_e32 v191, v79, v191
	v_cvt_pk_bf16_f32 v64, v64, v65
	v_cvt_pk_bf16_f32 v65, v66, v67
	v_cvt_pk_bf16_f32 v66, v68, v69
	v_cvt_pk_bf16_f32 v67, v70, v71
	v_cvt_pk_bf16_f32 v68, v72, v73
	v_cvt_pk_bf16_f32 v69, v74, v75
	v_cvt_pk_bf16_f32 v70, v76, v77
	v_cvt_pk_bf16_f32 v71, v78, v79
	v_add_f32_e32 v230, v230, v191
	s_nop 0
	s_waitcnt lgkmcnt(10)
	v_mfma_f32_32x32x16_bf16 v[48:63], v[64:67], v[172:175], v[48:63]
	ds_read_b64_tr_b16 v[172:173], v218 offset:0x2600
	ds_read_b64_tr_b16 v[174:175], v218 offset:0x2e00
	s_xor_b32 s7, s6, 1
	s_lshl_b32 s12, s7, 14
	s_mulk_i32 s7, 0x6000
	s_add_i32 s7, s0, s7
	v_add_u32_e32 v219, s12, v236
	s_waitcnt vmcnt(4)
	ds_write_b128 v219, v[152:155]
	s_waitcnt lgkmcnt(11)
	v_mfma_f32_32x32x16_bf16 v[48:63], v[68:71], v[176:179], v[48:63]
	ds_read_b64_tr_b16 v[176:177], v218 offset:0x3600
	ds_read_b64_tr_b16 v[178:179], v218 offset:0x3e00
	v_add_u32_e32 v219, s12, v237
	s_waitcnt vmcnt(3)
	ds_write_b128 v219, v[148:151]
	s_waitcnt lgkmcnt(12)
	v_mfma_f32_32x32x16_bf16 v[32:47], v[64:67], v[238:241], v[32:47]
	v_add_u32_e32 v219, s7, v225
	s_waitcnt vmcnt(2)
	ds_write_b128 v219, v[164:167]
	s_waitcnt lgkmcnt(11)
	v_mfma_f32_32x32x16_bf16 v[32:47], v[68:71], v[214:217], v[32:47]
	v_add_u32_e32 v219, s7, v226
	s_waitcnt vmcnt(1)
	ds_write_b128 v219, v[160:163]
	s_waitcnt lgkmcnt(10)
	v_mfma_f32_32x32x16_bf16 v[16:31], v[64:67], v[88:91], v[16:31]
	v_add_u32_e32 v219, s7, v227
	s_waitcnt vmcnt(0)
	ds_write_b128 v219, v[156:159]
	s_waitcnt lgkmcnt(9)
	v_mfma_f32_32x32x16_bf16 v[16:31], v[68:71], v[92:95], v[16:31]
	s_mov_b32 s38, s30
	s_mov_b32 s39, s31
	buffer_load_dwordx4 v[152:155], v228, s[28:31], s3 offen
	buffer_load_dwordx4 v[148:151], v229, s[28:31], s3 offen
	buffer_load_dwordx4 v[164:167], v186, s[36:39], s2 offen
	s_waitcnt lgkmcnt(7)
	v_mfma_f32_32x32x16_bf16 v[0:15], v[64:67], v[172:175], v[0:15]
	buffer_load_dwordx4 v[160:163], v188, s[36:39], s2 offen
	buffer_load_dwordx4 v[156:159], v190, s[36:39], s2 offen
	s_add_i32 s1, s1, 1
	s_add_i32 s2, s2, 0x18000
	s_add_i32 s3, s3, 0x20000
	s_cmp_eq_u32 s2, 0x1818000
	s_waitcnt lgkmcnt(4)
	v_mfma_f32_32x32x16_bf16 v[0:15], v[68:71], v[176:179], v[0:15]
	s_cbranch_scc0 .LBB0_578
	v_add_u32_e32 v220, 0x80, v224
	v_add_u32_e32 v219, 0x80, v223
	v_add_u32_e32 v218, 0x80, v222
	v_add_u32_e32 v217, 0x80, v221
	v_add_u32_e32 v216, 0x100, v224
	v_add_u32_e32 v215, 0x100, v223
	v_add_u32_e32 v214, 0x100, v222
	v_add_u32_e32 v191, 0x100, v221
	s_waitcnt lgkmcnt(0)
	s_barrier
; template <bool FIXM>
; __device__ __forceinline__ void partialSM(f32x16& p0, f32x16& p1, float& m_reg, float& mn, float& alpha, const float C, const float thrS, const int kb, const int hi) {
;     ...
;     for (int r = 0; r < 16; ++r) p0[r] = __builtin_amdgcn_exp2f(p0[r]);
;     if (kb + KVBLK > LROWS) {
; #pragma unroll
;       for (int r = 0; r < 16; ++r) { if (kb + crow(r, hi) >= LROWS) p0[r] = 0.f; }
;     }
;     return;
;   }
;   if (kb + KVBLK > LROWS) {
; #pragma unroll
;     for (int r = 0; r < 16; ++r) { const int k0 = kb + crow(r, hi); if (k0 >= LROWS) p0[r] = -1e30f; if (k0 + 32 >= LROWS) p1[r] = -1e30f; }
;   }
;   float pmax = p0[0];
; #pragma unroll
;   for (int r = 1; r < 16; ++r) pmax = fmaxf(pmax, p0[r]);
; #pragma unroll
;   for (int r = 0; r < 16; ++r) pmax = fmaxf(pmax, p1[r]);
;   { auto rr = __builtin_amdgcn_permlane32_swap(__float_as_uint(pmax), __float_as_uint(pmax), false, false);
;     pmax = fmaxf(__uint_as_float(rr[0]), __uint_as_float(rr[1])); }
;   if (__builtin_expect(__all(pmax - m_reg <= thrS), 1)) { mn = m_reg; alpha = 1.f; }
;   else { mn = fmaxf(m_reg, pmax); alpha = __builtin_amdgcn_exp2f((m_reg - mn) * C); m_reg = mn; }
;   const float mnC = -mn * C;
; #pragma unroll
; template <int DQK>
; __device__ __forceinline__ void qkt(f32x16& p0, f32x16& p1, const char* Ks, const bf16x8* qr, int r32, int hi) {
;   constexpr int KP = DQK * 2;
;   p0 = f32x16{}; p1 = f32x16{};
;   if constexpr (DQK == 64 && ATT_KPRELOAD) {
;     bf16x8 ka[4], kq[4];
; #pragma unroll
;     for (int d0 = 0; d0 < 4; ++d0) { const int cb = (d0 * 16 + hi * 8) * 2;
;       ka[d0] = *reinterpret_cast<const bf16x8*>(Ks + KSWZ(KP, r32, cb)); kq[d0] = *reinterpret_cast<const bf16x8*>(Ks + KSWZ(KP, 32 + r32, cb)); }
;     SBAR();
; #pragma unroll
;     for (int d0 = 0; d0 < 4; ++d0) { p0 = __builtin_amdgcn_mfma_f32_32x32x16_bf16(ka[d0], qr[d0], p0, 0, 0, 0); p1 = __builtin_amdgcn_mfma_f32_32x32x16_bf16(kq[d0], qr[d0], p1, 0, 0, 0); }
;     return;
;   }
; #pragma unroll
;   for (int d0 = 0; d0 < DQK / 16; ++d0) { const int cb = (d0 * 16 + hi * 8) * 2;
;     bf16x8 b0 = *reinterpret_cast<const bf16x8*>(Ks + KSWZ(KP, r32, cb));
;     bf16x8 b1 = *reinterpret_cast<const bf16x8*>(Ks + KSWZ(KP, 32 + r32, cb));
;     p0 = __builtin_amdgcn_mfma_f32_32x32x16_bf16(b0, qr[d0], p0, 0, 0, 0);
;     p1 = __builtin_amdgcn_mfma_f32_32x32x16_bf16(b1, qr[d0], p1, 0, 0, 0); }
	s_add_i32 s1, 0, 0x16000
	v_add3_u32 v68, s1, v224, v189
	ds_read_b128 v[64:67], v68
	v_add3_u32 v176, s1, v223, v189
	ds_read_b128 v[172:175], v176
	s_waitcnt lgkmcnt(1)
	v_mfma_f32_32x32x16_bf16 v[80:95], v[64:67], v[144:147], 0
	ds_read_b128 v[64:67], v68 offset:12288
	s_waitcnt lgkmcnt(1)
	v_mfma_f32_32x32x16_bf16 v[80:95], v[172:175], v[140:143], v[80:95]
	ds_read_b128 v[172:175], v176 offset:12288
	v_add3_u32 v176, s1, v222, v189
	s_waitcnt lgkmcnt(1)
	v_mfma_f32_32x32x16_bf16 v[64:79], v[64:67], v[144:147], 0
	s_waitcnt lgkmcnt(0)
	v_mfma_f32_32x32x16_bf16 v[64:79], v[172:175], v[140:143], v[64:79]
	ds_read_b128 v[172:175], v176
	s_waitcnt lgkmcnt(0)
	v_mfma_f32_32x32x16_bf16 v[80:95], v[172:175], v[136:139], v[80:95]
	ds_read_b128 v[172:175], v176 offset:12288
	v_add3_u32 v176, s1, v221, v189
	s_waitcnt lgkmcnt(0)
	v_mfma_f32_32x32x16_bf16 v[64:79], v[172:175], v[136:139], v[64:79]
	ds_read_b128 v[172:175], v176
	s_waitcnt lgkmcnt(0)
	v_mfma_f32_32x32x16_bf16 v[80:95], v[172:175], v[132:135], v[80:95]
	ds_read_b128 v[172:175], v176 offset:12288
	v_add3_u32 v176, s1, v220, v189
	s_waitcnt lgkmcnt(0)
	v_mfma_f32_32x32x16_bf16 v[64:79], v[172:175], v[132:135], v[64:79]
	ds_read_b128 v[172:175], v176
	s_waitcnt lgkmcnt(0)
	v_mfma_f32_32x32x16_bf16 v[80:95], v[172:175], v[128:131], v[80:95]
	ds_read_b128 v[172:175], v176 offset:12288
	v_add3_u32 v176, s1, v219, v189
	s_waitcnt lgkmcnt(0)
	v_mfma_f32_32x32x16_bf16 v[64:79], v[172:175], v[128:131], v[64:79]
	ds_read_b128 v[172:175], v176
	s_waitcnt lgkmcnt(0)
	v_mfma_f32_32x32x16_bf16 v[80:95], v[172:175], v[124:127], v[80:95]
	ds_read_b128 v[172:175], v176 offset:12288
	v_add3_u32 v176, s1, v218, v189
	s_waitcnt lgkmcnt(0)
	v_mfma_f32_32x32x16_bf16 v[64:79], v[172:175], v[124:127], v[64:79]
	ds_read_b128 v[172:175], v176
	s_waitcnt lgkmcnt(0)
	v_mfma_f32_32x32x16_bf16 v[80:95], v[172:175], v[120:123], v[80:95]
	ds_read_b128 v[172:175], v176 offset:12288
	v_add3_u32 v176, s1, v217, v189
	s_waitcnt lgkmcnt(0)
	v_mfma_f32_32x32x16_bf16 v[64:79], v[172:175], v[120:123], v[64:79]
	ds_read_b128 v[172:175], v176
	s_waitcnt lgkmcnt(0)
	v_mfma_f32_32x32x16_bf16 v[80:95], v[172:175], v[116:119], v[80:95]
	ds_read_b128 v[172:175], v176 offset:12288
	v_add3_u32 v176, s1, v216, v189
	s_waitcnt lgkmcnt(0)
	v_mfma_f32_32x32x16_bf16 v[64:79], v[172:175], v[116:119], v[64:79]
	ds_read_b128 v[172:175], v176
	s_waitcnt lgkmcnt(0)
	v_mfma_f32_32x32x16_bf16 v[80:95], v[172:175], v[112:115], v[80:95]
	ds_read_b128 v[172:175], v176 offset:12288
	v_add3_u32 v176, s1, v215, v189
	s_waitcnt lgkmcnt(0)
	v_mfma_f32_32x32x16_bf16 v[64:79], v[172:175], v[112:115], v[64:79]
	ds_read_b128 v[172:175], v176
	s_waitcnt lgkmcnt(0)
	v_mfma_f32_32x32x16_bf16 v[80:95], v[172:175], v[108:111], v[80:95]
	ds_read_b128 v[172:175], v176 offset:12288
	v_add3_u32 v176, s1, v214, v189
	s_waitcnt lgkmcnt(0)
	v_mfma_f32_32x32x16_bf16 v[64:79], v[172:175], v[108:111], v[64:79]
	ds_read_b128 v[172:175], v176
	s_waitcnt lgkmcnt(0)
	v_mfma_f32_32x32x16_bf16 v[80:95], v[172:175], v[104:107], v[80:95]
	ds_read_b128 v[172:175], v176 offset:12288
	v_add3_u32 v176, s1, v191, v189
	s_waitcnt lgkmcnt(0)
	v_mfma_f32_32x32x16_bf16 v[64:79], v[172:175], v[104:107], v[64:79]
	ds_read_b128 v[172:175], v176
	s_waitcnt lgkmcnt(0)
	v_mfma_f32_32x32x16_bf16 v[80:95], v[172:175], v[100:103], v[80:95]
	ds_read_b128 v[172:175], v176 offset:12288
	s_waitcnt lgkmcnt(0)
	v_mfma_f32_32x32x16_bf16 v[64:79], v[172:175], v[100:103], v[64:79]
	s_waitcnt vmcnt(4)
	ds_write_b128 v231, v[152:155]
	s_waitcnt vmcnt(3)
	ds_write_b128 v232, v[148:151]
	s_waitcnt vmcnt(2)
	ds_write_b128 v233, v[164:167]
	s_waitcnt vmcnt(1)
	ds_write_b128 v234, v[160:163]
	s_waitcnt vmcnt(0)
	ds_write_b128 v235, v[156:159]
	v_exp_f32_e32 v80, v80
	v_exp_f32_e32 v81, v81
	v_exp_f32_e32 v82, v82
	v_exp_f32_e32 v83, v83
	v_exp_f32_e32 v84, v84
	v_exp_f32_e32 v149, v64
	v_add_f32_e32 v64, 0, v80
	v_exp_f32_e32 v85, v85
	v_add_f32_e32 v64, v81, v64
	v_exp_f32_e32 v86, v86
	v_add_f32_e32 v64, v82, v64
	v_exp_f32_e32 v87, v87
	v_add_f32_e32 v64, v83, v64
	v_exp_f32_e32 v88, v88
	v_add_f32_e32 v64, v84, v64
	v_exp_f32_e32 v89, v89
	v_add_f32_e32 v64, v85, v64
	v_exp_f32_e32 v90, v90
	v_add_f32_e32 v64, v86, v64
	v_exp_f32_e32 v91, v91
	v_add_f32_e32 v64, v87, v64
	v_exp_f32_e32 v92, v92
	v_add_f32_e32 v64, v88, v64
	v_exp_f32_e32 v93, v93
	v_add_f32_e32 v64, v89, v64
	v_exp_f32_e32 v94, v94
	v_add_f32_e32 v64, v90, v64
	v_exp_f32_e32 v95, v95
	v_add_f32_e32 v64, v91, v64
	v_add_f32_e32 v64, v92, v64
	v_exp_f32_e32 v150, v65
	v_add_f32_e32 v64, v93, v64
	v_exp_f32_e32 v151, v66
	v_add_f32_e32 v64, v94, v64
	v_exp_f32_e32 v152, v67
	v_add_f32_e32 v64, v95, v64
	v_exp_f32_e32 v153, v68
	v_add_f32_e32 v64, v149, v64
	v_exp_f32_e32 v154, v69
	v_add_f32_e32 v64, v150, v64
	v_exp_f32_e32 v155, v70
	v_add_f32_e32 v64, v151, v64
	v_exp_f32_e32 v156, v71
	v_add_f32_e32 v64, v152, v64
	v_exp_f32_e32 v157, v72
	v_add_f32_e32 v64, v153, v64
	v_exp_f32_e32 v158, v73
	v_add_f32_e32 v64, v154, v64
	v_exp_f32_e32 v159, v74
	v_add_f32_e32 v64, v155, v64
	v_exp_f32_e32 v160, v75
	v_add_f32_e32 v64, v156, v64
	v_exp_f32_e32 v161, v76
	v_add_f32_e32 v64, v157, v64
	v_exp_f32_e32 v162, v77
	v_add_f32_e32 v64, v158, v64
	v_exp_f32_e32 v163, v78
	v_add_f32_e32 v64, v159, v64
	v_exp_f32_e32 v79, v79
	v_add_f32_e32 v64, v160, v64
	v_add_f32_e32 v64, v161, v64
	v_add_f32_e32 v64, v162, v64
	v_add_f32_e32 v64, v163, v64
	v_add_f32_e32 v64, v79, v64
	v_add_u32_e32 v148, 0x4000, v187
	v_add_f32_e32 v164, v230, v64
	v_cvt_pk_bf16_f32 v64, v80, v81
	v_cvt_pk_bf16_f32 v65, v82, v83
	v_cvt_pk_bf16_f32 v66, v84, v85
	v_cvt_pk_bf16_f32 v67, v86, v87
	v_cvt_pk_bf16_f32 v68, v88, v89
	v_cvt_pk_bf16_f32 v69, v90, v91
	v_cvt_pk_bf16_f32 v70, v92, v93
	v_cvt_pk_bf16_f32 v71, v94, v95
	v_cvt_pk_bf16_f32 v72, v149, v150
	v_cvt_pk_bf16_f32 v73, v151, v152
	v_cvt_pk_bf16_f32 v74, v153, v154
	v_cvt_pk_bf16_f32 v75, v155, v156
	v_cvt_pk_bf16_f32 v76, v157, v158
	v_cvt_pk_bf16_f32 v77, v159, v160
	v_cvt_pk_bf16_f32 v78, v161, v162
	v_cvt_pk_bf16_f32 v79, v163, v79
	ds_read_b64_tr_b16 v[80:81], v148 offset:0
	ds_read_b64_tr_b16 v[82:83], v148 offset:0x800
	ds_read_b64_tr_b16 v[84:85], v148 offset:0x1000
	ds_read_b64_tr_b16 v[86:87], v148 offset:0x1800
	ds_read_b64_tr_b16 v[88:89], v148 offset:0x2000
	ds_read_b64_tr_b16 v[90:91], v148 offset:0x2800
	ds_read_b64_tr_b16 v[92:93], v148 offset:0x3000
	ds_read_b64_tr_b16 v[94:95], v148 offset:0x3800
	s_waitcnt lgkmcnt(0)
; #define SBAR() __builtin_amdgcn_sched_barrier(0)
; template <bool FIXM>
; __device__ __forceinline__ void partialSM(f32x16& p0, f32x16& p1, float& m_reg, float& mn, float& alpha, const float C, const float thrS, const int kb, const int hi) {
;     ...
;     for (int r = 0; r < 16; ++r) p0[r] = __builtin_amdgcn_exp2f(p0[r]);
;     if (kb + KVBLK > LROWS) {
; #pragma unroll
;       for (int r = 0; r < 16; ++r) { if (kb + crow(r, hi) >= LROWS) p0[r] = 0.f; }
;     }
;     return;
;   }
;   if (kb + KVBLK > LROWS) {
; #pragma unroll
;     for (int r = 0; r < 16; ++r) { const int k0 = kb + crow(r, hi); if (k0 >= LROWS) p0[r] = -1e30f; if (k0 + 32 >= LROWS) p1[r] = -1e30f; }
;   }
;   float pmax = p0[0];
; #pragma unroll
;   for (int r = 1; r < 16; ++r) pmax = fmaxf(pmax, p0[r]);
; #pragma unroll
;   for (int r = 0; r < 16; ++r) pmax = fmaxf(pmax, p1[r]);
;   { auto rr = __builtin_amdgcn_permlane32_swap(__float_as_uint(pmax), __float_as_uint(pmax), false, false);
;     pmax = fmaxf(__uint_as_float(rr[0]), __uint_as_float(rr[1])); }
;   if (__builtin_expect(__all(pmax - m_reg <= thrS), 1)) { mn = m_reg; alpha = 1.f; }
;   else { mn = fmaxf(m_reg, pmax); alpha = __builtin_amdgcn_exp2f((m_reg - mn) * C); m_reg = mn; }
;   const float mnC = -mn * C;
; #pragma unroll
; template <int D0> __device__ __forceinline__ void pv_one(f32x16& od, int vb, bf16x8 pa0, bf16x8 pa1, bf16x8 pa2, bf16x8 pa3) {
;   const s16x4 l0 = tr_read<v_rd_off(D0, 0, 0)>(vb), h0 = tr_read<v_rd_off(D0, 0, 1)>(vb), l1 = tr_read<v_rd_off(D0, 1, 0)>(vb), h1 = tr_read<v_rd_off(D0, 1, 1)>(vb);
;   const s16x4 l2 = tr_read<v_rd_off(D0, 2, 0)>(vb), h2 = tr_read<v_rd_off(D0, 2, 1)>(vb), l3 = tr_read<v_rd_off(D0, 3, 0)>(vb), h3 = tr_read<v_rd_off(D0, 3, 1)>(vb);
;   asm volatile("s_waitcnt lgkmcnt(0)" ::: "memory"); SBAR();
;     ...
;   od = __builtin_amdgcn_mfma_f32_32x32x16_bf16(pa0, PK(l0, h0), od, 0, 0, 0);
;   od = __builtin_amdgcn_mfma_f32_32x32x16_bf16(pa1, PK(l1, h1), od, 0, 0, 0);
;   od = __builtin_amdgcn_mfma_f32_32x32x16_bf16(pa2, PK(l2, h2), od, 0, 0, 0);
;   od = __builtin_amdgcn_mfma_f32_32x32x16_bf16(pa3, PK(l3, h3), od, 0, 0, 0);
;     ...
; }
; __device__ __forceinline__ void pv_d0(f32x16* o, int vb, bf16x8 pa0, bf16x8 pa1, bf16x8 pa2, bf16x8 pa3) {
;   pv_one<0>(o[0], vb, pa0, pa1, pa2, pa3); pv_one<1>(o[1], vb, pa0, pa1, pa2, pa3); pv_one<2>(o[2], vb, pa0, pa1, pa2, pa3); pv_one<3>(o[3], vb, pa0, pa1, pa2, pa3);
	s_nop 0
	v_mfma_f32_32x32x16_bf16 v[48:63], v[64:67], v[80:83], v[48:63]
	ds_read_b64_tr_b16 v[80:81], v148 offset:0x200
	ds_read_b64_tr_b16 v[82:83], v148 offset:0xa00
	v_mfma_f32_32x32x16_bf16 v[48:63], v[68:71], v[84:87], v[48:63]
	ds_read_b64_tr_b16 v[84:85], v148 offset:0x1200
	ds_read_b64_tr_b16 v[86:87], v148 offset:0x1a00
	v_mfma_f32_32x32x16_bf16 v[48:63], v[72:75], v[88:91], v[48:63]
	ds_read_b64_tr_b16 v[88:89], v148 offset:0x2200
	ds_read_b64_tr_b16 v[90:91], v148 offset:0x2a00
	v_mfma_f32_32x32x16_bf16 v[48:63], v[76:79], v[92:95], v[48:63]
	ds_read_b64_tr_b16 v[92:93], v148 offset:0x3200
	ds_read_b64_tr_b16 v[94:95], v148 offset:0x3a00
	s_waitcnt lgkmcnt(0)
	v_mfma_f32_32x32x16_bf16 v[32:47], v[64:67], v[80:83], v[32:47]
	ds_read_b64_tr_b16 v[80:81], v148 offset:0x400
	ds_read_b64_tr_b16 v[82:83], v148 offset:0xc00
	v_mfma_f32_32x32x16_bf16 v[32:47], v[68:71], v[84:87], v[32:47]
	ds_read_b64_tr_b16 v[84:85], v148 offset:0x1400
	ds_read_b64_tr_b16 v[86:87], v148 offset:0x1c00
	v_mfma_f32_32x32x16_bf16 v[32:47], v[72:75], v[88:91], v[32:47]
	ds_read_b64_tr_b16 v[88:89], v148 offset:0x2400
	ds_read_b64_tr_b16 v[90:91], v148 offset:0x2c00
	v_mfma_f32_32x32x16_bf16 v[32:47], v[76:79], v[92:95], v[32:47]
	ds_read_b64_tr_b16 v[92:93], v148 offset:0x3400
	ds_read_b64_tr_b16 v[94:95], v148 offset:0x3c00
	s_waitcnt lgkmcnt(0)
	v_mfma_f32_32x32x16_bf16 v[16:31], v[64:67], v[80:83], v[16:31]
	ds_read_b64_tr_b16 v[80:81], v148 offset:0x600
	ds_read_b64_tr_b16 v[82:83], v148 offset:0xe00
	v_mfma_f32_32x32x16_bf16 v[16:31], v[68:71], v[84:87], v[16:31]
	ds_read_b64_tr_b16 v[84:85], v148 offset:0x1600
	ds_read_b64_tr_b16 v[86:87], v148 offset:0x1e00
	v_mfma_f32_32x32x16_bf16 v[16:31], v[72:75], v[88:91], v[16:31]
	ds_read_b64_tr_b16 v[88:89], v148 offset:0x2600
	ds_read_b64_tr_b16 v[90:91], v148 offset:0x2e00
	v_mfma_f32_32x32x16_bf16 v[16:31], v[76:79], v[92:95], v[16:31]
	ds_read_b64_tr_b16 v[92:93], v148 offset:0x3600
	ds_read_b64_tr_b16 v[94:95], v148 offset:0x3e00
	s_waitcnt lgkmcnt(0)
	v_mfma_f32_32x32x16_bf16 v[0:15], v[64:67], v[80:83], v[0:15]
	v_and_b32_e32 v148, 0x3fffffc0, v213
	s_waitcnt lgkmcnt(0)
	s_barrier
	v_mfma_f32_32x32x16_bf16 v[0:15], v[68:71], v[84:87], v[0:15]
	v_mfma_f32_32x32x16_bf16 v[0:15], v[72:75], v[88:91], v[0:15]
	v_mfma_f32_32x32x16_bf16 v[0:15], v[76:79], v[92:95], v[0:15]
	v_add3_u32 v64, s0, v224, v189
	ds_read_b128 v[64:67], v64
	v_add3_u32 v80, s0, v223, v189
	ds_read_b128 v[80:83], v80
	s_waitcnt lgkmcnt(1)
	v_mfma_f32_32x32x16_bf16 v[64:79], v[64:67], v[144:147], 0
	s_waitcnt lgkmcnt(0)
	v_mfma_f32_32x32x16_bf16 v[64:79], v[80:83], v[140:143], v[64:79]
	v_add3_u32 v80, s0, v222, v189
	ds_read_b128 v[80:83], v80
	s_waitcnt lgkmcnt(0)
	v_mfma_f32_32x32x16_bf16 v[64:79], v[80:83], v[136:139], v[64:79]
	v_add3_u32 v80, s0, v221, v189
	ds_read_b128 v[80:83], v80
	s_waitcnt lgkmcnt(0)
	v_mfma_f32_32x32x16_bf16 v[64:79], v[80:83], v[132:135], v[64:79]
	v_add3_u32 v80, s0, v220, v189
	ds_read_b128 v[80:83], v80
	s_waitcnt lgkmcnt(0)
	v_mfma_f32_32x32x16_bf16 v[64:79], v[80:83], v[128:131], v[64:79]
	v_add3_u32 v80, s0, v219, v189
	ds_read_b128 v[80:83], v80
	s_waitcnt lgkmcnt(0)
	v_mfma_f32_32x32x16_bf16 v[64:79], v[80:83], v[124:127], v[64:79]
	v_add3_u32 v80, s0, v218, v189
	ds_read_b128 v[80:83], v80
	s_waitcnt lgkmcnt(0)
	v_mfma_f32_32x32x16_bf16 v[64:79], v[80:83], v[120:123], v[64:79]
	v_add3_u32 v80, s0, v217, v189
	ds_read_b128 v[80:83], v80
	s_waitcnt lgkmcnt(0)
	v_mfma_f32_32x32x16_bf16 v[64:79], v[80:83], v[116:119], v[64:79]
	v_add3_u32 v80, s0, v216, v189
	ds_read_b128 v[80:83], v80
	s_waitcnt lgkmcnt(0)
	v_mfma_f32_32x32x16_bf16 v[64:79], v[80:83], v[112:115], v[64:79]
	v_add3_u32 v80, s0, v215, v189
	ds_read_b128 v[80:83], v80
	s_waitcnt lgkmcnt(0)
	v_mfma_f32_32x32x16_bf16 v[64:79], v[80:83], v[108:111], v[64:79]
	v_add3_u32 v80, s0, v214, v189
	ds_read_b128 v[80:83], v80
	s_waitcnt lgkmcnt(0)
	v_mfma_f32_32x32x16_bf16 v[64:79], v[80:83], v[104:107], v[64:79]
	v_add3_u32 v80, s0, v191, v189
	ds_read_b128 v[80:83], v80
	s_waitcnt lgkmcnt(0)
	v_mfma_f32_32x32x16_bf16 v[64:79], v[80:83], v[100:103], v[64:79]
	s_nop 11
	v_exp_f32_e32 v72, v64
	v_exp_f32_e32 v65, v65
	v_exp_f32_e32 v73, v66
	v_exp_f32_e32 v67, v67
	v_exp_f32_e32 v68, v68
	v_add_f32_e32 v64, 0, v72
	v_exp_f32_e32 v69, v69
	v_add_f32_e32 v64, v65, v64
	v_exp_f32_e32 v70, v70
	v_add_f32_e32 v64, v73, v64
	v_exp_f32_e32 v71, v71
	v_add_f32_e32 v64, v67, v64
	v_add_f32_e32 v64, v68, v64
	v_add_f32_e32 v64, v69, v64
	v_add_f32_e32 v64, v70, v64
	v_add_f32_e32 v64, v71, v64
	v_add_f32_e32 v64, 0, v64
	v_add_f32_e32 v64, v164, v64
	v_cvt_pk_bf16_f32 v66, v72, v65
	v_cvt_pk_bf16_f32 v67, v73, v67
	v_cvt_pk_bf16_f32 v68, v68, v69
	v_cvt_pk_bf16_f32 v69, v70, v71
	v_cvt_pk_bf16_f32 v70, v169, v169
	v_cvt_pk_bf16_f32 v71, v169, v169
	v_cvt_pk_bf16_f32 v72, v169, v169
	v_cvt_pk_bf16_f32 v73, v169, v169
	v_cvt_pk_bf16_f32 v74, v169, v169
	v_cvt_pk_bf16_f32 v75, v169, v169
	v_cvt_pk_bf16_f32 v76, v169, v169
	v_cvt_pk_bf16_f32 v77, v169, v169
	v_cvt_pk_bf16_f32 v78, v169, v169
	v_cvt_pk_bf16_f32 v79, v169, v169
	v_cvt_pk_bf16_f32 v80, v169, v169
	v_cvt_pk_bf16_f32 v81, v169, v169
	ds_read_b64_tr_b16 v[82:83], v187 offset:0
	ds_read_b64_tr_b16 v[84:85], v187 offset:0x800
	ds_read_b64_tr_b16 v[86:87], v187 offset:0x1000
	ds_read_b64_tr_b16 v[88:89], v187 offset:0x1800
	ds_read_b64_tr_b16 v[90:91], v187 offset:0x2000
	ds_read_b64_tr_b16 v[92:93], v187 offset:0x2800
	ds_read_b64_tr_b16 v[100:101], v187 offset:0x3000
	ds_read_b64_tr_b16 v[102:103], v187 offset:0x3800
	s_waitcnt lgkmcnt(0)
; __device__ __forceinline__ int crow(int r, int hi) { return (r & 3) + 8 * (r >> 2) + 4 * hi; }
; __device__ __forceinline__ float bf2f(unsigned short b) { return __uint_as_float((unsigned)b << 16); }
; __device__ __forceinline__ unsigned f2bf(float f) { unsigned u = __float_as_uint(f); return (u + 0x7fffu + ((u >> 16) & 1u)) >> 16; }
; template <int D0> __device__ __forceinline__ void pv_one(f32x16& od, int vb, bf16x8 pa0, bf16x8 pa1, bf16x8 pa2, bf16x8 pa3) {
;     ...
;   od = __builtin_amdgcn_mfma_f32_32x32x16_bf16(pa0, PK(l0, h0), od, 0, 0, 0);
;   od = __builtin_amdgcn_mfma_f32_32x32x16_bf16(pa1, PK(l1, h1), od, 0, 0, 0);
;   od = __builtin_amdgcn_mfma_f32_32x32x16_bf16(pa2, PK(l2, h2), od, 0, 0, 0);
;   od = __builtin_amdgcn_mfma_f32_32x32x16_bf16(pa3, PK(l3, h3), od, 0, 0, 0);
;     ...
; }
; __device__ __forceinline__ void pv_d0(f32x16* o, int vb, bf16x8 pa0, bf16x8 pa1, bf16x8 pa2, bf16x8 pa3) {
;   pv_one<0>(o[0], vb, pa0, pa1, pa2, pa3); pv_one<1>(o[1], vb, pa0, pa1, pa2, pa3); pv_one<2>(o[2], vb, pa0, pa1, pa2, pa3); pv_one<3>(o[3], vb, pa0, pa1, pa2, pa3);
;     ...
;   { auto rr = __builtin_amdgcn_permlane32_swap(__float_as_uint(l_reg), __float_as_uint(l_reg), false, false);
;     l_reg = __uint_as_float(rr[0]) + __uint_as_float(rr[1]); }
;   if constexpr (SPLIT) if (part != nullptr) {
;     if (wid == 0) {
; #pragma unroll
;       for (int r = 0; r < 16; ++r) { const int orow = crow(r, hi);
;         if (orow < 16) {
; #pragma unroll
;           for (int d0 = 0; d0 < 4; ++d0) part[orow * 132 + d0 * 32 + r32] = o[d0][r]; } }
;       if (hi == 0 && r32 < 16) { part[r32 * 132 + 128] = m_reg; part[r32 * 132 + 129] = l_reg; }
;     }
;     __syncthreads();
;     return;
;   }
;   if (hi == 0) li_l[r32] = l_reg; asm volatile("s_waitcnt lgkmcnt(0)" ::: "memory");
; #pragma unroll
;   for (int r = 0; r < 16; ++r) { const int orow = wid * QBLK + crow(r, hi); const float rli = __builtin_amdgcn_rcpf(li_l[crow(r, hi)]);
;     if (orow < nvalid) {
;       if constexpr (MODE == 0) {
; #pragma unroll
;         for (int d0 = 0; d0 < 4; ++d0) Of[(long)orow * ldo + d0 * 32 + r32] = o[d0][r] * rli;
;       } else {
; #pragma unroll
;         for (int d0 = 0; d0 < 4; ++d0) { const float g = bf2f(Gb[(long)orow * ldg + d0 * 32 + r32]); const float sg = g / (1.f + __expf(-g));
;           Yb[(long)orow * ldy + d0 * 32 + r32] = (bf16)f2bf(o[d0][r] * rli * sg); }
	s_nop 0
	v_mfma_f32_32x32x16_bf16 v[48:63], v[66:69], v[82:85], v[48:63]
	ds_read_b64_tr_b16 v[82:83], v187 offset:0x200
	ds_read_b64_tr_b16 v[84:85], v187 offset:0xa00
	v_mfma_f32_32x32x16_bf16 v[48:63], v[70:73], v[86:89], v[48:63]
	ds_read_b64_tr_b16 v[86:87], v187 offset:0x1200
	ds_read_b64_tr_b16 v[88:89], v187 offset:0x1a00
	v_mfma_f32_32x32x16_bf16 v[48:63], v[74:77], v[90:93], v[48:63]
	ds_read_b64_tr_b16 v[90:91], v187 offset:0x2200
	ds_read_b64_tr_b16 v[92:93], v187 offset:0x2a00
	v_mfma_f32_32x32x16_bf16 v[48:63], v[78:81], v[100:103], v[48:63]
	ds_read_b64_tr_b16 v[100:101], v187 offset:0x3200
	ds_read_b64_tr_b16 v[102:103], v187 offset:0x3a00
	s_waitcnt lgkmcnt(0)
	v_mfma_f32_32x32x16_bf16 v[32:47], v[66:69], v[82:85], v[32:47]
	ds_read_b64_tr_b16 v[82:83], v187 offset:0x400
	ds_read_b64_tr_b16 v[84:85], v187 offset:0xc00
	v_mfma_f32_32x32x16_bf16 v[32:47], v[70:73], v[86:89], v[32:47]
	ds_read_b64_tr_b16 v[86:87], v187 offset:0x1400
	ds_read_b64_tr_b16 v[88:89], v187 offset:0x1c00
	v_mfma_f32_32x32x16_bf16 v[32:47], v[74:77], v[90:93], v[32:47]
	ds_read_b64_tr_b16 v[90:91], v187 offset:0x2400
	ds_read_b64_tr_b16 v[92:93], v187 offset:0x2c00
	v_mfma_f32_32x32x16_bf16 v[32:47], v[78:81], v[100:103], v[32:47]
	ds_read_b64_tr_b16 v[100:101], v187 offset:0x3400
	ds_read_b64_tr_b16 v[102:103], v187 offset:0x3c00
	s_waitcnt lgkmcnt(0)
	v_mfma_f32_32x32x16_bf16 v[16:31], v[66:69], v[82:85], v[16:31]
	ds_read_b64_tr_b16 v[82:83], v187 offset:0x600
	ds_read_b64_tr_b16 v[84:85], v187 offset:0xe00
	v_mfma_f32_32x32x16_bf16 v[16:31], v[70:73], v[86:89], v[16:31]
	ds_read_b64_tr_b16 v[86:87], v187 offset:0x1600
	ds_read_b64_tr_b16 v[88:89], v187 offset:0x1e00
	v_mfma_f32_32x32x16_bf16 v[16:31], v[74:77], v[90:93], v[16:31]
	ds_read_b64_tr_b16 v[90:91], v187 offset:0x2600
	ds_read_b64_tr_b16 v[92:93], v187 offset:0x2e00
	v_mfma_f32_32x32x16_bf16 v[16:31], v[78:81], v[100:103], v[16:31]
	ds_read_b64_tr_b16 v[100:101], v187 offset:0x3600
	ds_read_b64_tr_b16 v[102:103], v187 offset:0x3e00
	s_waitcnt lgkmcnt(0)
	v_mfma_f32_32x32x16_bf16 v[0:15], v[66:69], v[82:85], v[0:15]
	s_add_i32 s0, 0, 0x20000
	v_mov_b32_e32 v65, v64
	v_lshl_add_u32 v69, v148, 2, s0
	s_nop 0
	v_permlane32_swap_b32_e32 v64, v65
	v_cmp_gt_u32_e32 vcc, 32, v195
	v_mfma_f32_32x32x16_bf16 v[0:15], v[70:73], v[86:89], v[0:15]
	v_mfma_f32_32x32x16_bf16 v[0:15], v[74:77], v[90:93], v[0:15]
	v_mfma_f32_32x32x16_bf16 v[0:15], v[78:81], v[100:103], v[0:15]
	s_and_saveexec_b64 s[0:1], vcc
	v_lshl_add_u32 v66, v193, 2, v69
	v_add_f32_e32 v64, v64, v65
	ds_write_b32 v66, v64
	s_or_b64 exec, exec, s[0:1]
	s_lshl_b64 s[0:1], s[4:5], 12
	s_lshl_b32 s2, s97, 7
	s_mul_i32 s6, s4, 0x2e00
	s_mul_hi_u32 s3, s4, 0x2e00
	s_add_u32 s6, s10, s6
	s_addc_u32 s7, s11, s3
	v_readlane_b32 s18, v252, 49
	v_readlane_b32 s19, v252, 50
	s_add_u32 s12, s18, s0
	s_addc_u32 s18, s19, s1
	s_ashr_i32 s3, s2, 31
	s_lshl_b64 s[0:1], s[2:3], 1
	s_add_u32 s2, s12, s0
	s_addc_u32 s3, s18, s1
	s_add_u32 s0, s6, s0
	s_addc_u32 s1, s7, s1
	s_waitcnt lgkmcnt(0)
	v_lshlrev_b32_e32 v72, 2, v194
	v_lshlrev_b32_e32 v64, 1, v193
	v_mov_b32_e32 v65, v169
	v_lshl_add_u64 v[66:67], s[0:1], 0, v[64:65]
	s_mov_b64 s[0:1], 0x2180
	v_or_b32_e32 v68, v72, v192
	v_lshl_add_u64 v[66:67], v[66:67], 0, s[0:1]
	v_lshl_add_u64 v[64:65], s[2:3], 0, v[64:65]
	v_cmp_gt_i32_e32 vcc, s96, v68
	v_lshl_add_u32 v73, v72, 2, v69
	s_and_saveexec_b64 s[0:1], vcc
	s_cbranch_execz .LBB0_583
	v_mad_i64_i32 v[70:71], s[2:3], v68, s20, v[66:67]
	global_load_ushort v75, v[70:71], off
	global_load_ushort v100, v[70:71], off offset:64
	global_load_ushort v101, v[70:71], off offset:128
	global_load_ushort v102, v[70:71], off offset:192
	ds_read_b32 v69, v73
	s_waitcnt lgkmcnt(0)
	v_rcp_f32_e32 v74, v69
	v_ashrrev_i32_e32 v69, 31, v68
	v_lshlrev_b64 v[68:69], 12, v[68:69]
	v_lshl_add_u64 v[68:69], v[64:65], 0, v[68:69]
	v_mul_f32_e32 v48, v48, v74
	v_mul_f32_e32 v32, v32, v74
	v_mul_f32_e32 v16, v16, v74
	v_mul_f32_e32 v0, v0, v74
	s_waitcnt vmcnt(0)
	v_lshlrev_b32_e32 v75, 16, v75
	v_mul_f32_e32 v76, 0xbfb8aa3b, v75
	v_exp_f32_e32 v76, v76
	s_nop 0
	v_add_f32_e32 v76, 1.0, v76
	v_div_scale_f32 v77, s[2:3], v76, v76, v75
	v_rcp_f32_e32 v78, v77
	s_nop 0
	v_fma_f32 v79, -v77, v78, 1.0
	v_fmac_f32_e32 v78, v79, v78
	v_div_scale_f32 v79, vcc, v75, v76, v75
	v_mul_f32_e32 v80, v79, v78
	v_fma_f32 v81, -v77, v80, v79
	v_fmac_f32_e32 v80, v81, v78
	v_fma_f32 v77, -v77, v80, v79
	v_div_fmas_f32 v77, v77, v78, v80
	v_div_fixup_f32 v75, v77, v76, v75
	v_mul_f32_e32 v48, v48, v75
	v_bfe_u32 v75, v48, 16, 1
	v_add3_u32 v48, v48, v75, s15
	global_store_short_d16_hi v[68:69], v48, off offset:2048


; __device__ __forceinline__ float bf2f(unsigned short b) { return __uint_as_float((unsigned)b << 16); }
; __device__ __forceinline__ unsigned f2bf(float f) { unsigned u = __float_as_uint(f); return (u + 0x7fffu + ((u >> 16) & 1u)) >> 16; }
; __device__ __forceinline__ float bf2f(unsigned short b) { return __uint_as_float((unsigned)b << 16); }
; __device__ __forceinline__ unsigned f2bf(float f) { unsigned u = __float_as_uint(f); return (u + 0x7fffu + ((u >> 16) & 1u)) >> 16; }
;     ...
;         for (int d0 = 0; d0 < 4; ++d0) { const float g = bf2f(Gb[(long)orow * ldg + d0 * 32 + r32]); const float sg = g / (1.f + __expf(-g));
;           Yb[(long)orow * ldy + d0 * 32 + r32] = (bf16)f2bf(o[d0][r] * rli * sg); }
	v_lshlrev_b32_e32 v48, 16, v100
	v_mul_f32_e32 v75, 0xbfb8aa3b, v48
	v_exp_f32_e32 v75, v75
	s_nop 0
	v_add_f32_e32 v75, 1.0, v75
	v_div_scale_f32 v76, s[2:3], v75, v75, v48
	v_rcp_f32_e32 v77, v76
	s_nop 0
	v_fma_f32 v78, -v76, v77, 1.0
	v_fmac_f32_e32 v77, v78, v77
	v_div_scale_f32 v78, vcc, v48, v75, v48
	v_mul_f32_e32 v79, v78, v77
	v_fma_f32 v80, -v76, v79, v78
	v_fmac_f32_e32 v79, v80, v77
	v_fma_f32 v76, -v76, v79, v78
	v_div_fmas_f32 v76, v76, v77, v79
	v_div_fixup_f32 v48, v76, v75, v48
	v_mul_f32_e32 v32, v32, v48
	v_bfe_u32 v48, v32, 16, 1
	v_add3_u32 v32, v32, v48, s15
	global_store_short_d16_hi v[68:69], v32, off offset:2112


; __device__ __forceinline__ float bf2f(unsigned short b) { return __uint_as_float((unsigned)b << 16); }
; __device__ __forceinline__ unsigned f2bf(float f) { unsigned u = __float_as_uint(f); return (u + 0x7fffu + ((u >> 16) & 1u)) >> 16; }
; __device__ __forceinline__ float bf2f(unsigned short b) { return __uint_as_float((unsigned)b << 16); }
; __device__ __forceinline__ unsigned f2bf(float f) { unsigned u = __float_as_uint(f); return (u + 0x7fffu + ((u >> 16) & 1u)) >> 16; }
;     ...
;         for (int d0 = 0; d0 < 4; ++d0) { const float g = bf2f(Gb[(long)orow * ldg + d0 * 32 + r32]); const float sg = g / (1.f + __expf(-g));
;           Yb[(long)orow * ldy + d0 * 32 + r32] = (bf16)f2bf(o[d0][r] * rli * sg); }
	v_lshlrev_b32_e32 v32, 16, v101
	v_mul_f32_e32 v48, 0xbfb8aa3b, v32
	v_exp_f32_e32 v48, v48
	s_nop 0
	v_add_f32_e32 v48, 1.0, v48
	v_div_scale_f32 v75, s[2:3], v48, v48, v32
	v_rcp_f32_e32 v76, v75
	s_nop 0
	v_fma_f32 v77, -v75, v76, 1.0
	v_fmac_f32_e32 v76, v77, v76
	v_div_scale_f32 v77, vcc, v32, v48, v32
	v_mul_f32_e32 v78, v77, v76
	v_fma_f32 v79, -v75, v78, v77
	v_fmac_f32_e32 v78, v79, v76
	v_fma_f32 v75, -v75, v78, v77
	v_div_fmas_f32 v75, v75, v76, v78
	v_div_fixup_f32 v32, v75, v48, v32
	v_mul_f32_e32 v16, v16, v32
	v_bfe_u32 v32, v16, 16, 1
	v_add3_u32 v16, v16, v32, s15
	global_store_short_d16_hi v[68:69], v16, off offset:2176


; __device__ __forceinline__ int crow(int r, int hi) { return (r & 3) + 8 * (r >> 2) + 4 * hi; }
; __device__ __forceinline__ float bf2f(unsigned short b) { return __uint_as_float((unsigned)b << 16); }
; __device__ __forceinline__ unsigned f2bf(float f) { unsigned u = __float_as_uint(f); return (u + 0x7fffu + ((u >> 16) & 1u)) >> 16; }
; __device__ __forceinline__ float bf2f(unsigned short b) { return __uint_as_float((unsigned)b << 16); }
; __device__ __forceinline__ unsigned f2bf(float f) { unsigned u = __float_as_uint(f); return (u + 0x7fffu + ((u >> 16) & 1u)) >> 16; }
;     ...
;   for (int r = 0; r < 16; ++r) { const int orow = wid * QBLK + crow(r, hi); const float rli = __builtin_amdgcn_rcpf(li_l[crow(r, hi)]);
;     if (orow < nvalid) {
;       if constexpr (MODE == 0) {
; #pragma unroll
;         for (int d0 = 0; d0 < 4; ++d0) Of[(long)orow * ldo + d0 * 32 + r32] = o[d0][r] * rli;
;       } else {
; #pragma unroll
;         for (int d0 = 0; d0 < 4; ++d0) { const float g = bf2f(Gb[(long)orow * ldg + d0 * 32 + r32]); const float sg = g / (1.f + __expf(-g));
;           Yb[(long)orow * ldy + d0 * 32 + r32] = (bf16)f2bf(o[d0][r] * rli * sg); }
	v_lshlrev_b32_e32 v16, 16, v102
	v_mul_f32_e32 v32, 0xbfb8aa3b, v16
	v_exp_f32_e32 v32, v32
	s_nop 0
	v_add_f32_e32 v32, 1.0, v32
	v_div_scale_f32 v48, s[2:3], v32, v32, v16
	v_rcp_f32_e32 v70, v48
	s_nop 0
	v_fma_f32 v71, -v48, v70, 1.0
	v_fmac_f32_e32 v70, v71, v70
	v_div_scale_f32 v71, vcc, v16, v32, v16
	v_mul_f32_e32 v75, v71, v70
	v_fma_f32 v76, -v48, v75, v71
	v_fmac_f32_e32 v75, v76, v70
	v_fma_f32 v48, -v48, v75, v71
	v_div_fmas_f32 v48, v48, v70, v75
	v_div_fixup_f32 v16, v48, v32, v16
	v_mul_f32_e32 v0, v0, v16
	v_bfe_u32 v16, v0, 16, 1
	v_add3_u32 v0, v0, v16, s15
	global_store_short_d16_hi v[68:69], v0, off offset:2240
.LBB0_583:
	s_or_b64 exec, exec, s[0:1]
	v_or3_b32 v68, v72, v192, 1
	v_cmp_gt_i32_e32 vcc, s96, v68
	s_and_saveexec_b64 s[0:1], vcc
	s_cbranch_execz .LBB0_585
	v_mad_i64_i32 v[70:71], s[2:3], v68, s20, v[66:67]
	global_load_ushort v16, v[70:71], off
	global_load_ushort v100, v[70:71], off offset:64
	global_load_ushort v101, v[70:71], off offset:128
	global_load_ushort v102, v[70:71], off offset:192
	ds_read_b32 v0, v73 offset:4
	v_ashrrev_i32_e32 v69, 31, v68
	v_lshlrev_b64 v[68:69], 12, v[68:69]
	v_lshl_add_u64 v[68:69], v[64:65], 0, v[68:69]
	s_waitcnt lgkmcnt(0)
	v_rcp_f32_e32 v0, v0
	s_nop 0
	v_mul_f32_e32 v17, v17, v0
	s_waitcnt vmcnt(0)
	v_lshlrev_b32_e32 v16, 16, v16
	v_mul_f32_e32 v32, 0xbfb8aa3b, v16
	v_exp_f32_e32 v32, v32
	s_nop 0
	v_add_f32_e32 v32, 1.0, v32
	v_div_scale_f32 v48, s[2:3], v32, v32, v16
	v_rcp_f32_e32 v74, v48
	s_nop 0
	v_fma_f32 v75, -v48, v74, 1.0
	v_fmac_f32_e32 v74, v75, v74
	v_div_scale_f32 v75, vcc, v16, v32, v16
	v_mul_f32_e32 v76, v75, v74
	v_fma_f32 v77, -v48, v76, v75
	v_fmac_f32_e32 v76, v77, v74
	v_fma_f32 v48, -v48, v76, v75
	v_div_fmas_f32 v48, v48, v74, v76
	v_div_fixup_f32 v16, v48, v32, v16
	v_mul_f32_e32 v32, v49, v0
	v_mul_f32_e32 v16, v32, v16
	v_bfe_u32 v32, v16, 16, 1
	v_add3_u32 v16, v16, v32, s15
	global_store_short_d16_hi v[68:69], v16, off offset:2048


; __device__ __forceinline__ float bf2f(unsigned short b) { return __uint_as_float((unsigned)b << 16); }
; __device__ __forceinline__ unsigned f2bf(float f) { unsigned u = __float_as_uint(f); return (u + 0x7fffu + ((u >> 16) & 1u)) >> 16; }
; __device__ __forceinline__ float bf2f(unsigned short b) { return __uint_as_float((unsigned)b << 16); }
; __device__ __forceinline__ unsigned f2bf(float f) { unsigned u = __float_as_uint(f); return (u + 0x7fffu + ((u >> 16) & 1u)) >> 16; }
;     ...
;         for (int d0 = 0; d0 < 4; ++d0) { const float g = bf2f(Gb[(long)orow * ldg + d0 * 32 + r32]); const float sg = g / (1.f + __expf(-g));
;           Yb[(long)orow * ldy + d0 * 32 + r32] = (bf16)f2bf(o[d0][r] * rli * sg); }
	v_lshlrev_b32_e32 v16, 16, v100
	v_mul_f32_e32 v32, 0xbfb8aa3b, v16
	v_exp_f32_e32 v32, v32
	s_nop 0
	v_add_f32_e32 v32, 1.0, v32
	v_div_scale_f32 v48, s[2:3], v32, v32, v16
	v_rcp_f32_e32 v49, v48
	s_nop 0
	v_fma_f32 v74, -v48, v49, 1.0
	v_fmac_f32_e32 v49, v74, v49
	v_div_scale_f32 v74, vcc, v16, v32, v16
	v_mul_f32_e32 v75, v74, v49
	v_fma_f32 v76, -v48, v75, v74
	v_fmac_f32_e32 v75, v76, v49
	v_fma_f32 v48, -v48, v75, v74
	v_div_fmas_f32 v48, v48, v49, v75
	v_div_fixup_f32 v16, v48, v32, v16
	v_mul_f32_e32 v32, v33, v0
	v_mul_f32_e32 v16, v32, v16
	v_bfe_u32 v32, v16, 16, 1
	v_add3_u32 v16, v16, v32, s15
	global_store_short_d16_hi v[68:69], v16, off offset:2112

; __device__ __forceinline__ float bf2f(unsigned short b) { return __uint_as_float((unsigned)b << 16); }
; __device__ __forceinline__ unsigned f2bf(float f) { unsigned u = __float_as_uint(f); return (u + 0x7fffu + ((u >> 16) & 1u)) >> 16; }
; __device__ __forceinline__ float bf2f(unsigned short b) { return __uint_as_float((unsigned)b << 16); }
; __device__ __forceinline__ unsigned f2bf(float f) { unsigned u = __float_as_uint(f); return (u + 0x7fffu + ((u >> 16) & 1u)) >> 16; }
;     ...
;         for (int d0 = 0; d0 < 4; ++d0) { const float g = bf2f(Gb[(long)orow * ldg + d0 * 32 + r32]); const float sg = g / (1.f + __expf(-g));
;           Yb[(long)orow * ldy + d0 * 32 + r32] = (bf16)f2bf(o[d0][r] * rli * sg); }
	v_mul_f32_e32 v0, v1, v0

; __device__ __forceinline__ float bf2f(unsigned short b) { return __uint_as_float((unsigned)b << 16); }
; __device__ __forceinline__ unsigned f2bf(float f) { unsigned u = __float_as_uint(f); return (u + 0x7fffu + ((u >> 16) & 1u)) >> 16; }
; __device__ __forceinline__ float bf2f(unsigned short b) { return __uint_as_float((unsigned)b << 16); }
; __device__ __forceinline__ unsigned f2bf(float f) { unsigned u = __float_as_uint(f); return (u + 0x7fffu + ((u >> 16) & 1u)) >> 16; }
;     ...
;         for (int d0 = 0; d0 < 4; ++d0) { const float g = bf2f(Gb[(long)orow * ldg + d0 * 32 + r32]); const float sg = g / (1.f + __expf(-g));
;           Yb[(long)orow * ldy + d0 * 32 + r32] = (bf16)f2bf(o[d0][r] * rli * sg); }
	v_lshlrev_b32_e32 v16, 16, v101
	v_mul_f32_e32 v32, 0xbfb8aa3b, v16
	v_exp_f32_e32 v32, v32
	s_nop 0
	v_add_f32_e32 v32, 1.0, v32
	v_div_scale_f32 v33, s[2:3], v32, v32, v16
	v_rcp_f32_e32 v48, v33
	s_nop 0
	v_fma_f32 v49, -v33, v48, 1.0
	v_fmac_f32_e32 v48, v49, v48
	v_div_scale_f32 v49, vcc, v16, v32, v16
	v_mul_f32_e32 v74, v49, v48
	v_fma_f32 v75, -v33, v74, v49
	v_fmac_f32_e32 v74, v75, v48
	v_fma_f32 v33, -v33, v74, v49
	v_div_fmas_f32 v33, v33, v48, v74
	v_div_fixup_f32 v16, v33, v32, v16
	v_mul_f32_e32 v16, v17, v16
	v_bfe_u32 v17, v16, 16, 1
	v_add3_u32 v16, v16, v17, s15
	global_store_short_d16_hi v[68:69], v16, off offset:2176


; __device__ __forceinline__ int crow(int r, int hi) { return (r & 3) + 8 * (r >> 2) + 4 * hi; }
; __device__ __forceinline__ float bf2f(unsigned short b) { return __uint_as_float((unsigned)b << 16); }
; __device__ __forceinline__ unsigned f2bf(float f) { unsigned u = __float_as_uint(f); return (u + 0x7fffu + ((u >> 16) & 1u)) >> 16; }
; __device__ __forceinline__ float bf2f(unsigned short b) { return __uint_as_float((unsigned)b << 16); }
; __device__ __forceinline__ unsigned f2bf(float f) { unsigned u = __float_as_uint(f); return (u + 0x7fffu + ((u >> 16) & 1u)) >> 16; }
;     ...
;   for (int r = 0; r < 16; ++r) { const int orow = wid * QBLK + crow(r, hi); const float rli = __builtin_amdgcn_rcpf(li_l[crow(r, hi)]);
;     if (orow < nvalid) {
;       if constexpr (MODE == 0) {
; #pragma unroll
;         for (int d0 = 0; d0 < 4; ++d0) Of[(long)orow * ldo + d0 * 32 + r32] = o[d0][r] * rli;
;       } else {
; #pragma unroll
;         for (int d0 = 0; d0 < 4; ++d0) { const float g = bf2f(Gb[(long)orow * ldg + d0 * 32 + r32]); const float sg = g / (1.f + __expf(-g));
;           Yb[(long)orow * ldy + d0 * 32 + r32] = (bf16)f2bf(o[d0][r] * rli * sg); }
	v_lshlrev_b32_e32 v16, 16, v102
	v_mul_f32_e32 v17, 0xbfb8aa3b, v16
	v_exp_f32_e32 v17, v17
	s_nop 0
	v_add_f32_e32 v17, 1.0, v17
	v_div_scale_f32 v32, s[2:3], v17, v17, v16
	v_rcp_f32_e32 v33, v32
	s_nop 0
	v_fma_f32 v48, -v32, v33, 1.0
	v_fmac_f32_e32 v33, v48, v33
	v_div_scale_f32 v48, vcc, v16, v17, v16
	v_mul_f32_e32 v49, v48, v33
	v_fma_f32 v70, -v32, v49, v48
	v_fmac_f32_e32 v49, v70, v33
	v_fma_f32 v32, -v32, v49, v48
	v_div_fmas_f32 v32, v32, v33, v49
	v_div_fixup_f32 v16, v32, v17, v16
	v_mul_f32_e32 v0, v0, v16
	v_bfe_u32 v1, v0, 16, 1
	v_add3_u32 v0, v0, v1, s15
	global_store_short_d16_hi v[68:69], v0, off offset:2240
.LBB0_585:
	s_or_b64 exec, exec, s[0:1]
	v_or3_b32 v0, v72, v192, 2
	v_cmp_gt_i32_e32 vcc, s96, v0
	s_and_saveexec_b64 s[0:1], vcc
	s_cbranch_execz .LBB0_587
	v_mad_i64_i32 v[16:17], s[2:3], v0, s20, v[66:67]
	global_load_ushort v33, v[16:17], off
	global_load_ushort v100, v[16:17], off offset:64
	global_load_ushort v101, v[16:17], off offset:128
	global_load_ushort v102, v[16:17], off offset:192
	ds_read_b32 v1, v73 offset:8
	s_waitcnt lgkmcnt(0)
	v_rcp_f32_e32 v32, v1
	v_ashrrev_i32_e32 v1, 31, v0
	v_lshlrev_b64 v[0:1], 12, v[0:1]
	v_lshl_add_u64 v[0:1], v[64:65], 0, v[0:1]
	v_mul_f32_e32 v34, v34, v32
	v_mul_f32_e32 v18, v18, v32
	v_mul_f32_e32 v2, v2, v32
	s_waitcnt vmcnt(0)
	v_lshlrev_b32_e32 v33, 16, v33
	v_mul_f32_e32 v48, 0xbfb8aa3b, v33
	v_exp_f32_e32 v48, v48
	s_nop 0
	v_add_f32_e32 v48, 1.0, v48
	v_div_scale_f32 v49, s[2:3], v48, v48, v33
	v_rcp_f32_e32 v68, v49
	s_nop 0
	v_fma_f32 v69, -v49, v68, 1.0
	v_fmac_f32_e32 v68, v69, v68
	v_div_scale_f32 v69, vcc, v33, v48, v33
	v_mul_f32_e32 v70, v69, v68
	v_fma_f32 v71, -v49, v70, v69
	v_fmac_f32_e32 v70, v71, v68
	v_fma_f32 v49, -v49, v70, v69
	v_div_fmas_f32 v49, v49, v68, v70
	v_div_fixup_f32 v33, v49, v48, v33
	v_mul_f32_e32 v48, v50, v32
	v_mul_f32_e32 v33, v48, v33
	v_bfe_u32 v48, v33, 16, 1
	v_add3_u32 v33, v33, v48, s15
	global_store_short_d16_hi v[0:1], v33, off offset:2048


; __device__ __forceinline__ float bf2f(unsigned short b) { return __uint_as_float((unsigned)b << 16); }
; __device__ __forceinline__ unsigned f2bf(float f) { unsigned u = __float_as_uint(f); return (u + 0x7fffu + ((u >> 16) & 1u)) >> 16; }
; __device__ __forceinline__ float bf2f(unsigned short b) { return __uint_as_float((unsigned)b << 16); }
; __device__ __forceinline__ unsigned f2bf(float f) { unsigned u = __float_as_uint(f); return (u + 0x7fffu + ((u >> 16) & 1u)) >> 16; }
;     ...
;         for (int d0 = 0; d0 < 4; ++d0) { const float g = bf2f(Gb[(long)orow * ldg + d0 * 32 + r32]); const float sg = g / (1.f + __expf(-g));
;           Yb[(long)orow * ldy + d0 * 32 + r32] = (bf16)f2bf(o[d0][r] * rli * sg); }
	v_lshlrev_b32_e32 v33, 16, v100
	v_mul_f32_e32 v48, 0xbfb8aa3b, v33
	v_exp_f32_e32 v48, v48
	s_nop 0
	v_add_f32_e32 v48, 1.0, v48
	v_div_scale_f32 v49, s[2:3], v48, v48, v33
	v_rcp_f32_e32 v50, v49
	s_nop 0
	v_fma_f32 v68, -v49, v50, 1.0
	v_fmac_f32_e32 v50, v68, v50
	v_div_scale_f32 v68, vcc, v33, v48, v33
	v_mul_f32_e32 v69, v68, v50
	v_fma_f32 v70, -v49, v69, v68
	v_fmac_f32_e32 v69, v70, v50
	v_fma_f32 v49, -v49, v69, v68
	v_div_fmas_f32 v49, v49, v50, v69
	v_div_fixup_f32 v33, v49, v48, v33
	v_mul_f32_e32 v33, v34, v33
	v_bfe_u32 v34, v33, 16, 1
	v_add3_u32 v33, v33, v34, s15
	global_store_short_d16_hi v[0:1], v33, off offset:2112


; __device__ __forceinline__ float bf2f(unsigned short b) { return __uint_as_float((unsigned)b << 16); }
; __device__ __forceinline__ float bf2f(unsigned short b) { return __uint_as_float((unsigned)b << 16); }
;     ...
;         for (int d0 = 0; d0 < 4; ++d0) { const float g = bf2f(Gb[(long)orow * ldg + d0 * 32 + r32]); const float sg = g / (1.f + __expf(-g));
	v_lshlrev_b32_e32 v33, 16, v101

; __device__ __forceinline__ float bf2f(unsigned short b) { return __uint_as_float((unsigned)b << 16); }
; __device__ __forceinline__ float bf2f(unsigned short b) { return __uint_as_float((unsigned)b << 16); }
;     ...
;         for (int d0 = 0; d0 < 4; ++d0) { const float g = bf2f(Gb[(long)orow * ldg + d0 * 32 + r32]); const float sg = g / (1.f + __expf(-g));
	v_mul_f32_e32 v34, 0xbfb8aa3b, v33
	v_exp_f32_e32 v34, v34

; __device__ __forceinline__ int crow(int r, int hi) { return (r & 3) + 8 * (r >> 2) + 4 * hi; }
; __device__ __forceinline__ float bf2f(unsigned short b) { return __uint_as_float((unsigned)b << 16); }
; __device__ __forceinline__ unsigned f2bf(float f) { unsigned u = __float_as_uint(f); return (u + 0x7fffu + ((u >> 16) & 1u)) >> 16; }
; __device__ __forceinline__ float bf2f(unsigned short b) { return __uint_as_float((unsigned)b << 16); }
; __device__ __forceinline__ unsigned f2bf(float f) { unsigned u = __float_as_uint(f); return (u + 0x7fffu + ((u >> 16) & 1u)) >> 16; }
;     ...
;   for (int r = 0; r < 16; ++r) { const int orow = wid * QBLK + crow(r, hi); const float rli = __builtin_amdgcn_rcpf(li_l[crow(r, hi)]);
;     if (orow < nvalid) {
;       if constexpr (MODE == 0) {
; #pragma unroll
;         for (int d0 = 0; d0 < 4; ++d0) Of[(long)orow * ldo + d0 * 32 + r32] = o[d0][r] * rli;
;       } else {
; #pragma unroll
;         for (int d0 = 0; d0 < 4; ++d0) { const float g = bf2f(Gb[(long)orow * ldg + d0 * 32 + r32]); const float sg = g / (1.f + __expf(-g));
;           Yb[(long)orow * ldy + d0 * 32 + r32] = (bf16)f2bf(o[d0][r] * rli * sg); }
	v_lshlrev_b32_e32 v16, 16, v102
	v_add_f32_e32 v34, 1.0, v34
	v_div_scale_f32 v48, s[2:3], v34, v34, v33
	v_rcp_f32_e32 v49, v48
	v_mul_f32_e32 v17, 0xbfb8aa3b, v16
	v_exp_f32_e32 v17, v17
	v_fma_f32 v50, -v48, v49, 1.0
	v_fmac_f32_e32 v49, v50, v49
	v_div_scale_f32 v50, vcc, v33, v34, v33
	v_mul_f32_e32 v68, v50, v49
	v_fma_f32 v69, -v48, v68, v50
	v_fmac_f32_e32 v68, v69, v49
	v_fma_f32 v48, -v48, v68, v50
	v_div_fmas_f32 v48, v48, v49, v68
	v_div_fixup_f32 v33, v48, v34, v33
	v_mul_f32_e32 v18, v18, v33
	v_bfe_u32 v33, v18, 16, 1
	v_add3_u32 v18, v18, v33, s15
	v_add_f32_e32 v17, 1.0, v17
	global_store_short_d16_hi v[0:1], v18, off offset:2176
	v_div_scale_f32 v18, s[2:3], v17, v17, v16
	v_rcp_f32_e32 v33, v18
	s_nop 0
	v_fma_f32 v34, -v18, v33, 1.0
	v_fmac_f32_e32 v33, v34, v33
	v_div_scale_f32 v34, vcc, v16, v17, v16
	v_mul_f32_e32 v48, v34, v33
	v_fma_f32 v49, -v18, v48, v34
	v_fmac_f32_e32 v48, v49, v33
	v_fma_f32 v18, -v18, v48, v34
	v_div_fmas_f32 v18, v18, v33, v48
	v_div_fixup_f32 v16, v18, v17, v16
	v_mul_f32_e32 v2, v2, v16
	v_bfe_u32 v16, v2, 16, 1
	v_add3_u32 v2, v2, v16, s15
	global_store_short_d16_hi v[0:1], v2, off offset:2240
.LBB0_587:
	s_or_b64 exec, exec, s[0:1]
	v_or3_b32 v0, v72, v192, 3
	v_cmp_gt_i32_e32 vcc, s96, v0
	s_and_saveexec_b64 s[0:1], vcc
	s_cbranch_execz .LBB0_589
	v_mad_i64_i32 v[16:17], s[2:3], v0, s20, v[66:67]
	global_load_ushort v18, v[16:17], off
	global_load_ushort v100, v[16:17], off offset:64
	global_load_ushort v101, v[16:17], off offset:128
	global_load_ushort v102, v[16:17], off offset:192
	ds_read_b32 v1, v73 offset:12
	s_waitcnt lgkmcnt(0)
	v_rcp_f32_e32 v2, v1
	v_ashrrev_i32_e32 v1, 31, v0
	v_lshlrev_b64 v[0:1], 12, v[0:1]
	v_lshl_add_u64 v[0:1], v[64:65], 0, v[0:1]
	v_mul_f32_e32 v19, v19, v2
	s_waitcnt vmcnt(0)
	v_lshlrev_b32_e32 v18, 16, v18
	v_mul_f32_e32 v32, 0xbfb8aa3b, v18
	v_exp_f32_e32 v32, v32
	s_nop 0
	v_add_f32_e32 v32, 1.0, v32
	v_div_scale_f32 v33, s[2:3], v32, v32, v18
	v_rcp_f32_e32 v34, v33
	s_nop 0
	v_fma_f32 v48, -v33, v34, 1.0
	v_fmac_f32_e32 v34, v48, v34
	v_div_scale_f32 v48, vcc, v18, v32, v18
	v_mul_f32_e32 v49, v48, v34
	v_fma_f32 v50, -v33, v49, v48
	v_fmac_f32_e32 v49, v50, v34
	v_fma_f32 v33, -v33, v49, v48
	v_div_fmas_f32 v33, v33, v34, v49
	v_div_fixup_f32 v18, v33, v32, v18
	v_mul_f32_e32 v32, v51, v2
	v_mul_f32_e32 v18, v32, v18
	v_bfe_u32 v32, v18, 16, 1
	v_add3_u32 v18, v18, v32, s15
	global_store_short_d16_hi v[0:1], v18, off offset:2048


; __device__ __forceinline__ float bf2f(unsigned short b) { return __uint_as_float((unsigned)b << 16); }
; __device__ __forceinline__ unsigned f2bf(float f) { unsigned u = __float_as_uint(f); return (u + 0x7fffu + ((u >> 16) & 1u)) >> 16; }
; __device__ __forceinline__ float bf2f(unsigned short b) { return __uint_as_float((unsigned)b << 16); }
; __device__ __forceinline__ unsigned f2bf(float f) { unsigned u = __float_as_uint(f); return (u + 0x7fffu + ((u >> 16) & 1u)) >> 16; }
;     ...
;         for (int d0 = 0; d0 < 4; ++d0) { const float g = bf2f(Gb[(long)orow * ldg + d0 * 32 + r32]); const float sg = g / (1.f + __expf(-g));
;           Yb[(long)orow * ldy + d0 * 32 + r32] = (bf16)f2bf(o[d0][r] * rli * sg); }
	v_lshlrev_b32_e32 v18, 16, v100
	v_mul_f32_e32 v32, 0xbfb8aa3b, v18
	v_exp_f32_e32 v32, v32
	s_nop 0
	v_add_f32_e32 v32, 1.0, v32
	v_div_scale_f32 v33, s[2:3], v32, v32, v18
	v_rcp_f32_e32 v34, v33
	s_nop 0
	v_fma_f32 v48, -v33, v34, 1.0
	v_fmac_f32_e32 v34, v48, v34
	v_div_scale_f32 v48, vcc, v18, v32, v18
	v_mul_f32_e32 v49, v48, v34
	v_fma_f32 v50, -v33, v49, v48
	v_fmac_f32_e32 v49, v50, v34
	v_fma_f32 v33, -v33, v49, v48
	v_div_fmas_f32 v33, v33, v34, v49
	v_div_fixup_f32 v18, v33, v32, v18
	v_mul_f32_e32 v32, v35, v2
	v_mul_f32_e32 v18, v32, v18
	v_bfe_u32 v32, v18, 16, 1
	v_add3_u32 v18, v18, v32, s15
	global_store_short_d16_hi v[0:1], v18, off offset:2112

; __device__ __forceinline__ float bf2f(unsigned short b) { return __uint_as_float((unsigned)b << 16); }
; __device__ __forceinline__ unsigned f2bf(float f) { unsigned u = __float_as_uint(f); return (u + 0x7fffu + ((u >> 16) & 1u)) >> 16; }
; __device__ __forceinline__ float bf2f(unsigned short b) { return __uint_as_float((unsigned)b << 16); }
; __device__ __forceinline__ unsigned f2bf(float f) { unsigned u = __float_as_uint(f); return (u + 0x7fffu + ((u >> 16) & 1u)) >> 16; }
;     ...
;         for (int d0 = 0; d0 < 4; ++d0) { const float g = bf2f(Gb[(long)orow * ldg + d0 * 32 + r32]); const float sg = g / (1.f + __expf(-g));
;           Yb[(long)orow * ldy + d0 * 32 + r32] = (bf16)f2bf(o[d0][r] * rli * sg); }
	v_mul_f32_e32 v2, v3, v2


; __device__ __forceinline__ float bf2f(unsigned short b) { return __uint_as_float((unsigned)b << 16); }
; __device__ __forceinline__ float bf2f(unsigned short b) { return __uint_as_float((unsigned)b << 16); }
;     ...
;         for (int d0 = 0; d0 < 4; ++d0) { const float g = bf2f(Gb[(long)orow * ldg + d0 * 32 + r32]); const float sg = g / (1.f + __expf(-g));
	v_lshlrev_b32_e32 v18, 16, v101
	v_mul_f32_e32 v32, 0xbfb8aa3b, v18
	v_exp_f32_e32 v32, v32

; __device__ __forceinline__ int crow(int r, int hi) { return (r & 3) + 8 * (r >> 2) + 4 * hi; }
; __device__ __forceinline__ float bf2f(unsigned short b) { return __uint_as_float((unsigned)b << 16); }
; __device__ __forceinline__ unsigned f2bf(float f) { unsigned u = __float_as_uint(f); return (u + 0x7fffu + ((u >> 16) & 1u)) >> 16; }
; __device__ __forceinline__ float bf2f(unsigned short b) { return __uint_as_float((unsigned)b << 16); }
; __device__ __forceinline__ unsigned f2bf(float f) { unsigned u = __float_as_uint(f); return (u + 0x7fffu + ((u >> 16) & 1u)) >> 16; }
;     ...
;   for (int r = 0; r < 16; ++r) { const int orow = wid * QBLK + crow(r, hi); const float rli = __builtin_amdgcn_rcpf(li_l[crow(r, hi)]);
;     if (orow < nvalid) {
;       if constexpr (MODE == 0) {
; #pragma unroll
;         for (int d0 = 0; d0 < 4; ++d0) Of[(long)orow * ldo + d0 * 32 + r32] = o[d0][r] * rli;
;       } else {
; #pragma unroll
;         for (int d0 = 0; d0 < 4; ++d0) { const float g = bf2f(Gb[(long)orow * ldg + d0 * 32 + r32]); const float sg = g / (1.f + __expf(-g));
;           Yb[(long)orow * ldy + d0 * 32 + r32] = (bf16)f2bf(o[d0][r] * rli * sg); }
	v_lshlrev_b32_e32 v16, 16, v102
	v_mul_f32_e32 v17, 0xbfb8aa3b, v16
	v_exp_f32_e32 v17, v17
	v_add_f32_e32 v32, 1.0, v32
	v_div_scale_f32 v33, s[2:3], v32, v32, v18
	v_rcp_f32_e32 v34, v33
	v_add_f32_e32 v17, 1.0, v17
	v_fma_f32 v35, -v33, v34, 1.0
	v_fmac_f32_e32 v34, v35, v34
	v_div_scale_f32 v35, vcc, v18, v32, v18
	v_mul_f32_e32 v48, v35, v34
	v_fma_f32 v49, -v33, v48, v35
	v_fmac_f32_e32 v48, v49, v34
	v_fma_f32 v33, -v33, v48, v35
	v_div_fmas_f32 v33, v33, v34, v48
	v_div_fixup_f32 v18, v33, v32, v18
	v_mul_f32_e32 v18, v19, v18
	v_bfe_u32 v19, v18, 16, 1
	v_add3_u32 v18, v18, v19, s15
	global_store_short_d16_hi v[0:1], v18, off offset:2176
	v_div_scale_f32 v18, s[2:3], v17, v17, v16
	v_rcp_f32_e32 v19, v18
	s_nop 0
	v_fma_f32 v32, -v18, v19, 1.0
	v_fmac_f32_e32 v19, v32, v19
	v_div_scale_f32 v32, vcc, v16, v17, v16
	v_mul_f32_e32 v33, v32, v19
	v_fma_f32 v34, -v18, v33, v32
	v_fmac_f32_e32 v33, v34, v19
	v_fma_f32 v18, -v18, v33, v32
	v_div_fmas_f32 v18, v18, v19, v33
	v_div_fixup_f32 v16, v18, v17, v16
	v_mul_f32_e32 v2, v2, v16
	v_bfe_u32 v3, v2, 16, 1
	v_add3_u32 v2, v2, v3, s15
	global_store_short_d16_hi v[0:1], v2, off offset:2240
.LBB0_589:
	s_or_b64 exec, exec, s[0:1]
	v_or3_b32 v0, v72, v192, 8
	v_cmp_gt_i32_e32 vcc, s96, v0
	s_and_saveexec_b64 s[0:1], vcc
	s_cbranch_execz .LBB0_591
	v_mad_i64_i32 v[2:3], s[2:3], v0, s20, v[66:67]
	global_load_ushort v17, v[2:3], off
	global_load_ushort v100, v[2:3], off offset:64
	global_load_ushort v101, v[2:3], off offset:128
	global_load_ushort v102, v[2:3], off offset:192
	ds_read_b32 v1, v73 offset:32
	s_waitcnt lgkmcnt(0)
	v_rcp_f32_e32 v16, v1
	v_ashrrev_i32_e32 v1, 31, v0
	v_lshlrev_b64 v[0:1], 12, v[0:1]
	v_lshl_add_u64 v[0:1], v[64:65], 0, v[0:1]
	s_waitcnt vmcnt(0)
	v_lshlrev_b32_e32 v17, 16, v17
	v_mul_f32_e32 v18, 0xbfb8aa3b, v17
	v_exp_f32_e32 v18, v18
	s_nop 0
	v_add_f32_e32 v18, 1.0, v18
	v_div_scale_f32 v19, s[2:3], v18, v18, v17
	v_rcp_f32_e32 v32, v19
	s_nop 0
	v_fma_f32 v33, -v19, v32, 1.0
	v_fmac_f32_e32 v32, v33, v32
	v_div_scale_f32 v33, vcc, v17, v18, v17
	v_mul_f32_e32 v34, v33, v32
	v_fma_f32 v35, -v19, v34, v33
	v_fmac_f32_e32 v34, v35, v32
	v_fma_f32 v19, -v19, v34, v33
	v_div_fmas_f32 v19, v19, v32, v34
	v_div_fixup_f32 v17, v19, v18, v17
	v_mul_f32_e32 v18, v52, v16
	v_mul_f32_e32 v17, v18, v17
	v_bfe_u32 v18, v17, 16, 1
	v_add3_u32 v17, v17, v18, s15
	global_store_short_d16_hi v[0:1], v17, off offset:2048


; __device__ __forceinline__ float bf2f(unsigned short b) { return __uint_as_float((unsigned)b << 16); }
; __device__ __forceinline__ unsigned f2bf(float f) { unsigned u = __float_as_uint(f); return (u + 0x7fffu + ((u >> 16) & 1u)) >> 16; }
; __device__ __forceinline__ float bf2f(unsigned short b) { return __uint_as_float((unsigned)b << 16); }
; __device__ __forceinline__ unsigned f2bf(float f) { unsigned u = __float_as_uint(f); return (u + 0x7fffu + ((u >> 16) & 1u)) >> 16; }
;     ...
;         for (int d0 = 0; d0 < 4; ++d0) { const float g = bf2f(Gb[(long)orow * ldg + d0 * 32 + r32]); const float sg = g / (1.f + __expf(-g));
;           Yb[(long)orow * ldy + d0 * 32 + r32] = (bf16)f2bf(o[d0][r] * rli * sg); }
	v_lshlrev_b32_e32 v17, 16, v100
	v_mul_f32_e32 v18, 0xbfb8aa3b, v17
	v_exp_f32_e32 v18, v18
	s_nop 0
	v_add_f32_e32 v18, 1.0, v18
	v_div_scale_f32 v19, s[2:3], v18, v18, v17
	v_rcp_f32_e32 v32, v19
	s_nop 0
	v_fma_f32 v33, -v19, v32, 1.0
	v_fmac_f32_e32 v32, v33, v32
	v_div_scale_f32 v33, vcc, v17, v18, v17
	v_mul_f32_e32 v34, v33, v32
	v_fma_f32 v35, -v19, v34, v33
	v_fmac_f32_e32 v34, v35, v32
	v_fma_f32 v19, -v19, v34, v33
	v_div_fmas_f32 v19, v19, v32, v34
	v_div_fixup_f32 v17, v19, v18, v17
	v_mul_f32_e32 v18, v36, v16
	v_mul_f32_e32 v17, v18, v17
	v_bfe_u32 v18, v17, 16, 1
	v_add3_u32 v17, v17, v18, s15
	global_store_short_d16_hi v[0:1], v17, off offset:2112


; __device__ __forceinline__ float bf2f(unsigned short b) { return __uint_as_float((unsigned)b << 16); }
; __device__ __forceinline__ float bf2f(unsigned short b) { return __uint_as_float((unsigned)b << 16); }
;     ...
;         for (int d0 = 0; d0 < 4; ++d0) { const float g = bf2f(Gb[(long)orow * ldg + d0 * 32 + r32]); const float sg = g / (1.f + __expf(-g));
	v_lshlrev_b32_e32 v17, 16, v101

; __device__ __forceinline__ float bf2f(unsigned short b) { return __uint_as_float((unsigned)b << 16); }
; __device__ __forceinline__ float bf2f(unsigned short b) { return __uint_as_float((unsigned)b << 16); }
;     ...
;         for (int d0 = 0; d0 < 4; ++d0) { const float g = bf2f(Gb[(long)orow * ldg + d0 * 32 + r32]); const float sg = g / (1.f + __expf(-g));
	v_mul_f32_e32 v18, 0xbfb8aa3b, v17
	v_exp_f32_e32 v18, v18

; __device__ __forceinline__ int crow(int r, int hi) { return (r & 3) + 8 * (r >> 2) + 4 * hi; }
; __device__ __forceinline__ float bf2f(unsigned short b) { return __uint_as_float((unsigned)b << 16); }
; __device__ __forceinline__ unsigned f2bf(float f) { unsigned u = __float_as_uint(f); return (u + 0x7fffu + ((u >> 16) & 1u)) >> 16; }
; __device__ __forceinline__ float bf2f(unsigned short b) { return __uint_as_float((unsigned)b << 16); }
; __device__ __forceinline__ unsigned f2bf(float f) { unsigned u = __float_as_uint(f); return (u + 0x7fffu + ((u >> 16) & 1u)) >> 16; }
;     ...
;   for (int r = 0; r < 16; ++r) { const int orow = wid * QBLK + crow(r, hi); const float rli = __builtin_amdgcn_rcpf(li_l[crow(r, hi)]);
;     if (orow < nvalid) {
;       if constexpr (MODE == 0) {
; #pragma unroll
;         for (int d0 = 0; d0 < 4; ++d0) Of[(long)orow * ldo + d0 * 32 + r32] = o[d0][r] * rli;
;       } else {
; #pragma unroll
;         for (int d0 = 0; d0 < 4; ++d0) { const float g = bf2f(Gb[(long)orow * ldg + d0 * 32 + r32]); const float sg = g / (1.f + __expf(-g));
;           Yb[(long)orow * ldy + d0 * 32 + r32] = (bf16)f2bf(o[d0][r] * rli * sg); }
	v_lshlrev_b32_e32 v2, 16, v102
	v_add_f32_e32 v18, 1.0, v18
	v_div_scale_f32 v19, s[2:3], v18, v18, v17
	v_rcp_f32_e32 v32, v19
	v_mul_f32_e32 v3, 0xbfb8aa3b, v2
	v_exp_f32_e32 v3, v3
	v_fma_f32 v33, -v19, v32, 1.0
	v_fmac_f32_e32 v32, v33, v32
	v_div_scale_f32 v33, vcc, v17, v18, v17
	v_mul_f32_e32 v34, v33, v32
	v_fma_f32 v35, -v19, v34, v33
	v_fmac_f32_e32 v34, v35, v32
	v_fma_f32 v19, -v19, v34, v33
	v_div_fmas_f32 v19, v19, v32, v34
	v_div_fixup_f32 v17, v19, v18, v17
	v_mul_f32_e32 v18, v20, v16
	v_mul_f32_e32 v17, v18, v17
	v_bfe_u32 v18, v17, 16, 1
	v_add3_u32 v17, v17, v18, s15
	v_add_f32_e32 v3, 1.0, v3
	global_store_short_d16_hi v[0:1], v17, off offset:2176
	v_div_scale_f32 v17, s[2:3], v3, v3, v2
	v_rcp_f32_e32 v18, v17
	s_nop 0
	v_fma_f32 v19, -v17, v18, 1.0
	v_fmac_f32_e32 v18, v19, v18
	v_div_scale_f32 v19, vcc, v2, v3, v2
	v_mul_f32_e32 v20, v19, v18
	v_fma_f32 v32, -v17, v20, v19
	v_fmac_f32_e32 v20, v32, v18
	v_fma_f32 v17, -v17, v20, v19
	v_div_fmas_f32 v17, v17, v18, v20
	v_div_fixup_f32 v2, v17, v3, v2
	v_mul_f32_e32 v3, v4, v16
	v_mul_f32_e32 v2, v3, v2
	v_bfe_u32 v3, v2, 16, 1
	v_add3_u32 v2, v2, v3, s15
	global_store_short_d16_hi v[0:1], v2, off offset:2240
.LBB0_591:
	s_or_b64 exec, exec, s[0:1]
	v_or3_b32 v0, v72, v192, 9
	v_cmp_gt_i32_e32 vcc, s96, v0
	s_and_saveexec_b64 s[0:1], vcc
	s_cbranch_execz .LBB0_593
	v_mad_i64_i32 v[2:3], s[2:3], v0, s20, v[66:67]
	global_load_ushort v16, v[2:3], off
	global_load_ushort v100, v[2:3], off offset:64
	global_load_ushort v101, v[2:3], off offset:128
	global_load_ushort v102, v[2:3], off offset:192
	ds_read_b32 v1, v73 offset:36
	s_waitcnt lgkmcnt(0)
	v_rcp_f32_e32 v4, v1
	v_ashrrev_i32_e32 v1, 31, v0
	v_lshlrev_b64 v[0:1], 12, v[0:1]
	v_lshl_add_u64 v[0:1], v[64:65], 0, v[0:1]
	s_waitcnt vmcnt(0)
	v_lshlrev_b32_e32 v16, 16, v16
	v_mul_f32_e32 v17, 0xbfb8aa3b, v16
	v_exp_f32_e32 v17, v17
	s_nop 0
	v_add_f32_e32 v17, 1.0, v17
	v_div_scale_f32 v18, s[2:3], v17, v17, v16
	v_rcp_f32_e32 v19, v18
	s_nop 0
	v_fma_f32 v20, -v18, v19, 1.0
	v_fmac_f32_e32 v19, v20, v19
	v_div_scale_f32 v20, vcc, v16, v17, v16
	v_mul_f32_e32 v32, v20, v19
	v_fma_f32 v33, -v18, v32, v20
	v_fmac_f32_e32 v32, v33, v19
	v_fma_f32 v18, -v18, v32, v20
	v_div_fmas_f32 v18, v18, v19, v32
	v_div_fixup_f32 v16, v18, v17, v16
	v_mul_f32_e32 v17, v53, v4
	v_mul_f32_e32 v16, v17, v16
	v_bfe_u32 v17, v16, 16, 1
	v_add3_u32 v16, v16, v17, s15
	global_store_short_d16_hi v[0:1], v16, off offset:2048


; __device__ __forceinline__ float bf2f(unsigned short b) { return __uint_as_float((unsigned)b << 16); }
; __device__ __forceinline__ unsigned f2bf(float f) { unsigned u = __float_as_uint(f); return (u + 0x7fffu + ((u >> 16) & 1u)) >> 16; }
; __device__ __forceinline__ float bf2f(unsigned short b) { return __uint_as_float((unsigned)b << 16); }
; __device__ __forceinline__ unsigned f2bf(float f) { unsigned u = __float_as_uint(f); return (u + 0x7fffu + ((u >> 16) & 1u)) >> 16; }
;     ...
;         for (int d0 = 0; d0 < 4; ++d0) { const float g = bf2f(Gb[(long)orow * ldg + d0 * 32 + r32]); const float sg = g / (1.f + __expf(-g));
;           Yb[(long)orow * ldy + d0 * 32 + r32] = (bf16)f2bf(o[d0][r] * rli * sg); }
	v_lshlrev_b32_e32 v16, 16, v100
	v_mul_f32_e32 v17, 0xbfb8aa3b, v16
	v_exp_f32_e32 v17, v17
	s_nop 0
	v_add_f32_e32 v17, 1.0, v17
	v_div_scale_f32 v18, s[2:3], v17, v17, v16
	v_rcp_f32_e32 v19, v18
	s_nop 0
	v_fma_f32 v20, -v18, v19, 1.0
	v_fmac_f32_e32 v19, v20, v19
	v_div_scale_f32 v20, vcc, v16, v17, v16
	v_mul_f32_e32 v32, v20, v19
	v_fma_f32 v33, -v18, v32, v20
	v_fmac_f32_e32 v32, v33, v19
	v_fma_f32 v18, -v18, v32, v20
	v_div_fmas_f32 v18, v18, v19, v32
	v_div_fixup_f32 v16, v18, v17, v16
	v_mul_f32_e32 v17, v37, v4
	v_mul_f32_e32 v16, v17, v16
	v_bfe_u32 v17, v16, 16, 1
	v_add3_u32 v16, v16, v17, s15
	global_store_short_d16_hi v[0:1], v16, off offset:2112


; __device__ __forceinline__ float bf2f(unsigned short b) { return __uint_as_float((unsigned)b << 16); }
; __device__ __forceinline__ float bf2f(unsigned short b) { return __uint_as_float((unsigned)b << 16); }
;     ...
;         for (int d0 = 0; d0 < 4; ++d0) { const float g = bf2f(Gb[(long)orow * ldg + d0 * 32 + r32]); const float sg = g / (1.f + __expf(-g));
	v_lshlrev_b32_e32 v16, 16, v101

; __device__ __forceinline__ float bf2f(unsigned short b) { return __uint_as_float((unsigned)b << 16); }
; __device__ __forceinline__ float bf2f(unsigned short b) { return __uint_as_float((unsigned)b << 16); }
;     ...
;         for (int d0 = 0; d0 < 4; ++d0) { const float g = bf2f(Gb[(long)orow * ldg + d0 * 32 + r32]); const float sg = g / (1.f + __expf(-g));
	v_mul_f32_e32 v17, 0xbfb8aa3b, v16
	v_exp_f32_e32 v17, v17

; __device__ __forceinline__ int crow(int r, int hi) { return (r & 3) + 8 * (r >> 2) + 4 * hi; }
; __device__ __forceinline__ float bf2f(unsigned short b) { return __uint_as_float((unsigned)b << 16); }
; __device__ __forceinline__ unsigned f2bf(float f) { unsigned u = __float_as_uint(f); return (u + 0x7fffu + ((u >> 16) & 1u)) >> 16; }
; __device__ __forceinline__ float bf2f(unsigned short b) { return __uint_as_float((unsigned)b << 16); }
; __device__ __forceinline__ unsigned f2bf(float f) { unsigned u = __float_as_uint(f); return (u + 0x7fffu + ((u >> 16) & 1u)) >> 16; }
;     ...
;   for (int r = 0; r < 16; ++r) { const int orow = wid * QBLK + crow(r, hi); const float rli = __builtin_amdgcn_rcpf(li_l[crow(r, hi)]);
;     if (orow < nvalid) {
;       if constexpr (MODE == 0) {
; #pragma unroll
;         for (int d0 = 0; d0 < 4; ++d0) Of[(long)orow * ldo + d0 * 32 + r32] = o[d0][r] * rli;
;       } else {
; #pragma unroll
;         for (int d0 = 0; d0 < 4; ++d0) { const float g = bf2f(Gb[(long)orow * ldg + d0 * 32 + r32]); const float sg = g / (1.f + __expf(-g));
;           Yb[(long)orow * ldy + d0 * 32 + r32] = (bf16)f2bf(o[d0][r] * rli * sg); }
	v_lshlrev_b32_e32 v2, 16, v102
	v_add_f32_e32 v17, 1.0, v17
	v_div_scale_f32 v18, s[2:3], v17, v17, v16
	v_rcp_f32_e32 v19, v18
	v_mul_f32_e32 v3, 0xbfb8aa3b, v2
	v_exp_f32_e32 v3, v3
	v_fma_f32 v20, -v18, v19, 1.0
	v_fmac_f32_e32 v19, v20, v19
	v_div_scale_f32 v20, vcc, v16, v17, v16
	v_mul_f32_e32 v32, v20, v19
	v_fma_f32 v33, -v18, v32, v20
	v_fmac_f32_e32 v32, v33, v19
	v_fma_f32 v18, -v18, v32, v20
	v_div_fmas_f32 v18, v18, v19, v32
	v_div_fixup_f32 v16, v18, v17, v16
	v_mul_f32_e32 v17, v21, v4
	v_mul_f32_e32 v16, v17, v16
	v_bfe_u32 v17, v16, 16, 1
	v_add3_u32 v16, v16, v17, s15
	v_add_f32_e32 v3, 1.0, v3
	global_store_short_d16_hi v[0:1], v16, off offset:2176
	v_div_scale_f32 v16, s[2:3], v3, v3, v2
	v_rcp_f32_e32 v17, v16
	s_nop 0
	v_fma_f32 v18, -v16, v17, 1.0
	v_fmac_f32_e32 v17, v18, v17
	v_div_scale_f32 v18, vcc, v2, v3, v2
	v_mul_f32_e32 v19, v18, v17
	v_fma_f32 v20, -v16, v19, v18
	v_fmac_f32_e32 v19, v20, v17
	v_fma_f32 v16, -v16, v19, v18
	v_div_fmas_f32 v16, v16, v17, v19
	v_div_fixup_f32 v2, v16, v3, v2
	v_mul_f32_e32 v3, v5, v4
	v_mul_f32_e32 v2, v3, v2
	v_bfe_u32 v3, v2, 16, 1
	v_add3_u32 v2, v2, v3, s15
	global_store_short_d16_hi v[0:1], v2, off offset:2240
.LBB0_593:
	s_or_b64 exec, exec, s[0:1]
	v_or3_b32 v0, v72, v192, 10
	v_cmp_gt_i32_e32 vcc, s96, v0
	s_and_saveexec_b64 s[0:1], vcc
	s_cbranch_execz .LBB0_595
	v_mad_i64_i32 v[2:3], s[2:3], v0, s20, v[66:67]
	global_load_ushort v5, v[2:3], off
	global_load_ushort v100, v[2:3], off offset:64
	global_load_ushort v101, v[2:3], off offset:128
	global_load_ushort v102, v[2:3], off offset:192
	ds_read_b32 v1, v73 offset:40
	s_waitcnt lgkmcnt(0)
	v_rcp_f32_e32 v4, v1
	v_ashrrev_i32_e32 v1, 31, v0
	v_lshlrev_b64 v[0:1], 12, v[0:1]
	v_lshl_add_u64 v[0:1], v[64:65], 0, v[0:1]
	s_waitcnt vmcnt(0)
	v_lshlrev_b32_e32 v5, 16, v5
	v_mul_f32_e32 v16, 0xbfb8aa3b, v5
	v_exp_f32_e32 v16, v16
	s_nop 0
	v_add_f32_e32 v16, 1.0, v16
	v_div_scale_f32 v17, s[2:3], v16, v16, v5
	v_rcp_f32_e32 v18, v17
	s_nop 0
	v_fma_f32 v19, -v17, v18, 1.0
	v_fmac_f32_e32 v18, v19, v18
	v_div_scale_f32 v19, vcc, v5, v16, v5
	v_mul_f32_e32 v20, v19, v18
	v_fma_f32 v21, -v17, v20, v19
	v_fmac_f32_e32 v20, v21, v18
	v_fma_f32 v17, -v17, v20, v19
	v_div_fmas_f32 v17, v17, v18, v20
	v_div_fixup_f32 v5, v17, v16, v5
	v_mul_f32_e32 v16, v54, v4
	v_mul_f32_e32 v5, v16, v5
	v_bfe_u32 v16, v5, 16, 1
	v_add3_u32 v5, v5, v16, s15
	global_store_short_d16_hi v[0:1], v5, off offset:2048


; __device__ __forceinline__ float bf2f(unsigned short b) { return __uint_as_float((unsigned)b << 16); }
; __device__ __forceinline__ unsigned f2bf(float f) { unsigned u = __float_as_uint(f); return (u + 0x7fffu + ((u >> 16) & 1u)) >> 16; }
; __device__ __forceinline__ float bf2f(unsigned short b) { return __uint_as_float((unsigned)b << 16); }
; __device__ __forceinline__ unsigned f2bf(float f) { unsigned u = __float_as_uint(f); return (u + 0x7fffu + ((u >> 16) & 1u)) >> 16; }
;     ...
;         for (int d0 = 0; d0 < 4; ++d0) { const float g = bf2f(Gb[(long)orow * ldg + d0 * 32 + r32]); const float sg = g / (1.f + __expf(-g));
;           Yb[(long)orow * ldy + d0 * 32 + r32] = (bf16)f2bf(o[d0][r] * rli * sg); }
	v_lshlrev_b32_e32 v5, 16, v100
	v_mul_f32_e32 v16, 0xbfb8aa3b, v5
	v_exp_f32_e32 v16, v16
	s_nop 0
	v_add_f32_e32 v16, 1.0, v16
	v_div_scale_f32 v17, s[2:3], v16, v16, v5
	v_rcp_f32_e32 v18, v17
	s_nop 0
	v_fma_f32 v19, -v17, v18, 1.0
	v_fmac_f32_e32 v18, v19, v18
	v_div_scale_f32 v19, vcc, v5, v16, v5
	v_mul_f32_e32 v20, v19, v18
	v_fma_f32 v21, -v17, v20, v19
	v_fmac_f32_e32 v20, v21, v18
	v_fma_f32 v17, -v17, v20, v19
	v_div_fmas_f32 v17, v17, v18, v20
	v_div_fixup_f32 v5, v17, v16, v5
	v_mul_f32_e32 v16, v38, v4
	v_mul_f32_e32 v5, v16, v5
	v_bfe_u32 v16, v5, 16, 1
	v_add3_u32 v5, v5, v16, s15
	global_store_short_d16_hi v[0:1], v5, off offset:2112


; __device__ __forceinline__ float bf2f(unsigned short b) { return __uint_as_float((unsigned)b << 16); }
; __device__ __forceinline__ float bf2f(unsigned short b) { return __uint_as_float((unsigned)b << 16); }
;     ...
;         for (int d0 = 0; d0 < 4; ++d0) { const float g = bf2f(Gb[(long)orow * ldg + d0 * 32 + r32]); const float sg = g / (1.f + __expf(-g));
	v_lshlrev_b32_e32 v5, 16, v101

; __device__ __forceinline__ float bf2f(unsigned short b) { return __uint_as_float((unsigned)b << 16); }
; __device__ __forceinline__ float bf2f(unsigned short b) { return __uint_as_float((unsigned)b << 16); }
;     ...
;         for (int d0 = 0; d0 < 4; ++d0) { const float g = bf2f(Gb[(long)orow * ldg + d0 * 32 + r32]); const float sg = g / (1.f + __expf(-g));
	v_mul_f32_e32 v16, 0xbfb8aa3b, v5
	v_exp_f32_e32 v16, v16

; __device__ __forceinline__ int crow(int r, int hi) { return (r & 3) + 8 * (r >> 2) + 4 * hi; }
; __device__ __forceinline__ float bf2f(unsigned short b) { return __uint_as_float((unsigned)b << 16); }
; __device__ __forceinline__ unsigned f2bf(float f) { unsigned u = __float_as_uint(f); return (u + 0x7fffu + ((u >> 16) & 1u)) >> 16; }
; __device__ __forceinline__ float bf2f(unsigned short b) { return __uint_as_float((unsigned)b << 16); }
; __device__ __forceinline__ unsigned f2bf(float f) { unsigned u = __float_as_uint(f); return (u + 0x7fffu + ((u >> 16) & 1u)) >> 16; }
;     ...
;   for (int r = 0; r < 16; ++r) { const int orow = wid * QBLK + crow(r, hi); const float rli = __builtin_amdgcn_rcpf(li_l[crow(r, hi)]);
;     if (orow < nvalid) {
;       if constexpr (MODE == 0) {
; #pragma unroll
;         for (int d0 = 0; d0 < 4; ++d0) Of[(long)orow * ldo + d0 * 32 + r32] = o[d0][r] * rli;
;       } else {
; #pragma unroll
;         for (int d0 = 0; d0 < 4; ++d0) { const float g = bf2f(Gb[(long)orow * ldg + d0 * 32 + r32]); const float sg = g / (1.f + __expf(-g));
;           Yb[(long)orow * ldy + d0 * 32 + r32] = (bf16)f2bf(o[d0][r] * rli * sg); }
	v_lshlrev_b32_e32 v2, 16, v102
	v_add_f32_e32 v16, 1.0, v16
	v_div_scale_f32 v17, s[2:3], v16, v16, v5
	v_rcp_f32_e32 v18, v17
	v_mul_f32_e32 v3, 0xbfb8aa3b, v2
	v_exp_f32_e32 v3, v3
	v_fma_f32 v19, -v17, v18, 1.0
	v_fmac_f32_e32 v18, v19, v18
	v_div_scale_f32 v19, vcc, v5, v16, v5
	v_mul_f32_e32 v20, v19, v18
	v_fma_f32 v21, -v17, v20, v19
	v_fmac_f32_e32 v20, v21, v18
	v_fma_f32 v17, -v17, v20, v19
	v_div_fmas_f32 v17, v17, v18, v20
	v_div_fixup_f32 v5, v17, v16, v5
	v_mul_f32_e32 v16, v22, v4
	v_mul_f32_e32 v5, v16, v5
	v_bfe_u32 v16, v5, 16, 1
	v_add3_u32 v5, v5, v16, s15
	v_add_f32_e32 v3, 1.0, v3
	global_store_short_d16_hi v[0:1], v5, off offset:2176
	v_div_scale_f32 v5, s[2:3], v3, v3, v2
	v_rcp_f32_e32 v16, v5
	s_nop 0
	v_fma_f32 v17, -v5, v16, 1.0
	v_fmac_f32_e32 v16, v17, v16
	v_div_scale_f32 v17, vcc, v2, v3, v2
	v_mul_f32_e32 v18, v17, v16
	v_fma_f32 v19, -v5, v18, v17
	v_fmac_f32_e32 v18, v19, v16
	v_fma_f32 v5, -v5, v18, v17
	v_div_fmas_f32 v5, v5, v16, v18
	v_div_fixup_f32 v2, v5, v3, v2
	v_mul_f32_e32 v3, v6, v4
	v_mul_f32_e32 v2, v3, v2
	v_bfe_u32 v3, v2, 16, 1
	v_add3_u32 v2, v2, v3, s15
	global_store_short_d16_hi v[0:1], v2, off offset:2240
.LBB0_595:
	s_or_b64 exec, exec, s[0:1]
	v_or3_b32 v0, v72, v192, 11
	v_cmp_gt_i32_e32 vcc, s96, v0
	s_and_saveexec_b64 s[0:1], vcc
	s_cbranch_execz .LBB0_597
	v_mad_i64_i32 v[2:3], s[2:3], v0, s20, v[66:67]
	global_load_ushort v5, v[2:3], off
	global_load_ushort v100, v[2:3], off offset:64
	global_load_ushort v101, v[2:3], off offset:128
	global_load_ushort v102, v[2:3], off offset:192
	ds_read_b32 v1, v73 offset:44
	s_waitcnt lgkmcnt(0)
	v_rcp_f32_e32 v4, v1
	v_ashrrev_i32_e32 v1, 31, v0
	v_lshlrev_b64 v[0:1], 12, v[0:1]
	v_lshl_add_u64 v[0:1], v[64:65], 0, v[0:1]
	s_waitcnt vmcnt(0)
	v_lshlrev_b32_e32 v5, 16, v5
	v_mul_f32_e32 v6, 0xbfb8aa3b, v5
	v_exp_f32_e32 v6, v6
	s_nop 0
	v_add_f32_e32 v6, 1.0, v6
	v_div_scale_f32 v16, s[2:3], v6, v6, v5
	v_rcp_f32_e32 v17, v16
	s_nop 0
	v_fma_f32 v18, -v16, v17, 1.0
	v_fmac_f32_e32 v17, v18, v17
	v_div_scale_f32 v18, vcc, v5, v6, v5
	v_mul_f32_e32 v19, v18, v17
	v_fma_f32 v20, -v16, v19, v18
	v_fmac_f32_e32 v19, v20, v17
	v_fma_f32 v16, -v16, v19, v18
	v_div_fmas_f32 v16, v16, v17, v19
	v_div_fixup_f32 v5, v16, v6, v5
	v_mul_f32_e32 v6, v55, v4
	v_mul_f32_e32 v5, v6, v5
	v_bfe_u32 v6, v5, 16, 1
	v_add3_u32 v5, v5, v6, s15
	global_store_short_d16_hi v[0:1], v5, off offset:2048


; __device__ __forceinline__ float bf2f(unsigned short b) { return __uint_as_float((unsigned)b << 16); }
; __device__ __forceinline__ unsigned f2bf(float f) { unsigned u = __float_as_uint(f); return (u + 0x7fffu + ((u >> 16) & 1u)) >> 16; }
; __device__ __forceinline__ float bf2f(unsigned short b) { return __uint_as_float((unsigned)b << 16); }
; __device__ __forceinline__ unsigned f2bf(float f) { unsigned u = __float_as_uint(f); return (u + 0x7fffu + ((u >> 16) & 1u)) >> 16; }
;     ...
;         for (int d0 = 0; d0 < 4; ++d0) { const float g = bf2f(Gb[(long)orow * ldg + d0 * 32 + r32]); const float sg = g / (1.f + __expf(-g));
;           Yb[(long)orow * ldy + d0 * 32 + r32] = (bf16)f2bf(o[d0][r] * rli * sg); }
	v_lshlrev_b32_e32 v5, 16, v100
	v_mul_f32_e32 v6, 0xbfb8aa3b, v5
	v_exp_f32_e32 v6, v6
	s_nop 0
	v_add_f32_e32 v6, 1.0, v6
	v_div_scale_f32 v16, s[2:3], v6, v6, v5
	v_rcp_f32_e32 v17, v16
	s_nop 0
	v_fma_f32 v18, -v16, v17, 1.0
	v_fmac_f32_e32 v17, v18, v17
	v_div_scale_f32 v18, vcc, v5, v6, v5
	v_mul_f32_e32 v19, v18, v17
	v_fma_f32 v20, -v16, v19, v18
	v_fmac_f32_e32 v19, v20, v17
	v_fma_f32 v16, -v16, v19, v18
	v_div_fmas_f32 v16, v16, v17, v19
	v_div_fixup_f32 v5, v16, v6, v5
	v_mul_f32_e32 v6, v39, v4
	v_mul_f32_e32 v5, v6, v5
	v_bfe_u32 v6, v5, 16, 1
	v_add3_u32 v5, v5, v6, s15
	global_store_short_d16_hi v[0:1], v5, off offset:2112


; __device__ __forceinline__ float bf2f(unsigned short b) { return __uint_as_float((unsigned)b << 16); }
; __device__ __forceinline__ float bf2f(unsigned short b) { return __uint_as_float((unsigned)b << 16); }
;     ...
;         for (int d0 = 0; d0 < 4; ++d0) { const float g = bf2f(Gb[(long)orow * ldg + d0 * 32 + r32]); const float sg = g / (1.f + __expf(-g));
	v_lshlrev_b32_e32 v5, 16, v101

; __device__ __forceinline__ float bf2f(unsigned short b) { return __uint_as_float((unsigned)b << 16); }
; __device__ __forceinline__ float bf2f(unsigned short b) { return __uint_as_float((unsigned)b << 16); }
;     ...
;         for (int d0 = 0; d0 < 4; ++d0) { const float g = bf2f(Gb[(long)orow * ldg + d0 * 32 + r32]); const float sg = g / (1.f + __expf(-g));
	v_mul_f32_e32 v6, 0xbfb8aa3b, v5
	v_exp_f32_e32 v6, v6

; __device__ __forceinline__ int crow(int r, int hi) { return (r & 3) + 8 * (r >> 2) + 4 * hi; }
; __device__ __forceinline__ float bf2f(unsigned short b) { return __uint_as_float((unsigned)b << 16); }
; __device__ __forceinline__ unsigned f2bf(float f) { unsigned u = __float_as_uint(f); return (u + 0x7fffu + ((u >> 16) & 1u)) >> 16; }
; __device__ __forceinline__ float bf2f(unsigned short b) { return __uint_as_float((unsigned)b << 16); }
; __device__ __forceinline__ unsigned f2bf(float f) { unsigned u = __float_as_uint(f); return (u + 0x7fffu + ((u >> 16) & 1u)) >> 16; }
;     ...
;   for (int r = 0; r < 16; ++r) { const int orow = wid * QBLK + crow(r, hi); const float rli = __builtin_amdgcn_rcpf(li_l[crow(r, hi)]);
;     if (orow < nvalid) {
;       if constexpr (MODE == 0) {
; #pragma unroll
;         for (int d0 = 0; d0 < 4; ++d0) Of[(long)orow * ldo + d0 * 32 + r32] = o[d0][r] * rli;
;       } else {
; #pragma unroll
;         for (int d0 = 0; d0 < 4; ++d0) { const float g = bf2f(Gb[(long)orow * ldg + d0 * 32 + r32]); const float sg = g / (1.f + __expf(-g));
;           Yb[(long)orow * ldy + d0 * 32 + r32] = (bf16)f2bf(o[d0][r] * rli * sg); }
	v_lshlrev_b32_e32 v2, 16, v102
	v_add_f32_e32 v6, 1.0, v6
	v_div_scale_f32 v16, s[2:3], v6, v6, v5
	v_rcp_f32_e32 v17, v16
	v_mul_f32_e32 v3, 0xbfb8aa3b, v2
	v_exp_f32_e32 v3, v3
	v_fma_f32 v18, -v16, v17, 1.0
	v_fmac_f32_e32 v17, v18, v17
	v_div_scale_f32 v18, vcc, v5, v6, v5
	v_mul_f32_e32 v19, v18, v17
	v_fma_f32 v20, -v16, v19, v18
	v_fmac_f32_e32 v19, v20, v17
	v_fma_f32 v16, -v16, v19, v18
	v_div_fmas_f32 v16, v16, v17, v19
	v_div_fixup_f32 v5, v16, v6, v5
	v_mul_f32_e32 v6, v23, v4
	v_mul_f32_e32 v5, v6, v5
	v_bfe_u32 v6, v5, 16, 1
	v_add3_u32 v5, v5, v6, s15
	v_add_f32_e32 v3, 1.0, v3
	global_store_short_d16_hi v[0:1], v5, off offset:2176
	v_div_scale_f32 v5, s[2:3], v3, v3, v2
	v_rcp_f32_e32 v6, v5
	s_nop 0
	v_fma_f32 v16, -v5, v6, 1.0
	v_fmac_f32_e32 v6, v16, v6
	v_div_scale_f32 v16, vcc, v2, v3, v2
	v_mul_f32_e32 v17, v16, v6
	v_fma_f32 v18, -v5, v17, v16
	v_fmac_f32_e32 v17, v18, v6
	v_fma_f32 v5, -v5, v17, v16
	v_div_fmas_f32 v5, v5, v6, v17
	v_div_fixup_f32 v2, v5, v3, v2
	v_mul_f32_e32 v3, v7, v4
	v_mul_f32_e32 v2, v3, v2
	v_bfe_u32 v3, v2, 16, 1
	v_add3_u32 v2, v2, v3, s15
	global_store_short_d16_hi v[0:1], v2, off offset:2240
.LBB0_597:
	s_or_b64 exec, exec, s[0:1]
	v_or3_b32 v0, v72, v192, 16
	v_cmp_gt_i32_e32 vcc, s96, v0
	s_and_saveexec_b64 s[0:1], vcc
	s_cbranch_execz .LBB0_599
	v_mad_i64_i32 v[2:3], s[2:3], v0, s20, v[66:67]
	global_load_ushort v5, v[2:3], off
	global_load_ushort v100, v[2:3], off offset:64
	global_load_ushort v101, v[2:3], off offset:128
	global_load_ushort v102, v[2:3], off offset:192
	ds_read_b32 v1, v73 offset:64
	s_waitcnt lgkmcnt(0)
	v_rcp_f32_e32 v4, v1
	v_ashrrev_i32_e32 v1, 31, v0
	v_lshlrev_b64 v[0:1], 12, v[0:1]
	v_lshl_add_u64 v[0:1], v[64:65], 0, v[0:1]
	s_waitcnt vmcnt(0)
	v_lshlrev_b32_e32 v5, 16, v5
	v_mul_f32_e32 v6, 0xbfb8aa3b, v5
	v_exp_f32_e32 v6, v6
	s_nop 0
	v_add_f32_e32 v6, 1.0, v6
	v_div_scale_f32 v7, s[2:3], v6, v6, v5
	v_rcp_f32_e32 v16, v7
	s_nop 0
	v_fma_f32 v17, -v7, v16, 1.0
	v_fmac_f32_e32 v16, v17, v16
	v_div_scale_f32 v17, vcc, v5, v6, v5
	v_mul_f32_e32 v18, v17, v16
	v_fma_f32 v19, -v7, v18, v17
	v_fmac_f32_e32 v18, v19, v16
	v_fma_f32 v7, -v7, v18, v17
	v_div_fmas_f32 v7, v7, v16, v18
	v_div_fixup_f32 v5, v7, v6, v5
	v_mul_f32_e32 v6, v56, v4
	v_mul_f32_e32 v5, v6, v5
	v_bfe_u32 v6, v5, 16, 1
	v_add3_u32 v5, v5, v6, s15
	global_store_short_d16_hi v[0:1], v5, off offset:2048


; __device__ __forceinline__ float bf2f(unsigned short b) { return __uint_as_float((unsigned)b << 16); }
; __device__ __forceinline__ unsigned f2bf(float f) { unsigned u = __float_as_uint(f); return (u + 0x7fffu + ((u >> 16) & 1u)) >> 16; }
; __device__ __forceinline__ float bf2f(unsigned short b) { return __uint_as_float((unsigned)b << 16); }
; __device__ __forceinline__ unsigned f2bf(float f) { unsigned u = __float_as_uint(f); return (u + 0x7fffu + ((u >> 16) & 1u)) >> 16; }
;     ...
;         for (int d0 = 0; d0 < 4; ++d0) { const float g = bf2f(Gb[(long)orow * ldg + d0 * 32 + r32]); const float sg = g / (1.f + __expf(-g));
;           Yb[(long)orow * ldy + d0 * 32 + r32] = (bf16)f2bf(o[d0][r] * rli * sg); }
	v_lshlrev_b32_e32 v5, 16, v100
	v_mul_f32_e32 v6, 0xbfb8aa3b, v5
	v_exp_f32_e32 v6, v6
	s_nop 0
	v_add_f32_e32 v6, 1.0, v6
	v_div_scale_f32 v7, s[2:3], v6, v6, v5
	v_rcp_f32_e32 v16, v7
	s_nop 0
	v_fma_f32 v17, -v7, v16, 1.0
	v_fmac_f32_e32 v16, v17, v16
	v_div_scale_f32 v17, vcc, v5, v6, v5
	v_mul_f32_e32 v18, v17, v16
	v_fma_f32 v19, -v7, v18, v17
	v_fmac_f32_e32 v18, v19, v16
	v_fma_f32 v7, -v7, v18, v17
	v_div_fmas_f32 v7, v7, v16, v18
	v_div_fixup_f32 v5, v7, v6, v5
	v_mul_f32_e32 v6, v40, v4
	v_mul_f32_e32 v5, v6, v5
	v_bfe_u32 v6, v5, 16, 1
	v_add3_u32 v5, v5, v6, s15
	global_store_short_d16_hi v[0:1], v5, off offset:2112


; __device__ __forceinline__ float bf2f(unsigned short b) { return __uint_as_float((unsigned)b << 16); }
; __device__ __forceinline__ float bf2f(unsigned short b) { return __uint_as_float((unsigned)b << 16); }
;     ...
;         for (int d0 = 0; d0 < 4; ++d0) { const float g = bf2f(Gb[(long)orow * ldg + d0 * 32 + r32]); const float sg = g / (1.f + __expf(-g));
	v_lshlrev_b32_e32 v5, 16, v101

; __device__ __forceinline__ float bf2f(unsigned short b) { return __uint_as_float((unsigned)b << 16); }
; __device__ __forceinline__ float bf2f(unsigned short b) { return __uint_as_float((unsigned)b << 16); }
;     ...
;         for (int d0 = 0; d0 < 4; ++d0) { const float g = bf2f(Gb[(long)orow * ldg + d0 * 32 + r32]); const float sg = g / (1.f + __expf(-g));
	v_mul_f32_e32 v6, 0xbfb8aa3b, v5
	v_exp_f32_e32 v6, v6

; __device__ __forceinline__ int crow(int r, int hi) { return (r & 3) + 8 * (r >> 2) + 4 * hi; }
; __device__ __forceinline__ float bf2f(unsigned short b) { return __uint_as_float((unsigned)b << 16); }
; __device__ __forceinline__ unsigned f2bf(float f) { unsigned u = __float_as_uint(f); return (u + 0x7fffu + ((u >> 16) & 1u)) >> 16; }
; __device__ __forceinline__ float bf2f(unsigned short b) { return __uint_as_float((unsigned)b << 16); }
; __device__ __forceinline__ unsigned f2bf(float f) { unsigned u = __float_as_uint(f); return (u + 0x7fffu + ((u >> 16) & 1u)) >> 16; }
;     ...
;   for (int r = 0; r < 16; ++r) { const int orow = wid * QBLK + crow(r, hi); const float rli = __builtin_amdgcn_rcpf(li_l[crow(r, hi)]);
;     if (orow < nvalid) {
;       if constexpr (MODE == 0) {
; #pragma unroll
;         for (int d0 = 0; d0 < 4; ++d0) Of[(long)orow * ldo + d0 * 32 + r32] = o[d0][r] * rli;
;       } else {
; #pragma unroll
;         for (int d0 = 0; d0 < 4; ++d0) { const float g = bf2f(Gb[(long)orow * ldg + d0 * 32 + r32]); const float sg = g / (1.f + __expf(-g));
;           Yb[(long)orow * ldy + d0 * 32 + r32] = (bf16)f2bf(o[d0][r] * rli * sg); }
	v_lshlrev_b32_e32 v2, 16, v102
	v_add_f32_e32 v6, 1.0, v6
	v_div_scale_f32 v7, s[2:3], v6, v6, v5
	v_rcp_f32_e32 v16, v7
	v_mul_f32_e32 v3, 0xbfb8aa3b, v2
	v_exp_f32_e32 v3, v3
	v_fma_f32 v17, -v7, v16, 1.0
	v_fmac_f32_e32 v16, v17, v16
	v_div_scale_f32 v17, vcc, v5, v6, v5
	v_mul_f32_e32 v18, v17, v16
	v_fma_f32 v19, -v7, v18, v17
	v_fmac_f32_e32 v18, v19, v16
	v_fma_f32 v7, -v7, v18, v17
	v_div_fmas_f32 v7, v7, v16, v18
	v_div_fixup_f32 v5, v7, v6, v5
	v_mul_f32_e32 v6, v24, v4
	v_mul_f32_e32 v5, v6, v5
	v_bfe_u32 v6, v5, 16, 1
	v_add3_u32 v5, v5, v6, s15
	v_add_f32_e32 v3, 1.0, v3
	global_store_short_d16_hi v[0:1], v5, off offset:2176
	v_div_scale_f32 v5, s[2:3], v3, v3, v2
	v_rcp_f32_e32 v6, v5
	s_nop 0
	v_fma_f32 v7, -v5, v6, 1.0
	v_fmac_f32_e32 v6, v7, v6
	v_div_scale_f32 v7, vcc, v2, v3, v2
	v_mul_f32_e32 v16, v7, v6
	v_fma_f32 v17, -v5, v16, v7
	v_fmac_f32_e32 v16, v17, v6
	v_fma_f32 v5, -v5, v16, v7
	v_div_fmas_f32 v5, v5, v6, v16
	v_div_fixup_f32 v2, v5, v3, v2
	v_mul_f32_e32 v3, v8, v4
	v_mul_f32_e32 v2, v3, v2
	v_bfe_u32 v3, v2, 16, 1
	v_add3_u32 v2, v2, v3, s15
	global_store_short_d16_hi v[0:1], v2, off offset:2240
.LBB0_599:
	s_or_b64 exec, exec, s[0:1]
	v_or3_b32 v0, v72, v192, 17
	v_cmp_gt_i32_e32 vcc, s96, v0
	s_and_saveexec_b64 s[0:1], vcc
	s_cbranch_execz .LBB0_601
	v_mad_i64_i32 v[2:3], s[2:3], v0, s20, v[66:67]
	global_load_ushort v5, v[2:3], off
	global_load_ushort v100, v[2:3], off offset:64
	global_load_ushort v101, v[2:3], off offset:128
	global_load_ushort v102, v[2:3], off offset:192
	ds_read_b32 v1, v73 offset:68
	s_waitcnt lgkmcnt(0)
	v_rcp_f32_e32 v4, v1
	v_ashrrev_i32_e32 v1, 31, v0
	v_lshlrev_b64 v[0:1], 12, v[0:1]
	v_lshl_add_u64 v[0:1], v[64:65], 0, v[0:1]
	s_waitcnt vmcnt(0)
	v_lshlrev_b32_e32 v5, 16, v5
	v_mul_f32_e32 v6, 0xbfb8aa3b, v5
	v_exp_f32_e32 v6, v6
	s_nop 0
	v_add_f32_e32 v6, 1.0, v6
	v_div_scale_f32 v7, s[2:3], v6, v6, v5
	v_rcp_f32_e32 v8, v7
	s_nop 0
	v_fma_f32 v16, -v7, v8, 1.0
	v_fmac_f32_e32 v8, v16, v8
	v_div_scale_f32 v16, vcc, v5, v6, v5
	v_mul_f32_e32 v17, v16, v8
	v_fma_f32 v18, -v7, v17, v16
	v_fmac_f32_e32 v17, v18, v8
	v_fma_f32 v7, -v7, v17, v16
	v_div_fmas_f32 v7, v7, v8, v17
	v_div_fixup_f32 v5, v7, v6, v5
	v_mul_f32_e32 v6, v57, v4
	v_mul_f32_e32 v5, v6, v5
	v_bfe_u32 v6, v5, 16, 1
	v_add3_u32 v5, v5, v6, s15
	global_store_short_d16_hi v[0:1], v5, off offset:2048


; __device__ __forceinline__ float bf2f(unsigned short b) { return __uint_as_float((unsigned)b << 16); }
; __device__ __forceinline__ unsigned f2bf(float f) { unsigned u = __float_as_uint(f); return (u + 0x7fffu + ((u >> 16) & 1u)) >> 16; }
; __device__ __forceinline__ float bf2f(unsigned short b) { return __uint_as_float((unsigned)b << 16); }
; __device__ __forceinline__ unsigned f2bf(float f) { unsigned u = __float_as_uint(f); return (u + 0x7fffu + ((u >> 16) & 1u)) >> 16; }
;     ...
;         for (int d0 = 0; d0 < 4; ++d0) { const float g = bf2f(Gb[(long)orow * ldg + d0 * 32 + r32]); const float sg = g / (1.f + __expf(-g));
;           Yb[(long)orow * ldy + d0 * 32 + r32] = (bf16)f2bf(o[d0][r] * rli * sg); }
	v_lshlrev_b32_e32 v5, 16, v100
	v_mul_f32_e32 v6, 0xbfb8aa3b, v5
	v_exp_f32_e32 v6, v6
	s_nop 0
	v_add_f32_e32 v6, 1.0, v6
	v_div_scale_f32 v7, s[2:3], v6, v6, v5
	v_rcp_f32_e32 v8, v7
	s_nop 0
	v_fma_f32 v16, -v7, v8, 1.0
	v_fmac_f32_e32 v8, v16, v8
	v_div_scale_f32 v16, vcc, v5, v6, v5
	v_mul_f32_e32 v17, v16, v8
	v_fma_f32 v18, -v7, v17, v16
	v_fmac_f32_e32 v17, v18, v8
	v_fma_f32 v7, -v7, v17, v16
	v_div_fmas_f32 v7, v7, v8, v17
	v_div_fixup_f32 v5, v7, v6, v5
	v_mul_f32_e32 v6, v41, v4
	v_mul_f32_e32 v5, v6, v5
	v_bfe_u32 v6, v5, 16, 1
	v_add3_u32 v5, v5, v6, s15
	global_store_short_d16_hi v[0:1], v5, off offset:2112


; __device__ __forceinline__ float bf2f(unsigned short b) { return __uint_as_float((unsigned)b << 16); }
; __device__ __forceinline__ float bf2f(unsigned short b) { return __uint_as_float((unsigned)b << 16); }
;     ...
;         for (int d0 = 0; d0 < 4; ++d0) { const float g = bf2f(Gb[(long)orow * ldg + d0 * 32 + r32]); const float sg = g / (1.f + __expf(-g));
	v_lshlrev_b32_e32 v5, 16, v101

; __device__ __forceinline__ float bf2f(unsigned short b) { return __uint_as_float((unsigned)b << 16); }
; __device__ __forceinline__ float bf2f(unsigned short b) { return __uint_as_float((unsigned)b << 16); }
;     ...
;         for (int d0 = 0; d0 < 4; ++d0) { const float g = bf2f(Gb[(long)orow * ldg + d0 * 32 + r32]); const float sg = g / (1.f + __expf(-g));
	v_mul_f32_e32 v6, 0xbfb8aa3b, v5
	v_exp_f32_e32 v6, v6

; __device__ __forceinline__ int crow(int r, int hi) { return (r & 3) + 8 * (r >> 2) + 4 * hi; }
; __device__ __forceinline__ float bf2f(unsigned short b) { return __uint_as_float((unsigned)b << 16); }
; __device__ __forceinline__ unsigned f2bf(float f) { unsigned u = __float_as_uint(f); return (u + 0x7fffu + ((u >> 16) & 1u)) >> 16; }
; __device__ __forceinline__ float bf2f(unsigned short b) { return __uint_as_float((unsigned)b << 16); }
; __device__ __forceinline__ unsigned f2bf(float f) { unsigned u = __float_as_uint(f); return (u + 0x7fffu + ((u >> 16) & 1u)) >> 16; }
;     ...
;   for (int r = 0; r < 16; ++r) { const int orow = wid * QBLK + crow(r, hi); const float rli = __builtin_amdgcn_rcpf(li_l[crow(r, hi)]);
;     if (orow < nvalid) {
;       if constexpr (MODE == 0) {
; #pragma unroll
;         for (int d0 = 0; d0 < 4; ++d0) Of[(long)orow * ldo + d0 * 32 + r32] = o[d0][r] * rli;
;       } else {
; #pragma unroll
;         for (int d0 = 0; d0 < 4; ++d0) { const float g = bf2f(Gb[(long)orow * ldg + d0 * 32 + r32]); const float sg = g / (1.f + __expf(-g));
;           Yb[(long)orow * ldy + d0 * 32 + r32] = (bf16)f2bf(o[d0][r] * rli * sg); }
	v_lshlrev_b32_e32 v2, 16, v102
	v_add_f32_e32 v6, 1.0, v6
	v_div_scale_f32 v7, s[2:3], v6, v6, v5
	v_rcp_f32_e32 v8, v7
	v_mul_f32_e32 v3, 0xbfb8aa3b, v2
	v_exp_f32_e32 v3, v3
	v_fma_f32 v16, -v7, v8, 1.0
	v_fmac_f32_e32 v8, v16, v8
	v_div_scale_f32 v16, vcc, v5, v6, v5
	v_mul_f32_e32 v17, v16, v8
	v_fma_f32 v18, -v7, v17, v16
	v_fmac_f32_e32 v17, v18, v8
	v_fma_f32 v7, -v7, v17, v16
	v_div_fmas_f32 v7, v7, v8, v17
	v_div_fixup_f32 v5, v7, v6, v5
	v_mul_f32_e32 v6, v25, v4
	v_mul_f32_e32 v5, v6, v5
	v_bfe_u32 v6, v5, 16, 1
	v_add3_u32 v5, v5, v6, s15
	v_add_f32_e32 v3, 1.0, v3
	global_store_short_d16_hi v[0:1], v5, off offset:2176
	v_div_scale_f32 v5, s[2:3], v3, v3, v2
	v_rcp_f32_e32 v6, v5
	s_nop 0
	v_fma_f32 v7, -v5, v6, 1.0
	v_fmac_f32_e32 v6, v7, v6
	v_div_scale_f32 v7, vcc, v2, v3, v2
	v_mul_f32_e32 v8, v7, v6
	v_fma_f32 v16, -v5, v8, v7
	v_fmac_f32_e32 v8, v16, v6
	v_fma_f32 v5, -v5, v8, v7
	v_div_fmas_f32 v5, v5, v6, v8
	v_div_fixup_f32 v2, v5, v3, v2
	v_mul_f32_e32 v3, v9, v4
	v_mul_f32_e32 v2, v3, v2
	v_bfe_u32 v3, v2, 16, 1
	v_add3_u32 v2, v2, v3, s15
	global_store_short_d16_hi v[0:1], v2, off offset:2240
.LBB0_601:
	s_or_b64 exec, exec, s[0:1]
	v_or3_b32 v0, v72, v192, 18
	v_cmp_gt_i32_e32 vcc, s96, v0
	s_and_saveexec_b64 s[0:1], vcc
	s_cbranch_execz .LBB0_603
	v_mad_i64_i32 v[2:3], s[2:3], v0, s20, v[66:67]
	global_load_ushort v5, v[2:3], off
	global_load_ushort v100, v[2:3], off offset:64
	global_load_ushort v101, v[2:3], off offset:128
	global_load_ushort v102, v[2:3], off offset:192
	ds_read_b32 v1, v73 offset:72
	s_waitcnt lgkmcnt(0)
	v_rcp_f32_e32 v4, v1
	v_ashrrev_i32_e32 v1, 31, v0
	v_lshlrev_b64 v[0:1], 12, v[0:1]
	v_lshl_add_u64 v[0:1], v[64:65], 0, v[0:1]
	s_waitcnt vmcnt(0)
	v_lshlrev_b32_e32 v5, 16, v5
	v_mul_f32_e32 v6, 0xbfb8aa3b, v5
	v_exp_f32_e32 v6, v6
	s_nop 0
	v_add_f32_e32 v6, 1.0, v6
	v_div_scale_f32 v7, s[2:3], v6, v6, v5
	v_rcp_f32_e32 v8, v7
	s_nop 0
	v_fma_f32 v9, -v7, v8, 1.0
	v_fmac_f32_e32 v8, v9, v8
	v_div_scale_f32 v9, vcc, v5, v6, v5
	v_mul_f32_e32 v16, v9, v8
	v_fma_f32 v17, -v7, v16, v9
	v_fmac_f32_e32 v16, v17, v8
	v_fma_f32 v7, -v7, v16, v9
	v_div_fmas_f32 v7, v7, v8, v16
	v_div_fixup_f32 v5, v7, v6, v5
	v_mul_f32_e32 v6, v58, v4
	v_mul_f32_e32 v5, v6, v5
	v_bfe_u32 v6, v5, 16, 1
	v_add3_u32 v5, v5, v6, s15
	global_store_short_d16_hi v[0:1], v5, off offset:2048


; __device__ __forceinline__ float bf2f(unsigned short b) { return __uint_as_float((unsigned)b << 16); }
; __device__ __forceinline__ unsigned f2bf(float f) { unsigned u = __float_as_uint(f); return (u + 0x7fffu + ((u >> 16) & 1u)) >> 16; }
; __device__ __forceinline__ float bf2f(unsigned short b) { return __uint_as_float((unsigned)b << 16); }
; __device__ __forceinline__ unsigned f2bf(float f) { unsigned u = __float_as_uint(f); return (u + 0x7fffu + ((u >> 16) & 1u)) >> 16; }
;     ...
;         for (int d0 = 0; d0 < 4; ++d0) { const float g = bf2f(Gb[(long)orow * ldg + d0 * 32 + r32]); const float sg = g / (1.f + __expf(-g));
;           Yb[(long)orow * ldy + d0 * 32 + r32] = (bf16)f2bf(o[d0][r] * rli * sg); }
	v_lshlrev_b32_e32 v5, 16, v100
	v_mul_f32_e32 v6, 0xbfb8aa3b, v5
	v_exp_f32_e32 v6, v6
	s_nop 0
	v_add_f32_e32 v6, 1.0, v6
	v_div_scale_f32 v7, s[2:3], v6, v6, v5
	v_rcp_f32_e32 v8, v7
	s_nop 0
	v_fma_f32 v9, -v7, v8, 1.0
	v_fmac_f32_e32 v8, v9, v8
	v_div_scale_f32 v9, vcc, v5, v6, v5
	v_mul_f32_e32 v16, v9, v8
	v_fma_f32 v17, -v7, v16, v9
	v_fmac_f32_e32 v16, v17, v8
	v_fma_f32 v7, -v7, v16, v9
	v_div_fmas_f32 v7, v7, v8, v16
	v_div_fixup_f32 v5, v7, v6, v5
	v_mul_f32_e32 v6, v42, v4
	v_mul_f32_e32 v5, v6, v5
	v_bfe_u32 v6, v5, 16, 1
	v_add3_u32 v5, v5, v6, s15
	global_store_short_d16_hi v[0:1], v5, off offset:2112


; __device__ __forceinline__ float bf2f(unsigned short b) { return __uint_as_float((unsigned)b << 16); }
; __device__ __forceinline__ float bf2f(unsigned short b) { return __uint_as_float((unsigned)b << 16); }
;     ...
;         for (int d0 = 0; d0 < 4; ++d0) { const float g = bf2f(Gb[(long)orow * ldg + d0 * 32 + r32]); const float sg = g / (1.f + __expf(-g));
	v_lshlrev_b32_e32 v5, 16, v101

; __device__ __forceinline__ float bf2f(unsigned short b) { return __uint_as_float((unsigned)b << 16); }
; __device__ __forceinline__ float bf2f(unsigned short b) { return __uint_as_float((unsigned)b << 16); }
;     ...
;         for (int d0 = 0; d0 < 4; ++d0) { const float g = bf2f(Gb[(long)orow * ldg + d0 * 32 + r32]); const float sg = g / (1.f + __expf(-g));
	v_mul_f32_e32 v6, 0xbfb8aa3b, v5
	v_exp_f32_e32 v6, v6

; __device__ __forceinline__ int crow(int r, int hi) { return (r & 3) + 8 * (r >> 2) + 4 * hi; }
; __device__ __forceinline__ float bf2f(unsigned short b) { return __uint_as_float((unsigned)b << 16); }
; __device__ __forceinline__ unsigned f2bf(float f) { unsigned u = __float_as_uint(f); return (u + 0x7fffu + ((u >> 16) & 1u)) >> 16; }
; __device__ __forceinline__ float bf2f(unsigned short b) { return __uint_as_float((unsigned)b << 16); }
; __device__ __forceinline__ unsigned f2bf(float f) { unsigned u = __float_as_uint(f); return (u + 0x7fffu + ((u >> 16) & 1u)) >> 16; }
;     ...
;   for (int r = 0; r < 16; ++r) { const int orow = wid * QBLK + crow(r, hi); const float rli = __builtin_amdgcn_rcpf(li_l[crow(r, hi)]);
;     if (orow < nvalid) {
;       if constexpr (MODE == 0) {
; #pragma unroll
;         for (int d0 = 0; d0 < 4; ++d0) Of[(long)orow * ldo + d0 * 32 + r32] = o[d0][r] * rli;
;       } else {
; #pragma unroll
;         for (int d0 = 0; d0 < 4; ++d0) { const float g = bf2f(Gb[(long)orow * ldg + d0 * 32 + r32]); const float sg = g / (1.f + __expf(-g));
;           Yb[(long)orow * ldy + d0 * 32 + r32] = (bf16)f2bf(o[d0][r] * rli * sg); }
	v_lshlrev_b32_e32 v2, 16, v102
	v_add_f32_e32 v6, 1.0, v6
	v_div_scale_f32 v7, s[2:3], v6, v6, v5
	v_rcp_f32_e32 v8, v7
	v_mul_f32_e32 v3, 0xbfb8aa3b, v2
	v_exp_f32_e32 v3, v3
	v_fma_f32 v9, -v7, v8, 1.0
	v_fmac_f32_e32 v8, v9, v8
	v_div_scale_f32 v9, vcc, v5, v6, v5
	v_mul_f32_e32 v16, v9, v8
	v_fma_f32 v17, -v7, v16, v9
	v_fmac_f32_e32 v16, v17, v8
	v_fma_f32 v7, -v7, v16, v9
	v_div_fmas_f32 v7, v7, v8, v16
	v_div_fixup_f32 v5, v7, v6, v5
	v_mul_f32_e32 v6, v26, v4
	v_mul_f32_e32 v5, v6, v5
	v_bfe_u32 v6, v5, 16, 1
	v_add3_u32 v5, v5, v6, s15
	v_add_f32_e32 v3, 1.0, v3
	global_store_short_d16_hi v[0:1], v5, off offset:2176
	v_div_scale_f32 v5, s[2:3], v3, v3, v2
	v_rcp_f32_e32 v6, v5
	s_nop 0
	v_fma_f32 v7, -v5, v6, 1.0
	v_fmac_f32_e32 v6, v7, v6
	v_div_scale_f32 v7, vcc, v2, v3, v2
	v_mul_f32_e32 v8, v7, v6
	v_fma_f32 v9, -v5, v8, v7
	v_fmac_f32_e32 v8, v9, v6
	v_fma_f32 v5, -v5, v8, v7
	v_div_fmas_f32 v5, v5, v6, v8
	v_div_fixup_f32 v2, v5, v3, v2
	v_mul_f32_e32 v3, v10, v4
	v_mul_f32_e32 v2, v3, v2
	v_bfe_u32 v3, v2, 16, 1
	v_add3_u32 v2, v2, v3, s15
	global_store_short_d16_hi v[0:1], v2, off offset:2240
.LBB0_603:
	s_or_b64 exec, exec, s[0:1]
	v_or3_b32 v0, v72, v192, 19
	v_cmp_gt_i32_e32 vcc, s96, v0
	s_and_saveexec_b64 s[0:1], vcc
	s_cbranch_execz .LBB0_605
	v_mad_i64_i32 v[2:3], s[2:3], v0, s20, v[66:67]
	global_load_ushort v5, v[2:3], off
	global_load_ushort v100, v[2:3], off offset:64
	global_load_ushort v101, v[2:3], off offset:128
	global_load_ushort v102, v[2:3], off offset:192
	ds_read_b32 v1, v73 offset:76
	s_waitcnt lgkmcnt(0)
	v_rcp_f32_e32 v4, v1
	v_ashrrev_i32_e32 v1, 31, v0
	v_lshlrev_b64 v[0:1], 12, v[0:1]
	v_lshl_add_u64 v[0:1], v[64:65], 0, v[0:1]
	s_waitcnt vmcnt(0)
	v_lshlrev_b32_e32 v5, 16, v5
	v_mul_f32_e32 v6, 0xbfb8aa3b, v5
	v_exp_f32_e32 v6, v6
	s_nop 0
	v_add_f32_e32 v6, 1.0, v6
	v_div_scale_f32 v7, s[2:3], v6, v6, v5
	v_rcp_f32_e32 v8, v7
	s_nop 0
	v_fma_f32 v9, -v7, v8, 1.0
	v_fmac_f32_e32 v8, v9, v8
	v_div_scale_f32 v9, vcc, v5, v6, v5
	v_mul_f32_e32 v10, v9, v8
	v_fma_f32 v16, -v7, v10, v9
	v_fmac_f32_e32 v10, v16, v8
	v_fma_f32 v7, -v7, v10, v9
	v_div_fmas_f32 v7, v7, v8, v10
	v_div_fixup_f32 v5, v7, v6, v5
	v_mul_f32_e32 v6, v59, v4
	v_mul_f32_e32 v5, v6, v5
	v_bfe_u32 v6, v5, 16, 1
	v_add3_u32 v5, v5, v6, s15
	global_store_short_d16_hi v[0:1], v5, off offset:2048


; __device__ __forceinline__ float bf2f(unsigned short b) { return __uint_as_float((unsigned)b << 16); }
; __device__ __forceinline__ unsigned f2bf(float f) { unsigned u = __float_as_uint(f); return (u + 0x7fffu + ((u >> 16) & 1u)) >> 16; }
; __device__ __forceinline__ float bf2f(unsigned short b) { return __uint_as_float((unsigned)b << 16); }
; __device__ __forceinline__ unsigned f2bf(float f) { unsigned u = __float_as_uint(f); return (u + 0x7fffu + ((u >> 16) & 1u)) >> 16; }
;     ...
;         for (int d0 = 0; d0 < 4; ++d0) { const float g = bf2f(Gb[(long)orow * ldg + d0 * 32 + r32]); const float sg = g / (1.f + __expf(-g));
;           Yb[(long)orow * ldy + d0 * 32 + r32] = (bf16)f2bf(o[d0][r] * rli * sg); }
	v_lshlrev_b32_e32 v5, 16, v100
	v_mul_f32_e32 v6, 0xbfb8aa3b, v5
	v_exp_f32_e32 v6, v6
	s_nop 0
	v_add_f32_e32 v6, 1.0, v6
	v_div_scale_f32 v7, s[2:3], v6, v6, v5
	v_rcp_f32_e32 v8, v7
	s_nop 0
	v_fma_f32 v9, -v7, v8, 1.0
	v_fmac_f32_e32 v8, v9, v8
	v_div_scale_f32 v9, vcc, v5, v6, v5
	v_mul_f32_e32 v10, v9, v8
	v_fma_f32 v16, -v7, v10, v9
	v_fmac_f32_e32 v10, v16, v8
	v_fma_f32 v7, -v7, v10, v9
	v_div_fmas_f32 v7, v7, v8, v10
	v_div_fixup_f32 v5, v7, v6, v5
	v_mul_f32_e32 v6, v43, v4
	v_mul_f32_e32 v5, v6, v5
	v_bfe_u32 v6, v5, 16, 1
	v_add3_u32 v5, v5, v6, s15
	global_store_short_d16_hi v[0:1], v5, off offset:2112


; __device__ __forceinline__ float bf2f(unsigned short b) { return __uint_as_float((unsigned)b << 16); }
; __device__ __forceinline__ unsigned f2bf(float f) { unsigned u = __float_as_uint(f); return (u + 0x7fffu + ((u >> 16) & 1u)) >> 16; }
; __device__ __forceinline__ float bf2f(unsigned short b) { return __uint_as_float((unsigned)b << 16); }
; __device__ __forceinline__ unsigned f2bf(float f) { unsigned u = __float_as_uint(f); return (u + 0x7fffu + ((u >> 16) & 1u)) >> 16; }
;     ...
;         for (int d0 = 0; d0 < 4; ++d0) { const float g = bf2f(Gb[(long)orow * ldg + d0 * 32 + r32]); const float sg = g / (1.f + __expf(-g));
;           Yb[(long)orow * ldy + d0 * 32 + r32] = (bf16)f2bf(o[d0][r] * rli * sg); }
	v_lshlrev_b32_e32 v5, 16, v101

; __device__ __forceinline__ float bf2f(unsigned short b) { return __uint_as_float((unsigned)b << 16); }
; __device__ __forceinline__ unsigned f2bf(float f) { unsigned u = __float_as_uint(f); return (u + 0x7fffu + ((u >> 16) & 1u)) >> 16; }
; __device__ __forceinline__ float bf2f(unsigned short b) { return __uint_as_float((unsigned)b << 16); }
; __device__ __forceinline__ unsigned f2bf(float f) { unsigned u = __float_as_uint(f); return (u + 0x7fffu + ((u >> 16) & 1u)) >> 16; }
;     ...
;         for (int d0 = 0; d0 < 4; ++d0) { const float g = bf2f(Gb[(long)orow * ldg + d0 * 32 + r32]); const float sg = g / (1.f + __expf(-g));
;           Yb[(long)orow * ldy + d0 * 32 + r32] = (bf16)f2bf(o[d0][r] * rli * sg); }
	v_mul_f32_e32 v6, 0xbfb8aa3b, v5
	v_exp_f32_e32 v6, v6

; __device__ __forceinline__ int crow(int r, int hi) { return (r & 3) + 8 * (r >> 2) + 4 * hi; }
; __device__ __forceinline__ float bf2f(unsigned short b) { return __uint_as_float((unsigned)b << 16); }
; __device__ __forceinline__ unsigned f2bf(float f) { unsigned u = __float_as_uint(f); return (u + 0x7fffu + ((u >> 16) & 1u)) >> 16; }
; __device__ __forceinline__ float bf2f(unsigned short b) { return __uint_as_float((unsigned)b << 16); }
; __device__ __forceinline__ unsigned f2bf(float f) { unsigned u = __float_as_uint(f); return (u + 0x7fffu + ((u >> 16) & 1u)) >> 16; }
;     ...
;   for (int r = 0; r < 16; ++r) { const int orow = wid * QBLK + crow(r, hi); const float rli = __builtin_amdgcn_rcpf(li_l[crow(r, hi)]);
;     if (orow < nvalid) {
;       if constexpr (MODE == 0) {
; #pragma unroll
;         for (int d0 = 0; d0 < 4; ++d0) Of[(long)orow * ldo + d0 * 32 + r32] = o[d0][r] * rli;
;       } else {
; #pragma unroll
;         for (int d0 = 0; d0 < 4; ++d0) { const float g = bf2f(Gb[(long)orow * ldg + d0 * 32 + r32]); const float sg = g / (1.f + __expf(-g));
;           Yb[(long)orow * ldy + d0 * 32 + r32] = (bf16)f2bf(o[d0][r] * rli * sg); }
	v_lshlrev_b32_e32 v2, 16, v102
	v_add_f32_e32 v6, 1.0, v6
	v_div_scale_f32 v7, s[2:3], v6, v6, v5
	v_rcp_f32_e32 v8, v7
	v_mul_f32_e32 v3, 0xbfb8aa3b, v2
	v_exp_f32_e32 v3, v3
	v_fma_f32 v9, -v7, v8, 1.0
	v_fmac_f32_e32 v8, v9, v8
	v_div_scale_f32 v9, vcc, v5, v6, v5
	v_mul_f32_e32 v10, v9, v8
	v_fma_f32 v16, -v7, v10, v9
	v_fmac_f32_e32 v10, v16, v8
	v_fma_f32 v7, -v7, v10, v9
	v_div_fmas_f32 v7, v7, v8, v10
	v_div_fixup_f32 v5, v7, v6, v5
	v_mul_f32_e32 v6, v27, v4
	v_mul_f32_e32 v5, v6, v5
	v_bfe_u32 v6, v5, 16, 1
	v_add3_u32 v5, v5, v6, s15
	v_add_f32_e32 v3, 1.0, v3
	global_store_short_d16_hi v[0:1], v5, off offset:2176
	v_div_scale_f32 v5, s[2:3], v3, v3, v2
	v_rcp_f32_e32 v6, v5
	s_nop 0
	v_fma_f32 v7, -v5, v6, 1.0
	v_fmac_f32_e32 v6, v7, v6
	v_div_scale_f32 v7, vcc, v2, v3, v2
	v_mul_f32_e32 v8, v7, v6
	v_fma_f32 v9, -v5, v8, v7
	v_fmac_f32_e32 v8, v9, v6
	v_fma_f32 v5, -v5, v8, v7
	v_div_fmas_f32 v5, v5, v6, v8
	v_div_fixup_f32 v2, v5, v3, v2
	v_mul_f32_e32 v3, v11, v4
	v_mul_f32_e32 v2, v3, v2
	v_bfe_u32 v3, v2, 16, 1
	v_add3_u32 v2, v2, v3, s15
	global_store_short_d16_hi v[0:1], v2, off offset:2240
.LBB0_605:
	s_or_b64 exec, exec, s[0:1]
	v_or3_b32 v0, v72, v192, 24
	v_cmp_gt_i32_e32 vcc, s96, v0
	s_and_saveexec_b64 s[0:1], vcc
	s_cbranch_execz .LBB0_607
	v_mad_i64_i32 v[2:3], s[2:3], v0, s20, v[66:67]
	global_load_ushort v5, v[2:3], off
	global_load_ushort v100, v[2:3], off offset:64
	global_load_ushort v101, v[2:3], off offset:128
	global_load_ushort v102, v[2:3], off offset:192
	ds_read_b32 v1, v73 offset:96
	s_waitcnt lgkmcnt(0)
	v_rcp_f32_e32 v4, v1
	v_ashrrev_i32_e32 v1, 31, v0
	v_lshlrev_b64 v[0:1], 12, v[0:1]
	v_lshl_add_u64 v[0:1], v[64:65], 0, v[0:1]
	s_waitcnt vmcnt(0)
	v_lshlrev_b32_e32 v5, 16, v5
	v_mul_f32_e32 v6, 0xbfb8aa3b, v5
	v_exp_f32_e32 v6, v6
	s_nop 0
	v_add_f32_e32 v6, 1.0, v6
	v_div_scale_f32 v7, s[2:3], v6, v6, v5
	v_rcp_f32_e32 v8, v7
	s_nop 0
	v_fma_f32 v9, -v7, v8, 1.0
	v_fmac_f32_e32 v8, v9, v8
	v_div_scale_f32 v9, vcc, v5, v6, v5
	v_mul_f32_e32 v10, v9, v8
	v_fma_f32 v11, -v7, v10, v9
	v_fmac_f32_e32 v10, v11, v8
	v_fma_f32 v7, -v7, v10, v9
	v_div_fmas_f32 v7, v7, v8, v10
	v_div_fixup_f32 v5, v7, v6, v5
	v_mul_f32_e32 v6, v60, v4
	v_mul_f32_e32 v5, v6, v5
	v_bfe_u32 v6, v5, 16, 1
	v_add3_u32 v5, v5, v6, s15
	global_store_short_d16_hi v[0:1], v5, off offset:2048


; __device__ __forceinline__ float bf2f(unsigned short b) { return __uint_as_float((unsigned)b << 16); }
; __device__ __forceinline__ unsigned f2bf(float f) { unsigned u = __float_as_uint(f); return (u + 0x7fffu + ((u >> 16) & 1u)) >> 16; }
; __device__ __forceinline__ float bf2f(unsigned short b) { return __uint_as_float((unsigned)b << 16); }
; __device__ __forceinline__ unsigned f2bf(float f) { unsigned u = __float_as_uint(f); return (u + 0x7fffu + ((u >> 16) & 1u)) >> 16; }
;     ...
;         for (int d0 = 0; d0 < 4; ++d0) { const float g = bf2f(Gb[(long)orow * ldg + d0 * 32 + r32]); const float sg = g / (1.f + __expf(-g));
;           Yb[(long)orow * ldy + d0 * 32 + r32] = (bf16)f2bf(o[d0][r] * rli * sg); }
	v_lshlrev_b32_e32 v5, 16, v100
	v_mul_f32_e32 v6, 0xbfb8aa3b, v5
	v_exp_f32_e32 v6, v6
	s_nop 0
	v_add_f32_e32 v6, 1.0, v6
	v_div_scale_f32 v7, s[2:3], v6, v6, v5
	v_rcp_f32_e32 v8, v7
	s_nop 0
	v_fma_f32 v9, -v7, v8, 1.0
	v_fmac_f32_e32 v8, v9, v8
	v_div_scale_f32 v9, vcc, v5, v6, v5
	v_mul_f32_e32 v10, v9, v8
	v_fma_f32 v11, -v7, v10, v9
	v_fmac_f32_e32 v10, v11, v8
	v_fma_f32 v7, -v7, v10, v9
	v_div_fmas_f32 v7, v7, v8, v10
	v_div_fixup_f32 v5, v7, v6, v5
	v_mul_f32_e32 v6, v44, v4
	v_mul_f32_e32 v5, v6, v5
	v_bfe_u32 v6, v5, 16, 1
	v_add3_u32 v5, v5, v6, s15
	global_store_short_d16_hi v[0:1], v5, off offset:2112


; __device__ __forceinline__ float bf2f(unsigned short b) { return __uint_as_float((unsigned)b << 16); }
; __device__ __forceinline__ unsigned f2bf(float f) { unsigned u = __float_as_uint(f); return (u + 0x7fffu + ((u >> 16) & 1u)) >> 16; }
; __device__ __forceinline__ float bf2f(unsigned short b) { return __uint_as_float((unsigned)b << 16); }
; __device__ __forceinline__ unsigned f2bf(float f) { unsigned u = __float_as_uint(f); return (u + 0x7fffu + ((u >> 16) & 1u)) >> 16; }
;     ...
;         for (int d0 = 0; d0 < 4; ++d0) { const float g = bf2f(Gb[(long)orow * ldg + d0 * 32 + r32]); const float sg = g / (1.f + __expf(-g));
;           Yb[(long)orow * ldy + d0 * 32 + r32] = (bf16)f2bf(o[d0][r] * rli * sg); }
	v_lshlrev_b32_e32 v5, 16, v101

; __device__ __forceinline__ float bf2f(unsigned short b) { return __uint_as_float((unsigned)b << 16); }
; __device__ __forceinline__ unsigned f2bf(float f) { unsigned u = __float_as_uint(f); return (u + 0x7fffu + ((u >> 16) & 1u)) >> 16; }
; __device__ __forceinline__ float bf2f(unsigned short b) { return __uint_as_float((unsigned)b << 16); }
; __device__ __forceinline__ unsigned f2bf(float f) { unsigned u = __float_as_uint(f); return (u + 0x7fffu + ((u >> 16) & 1u)) >> 16; }
;     ...
;         for (int d0 = 0; d0 < 4; ++d0) { const float g = bf2f(Gb[(long)orow * ldg + d0 * 32 + r32]); const float sg = g / (1.f + __expf(-g));
;           Yb[(long)orow * ldy + d0 * 32 + r32] = (bf16)f2bf(o[d0][r] * rli * sg); }
	v_mul_f32_e32 v6, 0xbfb8aa3b, v5
	v_exp_f32_e32 v6, v6

; __device__ __forceinline__ int crow(int r, int hi) { return (r & 3) + 8 * (r >> 2) + 4 * hi; }
; __device__ __forceinline__ float bf2f(unsigned short b) { return __uint_as_float((unsigned)b << 16); }
; __device__ __forceinline__ unsigned f2bf(float f) { unsigned u = __float_as_uint(f); return (u + 0x7fffu + ((u >> 16) & 1u)) >> 16; }
; __device__ __forceinline__ float bf2f(unsigned short b) { return __uint_as_float((unsigned)b << 16); }
; __device__ __forceinline__ unsigned f2bf(float f) { unsigned u = __float_as_uint(f); return (u + 0x7fffu + ((u >> 16) & 1u)) >> 16; }
;     ...
;   for (int r = 0; r < 16; ++r) { const int orow = wid * QBLK + crow(r, hi); const float rli = __builtin_amdgcn_rcpf(li_l[crow(r, hi)]);
;     if (orow < nvalid) {
;       if constexpr (MODE == 0) {
; #pragma unroll
;         for (int d0 = 0; d0 < 4; ++d0) Of[(long)orow * ldo + d0 * 32 + r32] = o[d0][r] * rli;
;       } else {
; #pragma unroll
;         for (int d0 = 0; d0 < 4; ++d0) { const float g = bf2f(Gb[(long)orow * ldg + d0 * 32 + r32]); const float sg = g / (1.f + __expf(-g));
;           Yb[(long)orow * ldy + d0 * 32 + r32] = (bf16)f2bf(o[d0][r] * rli * sg); }
	v_lshlrev_b32_e32 v2, 16, v102
	v_add_f32_e32 v6, 1.0, v6
	v_div_scale_f32 v7, s[2:3], v6, v6, v5
	v_rcp_f32_e32 v8, v7
	v_mul_f32_e32 v3, 0xbfb8aa3b, v2
	v_exp_f32_e32 v3, v3
	v_fma_f32 v9, -v7, v8, 1.0
	v_fmac_f32_e32 v8, v9, v8
	v_div_scale_f32 v9, vcc, v5, v6, v5
	v_mul_f32_e32 v10, v9, v8
	v_fma_f32 v11, -v7, v10, v9
	v_fmac_f32_e32 v10, v11, v8
	v_fma_f32 v7, -v7, v10, v9
	v_div_fmas_f32 v7, v7, v8, v10
	v_div_fixup_f32 v5, v7, v6, v5
	v_mul_f32_e32 v6, v28, v4
	v_mul_f32_e32 v5, v6, v5
	v_bfe_u32 v6, v5, 16, 1
	v_add3_u32 v5, v5, v6, s15
	v_add_f32_e32 v3, 1.0, v3
	global_store_short_d16_hi v[0:1], v5, off offset:2176
	v_div_scale_f32 v5, s[2:3], v3, v3, v2
	v_rcp_f32_e32 v6, v5
	s_nop 0
	v_fma_f32 v7, -v5, v6, 1.0
	v_fmac_f32_e32 v6, v7, v6
	v_div_scale_f32 v7, vcc, v2, v3, v2
	v_mul_f32_e32 v8, v7, v6
	v_fma_f32 v9, -v5, v8, v7
	v_fmac_f32_e32 v8, v9, v6
	v_fma_f32 v5, -v5, v8, v7
	v_div_fmas_f32 v5, v5, v6, v8
	v_div_fixup_f32 v2, v5, v3, v2
	v_mul_f32_e32 v3, v12, v4
	v_mul_f32_e32 v2, v3, v2
	v_bfe_u32 v3, v2, 16, 1
	v_add3_u32 v2, v2, v3, s15
	global_store_short_d16_hi v[0:1], v2, off offset:2240
.LBB0_607:
	s_or_b64 exec, exec, s[0:1]
	v_or3_b32 v0, v72, v192, 25
	v_cmp_gt_i32_e32 vcc, s96, v0
	s_and_saveexec_b64 s[0:1], vcc
	s_cbranch_execz .LBB0_609
	v_mad_i64_i32 v[2:3], s[2:3], v0, s20, v[66:67]
	global_load_ushort v5, v[2:3], off
	global_load_ushort v100, v[2:3], off offset:64
	global_load_ushort v101, v[2:3], off offset:128
	global_load_ushort v102, v[2:3], off offset:192
	ds_read_b32 v1, v73 offset:100
	s_waitcnt lgkmcnt(0)
	v_rcp_f32_e32 v4, v1
	v_ashrrev_i32_e32 v1, 31, v0
	v_lshlrev_b64 v[0:1], 12, v[0:1]
	v_lshl_add_u64 v[0:1], v[64:65], 0, v[0:1]
	s_waitcnt vmcnt(0)
	v_lshlrev_b32_e32 v5, 16, v5
	v_mul_f32_e32 v6, 0xbfb8aa3b, v5
	v_exp_f32_e32 v6, v6
	s_nop 0
	v_add_f32_e32 v6, 1.0, v6
	v_div_scale_f32 v7, s[2:3], v6, v6, v5
	v_rcp_f32_e32 v8, v7
	s_nop 0
	v_fma_f32 v9, -v7, v8, 1.0
	v_fmac_f32_e32 v8, v9, v8
	v_div_scale_f32 v9, vcc, v5, v6, v5
	v_mul_f32_e32 v10, v9, v8
	v_fma_f32 v11, -v7, v10, v9
	v_fmac_f32_e32 v10, v11, v8
	v_fma_f32 v7, -v7, v10, v9
	v_div_fmas_f32 v7, v7, v8, v10
	v_div_fixup_f32 v5, v7, v6, v5
	v_mul_f32_e32 v6, v61, v4
	v_mul_f32_e32 v5, v6, v5
	v_bfe_u32 v6, v5, 16, 1
	v_add3_u32 v5, v5, v6, s15
	global_store_short_d16_hi v[0:1], v5, off offset:2048


; __device__ __forceinline__ float bf2f(unsigned short b) { return __uint_as_float((unsigned)b << 16); }
; __device__ __forceinline__ unsigned f2bf(float f) { unsigned u = __float_as_uint(f); return (u + 0x7fffu + ((u >> 16) & 1u)) >> 16; }
; __device__ __forceinline__ float bf2f(unsigned short b) { return __uint_as_float((unsigned)b << 16); }
; __device__ __forceinline__ unsigned f2bf(float f) { unsigned u = __float_as_uint(f); return (u + 0x7fffu + ((u >> 16) & 1u)) >> 16; }
;     ...
;         for (int d0 = 0; d0 < 4; ++d0) { const float g = bf2f(Gb[(long)orow * ldg + d0 * 32 + r32]); const float sg = g / (1.f + __expf(-g));
;           Yb[(long)orow * ldy + d0 * 32 + r32] = (bf16)f2bf(o[d0][r] * rli * sg); }
	v_lshlrev_b32_e32 v5, 16, v100
	v_mul_f32_e32 v6, 0xbfb8aa3b, v5
	v_exp_f32_e32 v6, v6
	s_nop 0
	v_add_f32_e32 v6, 1.0, v6
	v_div_scale_f32 v7, s[2:3], v6, v6, v5
	v_rcp_f32_e32 v8, v7
	s_nop 0
	v_fma_f32 v9, -v7, v8, 1.0
	v_fmac_f32_e32 v8, v9, v8
	v_div_scale_f32 v9, vcc, v5, v6, v5
	v_mul_f32_e32 v10, v9, v8
	v_fma_f32 v11, -v7, v10, v9
	v_fmac_f32_e32 v10, v11, v8
	v_fma_f32 v7, -v7, v10, v9
	v_div_fmas_f32 v7, v7, v8, v10
	v_div_fixup_f32 v5, v7, v6, v5
	v_mul_f32_e32 v6, v45, v4
	v_mul_f32_e32 v5, v6, v5
	v_bfe_u32 v6, v5, 16, 1
	v_add3_u32 v5, v5, v6, s15
	global_store_short_d16_hi v[0:1], v5, off offset:2112


; __device__ __forceinline__ float bf2f(unsigned short b) { return __uint_as_float((unsigned)b << 16); }
; __device__ __forceinline__ unsigned f2bf(float f) { unsigned u = __float_as_uint(f); return (u + 0x7fffu + ((u >> 16) & 1u)) >> 16; }
; __device__ __forceinline__ float bf2f(unsigned short b) { return __uint_as_float((unsigned)b << 16); }
; __device__ __forceinline__ unsigned f2bf(float f) { unsigned u = __float_as_uint(f); return (u + 0x7fffu + ((u >> 16) & 1u)) >> 16; }
;     ...
;         for (int d0 = 0; d0 < 4; ++d0) { const float g = bf2f(Gb[(long)orow * ldg + d0 * 32 + r32]); const float sg = g / (1.f + __expf(-g));
;           Yb[(long)orow * ldy + d0 * 32 + r32] = (bf16)f2bf(o[d0][r] * rli * sg); }
	v_lshlrev_b32_e32 v5, 16, v101

; __device__ __forceinline__ float bf2f(unsigned short b) { return __uint_as_float((unsigned)b << 16); }
; __device__ __forceinline__ unsigned f2bf(float f) { unsigned u = __float_as_uint(f); return (u + 0x7fffu + ((u >> 16) & 1u)) >> 16; }
; __device__ __forceinline__ float bf2f(unsigned short b) { return __uint_as_float((unsigned)b << 16); }
; __device__ __forceinline__ unsigned f2bf(float f) { unsigned u = __float_as_uint(f); return (u + 0x7fffu + ((u >> 16) & 1u)) >> 16; }
;     ...
;         for (int d0 = 0; d0 < 4; ++d0) { const float g = bf2f(Gb[(long)orow * ldg + d0 * 32 + r32]); const float sg = g / (1.f + __expf(-g));
;           Yb[(long)orow * ldy + d0 * 32 + r32] = (bf16)f2bf(o[d0][r] * rli * sg); }
	v_mul_f32_e32 v6, 0xbfb8aa3b, v5
	v_exp_f32_e32 v6, v6

; __device__ __forceinline__ int crow(int r, int hi) { return (r & 3) + 8 * (r >> 2) + 4 * hi; }
; __device__ __forceinline__ float bf2f(unsigned short b) { return __uint_as_float((unsigned)b << 16); }
; __device__ __forceinline__ unsigned f2bf(float f) { unsigned u = __float_as_uint(f); return (u + 0x7fffu + ((u >> 16) & 1u)) >> 16; }
; __device__ __forceinline__ float bf2f(unsigned short b) { return __uint_as_float((unsigned)b << 16); }
; __device__ __forceinline__ unsigned f2bf(float f) { unsigned u = __float_as_uint(f); return (u + 0x7fffu + ((u >> 16) & 1u)) >> 16; }
;     ...
;   for (int r = 0; r < 16; ++r) { const int orow = wid * QBLK + crow(r, hi); const float rli = __builtin_amdgcn_rcpf(li_l[crow(r, hi)]);
;     if (orow < nvalid) {
;       if constexpr (MODE == 0) {
; #pragma unroll
;         for (int d0 = 0; d0 < 4; ++d0) Of[(long)orow * ldo + d0 * 32 + r32] = o[d0][r] * rli;
;       } else {
; #pragma unroll
;         for (int d0 = 0; d0 < 4; ++d0) { const float g = bf2f(Gb[(long)orow * ldg + d0 * 32 + r32]); const float sg = g / (1.f + __expf(-g));
;           Yb[(long)orow * ldy + d0 * 32 + r32] = (bf16)f2bf(o[d0][r] * rli * sg); }
	v_lshlrev_b32_e32 v2, 16, v102
	v_add_f32_e32 v6, 1.0, v6
	v_div_scale_f32 v7, s[2:3], v6, v6, v5
	v_rcp_f32_e32 v8, v7
	v_mul_f32_e32 v3, 0xbfb8aa3b, v2
	v_exp_f32_e32 v3, v3
	v_fma_f32 v9, -v7, v8, 1.0
	v_fmac_f32_e32 v8, v9, v8
	v_div_scale_f32 v9, vcc, v5, v6, v5
	v_mul_f32_e32 v10, v9, v8
	v_fma_f32 v11, -v7, v10, v9
	v_fmac_f32_e32 v10, v11, v8
	v_fma_f32 v7, -v7, v10, v9
	v_div_fmas_f32 v7, v7, v8, v10
	v_div_fixup_f32 v5, v7, v6, v5
	v_mul_f32_e32 v6, v29, v4
	v_mul_f32_e32 v5, v6, v5
	v_bfe_u32 v6, v5, 16, 1
	v_add3_u32 v5, v5, v6, s15
	v_add_f32_e32 v3, 1.0, v3
	global_store_short_d16_hi v[0:1], v5, off offset:2176
	v_div_scale_f32 v5, s[2:3], v3, v3, v2
	v_rcp_f32_e32 v6, v5
	s_nop 0
	v_fma_f32 v7, -v5, v6, 1.0
	v_fmac_f32_e32 v6, v7, v6
	v_div_scale_f32 v7, vcc, v2, v3, v2
	v_mul_f32_e32 v8, v7, v6
	v_fma_f32 v9, -v5, v8, v7
	v_fmac_f32_e32 v8, v9, v6
	v_fma_f32 v5, -v5, v8, v7
	v_div_fmas_f32 v5, v5, v6, v8
	v_div_fixup_f32 v2, v5, v3, v2
	v_mul_f32_e32 v3, v13, v4
	v_mul_f32_e32 v2, v3, v2
	v_bfe_u32 v3, v2, 16, 1
	v_add3_u32 v2, v2, v3, s15
	global_store_short_d16_hi v[0:1], v2, off offset:2240
.LBB0_609:
	s_or_b64 exec, exec, s[0:1]
	v_or3_b32 v0, v72, v192, 26
	v_cmp_gt_i32_e32 vcc, s96, v0
	s_and_saveexec_b64 s[0:1], vcc
	s_cbranch_execz .LBB0_611
	v_mad_i64_i32 v[2:3], s[2:3], v0, s20, v[66:67]
	global_load_ushort v5, v[2:3], off
	global_load_ushort v100, v[2:3], off offset:64
	global_load_ushort v101, v[2:3], off offset:128
	global_load_ushort v102, v[2:3], off offset:192
	ds_read_b32 v1, v73 offset:104
	s_waitcnt lgkmcnt(0)
	v_rcp_f32_e32 v4, v1
	v_ashrrev_i32_e32 v1, 31, v0
	v_lshlrev_b64 v[0:1], 12, v[0:1]
	v_lshl_add_u64 v[0:1], v[64:65], 0, v[0:1]
	s_waitcnt vmcnt(0)
	v_lshlrev_b32_e32 v5, 16, v5
	v_mul_f32_e32 v6, 0xbfb8aa3b, v5
	v_exp_f32_e32 v6, v6
	s_nop 0
	v_add_f32_e32 v6, 1.0, v6
	v_div_scale_f32 v7, s[2:3], v6, v6, v5
	v_rcp_f32_e32 v8, v7
	s_nop 0
	v_fma_f32 v9, -v7, v8, 1.0
	v_fmac_f32_e32 v8, v9, v8
	v_div_scale_f32 v9, vcc, v5, v6, v5
	v_mul_f32_e32 v10, v9, v8
	v_fma_f32 v11, -v7, v10, v9
	v_fmac_f32_e32 v10, v11, v8
	v_fma_f32 v7, -v7, v10, v9
	v_div_fmas_f32 v7, v7, v8, v10
	v_div_fixup_f32 v5, v7, v6, v5
	v_mul_f32_e32 v6, v62, v4
	v_mul_f32_e32 v5, v6, v5
	v_bfe_u32 v6, v5, 16, 1
	v_add3_u32 v5, v5, v6, s15
	global_store_short_d16_hi v[0:1], v5, off offset:2048


; __device__ __forceinline__ float bf2f(unsigned short b) { return __uint_as_float((unsigned)b << 16); }
; __device__ __forceinline__ unsigned f2bf(float f) { unsigned u = __float_as_uint(f); return (u + 0x7fffu + ((u >> 16) & 1u)) >> 16; }
; __device__ __forceinline__ float bf2f(unsigned short b) { return __uint_as_float((unsigned)b << 16); }
; __device__ __forceinline__ unsigned f2bf(float f) { unsigned u = __float_as_uint(f); return (u + 0x7fffu + ((u >> 16) & 1u)) >> 16; }
;     ...
;         for (int d0 = 0; d0 < 4; ++d0) { const float g = bf2f(Gb[(long)orow * ldg + d0 * 32 + r32]); const float sg = g / (1.f + __expf(-g));
;           Yb[(long)orow * ldy + d0 * 32 + r32] = (bf16)f2bf(o[d0][r] * rli * sg); }
	v_lshlrev_b32_e32 v5, 16, v100
	v_mul_f32_e32 v6, 0xbfb8aa3b, v5
	v_exp_f32_e32 v6, v6
	s_nop 0
	v_add_f32_e32 v6, 1.0, v6
	v_div_scale_f32 v7, s[2:3], v6, v6, v5
	v_rcp_f32_e32 v8, v7
	s_nop 0
	v_fma_f32 v9, -v7, v8, 1.0
	v_fmac_f32_e32 v8, v9, v8
	v_div_scale_f32 v9, vcc, v5, v6, v5
	v_mul_f32_e32 v10, v9, v8
	v_fma_f32 v11, -v7, v10, v9
	v_fmac_f32_e32 v10, v11, v8
	v_fma_f32 v7, -v7, v10, v9
	v_div_fmas_f32 v7, v7, v8, v10
	v_div_fixup_f32 v5, v7, v6, v5
	v_mul_f32_e32 v6, v46, v4
	v_mul_f32_e32 v5, v6, v5
	v_bfe_u32 v6, v5, 16, 1
	v_add3_u32 v5, v5, v6, s15
	global_store_short_d16_hi v[0:1], v5, off offset:2112


; __device__ __forceinline__ float bf2f(unsigned short b) { return __uint_as_float((unsigned)b << 16); }
; __device__ __forceinline__ unsigned f2bf(float f) { unsigned u = __float_as_uint(f); return (u + 0x7fffu + ((u >> 16) & 1u)) >> 16; }
; __device__ __forceinline__ float bf2f(unsigned short b) { return __uint_as_float((unsigned)b << 16); }
; __device__ __forceinline__ unsigned f2bf(float f) { unsigned u = __float_as_uint(f); return (u + 0x7fffu + ((u >> 16) & 1u)) >> 16; }
;     ...
;         for (int d0 = 0; d0 < 4; ++d0) { const float g = bf2f(Gb[(long)orow * ldg + d0 * 32 + r32]); const float sg = g / (1.f + __expf(-g));
;           Yb[(long)orow * ldy + d0 * 32 + r32] = (bf16)f2bf(o[d0][r] * rli * sg); }
	v_lshlrev_b32_e32 v5, 16, v101

; __device__ __forceinline__ float bf2f(unsigned short b) { return __uint_as_float((unsigned)b << 16); }
; __device__ __forceinline__ unsigned f2bf(float f) { unsigned u = __float_as_uint(f); return (u + 0x7fffu + ((u >> 16) & 1u)) >> 16; }
; __device__ __forceinline__ float bf2f(unsigned short b) { return __uint_as_float((unsigned)b << 16); }
; __device__ __forceinline__ unsigned f2bf(float f) { unsigned u = __float_as_uint(f); return (u + 0x7fffu + ((u >> 16) & 1u)) >> 16; }
;     ...
;         for (int d0 = 0; d0 < 4; ++d0) { const float g = bf2f(Gb[(long)orow * ldg + d0 * 32 + r32]); const float sg = g / (1.f + __expf(-g));
;           Yb[(long)orow * ldy + d0 * 32 + r32] = (bf16)f2bf(o[d0][r] * rli * sg); }
	v_mul_f32_e32 v6, 0xbfb8aa3b, v5
	v_exp_f32_e32 v6, v6

; __device__ __forceinline__ int crow(int r, int hi) { return (r & 3) + 8 * (r >> 2) + 4 * hi; }
; __device__ __forceinline__ float bf2f(unsigned short b) { return __uint_as_float((unsigned)b << 16); }
; __device__ __forceinline__ unsigned f2bf(float f) { unsigned u = __float_as_uint(f); return (u + 0x7fffu + ((u >> 16) & 1u)) >> 16; }
; __device__ __forceinline__ float bf2f(unsigned short b) { return __uint_as_float((unsigned)b << 16); }
; __device__ __forceinline__ unsigned f2bf(float f) { unsigned u = __float_as_uint(f); return (u + 0x7fffu + ((u >> 16) & 1u)) >> 16; }
;     ...
;   for (int r = 0; r < 16; ++r) { const int orow = wid * QBLK + crow(r, hi); const float rli = __builtin_amdgcn_rcpf(li_l[crow(r, hi)]);
;     if (orow < nvalid) {
;       if constexpr (MODE == 0) {
; #pragma unroll
;         for (int d0 = 0; d0 < 4; ++d0) Of[(long)orow * ldo + d0 * 32 + r32] = o[d0][r] * rli;
;       } else {
; #pragma unroll
;         for (int d0 = 0; d0 < 4; ++d0) { const float g = bf2f(Gb[(long)orow * ldg + d0 * 32 + r32]); const float sg = g / (1.f + __expf(-g));
;           Yb[(long)orow * ldy + d0 * 32 + r32] = (bf16)f2bf(o[d0][r] * rli * sg); }
	v_lshlrev_b32_e32 v2, 16, v102
	v_add_f32_e32 v6, 1.0, v6
	v_div_scale_f32 v7, s[2:3], v6, v6, v5
	v_rcp_f32_e32 v8, v7
	v_mul_f32_e32 v3, 0xbfb8aa3b, v2
	v_exp_f32_e32 v3, v3
	v_fma_f32 v9, -v7, v8, 1.0
	v_fmac_f32_e32 v8, v9, v8
	v_div_scale_f32 v9, vcc, v5, v6, v5
	v_mul_f32_e32 v10, v9, v8
	v_fma_f32 v11, -v7, v10, v9
	v_fmac_f32_e32 v10, v11, v8
	v_fma_f32 v7, -v7, v10, v9
	v_div_fmas_f32 v7, v7, v8, v10
	v_div_fixup_f32 v5, v7, v6, v5
	v_mul_f32_e32 v6, v30, v4
	v_mul_f32_e32 v5, v6, v5
	v_bfe_u32 v6, v5, 16, 1
	v_add3_u32 v5, v5, v6, s15
	v_add_f32_e32 v3, 1.0, v3
	global_store_short_d16_hi v[0:1], v5, off offset:2176
	v_div_scale_f32 v5, s[2:3], v3, v3, v2
	v_rcp_f32_e32 v6, v5
	s_nop 0
	v_fma_f32 v7, -v5, v6, 1.0
	v_fmac_f32_e32 v6, v7, v6
	v_div_scale_f32 v7, vcc, v2, v3, v2
	v_mul_f32_e32 v8, v7, v6
	v_fma_f32 v9, -v5, v8, v7
	v_fmac_f32_e32 v8, v9, v6
	v_fma_f32 v5, -v5, v8, v7
	v_div_fmas_f32 v5, v5, v6, v8
	v_div_fixup_f32 v2, v5, v3, v2
	v_mul_f32_e32 v3, v14, v4
	v_mul_f32_e32 v2, v3, v2
	v_bfe_u32 v3, v2, 16, 1
	v_add3_u32 v2, v2, v3, s15
	global_store_short_d16_hi v[0:1], v2, off offset:2240
.LBB0_611:
	s_or_b64 exec, exec, s[0:1]
	v_or3_b32 v0, v72, v192, 27
	v_cmp_gt_i32_e32 vcc, s96, v0
	s_and_saveexec_b64 s[0:1], vcc
	s_cbranch_execz .LBB0_613
	v_mad_i64_i32 v[2:3], s[2:3], v0, s20, v[66:67]
	global_load_ushort v5, v[2:3], off
	global_load_ushort v100, v[2:3], off offset:64
	global_load_ushort v101, v[2:3], off offset:128
	global_load_ushort v102, v[2:3], off offset:192
	ds_read_b32 v1, v73 offset:108
	s_waitcnt lgkmcnt(0)
	v_rcp_f32_e32 v4, v1
	v_ashrrev_i32_e32 v1, 31, v0
	v_lshlrev_b64 v[0:1], 12, v[0:1]
	v_lshl_add_u64 v[0:1], v[64:65], 0, v[0:1]
	s_waitcnt vmcnt(0)
	v_lshlrev_b32_e32 v5, 16, v5
	v_mul_f32_e32 v6, 0xbfb8aa3b, v5
	v_exp_f32_e32 v6, v6
	s_nop 0
	v_add_f32_e32 v6, 1.0, v6
	v_div_scale_f32 v7, s[2:3], v6, v6, v5
	v_rcp_f32_e32 v8, v7
	s_nop 0
	v_fma_f32 v9, -v7, v8, 1.0
	v_fmac_f32_e32 v8, v9, v8
	v_div_scale_f32 v9, vcc, v5, v6, v5
	v_mul_f32_e32 v10, v9, v8
	v_fma_f32 v11, -v7, v10, v9
	v_fmac_f32_e32 v10, v11, v8
	v_fma_f32 v7, -v7, v10, v9
	v_div_fmas_f32 v7, v7, v8, v10
	v_div_fixup_f32 v5, v7, v6, v5
	v_mul_f32_e32 v6, v63, v4
	v_mul_f32_e32 v5, v6, v5
	v_bfe_u32 v6, v5, 16, 1
	v_add3_u32 v5, v5, v6, s15
	global_store_short_d16_hi v[0:1], v5, off offset:2048


; __device__ __forceinline__ float bf2f(unsigned short b) { return __uint_as_float((unsigned)b << 16); }
; __device__ __forceinline__ unsigned f2bf(float f) { unsigned u = __float_as_uint(f); return (u + 0x7fffu + ((u >> 16) & 1u)) >> 16; }
; __device__ __forceinline__ float bf2f(unsigned short b) { return __uint_as_float((unsigned)b << 16); }
; __device__ __forceinline__ unsigned f2bf(float f) { unsigned u = __float_as_uint(f); return (u + 0x7fffu + ((u >> 16) & 1u)) >> 16; }
;     ...
;         for (int d0 = 0; d0 < 4; ++d0) { const float g = bf2f(Gb[(long)orow * ldg + d0 * 32 + r32]); const float sg = g / (1.f + __expf(-g));
;           Yb[(long)orow * ldy + d0 * 32 + r32] = (bf16)f2bf(o[d0][r] * rli * sg); }
	v_lshlrev_b32_e32 v5, 16, v100
	v_mul_f32_e32 v6, 0xbfb8aa3b, v5
	v_exp_f32_e32 v6, v6
	s_nop 0
	v_add_f32_e32 v6, 1.0, v6
	v_div_scale_f32 v7, s[2:3], v6, v6, v5
	v_rcp_f32_e32 v8, v7
	s_nop 0
	v_fma_f32 v9, -v7, v8, 1.0
	v_fmac_f32_e32 v8, v9, v8
	v_div_scale_f32 v9, vcc, v5, v6, v5
	v_mul_f32_e32 v10, v9, v8
	v_fma_f32 v11, -v7, v10, v9
	v_fmac_f32_e32 v10, v11, v8
	v_fma_f32 v7, -v7, v10, v9
	v_div_fmas_f32 v7, v7, v8, v10
	v_div_fixup_f32 v5, v7, v6, v5
	v_mul_f32_e32 v6, v47, v4
	v_mul_f32_e32 v5, v6, v5
	v_bfe_u32 v6, v5, 16, 1
	v_add3_u32 v5, v5, v6, s15
	global_store_short_d16_hi v[0:1], v5, off offset:2112


; __device__ __forceinline__ float bf2f(unsigned short b) { return __uint_as_float((unsigned)b << 16); }
; __device__ __forceinline__ unsigned f2bf(float f) { unsigned u = __float_as_uint(f); return (u + 0x7fffu + ((u >> 16) & 1u)) >> 16; }
; __device__ __forceinline__ float bf2f(unsigned short b) { return __uint_as_float((unsigned)b << 16); }
; __device__ __forceinline__ unsigned f2bf(float f) { unsigned u = __float_as_uint(f); return (u + 0x7fffu + ((u >> 16) & 1u)) >> 16; }
;     ...
;         for (int d0 = 0; d0 < 4; ++d0) { const float g = bf2f(Gb[(long)orow * ldg + d0 * 32 + r32]); const float sg = g / (1.f + __expf(-g));
;           Yb[(long)orow * ldy + d0 * 32 + r32] = (bf16)f2bf(o[d0][r] * rli * sg); }
	v_lshlrev_b32_e32 v5, 16, v101

; __device__ __forceinline__ float bf2f(unsigned short b) { return __uint_as_float((unsigned)b << 16); }
; __device__ __forceinline__ unsigned f2bf(float f) { unsigned u = __float_as_uint(f); return (u + 0x7fffu + ((u >> 16) & 1u)) >> 16; }
; __device__ __forceinline__ float bf2f(unsigned short b) { return __uint_as_float((unsigned)b << 16); }
; __device__ __forceinline__ unsigned f2bf(float f) { unsigned u = __float_as_uint(f); return (u + 0x7fffu + ((u >> 16) & 1u)) >> 16; }
;     ...
;         for (int d0 = 0; d0 < 4; ++d0) { const float g = bf2f(Gb[(long)orow * ldg + d0 * 32 + r32]); const float sg = g / (1.f + __expf(-g));
;           Yb[(long)orow * ldy + d0 * 32 + r32] = (bf16)f2bf(o[d0][r] * rli * sg); }
	v_mul_f32_e32 v6, 0xbfb8aa3b, v5
	v_exp_f32_e32 v6, v6

; __device__ __forceinline__ float bf2f(unsigned short b) { return __uint_as_float((unsigned)b << 16); }
; __device__ __forceinline__ unsigned f2bf(float f) { unsigned u = __float_as_uint(f); return (u + 0x7fffu + ((u >> 16) & 1u)) >> 16; }
; __device__ __forceinline__ float bf2f(unsigned short b) { return __uint_as_float((unsigned)b << 16); }
; __device__ __forceinline__ unsigned f2bf(float f) { unsigned u = __float_as_uint(f); return (u + 0x7fffu + ((u >> 16) & 1u)) >> 16; }
;     ...
;         for (int d0 = 0; d0 < 4; ++d0) { const float g = bf2f(Gb[(long)orow * ldg + d0 * 32 + r32]); const float sg = g / (1.f + __expf(-g));
;           Yb[(long)orow * ldy + d0 * 32 + r32] = (bf16)f2bf(o[d0][r] * rli * sg); }
	v_lshlrev_b32_e32 v2, 16, v102
	v_add_f32_e32 v6, 1.0, v6
	v_div_scale_f32 v7, s[2:3], v6, v6, v5
	v_rcp_f32_e32 v8, v7
	v_mul_f32_e32 v3, 0xbfb8aa3b, v2
	v_exp_f32_e32 v3, v3
	v_fma_f32 v9, -v7, v8, 1.0
	v_fmac_f32_e32 v8, v9, v8
	v_div_scale_f32 v9, vcc, v5, v6, v5
	v_mul_f32_e32 v10, v9, v8
	v_fma_f32 v11, -v7, v10, v9
	v_fmac_f32_e32 v10, v11, v8
	v_fma_f32 v7, -v7, v10, v9
	v_div_fmas_f32 v7, v7, v8, v10
	v_div_fixup_f32 v5, v7, v6, v5
	v_mul_f32_e32 v6, v31, v4
	v_mul_f32_e32 v5, v6, v5
	v_bfe_u32 v6, v5, 16, 1
	v_add3_u32 v5, v5, v6, s15
	v_add_f32_e32 v3, 1.0, v3
	global_store_short_d16_hi v[0:1], v5, off offset:2176
	v_div_scale_f32 v5, s[2:3], v3, v3, v2
	v_rcp_f32_e32 v6, v5
	s_nop 0
	v_fma_f32 v7, -v5, v6, 1.0
	v_fmac_f32_e32 v6, v7, v6
	v_div_scale_f32 v7, vcc, v2, v3, v2
	v_mul_f32_e32 v8, v7, v6
	v_fma_f32 v9, -v5, v8, v7
	v_fmac_f32_e32 v8, v9, v6
	v_fma_f32 v5, -v5, v8, v7
	v_div_fmas_f32 v5, v5, v6, v8
	v_div_fixup_f32 v2, v5, v3, v2
	v_mul_f32_e32 v3, v15, v4
	v_mul_f32_e32 v2, v3, v2
	v_bfe_u32 v3, v2, 16, 1
	v_add3_u32 v2, v2, v3, s15
	global_store_short_d16_hi v[0:1], v2, off offset:2240
